# hoisted serialized RMW epilogue loads (ssd_p3 z, GLU, fnet) into batched prefetch; bit-identical math
# speedup vs baseline: 1.0440x; 1.0440x over previous
.LBB0_174:
	s_cmp_ge_i32 s20, s19
	s_mov_b64 s[0:1], -1
	s_cbranch_scc0 .LBB0_210
	v_readlane_b32 s0, v254, 56
	s_cmp_ge_i32 s20, s0
	s_mov_b64 s[0:1], -1
	s_cbranch_scc0 .LBB0_179
	v_readlane_b32 s0, v254, 60
	s_add_i32 s0, s20, s0
	s_ashr_i32 s0, s0, 2
	s_cmpk_gt_i32 s0, 0x7f
	v_readlane_b32 s4, v254, 47
	s_cselect_b64 s[2:3], -1, 0
	v_readlane_b32 s5, v254, 48
	s_and_b64 s[2:3], s[4:5], s[2:3]
	s_and_b64 vcc, exec, s[2:3]
	s_cbranch_vccnz .LBB0_178
	v_mov_b32_e32 v52, v0
	s_lshl_b32 s1, s0, 7
	s_lshl_b32 s0, s20, 7
	s_and_b32 s0, s0, 0x180
	v_ashrrev_i32_e32 v36, 3, v52
	s_waitcnt vmcnt(0)
	v_add_u32_e32 v2, s0, v36
	v_ashrrev_i32_e32 v3, 31, v2
	v_lshlrev_b32_e32 v4, 3, v52
	v_readlane_b32 s2, v253, 33
	v_lshlrev_b64 v[2:3], 10, v[2:3]
	v_and_b32_e32 v5, 56, v4
	v_readlane_b32 s3, v253, 34
	v_add_u32_e32 v118, s1, v36
	v_lshlrev_b32_e32 v130, 1, v5
	v_lshl_add_u64 v[2:3], s[2:3], 0, v[2:3]
	v_bfe_u32 v157, v4, 4, 2
	v_lshl_add_u64 v[110:111], v[2:3], 0, v[130:131]
	v_mul_u32_u24_e32 v130, 0x4400, v157
	v_ashrrev_i32_e32 v119, 31, v118
	v_lshl_add_u64 v[2:3], v[130:131], 0, v[118:119]
	v_readlane_b32 s2, v253, 57
	v_lshlrev_b64 v[2:3], 5, v[2:3]
	v_readlane_b32 s3, v253, 58
	v_lshlrev_b32_e32 v4, 4, v52
	v_add_u32_e32 v122, 32, v118
	v_lshl_add_u64 v[2:3], s[2:3], 0, v[2:3]
	v_and_b32_e32 v120, 16, v4
	v_mov_b32_e32 v121, v131
	v_ashrrev_i32_e32 v123, 31, v122
	v_lshl_add_u64 v[34:35], v[2:3], 0, v[120:121]
	v_lshl_add_u64 v[2:3], v[130:131], 0, v[122:123]
	v_lshlrev_b64 v[2:3], 5, v[2:3]
	v_add_u32_e32 v124, 64, v118
	v_lshl_add_u64 v[2:3], s[2:3], 0, v[2:3]
	v_ashrrev_i32_e32 v125, 31, v124
	v_lshl_add_u64 v[38:39], v[2:3], 0, v[120:121]
	v_lshl_add_u64 v[2:3], v[130:131], 0, v[124:125]
	v_lshlrev_b64 v[2:3], 5, v[2:3]
	v_add_u32_e32 v126, 0x60, v118
	v_lshl_add_u64 v[2:3], s[2:3], 0, v[2:3]
	v_ashrrev_i32_e32 v127, 31, v126
	v_lshl_add_u64 v[42:43], v[2:3], 0, v[120:121]
	v_lshl_add_u64 v[2:3], v[130:131], 0, v[126:127]
	s_mov_b32 s4, 0x8000
	v_lshlrev_b64 v[2:3], 5, v[2:3]
	v_add_co_u32_e32 v112, vcc, s4, v110
	v_lshl_add_u64 v[2:3], s[2:3], 0, v[2:3]
	s_nop 0
	v_addc_co_u32_e32 v113, vcc, 0, v111, vcc
	s_mov_b32 s4, 0x10000
	v_lshl_add_u64 v[48:49], v[2:3], 0, v[120:121]
	v_add_co_u32_e32 v114, vcc, s4, v110
	s_movk_i32 s4, 0x4400
	v_mov_b32_e32 v2, 0x11000
	v_mad_u32_u24 v130, v157, s4, v2
	v_lshl_add_u64 v[2:3], v[130:131], 0, v[118:119]
	v_lshlrev_b64 v[2:3], 5, v[2:3]
	v_lshl_add_u64 v[2:3], s[2:3], 0, v[2:3]
	v_lshl_add_u64 v[46:47], v[2:3], 0, v[120:121]
	v_lshl_add_u64 v[2:3], v[130:131], 0, v[122:123]
	v_lshlrev_b64 v[2:3], 5, v[2:3]
	v_lshl_add_u64 v[2:3], s[2:3], 0, v[2:3]
	v_lshl_add_u64 v[50:51], v[2:3], 0, v[120:121]
	v_lshl_add_u64 v[2:3], v[130:131], 0, v[124:125]
	v_lshlrev_b64 v[2:3], 5, v[2:3]
	v_lshrrev_b32_e32 v53, 4, v52
	v_lshl_add_u64 v[2:3], s[2:3], 0, v[2:3]
	v_xor_b32_e32 v37, v53, v52
	v_addc_co_u32_e32 v115, vcc, 0, v111, vcc
	v_lshl_add_u64 v[54:55], v[2:3], 0, v[120:121]
	v_lshl_add_u64 v[2:3], v[130:131], 0, v[126:127]
	v_add_co_u32_e32 v116, vcc, s28, v110
	v_lshlrev_b64 v[2:3], 5, v[2:3]
	v_lshlrev_b32_e32 v37, 4, v37
	v_addc_co_u32_e32 v117, vcc, 0, v111, vcc
	v_lshl_add_u64 v[2:3], s[2:3], 0, v[2:3]
	v_and_b32_e32 v37, 0x70, v37
	v_and_b32_e32 v1, 15, v52
	v_bfe_u32 v137, v52, 4, 2
	global_load_dwordx4 v[18:21], v[110:111], off
	global_load_dwordx4 v[22:25], v[112:113], off
	global_load_dwordx4 v[26:29], v[114:115], off
	global_load_dwordx4 v[30:33], v[116:117], off
	v_lshl_add_u64 v[58:59], v[2:3], 0, v[120:121]
	global_load_dwordx4 v[2:5], v[110:111], off offset:128
	global_load_dwordx4 v[6:9], v[112:113], off offset:128
	global_load_dwordx4 v[10:13], v[114:115], off offset:128
	global_load_dwordx4 v[14:17], v[116:117], off offset:128
	v_lshl_or_b32 v152, v36, 7, v37
	global_load_dwordx4 v[34:37], v[34:35], off
	s_nop 0
	global_load_dwordx4 v[38:41], v[38:39], off
	s_nop 0
	global_load_dwordx4 v[42:45], v[42:43], off
	s_nop 0
	global_load_dwordx4 v[62:65], v[48:49], off
	v_bfe_u32 v48, v52, 1, 3
	v_bfe_u32 v133, v52, 6, 1
	v_ashrrev_i32_e32 v134, 7, v52
	v_bitop3_b32 v49, v53, v48, 3 bitop3:0x6c
	v_lshlrev_b32_e32 v52, 7, v1
	v_bitop3_b32 v48, v137, v48, 4 bitop3:0x36
	v_lshl_or_b32 v53, v134, 13, v52
	v_lshl_or_b32 v52, v133, 13, v52
	v_lshlrev_b32_e32 v48, 4, v48
	v_or_b32_e32 v153, v48, v53
	v_or_b32_e32 v154, v48, v52
	v_mov_b32_e32 v48, 0x22000
	v_lshlrev_b32_e32 v49, 4, v49
	v_mad_u32_u24 v130, v157, s4, v48
	v_or_b32_e32 v155, v49, v53
	v_or_b32_e32 v156, v49, v52
	v_lshl_add_u64 v[48:49], v[130:131], 0, v[118:119]
	v_lshlrev_b64 v[48:49], 5, v[48:49]
	v_lshl_add_u64 v[48:49], s[2:3], 0, v[48:49]
	v_lshl_add_u64 v[102:103], v[48:49], 0, v[120:121]
	v_lshl_add_u64 v[48:49], v[130:131], 0, v[122:123]
	v_lshlrev_b64 v[48:49], 5, v[48:49]
	v_lshl_add_u64 v[48:49], s[2:3], 0, v[48:49]
	v_lshl_add_u64 v[104:105], v[48:49], 0, v[120:121]
	v_lshl_add_u64 v[48:49], v[130:131], 0, v[124:125]
	v_lshlrev_b64 v[48:49], 5, v[48:49]
	v_lshl_add_u64 v[48:49], s[2:3], 0, v[48:49]
	v_lshl_add_u64 v[106:107], v[48:49], 0, v[120:121]
	v_lshl_add_u64 v[48:49], v[130:131], 0, v[126:127]
	v_lshlrev_b64 v[48:49], 5, v[48:49]
	v_lshl_add_u64 v[48:49], s[2:3], 0, v[48:49]
	v_lshl_add_u64 v[108:109], v[48:49], 0, v[120:121]
	global_load_dwordx4 v[46:49], v[46:47], off
	s_nop 0
	global_load_dwordx4 v[50:53], v[50:51], off
	s_nop 0
	global_load_dwordx4 v[54:57], v[54:55], off
	s_nop 0
	global_load_dwordx4 v[58:61], v[58:59], off
	s_waitcnt vmcnt(63) expcnt(7) lgkmcnt(15)
	s_barrier
	s_waitcnt vmcnt(7)
	ds_write_b128 v152, v[34:37]
	s_waitcnt vmcnt(6)
	ds_write_b128 v152, v[38:41] offset:4096
	s_waitcnt vmcnt(5)
	ds_write_b128 v152, v[42:45] offset:8192
	s_waitcnt vmcnt(4)
	ds_write_b128 v152, v[62:65] offset:12288
	ds_write_b128 v152, v[18:21] offset:32768
	ds_write_b128 v152, v[22:25] offset:36864
	ds_write_b128 v152, v[26:29] offset:40960
	ds_write_b128 v152, v[30:33] offset:45056
	s_waitcnt lgkmcnt(0)
	s_barrier
	global_load_dwordx4 v[30:33], v[110:111], off offset:256
	global_load_dwordx4 v[34:37], v[112:113], off offset:256
	global_load_dwordx4 v[38:41], v[114:115], off offset:256
	global_load_dwordx4 v[42:45], v[116:117], off offset:256
	ds_read_b128 v[18:21], v155
	ds_read_b128 v[22:25], v156 offset:32768
	ds_read_b128 v[26:29], v155 offset:2048
	ds_read_b128 v[62:65], v156 offset:34816
	ds_read_b128 v[66:69], v155 offset:4096
	ds_read_b128 v[70:73], v156 offset:36864
	ds_read_b128 v[74:77], v155 offset:6144
	ds_read_b128 v[78:81], v156 offset:38912
	s_waitcnt lgkmcnt(6)
	v_mfma_f32_16x16x32_bf16 v[82:85], v[18:21], v[22:25], 0
	v_readlane_b32 s14, v255, 0
	v_readlane_b32 s15, v255, 1
	s_waitcnt lgkmcnt(5)
	v_mfma_f32_16x16x32_bf16 v[94:97], v[26:29], v[22:25], 0
	s_waitcnt lgkmcnt(3)
	v_mfma_f32_16x16x32_bf16 v[142:145], v[66:69], v[22:25], 0
	s_waitcnt lgkmcnt(1)
	v_mfma_f32_16x16x32_bf16 v[22:25], v[74:77], v[22:25], 0
	v_mfma_f32_16x16x32_bf16 v[174:177], v[74:77], v[62:65], 0
	v_mfma_f32_16x16x32_bf16 v[180:183], v[74:77], v[70:73], 0
	s_waitcnt lgkmcnt(0)
	v_mfma_f32_16x16x32_bf16 v[184:187], v[74:77], v[78:81], 0
	ds_read_b128 v[74:77], v153
	ds_read_b128 v[188:191], v154 offset:32768
	ds_read_b128 v[192:195], v153 offset:2048
	ds_read_b128 v[218:221], v154 offset:34816
	ds_read_b128 v[222:225], v153 offset:4096
	ds_read_b128 v[226:229], v154 offset:36864
	ds_read_b128 v[230:233], v153 offset:6144
	ds_read_b128 v[234:237], v154 offset:38912
	s_waitcnt vmcnt(7)
	ds_write_b128 v152, v[46:49] offset:16384
	s_waitcnt vmcnt(6)
	ds_write_b128 v152, v[50:53] offset:20480
	s_waitcnt vmcnt(5)
	ds_write_b128 v152, v[54:57] offset:24576
	s_waitcnt vmcnt(4)
	ds_write_b128 v152, v[58:61] offset:28672
	ds_write_b128 v152, v[2:5] offset:49152
	ds_write_b128 v152, v[6:9] offset:53248
	ds_write_b128 v152, v[10:13] offset:57344
	ds_write_b128 v152, v[14:17] offset:61440
	global_load_dwordx4 v[10:13], v[102:103], off
	global_load_dwordx4 v[46:49], v[104:105], off
	s_nop 0
	global_load_dwordx4 v[102:105], v[106:107], off
	s_nop 0
	global_load_dwordx4 v[106:109], v[108:109], off
	v_mfma_f32_16x16x32_bf16 v[86:89], v[18:21], v[62:65], 0
	s_waitcnt lgkmcnt(0)
	s_barrier
	v_mfma_f32_16x16x32_bf16 v[90:93], v[18:21], v[70:73], 0
	v_mov_b32_e32 v2, 0x33000
	v_mad_u32_u24 v130, v157, s4, v2
	v_lshl_add_u64 v[2:3], v[130:131], 0, v[118:119]
	v_mfma_f32_16x16x32_bf16 v[18:21], v[18:21], v[78:81], 0
	v_lshlrev_b64 v[2:3], 5, v[2:3]
	v_lshl_add_u64 v[4:5], v[130:131], 0, v[122:123]
	v_lshl_add_u64 v[6:7], v[130:131], 0, v[124:125]
	v_mfma_f32_16x16x32_bf16 v[98:101], v[26:29], v[62:65], 0
	v_lshl_add_u64 v[8:9], v[130:131], 0, v[126:127]
	v_lshl_add_u64 v[2:3], s[2:3], 0, v[2:3]
	v_lshlrev_b64 v[4:5], 5, v[4:5]
	v_mfma_f32_16x16x32_bf16 v[138:141], v[26:29], v[70:73], 0
	v_lshlrev_b64 v[6:7], 5, v[6:7]
	v_lshlrev_b64 v[8:9], 5, v[8:9]
	v_lshl_add_u64 v[2:3], v[2:3], 0, v[120:121]
	v_mfma_f32_16x16x32_bf16 v[26:29], v[26:29], v[78:81], 0
	v_lshl_add_u64 v[4:5], s[2:3], 0, v[4:5]
	v_lshl_add_u64 v[6:7], s[2:3], 0, v[6:7]
	v_lshl_add_u64 v[8:9], s[2:3], 0, v[8:9]
	v_mfma_f32_16x16x32_bf16 v[146:149], v[66:69], v[62:65], 0
	v_lshl_add_u64 v[4:5], v[4:5], 0, v[120:121]
	v_lshl_add_u64 v[6:7], v[6:7], 0, v[120:121]
	v_lshl_add_u64 v[8:9], v[8:9], 0, v[120:121]
	v_mfma_f32_16x16x32_bf16 v[162:165], v[66:69], v[70:73], 0
	v_mfma_f32_16x16x32_bf16 v[168:171], v[66:69], v[78:81], 0
	v_mfma_f32_16x16x32_bf16 v[62:65], v[74:77], v[188:191], v[82:85]
	v_mfma_f32_16x16x32_bf16 v[66:69], v[74:77], v[218:221], v[86:89]
	v_mfma_f32_16x16x32_bf16 v[70:73], v[74:77], v[226:229], v[90:93]
	v_mfma_f32_16x16x32_bf16 v[74:77], v[74:77], v[234:237], v[18:21]
	v_mfma_f32_16x16x32_bf16 v[78:81], v[192:195], v[188:191], v[94:97]
	v_mfma_f32_16x16x32_bf16 v[82:85], v[192:195], v[218:221], v[98:101]
	v_mfma_f32_16x16x32_bf16 v[86:89], v[192:195], v[226:229], v[138:141]
	v_mfma_f32_16x16x32_bf16 v[90:93], v[192:195], v[234:237], v[26:29]
	v_mfma_f32_16x16x32_bf16 v[94:97], v[222:225], v[188:191], v[142:145]
	v_mfma_f32_16x16x32_bf16 v[98:101], v[222:225], v[218:221], v[146:149]
	v_mfma_f32_16x16x32_bf16 v[138:141], v[222:225], v[226:229], v[162:165]
	v_mfma_f32_16x16x32_bf16 v[142:145], v[222:225], v[234:237], v[168:171]
	v_mfma_f32_16x16x32_bf16 v[146:149], v[230:233], v[188:191], v[22:25]
	global_load_dwordx4 v[26:29], v[110:111], off offset:384
	global_load_dwordx4 v[18:21], v[112:113], off offset:384
	s_nop 0
	global_load_dwordx4 v[22:25], v[114:115], off offset:384
	global_load_dwordx4 v[14:17], v[116:117], off offset:384
	v_mfma_f32_16x16x32_bf16 v[162:165], v[230:233], v[218:221], v[174:177]
	v_mfma_f32_16x16x32_bf16 v[168:171], v[230:233], v[226:229], v[180:183]
	v_mfma_f32_16x16x32_bf16 v[174:177], v[230:233], v[234:237], v[184:187]
	ds_read_b128 v[50:53], v155 offset:16384
	ds_read_b128 v[54:57], v156 offset:49152
	ds_read_b128 v[58:61], v155 offset:18432
	ds_read_b128 v[180:183], v156 offset:51200
	ds_read_b128 v[184:187], v155 offset:20480
	ds_read_b128 v[188:191], v156 offset:53248
	ds_read_b128 v[192:195], v155 offset:22528
	ds_read_b128 v[218:221], v156 offset:55296
	s_waitcnt lgkmcnt(4)
	v_mfma_f32_16x16x32_bf16 v[66:69], v[50:53], v[180:183], v[66:69]
	s_waitcnt lgkmcnt(2)
	v_mfma_f32_16x16x32_bf16 v[70:73], v[50:53], v[188:191], v[70:73]
	v_mfma_f32_16x16x32_bf16 v[78:81], v[58:61], v[54:57], v[78:81]
	v_mfma_f32_16x16x32_bf16 v[82:85], v[58:61], v[180:183], v[82:85]
	s_waitcnt lgkmcnt(0)
	v_mfma_f32_16x16x32_bf16 v[74:77], v[50:53], v[218:221], v[74:77]
	v_mfma_f32_16x16x32_bf16 v[86:89], v[58:61], v[188:191], v[86:89]
	v_mfma_f32_16x16x32_bf16 v[90:93], v[58:61], v[218:221], v[90:93]
	v_mfma_f32_16x16x32_bf16 v[94:97], v[184:187], v[54:57], v[94:97]
	v_mfma_f32_16x16x32_bf16 v[98:101], v[184:187], v[180:183], v[98:101]
	v_mfma_f32_16x16x32_bf16 v[138:141], v[184:187], v[188:191], v[138:141]
	v_mfma_f32_16x16x32_bf16 v[142:145], v[184:187], v[218:221], v[142:145]
	v_mfma_f32_16x16x32_bf16 v[146:149], v[192:195], v[54:57], v[146:149]
	v_mfma_f32_16x16x32_bf16 v[162:165], v[192:195], v[180:183], v[162:165]
	v_mfma_f32_16x16x32_bf16 v[168:171], v[192:195], v[188:191], v[168:171]
	v_mfma_f32_16x16x32_bf16 v[174:177], v[192:195], v[218:221], v[174:177]
	ds_read_b128 v[180:183], v153 offset:16384
	ds_read_b128 v[184:187], v154 offset:49152
	ds_read_b128 v[188:191], v153 offset:18432
	ds_read_b128 v[192:195], v154 offset:51200
	ds_read_b128 v[218:221], v153 offset:20480
	ds_read_b128 v[222:225], v154 offset:53248
	ds_read_b128 v[226:229], v153 offset:22528
	ds_read_b128 v[230:233], v154 offset:55296
	s_waitcnt vmcnt(7)
	ds_write_b128 v152, v[10:13]
	s_waitcnt vmcnt(6)
	ds_write_b128 v152, v[46:49] offset:4096
	s_waitcnt vmcnt(5)
	ds_write_b128 v152, v[102:105] offset:8192
	s_waitcnt vmcnt(4)
	ds_write_b128 v152, v[106:109] offset:12288
	ds_write_b128 v152, v[30:33] offset:32768
	ds_write_b128 v152, v[34:37] offset:36864
	ds_write_b128 v152, v[38:41] offset:40960
	ds_write_b128 v152, v[42:45] offset:45056
	v_mov_b32_e32 v10, 0x44000
	v_mfma_f32_16x16x32_bf16 v[62:65], v[50:53], v[54:57], v[62:65]
	v_mad_u32_u24 v130, v157, s4, v10
	v_lshl_add_u64 v[10:11], v[130:131], 0, v[118:119]
	v_lshlrev_b64 v[10:11], 5, v[10:11]
	s_waitcnt lgkmcnt(12)
	v_mfma_f32_16x16x32_bf16 v[54:57], v[180:183], v[192:195], v[66:69]
	v_lshl_add_u64 v[10:11], s[2:3], 0, v[10:11]
	v_lshl_add_u64 v[128:129], v[10:11], 0, v[120:121]
	v_lshl_add_u64 v[10:11], v[130:131], 0, v[122:123]
	s_waitcnt lgkmcnt(10)
	v_mfma_f32_16x16x32_bf16 v[58:61], v[180:183], v[222:225], v[70:73]
	v_lshlrev_b64 v[10:11], 5, v[10:11]
	v_lshl_add_u64 v[10:11], s[2:3], 0, v[10:11]
	v_mfma_f32_16x16x32_bf16 v[66:69], v[188:191], v[184:187], v[78:81]
	v_mfma_f32_16x16x32_bf16 v[70:73], v[188:191], v[192:195], v[82:85]
	s_nop 2
	global_load_dwordx4 v[82:85], v[2:3], off
	global_load_dwordx4 v[78:81], v[4:5], off
	global_load_dwordx4 v[42:45], v[6:7], off
	global_load_dwordx4 v[46:49], v[8:9], off
	s_waitcnt lgkmcnt(0)
	s_barrier
	v_mfma_f32_16x16x32_bf16 v[50:53], v[180:183], v[184:187], v[62:65]
	v_mfma_f32_16x16x32_bf16 v[62:65], v[180:183], v[230:233], v[74:77]
	v_mfma_f32_16x16x32_bf16 v[74:77], v[188:191], v[222:225], v[86:89]
	v_mfma_f32_16x16x32_bf16 v[86:89], v[188:191], v[230:233], v[90:93]
	v_mfma_f32_16x16x32_bf16 v[90:93], v[218:221], v[184:187], v[94:97]
	v_mfma_f32_16x16x32_bf16 v[94:97], v[218:221], v[192:195], v[98:101]
	v_mfma_f32_16x16x32_bf16 v[98:101], v[218:221], v[222:225], v[138:141]
	s_nop 2
	v_lshl_add_u64 v[138:139], v[10:11], 0, v[120:121]
	v_lshl_add_u64 v[10:11], v[130:131], 0, v[124:125]
	v_lshlrev_b64 v[10:11], 5, v[10:11]
	v_lshl_add_u64 v[10:11], s[2:3], 0, v[10:11]
	v_mfma_f32_16x16x32_bf16 v[140:143], v[218:221], v[230:233], v[142:145]
	v_mfma_f32_16x16x32_bf16 v[144:147], v[226:229], v[184:187], v[146:149]
	s_nop 2
	v_lshl_add_u64 v[148:149], v[10:11], 0, v[120:121]
	v_lshl_add_u64 v[10:11], v[130:131], 0, v[126:127]
	v_lshlrev_b64 v[10:11], 5, v[10:11]
	v_lshl_add_u64 v[10:11], s[2:3], 0, v[10:11]
	v_mfma_f32_16x16x32_bf16 v[162:165], v[226:229], v[192:195], v[162:165]
	v_lshl_add_u64 v[150:151], v[10:11], 0, v[120:121]
	global_load_dwordx4 v[30:33], v[110:111], off offset:512
	global_load_dwordx4 v[10:13], v[112:113], off offset:512
	global_load_dwordx4 v[2:5], v[114:115], off offset:512
	global_load_dwordx4 v[6:9], v[116:117], off offset:512
	ds_read_b128 v[34:37], v155
	ds_read_b128 v[38:41], v156 offset:32768
	ds_read_b128 v[102:105], v155 offset:2048
	ds_read_b128 v[106:109], v156 offset:34816
	ds_read_b128 v[180:183], v155 offset:4096
	ds_read_b128 v[184:187], v156 offset:36864
	ds_read_b128 v[188:191], v155 offset:6144
	ds_read_b128 v[192:195], v156 offset:38912
	v_mfma_f32_16x16x32_bf16 v[168:171], v[226:229], v[222:225], v[168:171]
	v_mfma_f32_16x16x32_bf16 v[174:177], v[226:229], v[230:233], v[174:177]
	s_waitcnt lgkmcnt(6)
	v_mfma_f32_16x16x32_bf16 v[50:53], v[34:37], v[38:41], v[50:53]
	s_waitcnt lgkmcnt(4)
	v_mfma_f32_16x16x32_bf16 v[54:57], v[34:37], v[106:109], v[54:57]
	s_waitcnt lgkmcnt(2)
	v_mfma_f32_16x16x32_bf16 v[58:61], v[34:37], v[184:187], v[58:61]
	s_waitcnt lgkmcnt(0)
	v_mfma_f32_16x16x32_bf16 v[62:65], v[34:37], v[192:195], v[62:65]
	v_mfma_f32_16x16x32_bf16 v[66:69], v[102:105], v[38:41], v[66:69]
	v_mfma_f32_16x16x32_bf16 v[70:73], v[102:105], v[106:109], v[70:73]
	v_mfma_f32_16x16x32_bf16 v[74:77], v[102:105], v[184:187], v[74:77]
	v_mfma_f32_16x16x32_bf16 v[86:89], v[102:105], v[192:195], v[86:89]
	v_mfma_f32_16x16x32_bf16 v[90:93], v[180:183], v[38:41], v[90:93]
	v_mfma_f32_16x16x32_bf16 v[94:97], v[180:183], v[106:109], v[94:97]
	v_mfma_f32_16x16x32_bf16 v[98:101], v[180:183], v[184:187], v[98:101]
	v_mfma_f32_16x16x32_bf16 v[102:105], v[180:183], v[192:195], v[140:143]
	v_mfma_f32_16x16x32_bf16 v[140:143], v[188:191], v[38:41], v[144:147]
	v_mfma_f32_16x16x32_bf16 v[106:109], v[188:191], v[106:109], v[162:165]
	v_mfma_f32_16x16x32_bf16 v[144:147], v[188:191], v[184:187], v[168:171]
	v_mfma_f32_16x16x32_bf16 v[162:165], v[188:191], v[192:195], v[174:177]
	s_nop 1
	ds_read_b128 v[168:171], v153
	ds_read_b128 v[174:177], v154 offset:32768
	ds_read_b128 v[180:183], v153 offset:2048
	ds_read_b128 v[184:187], v154 offset:34816
	ds_read_b128 v[188:191], v153 offset:4096
	ds_read_b128 v[192:195], v154 offset:36864
	ds_read_b128 v[218:221], v153 offset:6144
	ds_read_b128 v[222:225], v154 offset:38912
	s_waitcnt vmcnt(7)
	ds_write_b128 v152, v[82:85] offset:16384
	s_waitcnt vmcnt(6)
	ds_write_b128 v152, v[78:81] offset:20480
	s_waitcnt vmcnt(5)
	ds_write_b128 v152, v[42:45] offset:24576
	s_waitcnt vmcnt(4)
	ds_write_b128 v152, v[46:49] offset:28672
	ds_write_b128 v152, v[26:29] offset:49152
	ds_write_b128 v152, v[18:21] offset:53248
	ds_write_b128 v152, v[22:25] offset:57344
	ds_write_b128 v152, v[14:17] offset:61440
	v_mov_b32_e32 v14, 0x55000
	s_waitcnt lgkmcnt(14)
	v_mfma_f32_16x16x32_bf16 v[34:37], v[168:171], v[174:177], v[50:53]
	v_mad_u32_u24 v130, v157, s4, v14
	v_lshl_add_u64 v[14:15], v[130:131], 0, v[118:119]
	v_lshlrev_b64 v[14:15], 5, v[14:15]
	s_waitcnt lgkmcnt(12)
	v_mfma_f32_16x16x32_bf16 v[38:41], v[168:171], v[184:187], v[54:57]
	global_load_dwordx4 v[50:53], v[128:129], off
	s_nop 1
	global_load_dwordx4 v[54:57], v[138:139], off
	global_load_dwordx4 v[46:49], v[148:149], off
	global_load_dwordx4 v[42:45], v[150:151], off
	v_lshl_add_u64 v[14:15], s[2:3], 0, v[14:15]
	s_waitcnt lgkmcnt(0)
	v_mfma_f32_16x16x32_bf16 v[226:229], v[188:191], v[184:187], v[94:97]
	s_barrier
	v_mfma_f32_16x16x32_bf16 v[94:97], v[218:221], v[174:177], v[140:143]
	s_nop 2
	v_lshl_add_u64 v[140:141], v[14:15], 0, v[120:121]
	v_lshl_add_u64 v[14:15], v[130:131], 0, v[122:123]
	v_lshlrev_b64 v[14:15], 5, v[14:15]
	v_lshl_add_u64 v[14:15], s[2:3], 0, v[14:15]
	v_lshl_add_u64 v[142:143], v[14:15], 0, v[120:121]
	v_lshl_add_u64 v[14:15], v[130:131], 0, v[124:125]
	v_lshlrev_b64 v[14:15], 5, v[14:15]
	v_lshl_add_u64 v[14:15], s[2:3], 0, v[14:15]
	v_mfma_f32_16x16x32_bf16 v[58:61], v[168:171], v[192:195], v[58:61]
	v_mfma_f32_16x16x32_bf16 v[62:65], v[168:171], v[222:225], v[62:65]
	v_mfma_f32_16x16x32_bf16 v[66:69], v[180:183], v[174:177], v[66:69]
	v_mfma_f32_16x16x32_bf16 v[70:73], v[180:183], v[184:187], v[70:73]
	v_mfma_f32_16x16x32_bf16 v[74:77], v[180:183], v[192:195], v[74:77]
	v_mfma_f32_16x16x32_bf16 v[168:171], v[180:183], v[222:225], v[86:89]
	v_mfma_f32_16x16x32_bf16 v[180:183], v[188:191], v[174:177], v[90:93]
	v_mfma_f32_16x16x32_bf16 v[90:93], v[188:191], v[222:225], v[102:105]
	v_mfma_f32_16x16x32_bf16 v[102:105], v[218:221], v[192:195], v[144:147]
	s_nop 2
	v_lshl_add_u64 v[144:145], v[14:15], 0, v[120:121]
	v_lshl_add_u64 v[14:15], v[130:131], 0, v[126:127]
	v_lshlrev_b64 v[14:15], 5, v[14:15]
	v_lshl_add_u64 v[14:15], s[2:3], 0, v[14:15]
	v_mfma_f32_16x16x32_bf16 v[86:89], v[188:191], v[192:195], v[98:101]
	v_lshl_add_u64 v[146:147], v[14:15], 0, v[120:121]
	global_load_dwordx4 v[26:29], v[110:111], off offset:640
	global_load_dwordx4 v[22:25], v[112:113], off offset:640
	global_load_dwordx4 v[14:17], v[114:115], off offset:640
	global_load_dwordx4 v[18:21], v[116:117], off offset:640
	v_mfma_f32_16x16x32_bf16 v[98:101], v[218:221], v[184:187], v[106:109]
	v_mfma_f32_16x16x32_bf16 v[106:109], v[218:221], v[222:225], v[162:165]
	ds_read_b128 v[78:81], v155 offset:16384
	ds_read_b128 v[82:85], v156 offset:49152
	ds_read_b128 v[148:151], v155 offset:18432
	ds_read_b128 v[162:165], v156 offset:51200
	ds_read_b128 v[174:177], v155 offset:20480
	ds_read_b128 v[184:187], v156 offset:53248
	ds_read_b128 v[188:191], v155 offset:22528
	ds_read_b128 v[192:195], v156 offset:55296
	s_waitcnt lgkmcnt(6)
	v_mfma_f32_16x16x32_bf16 v[34:37], v[78:81], v[82:85], v[34:37]
	s_waitcnt lgkmcnt(4)
	v_mfma_f32_16x16x32_bf16 v[38:41], v[78:81], v[162:165], v[38:41]
	s_waitcnt lgkmcnt(2)
	v_mfma_f32_16x16x32_bf16 v[218:221], v[78:81], v[184:187], v[58:61]
	s_waitcnt lgkmcnt(0)
	v_mfma_f32_16x16x32_bf16 v[78:81], v[78:81], v[192:195], v[62:65]
	v_mfma_f32_16x16x32_bf16 v[222:225], v[148:151], v[82:85], v[66:69]
	v_mfma_f32_16x16x32_bf16 v[230:233], v[148:151], v[162:165], v[70:73]
	v_mfma_f32_16x16x32_bf16 v[234:237], v[148:151], v[184:187], v[74:77]
	v_mfma_f32_16x16x32_bf16 v[148:151], v[148:151], v[192:195], v[168:171]
	v_mfma_f32_16x16x32_bf16 v[168:171], v[174:177], v[82:85], v[180:183]
	v_mfma_f32_16x16x32_bf16 v[180:183], v[174:177], v[162:165], v[226:229]
	v_mfma_f32_16x16x32_bf16 v[86:89], v[174:177], v[184:187], v[86:89]
	v_mfma_f32_16x16x32_bf16 v[90:93], v[174:177], v[192:195], v[90:93]
	v_mfma_f32_16x16x32_bf16 v[94:97], v[188:191], v[82:85], v[94:97]
	v_mfma_f32_16x16x32_bf16 v[98:101], v[188:191], v[162:165], v[98:101]
	v_mfma_f32_16x16x32_bf16 v[162:165], v[188:191], v[184:187], v[102:105]
	v_mfma_f32_16x16x32_bf16 v[106:109], v[188:191], v[192:195], v[106:109]
	ds_read_b128 v[70:73], v153 offset:16384
	ds_read_b128 v[174:177], v154 offset:49152
	ds_read_b128 v[82:85], v153 offset:18432
	ds_read_b128 v[184:187], v154 offset:51200
	ds_read_b128 v[188:191], v153 offset:20480
	ds_read_b128 v[192:195], v154 offset:53248
	ds_read_b128 v[226:229], v153 offset:22528
	ds_read_b128 v[238:241], v154 offset:55296
	s_waitcnt vmcnt(7)
	ds_write_b128 v152, v[50:53]
	s_waitcnt vmcnt(6)
	ds_write_b128 v152, v[54:57] offset:4096
	s_waitcnt vmcnt(5)
	ds_write_b128 v152, v[46:49] offset:8192
	s_waitcnt vmcnt(4)
	ds_write_b128 v152, v[42:45] offset:12288
	ds_write_b128 v152, v[30:33] offset:32768
	ds_write_b128 v152, v[10:13] offset:36864
	ds_write_b128 v152, v[2:5] offset:40960
	ds_write_b128 v152, v[6:9] offset:45056
	v_mov_b32_e32 v2, 0x66000
	s_waitcnt lgkmcnt(14)
	v_mfma_f32_16x16x32_bf16 v[58:61], v[70:73], v[174:177], v[34:37]
	v_mad_u32_u24 v130, v157, s4, v2
	v_lshl_add_u64 v[2:3], v[130:131], 0, v[118:119]
	v_lshlrev_b64 v[2:3], 5, v[2:3]
	s_waitcnt lgkmcnt(12)
	v_mfma_f32_16x16x32_bf16 v[62:65], v[70:73], v[184:187], v[38:41]
	global_load_dwordx4 v[46:49], v[140:141], off
	global_load_dwordx4 v[50:53], v[142:143], off
	s_nop 0
	global_load_dwordx4 v[38:41], v[144:145], off
	global_load_dwordx4 v[34:37], v[146:147], off
	v_lshl_add_u64 v[2:3], s[2:3], 0, v[2:3]
	s_waitcnt lgkmcnt(0)
	v_mfma_f32_16x16x32_bf16 v[66:69], v[70:73], v[192:195], v[218:221]
	s_barrier
	v_mfma_f32_16x16x32_bf16 v[74:77], v[82:85], v[174:177], v[222:225]
	v_mfma_f32_16x16x32_bf16 v[102:105], v[82:85], v[184:187], v[230:233]
	v_mfma_f32_16x16x32_bf16 v[218:221], v[82:85], v[192:195], v[234:237]
	v_mfma_f32_16x16x32_bf16 v[148:151], v[82:85], v[238:241], v[148:151]
	v_mfma_f32_16x16x32_bf16 v[82:85], v[188:191], v[238:241], v[90:93]
	v_mfma_f32_16x16x32_bf16 v[90:93], v[226:229], v[184:187], v[98:101]
	v_mfma_f32_16x16x32_bf16 v[98:101], v[226:229], v[238:241], v[106:109]
	s_nop 2
	v_lshl_add_u64 v[106:107], v[2:3], 0, v[120:121]
	v_lshl_add_u64 v[2:3], v[130:131], 0, v[122:123]
	v_lshlrev_b64 v[2:3], 5, v[2:3]
	v_lshl_add_u64 v[2:3], s[2:3], 0, v[2:3]
	v_lshl_add_u64 v[108:109], v[2:3], 0, v[120:121]
	v_lshl_add_u64 v[2:3], v[130:131], 0, v[124:125]
	v_lshlrev_b64 v[2:3], 5, v[2:3]
	v_lshl_add_u64 v[2:3], s[2:3], 0, v[2:3]
	v_lshl_add_u64 v[128:129], v[2:3], 0, v[120:121]
	v_lshl_add_u64 v[2:3], v[130:131], 0, v[126:127]
	v_lshlrev_b64 v[2:3], 5, v[2:3]
	v_lshl_add_u64 v[2:3], s[2:3], 0, v[2:3]
	v_mfma_f32_16x16x32_bf16 v[70:73], v[70:73], v[238:241], v[78:81]
	v_lshl_add_u64 v[138:139], v[2:3], 0, v[120:121]
	global_load_dwordx4 v[30:33], v[110:111], off offset:768
	global_load_dwordx4 v[10:13], v[112:113], off offset:768
	global_load_dwordx4 v[2:5], v[114:115], off offset:768
	global_load_dwordx4 v[6:9], v[116:117], off offset:768
	v_mfma_f32_16x16x32_bf16 v[168:171], v[188:191], v[174:177], v[168:171]
	v_mfma_f32_16x16x32_bf16 v[180:183], v[188:191], v[184:187], v[180:183]
	v_mfma_f32_16x16x32_bf16 v[78:81], v[188:191], v[192:195], v[86:89]
	v_mfma_f32_16x16x32_bf16 v[86:89], v[226:229], v[174:177], v[94:97]
	v_mfma_f32_16x16x32_bf16 v[94:97], v[226:229], v[192:195], v[162:165]
	ds_read_b128 v[42:45], v155
	ds_read_b128 v[54:57], v156 offset:32768
	ds_read_b128 v[140:143], v155 offset:2048
	ds_read_b128 v[144:147], v156 offset:34816
	ds_read_b128 v[162:165], v155 offset:4096
	ds_read_b128 v[174:177], v156 offset:36864
	ds_read_b128 v[184:187], v155 offset:6144
	ds_read_b128 v[188:191], v156 offset:38912
	s_waitcnt lgkmcnt(4)
	v_mfma_f32_16x16x32_bf16 v[62:65], v[42:45], v[144:147], v[62:65]
	s_waitcnt lgkmcnt(2)
	v_mfma_f32_16x16x32_bf16 v[66:69], v[42:45], v[174:177], v[66:69]
	s_waitcnt lgkmcnt(0)
	v_mfma_f32_16x16x32_bf16 v[70:73], v[42:45], v[188:191], v[70:73]
	v_mfma_f32_16x16x32_bf16 v[74:77], v[140:143], v[54:57], v[74:77]
	v_mfma_f32_16x16x32_bf16 v[102:105], v[140:143], v[144:147], v[102:105]
	v_mfma_f32_16x16x32_bf16 v[192:195], v[140:143], v[174:177], v[218:221]
	v_mfma_f32_16x16x32_bf16 v[140:143], v[140:143], v[188:191], v[148:151]
	v_mfma_f32_16x16x32_bf16 v[148:151], v[162:165], v[54:57], v[168:171]
	v_mfma_f32_16x16x32_bf16 v[168:171], v[162:165], v[144:147], v[180:183]
	v_mfma_f32_16x16x32_bf16 v[78:81], v[162:165], v[174:177], v[78:81]
	v_mfma_f32_16x16x32_bf16 v[82:85], v[162:165], v[188:191], v[82:85]
	v_mfma_f32_16x16x32_bf16 v[86:89], v[184:187], v[54:57], v[86:89]
	v_mfma_f32_16x16x32_bf16 v[90:93], v[184:187], v[144:147], v[90:93]
	v_mfma_f32_16x16x32_bf16 v[144:147], v[184:187], v[174:177], v[94:97]
	v_mfma_f32_16x16x32_bf16 v[162:165], v[184:187], v[188:191], v[98:101]
	s_nop 1
	ds_read_b128 v[94:97], v153
	ds_read_b128 v[174:177], v154 offset:32768
	ds_read_b128 v[98:101], v153 offset:2048
	ds_read_b128 v[180:183], v154 offset:34816
	ds_read_b128 v[184:187], v153 offset:4096
	ds_read_b128 v[188:191], v154 offset:36864
	ds_read_b128 v[218:221], v153 offset:6144
	ds_read_b128 v[222:225], v154 offset:38912
	s_waitcnt vmcnt(7)
	ds_write_b128 v152, v[46:49] offset:16384
	s_waitcnt vmcnt(6)
	ds_write_b128 v152, v[50:53] offset:20480
	s_waitcnt vmcnt(5)
	ds_write_b128 v152, v[38:41] offset:24576
	s_waitcnt vmcnt(4)
	ds_write_b128 v152, v[34:37] offset:28672
	ds_write_b128 v152, v[26:29] offset:49152
	ds_write_b128 v152, v[22:25] offset:53248
	ds_write_b128 v152, v[14:17] offset:57344
	ds_write_b128 v152, v[18:21] offset:61440
	global_load_dwordx4 v[50:53], v[106:107], off
	global_load_dwordx4 v[46:49], v[108:109], off
	global_load_dwordx4 v[34:37], v[128:129], off
	global_load_dwordx4 v[38:41], v[138:139], off
	v_mov_b32_e32 v14, 0x77000
	v_mad_u32_u24 v130, v157, s4, v14
	v_lshl_add_u64 v[14:15], v[130:131], 0, v[118:119]
	v_lshlrev_b64 v[14:15], 5, v[14:15]
	v_lshl_add_u64 v[14:15], s[2:3], 0, v[14:15]
	v_lshl_add_u64 v[118:119], v[14:15], 0, v[120:121]
	v_lshl_add_u64 v[14:15], v[130:131], 0, v[122:123]
	v_lshlrev_b64 v[14:15], 5, v[14:15]
	v_lshl_add_u64 v[14:15], s[2:3], 0, v[14:15]
	v_lshl_add_u64 v[122:123], v[14:15], 0, v[120:121]
	v_lshl_add_u64 v[14:15], v[130:131], 0, v[124:125]
	v_lshlrev_b64 v[14:15], 5, v[14:15]
	v_mfma_f32_16x16x32_bf16 v[58:61], v[42:45], v[54:57], v[58:61]
	v_lshl_add_u64 v[14:15], s[2:3], 0, v[14:15]
	v_lshl_add_u64 v[124:125], v[14:15], 0, v[120:121]
	v_lshl_add_u64 v[14:15], v[130:131], 0, v[126:127]
	v_lshlrev_b64 v[14:15], 5, v[14:15]
	v_lshl_add_u64 v[14:15], s[2:3], 0, v[14:15]
	s_waitcnt lgkmcnt(14)
	v_mfma_f32_16x16x32_bf16 v[42:45], v[94:97], v[174:177], v[58:61]
	v_lshl_add_u64 v[120:121], v[14:15], 0, v[120:121]
	s_waitcnt lgkmcnt(0)
	s_barrier
	v_mfma_f32_16x16x32_bf16 v[54:57], v[94:97], v[180:183], v[62:65]
	global_load_dwordx4 v[26:29], v[110:111], off offset:896
	global_load_dwordx4 v[14:17], v[112:113], off offset:896
	global_load_dwordx4 v[18:21], v[114:115], off offset:896
	global_load_dwordx4 v[22:25], v[116:117], off offset:896
	v_readlane_b32 s4, v253, 4
	v_mfma_f32_16x16x32_bf16 v[58:61], v[94:97], v[188:191], v[66:69]
	v_readlane_b32 s5, v253, 5
	v_lshlrev_b32_e32 v130, 1, v1
	v_readlane_b32 s6, v253, 6
	v_mfma_f32_16x16x32_bf16 v[62:65], v[94:97], v[222:225], v[70:73]
	v_readlane_b32 s7, v253, 7
	v_readlane_b32 s8, v253, 8
	v_readlane_b32 s9, v253, 9
	v_mfma_f32_16x16x32_bf16 v[66:69], v[98:101], v[174:177], v[74:77]
	v_readlane_b32 s10, v253, 10
	v_readlane_b32 s11, v253, 11
	v_mfma_f32_16x16x32_bf16 v[102:105], v[98:101], v[180:183], v[102:105]
	v_mfma_f32_16x16x32_bf16 v[192:195], v[98:101], v[188:191], v[192:195]
	v_mfma_f32_16x16x32_bf16 v[140:143], v[98:101], v[222:225], v[140:143]
	v_mfma_f32_16x16x32_bf16 v[94:97], v[184:187], v[174:177], v[148:151]
	v_mfma_f32_16x16x32_bf16 v[98:101], v[184:187], v[180:183], v[168:171]
	v_mfma_f32_16x16x32_bf16 v[70:73], v[184:187], v[188:191], v[78:81]
	v_mfma_f32_16x16x32_bf16 v[74:77], v[184:187], v[222:225], v[82:85]
	v_mfma_f32_16x16x32_bf16 v[78:81], v[218:221], v[174:177], v[86:89]
	v_mfma_f32_16x16x32_bf16 v[82:85], v[218:221], v[180:183], v[90:93]
	v_mfma_f32_16x16x32_bf16 v[86:89], v[218:221], v[188:191], v[144:147]
	v_mfma_f32_16x16x32_bf16 v[90:93], v[218:221], v[222:225], v[162:165]
	ds_read_b128 v[106:109], v155 offset:16384
	ds_read_b128 v[110:113], v156 offset:49152
	ds_read_b128 v[114:117], v155 offset:18432
	ds_read_b128 v[126:129], v156 offset:51200
	ds_read_b128 v[144:147], v155 offset:20480
	ds_read_b128 v[148:151], v156 offset:53248
	ds_read_b128 v[162:165], v155 offset:22528
	ds_read_b128 v[168:171], v156 offset:55296
	s_waitcnt lgkmcnt(6)
	v_mfma_f32_16x16x32_bf16 v[42:45], v[106:109], v[110:113], v[42:45]
	s_waitcnt lgkmcnt(4)
	v_mfma_f32_16x16x32_bf16 v[54:57], v[106:109], v[126:129], v[54:57]
	s_waitcnt lgkmcnt(2)
	v_mfma_f32_16x16x32_bf16 v[58:61], v[106:109], v[148:151], v[58:61]
	s_waitcnt lgkmcnt(0)
	v_mfma_f32_16x16x32_bf16 v[62:65], v[106:109], v[168:171], v[62:65]
	v_mfma_f32_16x16x32_bf16 v[66:69], v[114:117], v[110:113], v[66:69]
	v_mfma_f32_16x16x32_bf16 v[102:105], v[114:117], v[126:129], v[102:105]
	v_mfma_f32_16x16x32_bf16 v[106:109], v[114:117], v[148:151], v[192:195]
	v_mfma_f32_16x16x32_bf16 v[114:117], v[114:117], v[168:171], v[140:143]
	v_mfma_f32_16x16x32_bf16 v[94:97], v[144:147], v[110:113], v[94:97]
	v_mfma_f32_16x16x32_bf16 v[98:101], v[144:147], v[126:129], v[98:101]
	v_mfma_f32_16x16x32_bf16 v[70:73], v[144:147], v[148:151], v[70:73]
	v_mfma_f32_16x16x32_bf16 v[74:77], v[144:147], v[168:171], v[74:77]
	v_mfma_f32_16x16x32_bf16 v[78:81], v[162:165], v[110:113], v[78:81]
	v_mfma_f32_16x16x32_bf16 v[82:85], v[162:165], v[126:129], v[82:85]
	v_mfma_f32_16x16x32_bf16 v[86:89], v[162:165], v[148:151], v[86:89]
	v_mfma_f32_16x16x32_bf16 v[90:93], v[162:165], v[168:171], v[90:93]
	ds_read_b128 v[110:113], v153 offset:16384
	ds_read_b128 v[126:129], v154 offset:49152
	ds_read_b128 v[138:141], v153 offset:18432
	ds_read_b128 v[142:145], v154 offset:51200
	ds_read_b128 v[146:149], v153 offset:20480
	ds_read_b128 v[162:165], v154 offset:53248
	ds_read_b128 v[168:171], v153 offset:22528
	ds_read_b128 v[174:177], v154 offset:55296
	s_waitcnt vmcnt(7)
	ds_write_b128 v152, v[50:53]
	s_waitcnt vmcnt(6)
	ds_write_b128 v152, v[46:49] offset:4096
	s_waitcnt vmcnt(5)
	ds_write_b128 v152, v[34:37] offset:8192
	s_waitcnt vmcnt(4)
	ds_write_b128 v152, v[38:41] offset:12288
	ds_write_b128 v152, v[30:33] offset:32768
	ds_write_b128 v152, v[10:13] offset:36864
	ds_write_b128 v152, v[2:5] offset:40960
	ds_write_b128 v152, v[6:9] offset:45056
	global_load_dwordx4 v[2:5], v[118:119], off
	global_load_dwordx4 v[6:9], v[122:123], off
	global_load_dwordx4 v[10:13], v[124:125], off
	global_load_dwordx4 v[30:33], v[120:121], off
	s_waitcnt lgkmcnt(14)
	v_mfma_f32_16x16x32_bf16 v[42:45], v[110:113], v[126:129], v[42:45]
	s_waitcnt lgkmcnt(0)
	s_barrier
	v_mfma_f32_16x16x32_bf16 v[54:57], v[110:113], v[142:145], v[54:57]
	v_mfma_f32_16x16x32_bf16 v[58:61], v[110:113], v[162:165], v[58:61]
	v_mfma_f32_16x16x32_bf16 v[62:65], v[110:113], v[174:177], v[62:65]
	v_mfma_f32_16x16x32_bf16 v[66:69], v[138:141], v[126:129], v[66:69]
	v_mfma_f32_16x16x32_bf16 v[110:113], v[138:141], v[174:177], v[114:117]
	v_mfma_f32_16x16x32_bf16 v[94:97], v[146:149], v[126:129], v[94:97]
	v_mfma_f32_16x16x32_bf16 v[78:81], v[168:171], v[126:129], v[78:81]
	ds_read_b128 v[34:37], v155
	ds_read_b128 v[38:41], v156 offset:32768
	ds_read_b128 v[46:49], v155 offset:2048
	ds_read_b128 v[50:53], v156 offset:34816
	ds_read_b128 v[114:117], v155 offset:4096
	ds_read_b128 v[118:121], v156 offset:36864
	ds_read_b128 v[122:125], v155 offset:6144
	ds_read_b128 v[126:129], v156 offset:38912
	v_mfma_f32_16x16x32_bf16 v[102:105], v[138:141], v[142:145], v[102:105]
	v_mfma_f32_16x16x32_bf16 v[106:109], v[138:141], v[162:165], v[106:109]
	v_mfma_f32_16x16x32_bf16 v[98:101], v[146:149], v[142:145], v[98:101]
	v_mfma_f32_16x16x32_bf16 v[70:73], v[146:149], v[162:165], v[70:73]
	v_mfma_f32_16x16x32_bf16 v[74:77], v[146:149], v[174:177], v[74:77]
	v_mfma_f32_16x16x32_bf16 v[82:85], v[168:171], v[142:145], v[82:85]
	v_mfma_f32_16x16x32_bf16 v[86:89], v[168:171], v[162:165], v[86:89]
	v_mfma_f32_16x16x32_bf16 v[90:93], v[168:171], v[174:177], v[90:93]
	s_waitcnt lgkmcnt(6)
	v_mfma_f32_16x16x32_bf16 v[42:45], v[34:37], v[38:41], v[42:45]
	s_waitcnt lgkmcnt(4)
	v_mfma_f32_16x16x32_bf16 v[54:57], v[34:37], v[50:53], v[54:57]
	s_waitcnt lgkmcnt(2)
	v_mfma_f32_16x16x32_bf16 v[58:61], v[34:37], v[118:121], v[58:61]
	s_waitcnt lgkmcnt(0)
	v_mfma_f32_16x16x32_bf16 v[34:37], v[34:37], v[126:129], v[62:65]
	v_mfma_f32_16x16x32_bf16 v[62:65], v[46:49], v[38:41], v[66:69]
	v_mfma_f32_16x16x32_bf16 v[66:69], v[46:49], v[50:53], v[102:105]
	v_mfma_f32_16x16x32_bf16 v[102:105], v[46:49], v[118:121], v[106:109]
	v_mfma_f32_16x16x32_bf16 v[46:49], v[46:49], v[126:129], v[110:113]
	v_mfma_f32_16x16x32_bf16 v[94:97], v[114:117], v[38:41], v[94:97]
	v_mfma_f32_16x16x32_bf16 v[98:101], v[114:117], v[50:53], v[98:101]
	v_mfma_f32_16x16x32_bf16 v[70:73], v[114:117], v[118:121], v[70:73]
	v_mfma_f32_16x16x32_bf16 v[74:77], v[114:117], v[126:129], v[74:77]
	v_mfma_f32_16x16x32_bf16 v[38:41], v[122:125], v[38:41], v[78:81]
	v_mfma_f32_16x16x32_bf16 v[50:53], v[122:125], v[50:53], v[82:85]
	v_mfma_f32_16x16x32_bf16 v[78:81], v[122:125], v[118:121], v[86:89]
	v_mfma_f32_16x16x32_bf16 v[82:85], v[122:125], v[126:129], v[90:93]
	s_nop 1
	ds_read_b128 v[86:89], v153
	ds_read_b128 v[90:93], v154 offset:32768
	ds_read_b128 v[106:109], v153 offset:2048
	ds_read_b128 v[110:113], v154 offset:34816
	ds_read_b128 v[114:117], v153 offset:4096
	ds_read_b128 v[118:121], v154 offset:36864
	ds_read_b128 v[122:125], v153 offset:6144
	ds_read_b128 v[126:129], v154 offset:38912
	s_waitcnt vmcnt(3)
	ds_write_b128 v152, v[2:5] offset:16384
	s_waitcnt vmcnt(2)
	ds_write_b128 v152, v[6:9] offset:20480
	s_waitcnt vmcnt(1)
	ds_write_b128 v152, v[10:13] offset:24576
	s_waitcnt vmcnt(0)
	ds_write_b128 v152, v[30:33] offset:28672
	ds_write_b128 v152, v[26:29] offset:49152
	ds_write_b128 v152, v[14:17] offset:53248
	ds_write_b128 v152, v[18:21] offset:57344
	ds_write_b128 v152, v[22:25] offset:61440
	s_waitcnt lgkmcnt(0)
	s_barrier
	ds_read_b128 v[2:5], v155 offset:16384
	ds_read_b128 v[6:9], v156 offset:49152
	ds_read_b128 v[10:13], v155 offset:18432
	ds_read_b128 v[14:17], v156 offset:51200
	ds_read_b128 v[18:21], v155 offset:20480
	ds_read_b128 v[22:25], v156 offset:53248
	ds_read_b128 v[26:29], v155 offset:22528
	ds_read_b128 v[30:33], v156 offset:55296
	v_mfma_f32_16x16x32_bf16 v[42:45], v[86:89], v[90:93], v[42:45]
	v_mfma_f32_16x16x32_bf16 v[54:57], v[86:89], v[110:113], v[54:57]
	v_mfma_f32_16x16x32_bf16 v[58:61], v[86:89], v[118:121], v[58:61]
	v_mfma_f32_16x16x32_bf16 v[34:37], v[86:89], v[126:129], v[34:37]
	v_mfma_f32_16x16x32_bf16 v[66:69], v[106:109], v[110:113], v[66:69]
	v_mfma_f32_16x16x32_bf16 v[86:89], v[106:109], v[118:121], v[102:105]
	v_mfma_f32_16x16x32_bf16 v[94:97], v[114:117], v[90:93], v[94:97]
	v_mfma_f32_16x16x32_bf16 v[98:101], v[114:117], v[110:113], v[98:101]
	v_mfma_f32_16x16x32_bf16 v[70:73], v[114:117], v[118:121], v[70:73]
	v_mfma_f32_16x16x32_bf16 v[74:77], v[114:117], v[126:129], v[74:77]
	v_mfma_f32_16x16x32_bf16 v[50:53], v[122:125], v[110:113], v[50:53]
	v_mfma_f32_16x16x32_bf16 v[78:81], v[122:125], v[118:121], v[78:81]
	v_mfma_f32_16x16x32_bf16 v[82:85], v[122:125], v[126:129], v[82:85]
	v_mfma_f32_16x16x32_bf16 v[62:65], v[106:109], v[90:93], v[62:65]
	v_mfma_f32_16x16x32_bf16 v[46:49], v[106:109], v[126:129], v[46:49]
	v_mfma_f32_16x16x32_bf16 v[38:41], v[122:125], v[90:93], v[38:41]
	s_waitcnt lgkmcnt(4)
	v_mfma_f32_16x16x32_bf16 v[54:57], v[2:5], v[14:17], v[54:57]
	s_waitcnt lgkmcnt(2)
	v_mfma_f32_16x16x32_bf16 v[90:93], v[2:5], v[22:25], v[58:61]
	v_mfma_f32_16x16x32_bf16 v[66:69], v[10:13], v[14:17], v[66:69]
	v_mfma_f32_16x16x32_bf16 v[86:89], v[10:13], v[22:25], v[86:89]
	v_mfma_f32_16x16x32_bf16 v[94:97], v[18:21], v[6:9], v[94:97]
	v_mfma_f32_16x16x32_bf16 v[98:101], v[18:21], v[14:17], v[98:101]
	v_mfma_f32_16x16x32_bf16 v[70:73], v[18:21], v[22:25], v[70:73]
	s_waitcnt lgkmcnt(0)
	v_mfma_f32_16x16x32_bf16 v[18:21], v[18:21], v[30:33], v[74:77]
	v_mfma_f32_16x16x32_bf16 v[74:77], v[26:29], v[14:17], v[50:53]
	v_mfma_f32_16x16x32_bf16 v[78:81], v[26:29], v[22:25], v[78:81]
	ds_read_b128 v[14:17], v153 offset:16384
	ds_read_b128 v[102:105], v154 offset:49152
	ds_read_b128 v[22:25], v153 offset:18432
	ds_read_b128 v[106:109], v154 offset:51200
	ds_read_b128 v[110:113], v153 offset:20480
	ds_read_b128 v[114:117], v154 offset:53248
	ds_read_b128 v[118:121], v153 offset:22528
	ds_read_b128 v[122:125], v154 offset:55296
	s_waitcnt lgkmcnt(0)
	s_barrier
	v_lshl_or_b32 v126, v133, 6, s0
	v_or_b32_e32 v127, v126, v1
	v_mov_b32_e32 v128, v131
	v_or_b32_e32 v129, s14, v127
	v_ashrrev_i32_e32 v138, 31, v129
	v_lshl_add_u32 v139, v134, 6, s1
	v_mov_b32_e32 v140, v129
	v_mov_b32_e32 v141, v138
	v_lshl_add_u64 v[142:143], v[140:141], 2, s[4:5]
	global_load_dword v129, v[142:143], off
	v_lshrrev_b32_e32 v138, 4, v126
	v_mov_b32_e32 v140, v131
	v_lshl_or_b32 v141, v137, 2, v139
	v_lshl_add_u64 v[142:143], s[2:3], 0, v[130:131]
	v_ashrrev_i32_e32 v139, 31, v141
	v_mul_u32_u24_e32 v144, 0x4400, v138
	v_mov_b32_e32 v146, v144
	v_mov_b32_e32 v147, v131
	v_mov_b32_e32 v148, v141
	v_mov_b32_e32 v149, v139
	v_lshl_add_u64 v[150:151], v[146:147], 0, v[148:149]
	v_lshlrev_b64 v[146:147], 5, v[150:151]
	v_lshl_add_u64 v[148:149], v[142:143], 0, v[146:147]
	global_load_ushort v138, v[148:149], off
	v_readlane_b32 s7, v253, 59
	v_lshlrev_b32_e32 v145, 1, v127
	v_readlane_b32 s10, v253, 60
	v_mov_b32_e32 v146, v141
	v_mov_b32_e32 v147, v139
	v_lshlrev_b64 v[148:149], 10, v[146:147]
	s_mov_b32 s62, s7
	s_mov_b32 s63, s10
	v_mov_b32_e32 v146, v145
	v_mov_b32_e32 v147, v140
	v_lshl_add_u64 v[150:151], s[62:63], 0, v[146:147]
	v_or_b32_e32 v140, 3, v141
	v_ashrrev_i32_e32 v145, 31, v140
	v_or_b32_e32 v146, 1, v141
	v_ashrrev_i32_e32 v147, 31, v146
	v_lshlrev_b64 v[152:153], 10, v[146:147]
	v_or_b32_e32 v154, 2, v141
	v_ashrrev_i32_e32 v155, 31, v154
	v_lshlrev_b64 v[156:157], 10, v[154:155]
	v_mov_b32_e32 v158, v140
	v_mov_b32_e32 v159, v145
	v_lshlrev_b64 v[162:163], 10, v[158:159]
	v_lshl_add_u64 v[158:159], v[150:151], 0, v[148:149]
	global_load_ushort v160, v[158:159], off
	v_mov_b32_e32 v158, v144
	v_mov_b32_e32 v159, v131
	v_lshl_add_u64 v[164:165], v[158:159], 0, v[146:147]
	v_lshlrev_b64 v[158:159], 5, v[164:165]
	v_lshl_add_u64 v[164:165], v[142:143], 0, v[158:159]
	global_load_ushort v158, v[164:165], off
	v_lshl_add_u64 v[164:165], v[150:151], 0, v[152:153]
	global_load_ushort v159, v[164:165], off
	s_mov_b32 s62, s7
	s_mov_b32 s63, s10
	v_lshl_add_u64 v[164:165], s[62:63], 0, v[152:153]
	v_mov_b32_e32 v152, v144
	v_mov_b32_e32 v153, v131
	v_lshl_add_u64 v[168:169], v[152:153], 0, v[154:155]
	v_lshlrev_b64 v[152:153], 5, v[168:169]
	v_lshl_add_u64 v[168:169], v[142:143], 0, v[152:153]
	global_load_ushort v152, v[168:169], off
	v_lshl_add_u64 v[168:169], v[150:151], 0, v[156:157]
	global_load_ushort v153, v[168:169], off
	s_mov_b32 s62, s7
	s_mov_b32 s63, s10
	v_lshl_add_u64 v[168:169], s[62:63], 0, v[156:157]
	v_mov_b32_e32 v156, v144
	v_mov_b32_e32 v157, v131
	v_mov_b32_e32 v170, v140
	v_mov_b32_e32 v171, v145
	v_lshl_add_u64 v[174:175], v[156:157], 0, v[170:171]
	v_lshlrev_b64 v[156:157], 5, v[174:175]
	v_lshl_add_u64 v[170:171], v[142:143], 0, v[156:157]
	global_load_ushort v144, v[170:171], off
	v_lshl_add_u64 v[156:157], v[150:151], 0, v[162:163]
	global_load_ushort v150, v[156:157], off
	s_mov_b32 s62, s7
	s_mov_b32 s63, s10
	v_lshl_add_u64 v[156:157], s[62:63], 0, v[162:163]
	v_or_b32_e32 v151, 16, v126
	v_mov_b32_e32 v162, v127
	v_mov_b32_e32 v163, v128
	v_lshl_add_u64 v[170:171], v[162:163], 0, s[14:15]
	v_lshl_add_u64 v[126:127], v[170:171], 2, s[4:5]
	v_lshrrev_b32_e32 v128, 4, v151
	v_or_b32_e32 v162, v151, v1
	v_mul_u32_u24_e32 v151, 0x4400, v128
	v_mov_b32_e32 v128, v131
	v_mov_b32_e32 v170, v151
	v_mov_b32_e32 v171, v128
	v_mov_b32_e32 v174, v141
	v_mov_b32_e32 v175, v139
	v_lshl_add_u64 v[176:177], v[170:171], 0, v[174:175]
	v_lshlrev_b64 v[170:171], 5, v[176:177]
	v_lshl_add_u64 v[174:175], v[142:143], 0, v[170:171]
	global_load_ushort v139, v[174:175], off
	s_mov_b32 s62, s7
	s_mov_b32 s63, s10
	v_lshl_add_u64 v[170:171], s[62:63], 0, v[148:149]
	global_load_dword v141, v[126:127], off offset:64
	v_mov_b32_e32 v126, v131
	v_lshlrev_b32_e32 v127, 1, v162
	v_mov_b32_e32 v148, v127
	v_mov_b32_e32 v149, v126
	v_lshl_add_u64 v[162:163], v[170:171], 0, v[148:149]
	global_load_ushort v148, v[162:163], off
	v_mov_b32_e32 v162, v151
	v_mov_b32_e32 v163, v128
	v_lshl_add_u64 v[170:171], v[162:163], 0, v[146:147]
	v_lshlrev_b64 v[146:147], 5, v[170:171]
	v_lshl_add_u64 v[162:163], v[142:143], 0, v[146:147]
	global_load_ushort v146, v[162:163], off
	v_mov_b32_e32 v162, v127
	v_mov_b32_e32 v163, v126
	v_lshl_add_u64 v[170:171], v[164:165], 0, v[162:163]
	global_load_ushort v147, v[170:171], off
	v_mov_b32_e32 v162, v151
	v_mov_b32_e32 v163, v128
	v_lshl_add_u64 v[164:165], v[162:163], 0, v[154:155]
	v_lshlrev_b64 v[154:155], 5, v[164:165]
	v_lshl_add_u64 v[162:163], v[142:143], 0, v[154:155]
	global_load_ushort v149, v[162:163], off
	v_mov_b32_e32 v154, v127
	v_mov_b32_e32 v155, v126
	v_lshl_add_u64 v[162:163], v[168:169], 0, v[154:155]
	global_load_ushort v154, v[162:163], off
	v_mov_b32_e32 v162, v151
	v_mov_b32_e32 v163, v128
	v_mov_b32_e32 v164, v140
	v_mov_b32_e32 v165, v145
	v_lshl_add_u64 v[168:169], v[162:163], 0, v[164:165]
	v_lshlrev_b64 v[162:163], 5, v[168:169]
	v_lshl_add_u64 v[164:165], v[142:143], 0, v[162:163]
	global_load_ushort v128, v[164:165], off
	v_mov_b32_e32 v142, v127
	v_mov_b32_e32 v143, v126
	v_lshl_add_u64 v[162:163], v[156:157], 0, v[142:143]
	global_load_ushort v126, v[162:163], off
	v_mfma_f32_16x16x32_bf16 v[42:45], v[2:5], v[6:9], v[42:45]
	v_mfma_f32_16x16x32_bf16 v[2:5], v[2:5], v[30:33], v[34:37]
	v_mfma_f32_16x16x32_bf16 v[82:85], v[26:29], v[30:33], v[82:85]
	v_mfma_f32_16x16x32_bf16 v[58:61], v[14:17], v[106:109], v[54:57]
	v_mfma_f32_16x16x32_bf16 v[54:57], v[14:17], v[114:117], v[90:93]
	s_nop 2
	v_lshl_or_b32 v92, v133, 6, s0
	v_mfma_f32_16x16x32_bf16 v[34:37], v[10:13], v[6:9], v[62:65]
	v_mfma_f32_16x16x32_bf16 v[10:13], v[10:13], v[30:33], v[46:49]
	v_mfma_f32_16x16x32_bf16 v[50:53], v[14:17], v[122:125], v[2:5]
	v_mfma_f32_16x16x32_bf16 v[2:5], v[118:121], v[122:125], v[82:85]
	s_nop 2
	v_or_b32_e32 v84, v92, v1
	v_mfma_f32_16x16x32_bf16 v[62:65], v[14:17], v[102:105], v[42:45]
	v_mov_b32_e32 v85, v131
	v_mfma_f32_16x16x32_bf16 v[42:45], v[22:25], v[106:109], v[66:69]
	s_nop 2
	v_or_b32_e32 v68, s14, v84
	v_ashrrev_i32_e32 v69, 31, v68
	v_lshl_add_u32 v66, v134, 6, s1
	v_lshl_add_u64 v[68:69], v[68:69], 2, s[4:5]
	v_mfma_f32_16x16x32_bf16 v[6:9], v[26:29], v[6:9], v[38:41]
	s_waitcnt vmcnt(0)
	v_mov_b32_e32 v91, v129
	v_lshrrev_b32_e32 v68, 4, v92
	v_mov_b32_e32 v69, v131
	v_mfma_f32_16x16x32_bf16 v[46:49], v[22:25], v[102:105], v[34:37]
	v_add_f32_e32 v62, v62, v91
	v_mfma_f32_16x16x32_bf16 v[38:41], v[22:25], v[114:117], v[86:89]
	v_mul_f32_e32 v62, 0xbfb8aa3b, v62
	v_exp_f32_e32 v62, v62
	v_add_f32_e32 v63, v63, v91
	v_mfma_f32_16x16x32_bf16 v[34:37], v[22:25], v[122:125], v[10:13]
	v_mul_f32_e32 v63, 0xbfb8aa3b, v63
	v_add_f32_e32 v62, 1.0, v62
	v_exp_f32_e32 v63, v63
	v_mfma_f32_16x16x32_bf16 v[22:25], v[110:113], v[114:117], v[70:73]
	v_add_f32_e32 v64, v64, v91
	v_mul_f32_e32 v64, 0xbfb8aa3b, v64
	v_add_f32_e32 v63, 1.0, v63
	v_lshl_or_b32 v70, v137, 2, v66
	v_lshl_add_u64 v[66:67], s[2:3], 0, v[130:131]
	v_ashrrev_i32_e32 v71, 31, v70
	v_mul_u32_u24_e32 v130, 0x4400, v68
	v_lshl_add_u64 v[86:87], v[130:131], 0, v[70:71]
	v_lshlrev_b64 v[86:87], 5, v[86:87]
	v_lshl_add_u64 v[86:87], v[66:67], 0, v[86:87]
	v_mov_b32_e32 v86, v138
	v_readlane_b32 s2, v253, 59
	v_lshlrev_b32_e32 v68, 1, v84
	v_readlane_b32 s3, v253, 60
	v_lshlrev_b64 v[88:89], 10, v[70:71]
	v_mfma_f32_16x16x32_bf16 v[30:33], v[110:113], v[102:105], v[94:97]
	v_lshl_add_u64 v[68:69], s[2:3], 0, v[68:69]
	v_exp_f32_e32 v64, v64
	v_or_b32_e32 v72, 3, v70
	v_div_scale_f32 v94, s[0:1], v62, v62, 1.0
	v_rcp_f32_e32 v95, v94
	v_mfma_f32_16x16x32_bf16 v[26:29], v[110:113], v[106:109], v[98:101]
	v_add_f32_e32 v64, 1.0, v64
	v_ashrrev_i32_e32 v73, 31, v72
	v_fma_f32 v96, -v94, v95, 1.0
	v_fmac_f32_e32 v95, v96, v95
	v_div_scale_f32 v96, vcc, 1.0, v62, 1.0
	v_mul_f32_e32 v97, v96, v95
	v_fma_f32 v98, -v94, v97, v96
	v_fmac_f32_e32 v97, v98, v95
	v_fma_f32 v94, -v94, v97, v96
	v_div_fmas_f32 v94, v94, v95, v97
	v_div_fixup_f32 v62, v94, v62, 1.0
	v_mfma_f32_16x16x32_bf16 v[10:13], v[118:121], v[106:109], v[74:77]
	v_add_f32_e32 v65, v65, v91
	v_mul_f32_e32 v65, 0xbfb8aa3b, v65
	v_exp_f32_e32 v65, v65
	v_or_b32_e32 v76, 1, v70
	v_ashrrev_i32_e32 v77, 31, v76
	v_lshlrev_b64 v[82:83], 10, v[76:77]
	v_or_b32_e32 v74, 2, v70
	v_ashrrev_i32_e32 v75, 31, v74
	v_mfma_f32_16x16x32_bf16 v[14:17], v[118:121], v[102:105], v[6:9]
	v_add_f32_e32 v65, 1.0, v65
	v_add_f32_e32 v46, v46, v91
	v_mul_f32_e32 v46, 0xbfb8aa3b, v46
	v_mfma_f32_16x16x32_bf16 v[6:9], v[118:121], v[114:117], v[78:81]
	v_exp_f32_e32 v46, v46
	v_add_f32_e32 v47, v47, v91
	v_mul_f32_e32 v47, 0xbfb8aa3b, v47
	v_lshlrev_b64 v[80:81], 10, v[74:75]
	v_lshlrev_b64 v[78:79], 10, v[72:73]
	v_add_f32_e32 v46, 1.0, v46
	v_exp_f32_e32 v47, v47
	v_add_f32_e32 v48, v48, v91
	v_mul_f32_e32 v48, 0xbfb8aa3b, v48
	v_exp_f32_e32 v48, v48
	v_add_f32_e32 v47, 1.0, v47
	v_add_f32_e32 v49, v49, v91
	v_mul_f32_e32 v49, 0xbfb8aa3b, v49
	v_add_f32_e32 v48, 1.0, v48
	v_exp_f32_e32 v49, v49
	v_add_f32_e32 v30, v30, v91
	v_mul_f32_e32 v30, 0xbfb8aa3b, v30
	v_exp_f32_e32 v30, v30
	v_add_f32_e32 v49, 1.0, v49
	v_add_f32_e32 v31, v31, v91
	v_mul_f32_e32 v31, 0xbfb8aa3b, v31
	v_add_f32_e32 v30, 1.0, v30
	v_exp_f32_e32 v31, v31
	v_add_f32_e32 v32, v32, v91
	v_mul_f32_e32 v32, 0xbfb8aa3b, v32
	v_exp_f32_e32 v32, v32
	v_add_f32_e32 v31, 1.0, v31
	v_add_f32_e32 v33, v33, v91
	v_mul_f32_e32 v33, 0xbfb8aa3b, v33
	v_add_f32_e32 v32, 1.0, v32
	v_exp_f32_e32 v33, v33
	v_mfma_f32_16x16x32_bf16 v[18:21], v[110:113], v[122:125], v[18:21]
	v_add_f32_e32 v14, v14, v91
	v_mul_f32_e32 v14, 0xbfb8aa3b, v14
	v_add_f32_e32 v33, 1.0, v33
	v_exp_f32_e32 v14, v14
	v_add_f32_e32 v15, v15, v91
	v_mul_f32_e32 v15, 0xbfb8aa3b, v15
	v_exp_f32_e32 v15, v15
	v_add_f32_e32 v14, 1.0, v14
	v_add_f32_e32 v16, v16, v91
	v_lshlrev_b32_e32 v90, 16, v86
	v_lshl_add_u64 v[86:87], v[68:69], 0, v[88:89]
	v_mov_b32_e32 v93, v160
	v_mul_f32_e32 v62, v62, v90
	v_add_f32_e32 v15, 1.0, v15
	v_mul_f32_e32 v16, 0xbfb8aa3b, v16
	v_exp_f32_e32 v16, v16
	v_add_f32_e32 v17, v17, v91
	v_mul_f32_e32 v17, 0xbfb8aa3b, v17
	v_exp_f32_e32 v17, v17
	v_add_f32_e32 v16, 1.0, v16
	v_add_f32_e32 v17, 1.0, v17
	v_lshlrev_b32_e32 v93, 16, v93
	v_mul_f32_e32 v90, 0xbfb8aa3b, v93
	v_exp_f32_e32 v90, v90
	s_nop 0
	v_add_f32_e32 v90, 1.0, v90
	v_div_scale_f32 v94, s[0:1], v90, v90, v93
	v_rcp_f32_e32 v95, v94
	s_nop 0
	v_fma_f32 v96, -v94, v95, 1.0
	v_fmac_f32_e32 v95, v96, v95
	v_div_scale_f32 v96, vcc, v93, v90, v93
	v_mul_f32_e32 v97, v96, v95
	v_fma_f32 v98, -v94, v97, v96
	v_fmac_f32_e32 v97, v98, v95
	v_fma_f32 v94, -v94, v97, v96
	v_div_fmas_f32 v94, v94, v95, v97
	v_div_fixup_f32 v90, v94, v90, v93
	v_mul_f32_e32 v62, v62, v90
	v_cvt_pk_bf16_f32 v62, v62, s0
	global_store_short v[86:87], v62, off
	v_lshl_add_u64 v[86:87], v[130:131], 0, v[76:77]
	v_lshlrev_b64 v[86:87], 5, v[86:87]
	v_lshl_add_u64 v[86:87], v[66:67], 0, v[86:87]
	v_mov_b32_e32 v62, v158
	v_lshl_add_u64 v[86:87], v[68:69], 0, v[82:83]
	v_mov_b32_e32 v90, v159
	v_div_scale_f32 v93, s[0:1], v63, v63, 1.0
	v_rcp_f32_e32 v94, v93
	v_lshl_add_u64 v[82:83], s[2:3], 0, v[82:83]
	v_fma_f32 v95, -v93, v94, 1.0
	v_fmac_f32_e32 v94, v95, v94
	v_div_scale_f32 v95, vcc, 1.0, v63, 1.0
	v_mul_f32_e32 v96, v95, v94
	v_fma_f32 v97, -v93, v96, v95
	v_fmac_f32_e32 v96, v97, v94
	v_fma_f32 v93, -v93, v96, v95
	v_div_fmas_f32 v93, v93, v94, v96
	v_div_fixup_f32 v63, v93, v63, 1.0
	v_lshlrev_b32_e32 v62, 16, v62
	v_mul_f32_e32 v62, v63, v62
	v_lshlrev_b32_e32 v90, 16, v90
	v_mul_f32_e32 v63, 0xbfb8aa3b, v90
	v_exp_f32_e32 v63, v63
	s_nop 0
	v_add_f32_e32 v63, 1.0, v63
	v_div_scale_f32 v93, s[0:1], v63, v63, v90
	v_rcp_f32_e32 v94, v93
	s_nop 0
	v_fma_f32 v95, -v93, v94, 1.0
	v_fmac_f32_e32 v94, v95, v94
	v_div_scale_f32 v95, vcc, v90, v63, v90
	v_mul_f32_e32 v96, v95, v94
	v_fma_f32 v97, -v93, v96, v95
	v_fmac_f32_e32 v96, v97, v94
	v_fma_f32 v93, -v93, v96, v95
	v_div_fmas_f32 v93, v93, v94, v96
	v_div_fixup_f32 v63, v93, v63, v90
	v_mul_f32_e32 v62, v62, v63
	v_cvt_pk_bf16_f32 v62, v62, s0
	global_store_short v[86:87], v62, off
	v_lshl_add_u64 v[62:63], v[130:131], 0, v[74:75]
	v_lshlrev_b64 v[62:63], 5, v[62:63]
	v_lshl_add_u64 v[62:63], v[66:67], 0, v[62:63]
	v_mov_b32_e32 v62, v152
	v_div_scale_f32 v90, s[0:1], v64, v64, 1.0
	v_rcp_f32_e32 v93, v90
	v_lshlrev_b32_e32 v86, 16, v62
	v_lshl_add_u64 v[62:63], v[68:69], 0, v[80:81]
	v_mov_b32_e32 v87, v153
	v_fma_f32 v94, -v90, v93, 1.0
	v_fmac_f32_e32 v93, v94, v93
	v_div_scale_f32 v94, vcc, 1.0, v64, 1.0
	v_mul_f32_e32 v95, v94, v93
	v_fma_f32 v96, -v90, v95, v94
	v_fmac_f32_e32 v95, v96, v93
	v_fma_f32 v90, -v90, v95, v94
	v_div_fmas_f32 v90, v90, v93, v95
	v_div_fixup_f32 v64, v90, v64, 1.0
	v_mul_f32_e32 v64, v64, v86
	v_lshl_add_u64 v[80:81], s[2:3], 0, v[80:81]
	v_lshlrev_b32_e32 v87, 16, v87
	v_mul_f32_e32 v86, 0xbfb8aa3b, v87
	v_exp_f32_e32 v86, v86
	s_nop 0
	v_add_f32_e32 v86, 1.0, v86
	v_div_scale_f32 v90, s[0:1], v86, v86, v87
	v_rcp_f32_e32 v93, v90
	s_nop 0
	v_fma_f32 v94, -v90, v93, 1.0
	v_fmac_f32_e32 v93, v94, v93
	v_div_scale_f32 v94, vcc, v87, v86, v87
	v_mul_f32_e32 v95, v94, v93
	v_fma_f32 v96, -v90, v95, v94
	v_fmac_f32_e32 v95, v96, v93
	v_fma_f32 v90, -v90, v95, v94
	v_div_fmas_f32 v90, v90, v93, v95
	v_div_fixup_f32 v86, v90, v86, v87
	v_mul_f32_e32 v64, v64, v86
	v_cvt_pk_bf16_f32 v64, v64, s0
	global_store_short v[62:63], v64, off
	v_lshl_add_u64 v[62:63], v[130:131], 0, v[72:73]
	v_lshlrev_b64 v[62:63], 5, v[62:63]
	v_lshl_add_u64 v[62:63], v[66:67], 0, v[62:63]
	v_mov_b32_e32 v62, v144
	v_div_scale_f32 v87, s[0:1], v65, v65, 1.0
	v_rcp_f32_e32 v90, v87
	v_lshlrev_b32_e32 v64, 16, v62
	v_lshl_add_u64 v[62:63], v[68:69], 0, v[78:79]
	v_mov_b32_e32 v86, v150
	v_fma_f32 v93, -v87, v90, 1.0
	v_fmac_f32_e32 v90, v93, v90
	v_div_scale_f32 v93, vcc, 1.0, v65, 1.0
	v_mul_f32_e32 v94, v93, v90
	v_fma_f32 v95, -v87, v94, v93
	v_fmac_f32_e32 v94, v95, v90
	v_fma_f32 v87, -v87, v94, v93
	v_div_fmas_f32 v87, v87, v90, v94
	v_div_fixup_f32 v65, v87, v65, 1.0
	v_mul_f32_e32 v64, v65, v64
	v_lshl_add_u64 v[78:79], s[2:3], 0, v[78:79]
	v_lshlrev_b32_e32 v86, 16, v86
	v_mul_f32_e32 v65, 0xbfb8aa3b, v86
	v_exp_f32_e32 v65, v65
	s_nop 0
	v_add_f32_e32 v65, 1.0, v65
	v_div_scale_f32 v87, s[0:1], v65, v65, v86
	v_rcp_f32_e32 v90, v87
	s_nop 0
	v_fma_f32 v93, -v87, v90, 1.0
	v_fmac_f32_e32 v90, v93, v90
	v_div_scale_f32 v93, vcc, v86, v65, v86
	v_mul_f32_e32 v94, v93, v90
	v_fma_f32 v95, -v87, v94, v93
	v_fmac_f32_e32 v94, v95, v90
	v_fma_f32 v87, -v87, v94, v93
	v_div_fmas_f32 v87, v87, v90, v94
	v_div_fixup_f32 v65, v87, v65, v86
	v_mul_f32_e32 v64, v64, v65
	v_cvt_pk_bf16_f32 v64, v64, s0
	global_store_short v[62:63], v64, off
	v_or_b32_e32 v64, 16, v92
	v_lshl_add_u64 v[62:63], v[84:85], 0, s[14:15]
	v_lshl_add_u64 v[86:87], v[62:63], 2, s[4:5]
	v_lshrrev_b32_e32 v62, 4, v64
	v_or_b32_e32 v93, v64, v1
	v_mul_u32_u24_e32 v64, 0x4400, v62
	v_mov_b32_e32 v65, v131
	v_lshl_add_u64 v[62:63], v[64:65], 0, v[70:71]
	v_lshlrev_b64 v[62:63], 5, v[62:63]
	v_lshl_add_u64 v[62:63], v[66:67], 0, v[62:63]
	v_mov_b32_e32 v62, v139
	v_lshl_add_u64 v[84:85], s[2:3], 0, v[88:89]
	v_mov_b32_e32 v90, v141
	v_mov_b32_e32 v63, v131
	v_lshlrev_b32_e32 v94, 16, v62
	v_lshlrev_b32_e32 v62, 1, v93
	v_lshl_add_u64 v[88:89], v[84:85], 0, v[62:63]
	v_mov_b32_e32 v93, v148
	v_add_f32_e32 v58, v58, v90
	v_mul_f32_e32 v58, 0xbfb8aa3b, v58
	v_exp_f32_e32 v58, v58
	v_add_f32_e32 v59, v59, v90
	v_mul_f32_e32 v59, 0xbfb8aa3b, v59
	v_exp_f32_e32 v59, v59
	v_add_f32_e32 v58, 1.0, v58
	v_div_scale_f32 v95, s[0:1], v58, v58, 1.0
	v_rcp_f32_e32 v96, v95
	v_add_f32_e32 v59, 1.0, v59
	v_add_f32_e32 v60, v60, v90
	v_mul_f32_e32 v60, 0xbfb8aa3b, v60
	v_fma_f32 v97, -v95, v96, 1.0
	v_fmac_f32_e32 v96, v97, v96
	v_div_scale_f32 v97, vcc, 1.0, v58, 1.0
	v_mul_f32_e32 v98, v97, v96
	v_fma_f32 v99, -v95, v98, v97
	v_fmac_f32_e32 v98, v99, v96
	v_fma_f32 v95, -v95, v98, v97
	v_div_fmas_f32 v95, v95, v96, v98
	v_div_fixup_f32 v58, v95, v58, 1.0
	v_mul_f32_e32 v58, v58, v94
	v_exp_f32_e32 v60, v60
	v_add_f32_e32 v61, v61, v90
	v_mul_f32_e32 v61, 0xbfb8aa3b, v61
	v_exp_f32_e32 v61, v61
	v_add_f32_e32 v60, 1.0, v60
	v_add_f32_e32 v42, v42, v90
	v_mul_f32_e32 v42, 0xbfb8aa3b, v42
	v_add_f32_e32 v61, 1.0, v61
	v_exp_f32_e32 v42, v42
	v_add_f32_e32 v43, v43, v90
	v_mul_f32_e32 v43, 0xbfb8aa3b, v43
	v_exp_f32_e32 v43, v43
	v_add_f32_e32 v42, 1.0, v42
	v_add_f32_e32 v44, v44, v90
	v_mul_f32_e32 v44, 0xbfb8aa3b, v44
	v_add_f32_e32 v43, 1.0, v43
	v_exp_f32_e32 v44, v44
	v_add_f32_e32 v45, v45, v90
	v_mul_f32_e32 v45, 0xbfb8aa3b, v45
	v_exp_f32_e32 v45, v45
	v_add_f32_e32 v44, 1.0, v44
	v_add_f32_e32 v26, v26, v90
	v_mul_f32_e32 v26, 0xbfb8aa3b, v26
	v_add_f32_e32 v45, 1.0, v45
	v_exp_f32_e32 v26, v26
	v_add_f32_e32 v27, v27, v90
	v_mul_f32_e32 v27, 0xbfb8aa3b, v27
	v_exp_f32_e32 v27, v27
	v_add_f32_e32 v26, 1.0, v26
	v_add_f32_e32 v28, v28, v90
	v_mul_f32_e32 v28, 0xbfb8aa3b, v28
	v_add_f32_e32 v27, 1.0, v27
	v_exp_f32_e32 v28, v28
	v_add_f32_e32 v29, v29, v90
	v_mul_f32_e32 v29, 0xbfb8aa3b, v29
	v_exp_f32_e32 v29, v29
	v_add_f32_e32 v28, 1.0, v28
	v_add_f32_e32 v10, v10, v90
	v_mul_f32_e32 v10, 0xbfb8aa3b, v10
	v_add_f32_e32 v29, 1.0, v29
	v_exp_f32_e32 v10, v10
	v_add_f32_e32 v11, v11, v90
	v_mul_f32_e32 v11, 0xbfb8aa3b, v11
	v_exp_f32_e32 v11, v11
	v_add_f32_e32 v10, 1.0, v10
	v_add_f32_e32 v12, v12, v90
	v_mul_f32_e32 v12, 0xbfb8aa3b, v12
	v_add_f32_e32 v11, 1.0, v11
	v_exp_f32_e32 v12, v12
	v_add_f32_e32 v13, v13, v90
	v_mul_f32_e32 v13, 0xbfb8aa3b, v13
	v_exp_f32_e32 v13, v13
	v_add_f32_e32 v12, 1.0, v12
	v_lshlrev_b32_e32 v93, 16, v93
	v_mul_f32_e32 v94, 0xbfb8aa3b, v93
	v_exp_f32_e32 v94, v94
	v_add_f32_e32 v13, 1.0, v13
	v_add_f32_e32 v94, 1.0, v94
	v_div_scale_f32 v95, s[0:1], v94, v94, v93
	v_rcp_f32_e32 v96, v95
	s_nop 0
	v_fma_f32 v97, -v95, v96, 1.0
	v_fmac_f32_e32 v96, v97, v96
	v_div_scale_f32 v97, vcc, v93, v94, v93
	v_mul_f32_e32 v98, v97, v96
	v_fma_f32 v99, -v95, v98, v97
	v_fmac_f32_e32 v98, v99, v96
	v_fma_f32 v95, -v95, v98, v97
	v_div_fmas_f32 v95, v95, v96, v98
	v_div_fixup_f32 v93, v95, v94, v93
	v_mul_f32_e32 v58, v58, v93
	v_cvt_pk_bf16_f32 v58, v58, s0
	global_store_short v[88:89], v58, off
	v_lshl_add_u64 v[88:89], v[64:65], 0, v[76:77]
	v_lshlrev_b64 v[88:89], 5, v[88:89]
	v_lshl_add_u64 v[88:89], v[66:67], 0, v[88:89]
	v_mov_b32_e32 v58, v146
	v_lshl_add_u64 v[88:89], v[82:83], 0, v[62:63]
	v_mov_b32_e32 v93, v147
	v_div_scale_f32 v94, s[0:1], v59, v59, 1.0
	v_rcp_f32_e32 v95, v94
	v_lshlrev_b32_e32 v58, 16, v58
	v_fma_f32 v96, -v94, v95, 1.0
	v_fmac_f32_e32 v95, v96, v95
	v_div_scale_f32 v96, vcc, 1.0, v59, 1.0
	v_mul_f32_e32 v97, v96, v95
	v_fma_f32 v98, -v94, v97, v96
	v_fmac_f32_e32 v97, v98, v95
	v_fma_f32 v94, -v94, v97, v96
	v_div_fmas_f32 v94, v94, v95, v97
	v_lshlrev_b32_e32 v93, 16, v93
	v_div_fixup_f32 v59, v94, v59, 1.0
	v_mul_f32_e32 v58, v59, v58
	v_mul_f32_e32 v59, 0xbfb8aa3b, v93
	v_exp_f32_e32 v59, v59
	s_nop 0
	v_add_f32_e32 v59, 1.0, v59
	v_div_scale_f32 v94, s[0:1], v59, v59, v93
	v_rcp_f32_e32 v95, v94
	s_nop 0
	v_fma_f32 v96, -v94, v95, 1.0
	v_fmac_f32_e32 v95, v96, v95
	v_div_scale_f32 v96, vcc, v93, v59, v93
	v_mul_f32_e32 v97, v96, v95
	v_fma_f32 v98, -v94, v97, v96
	v_fmac_f32_e32 v97, v98, v95
	v_fma_f32 v94, -v94, v97, v96
	v_div_fmas_f32 v94, v94, v95, v97
	v_div_fixup_f32 v59, v94, v59, v93
	v_mul_f32_e32 v58, v58, v59
	v_cvt_pk_bf16_f32 v58, v58, s0
	global_store_short v[88:89], v58, off
	v_lshl_add_u64 v[58:59], v[64:65], 0, v[74:75]
	v_lshlrev_b64 v[58:59], 5, v[58:59]
	v_lshl_add_u64 v[58:59], v[66:67], 0, v[58:59]
	v_mov_b32_e32 v58, v149
	v_div_scale_f32 v93, s[0:1], v60, v60, 1.0
	v_rcp_f32_e32 v94, v93
	v_lshlrev_b32_e32 v88, 16, v58
	v_lshl_add_u64 v[58:59], v[80:81], 0, v[62:63]
	v_mov_b32_e32 v89, v154
	v_fma_f32 v95, -v93, v94, 1.0
	v_fmac_f32_e32 v94, v95, v94
	v_div_scale_f32 v95, vcc, 1.0, v60, 1.0
	v_mul_f32_e32 v96, v95, v94
	v_fma_f32 v97, -v93, v96, v95
	v_fmac_f32_e32 v96, v97, v94
	v_fma_f32 v93, -v93, v96, v95
	v_div_fmas_f32 v93, v93, v94, v96
	v_div_fixup_f32 v60, v93, v60, 1.0
	v_mul_f32_e32 v60, v60, v88
	v_lshlrev_b32_e32 v89, 16, v89
	v_mul_f32_e32 v88, 0xbfb8aa3b, v89
	v_exp_f32_e32 v88, v88
	s_nop 0
	v_add_f32_e32 v88, 1.0, v88
	v_div_scale_f32 v93, s[0:1], v88, v88, v89
	v_rcp_f32_e32 v94, v93
	s_nop 0
	v_fma_f32 v95, -v93, v94, 1.0
	v_fmac_f32_e32 v94, v95, v94
	v_div_scale_f32 v95, vcc, v89, v88, v89
	v_mul_f32_e32 v96, v95, v94
	v_fma_f32 v97, -v93, v96, v95
	v_fmac_f32_e32 v96, v97, v94
	v_fma_f32 v93, -v93, v96, v95
	v_div_fmas_f32 v93, v93, v94, v96
	v_div_fixup_f32 v88, v93, v88, v89
	v_mul_f32_e32 v60, v60, v88
	v_cvt_pk_bf16_f32 v60, v60, s0
	global_store_short v[58:59], v60, off
	v_lshl_add_u64 v[58:59], v[64:65], 0, v[72:73]
	v_lshlrev_b64 v[58:59], 5, v[58:59]
	v_lshl_add_u64 v[58:59], v[66:67], 0, v[58:59]
	v_mov_b32_e32 v58, v128
	v_div_scale_f32 v89, s[0:1], v61, v61, 1.0
	v_rcp_f32_e32 v93, v89
	v_lshlrev_b32_e32 v60, 16, v58
	v_lshl_add_u64 v[58:59], v[78:79], 0, v[62:63]
	v_mov_b32_e32 v88, v126
	v_fma_f32 v94, -v89, v93, 1.0
	v_fmac_f32_e32 v93, v94, v93
	v_div_scale_f32 v94, vcc, 1.0, v61, 1.0
	v_mul_f32_e32 v95, v94, v93
	v_fma_f32 v96, -v89, v95, v94
	v_fmac_f32_e32 v95, v96, v93
	v_fma_f32 v89, -v89, v95, v94
	v_div_fmas_f32 v89, v89, v93, v95
	v_div_fixup_f32 v61, v89, v61, 1.0
	v_mul_f32_e32 v60, v61, v60
	v_lshlrev_b32_e32 v88, 16, v88
	v_mul_f32_e32 v61, 0xbfb8aa3b, v88
	v_exp_f32_e32 v61, v61
	s_nop 0
	v_add_f32_e32 v61, 1.0, v61
	v_div_scale_f32 v89, s[0:1], v61, v61, v88
	v_rcp_f32_e32 v93, v89
	s_nop 0
	v_fma_f32 v94, -v89, v93, 1.0
	v_fmac_f32_e32 v93, v94, v93
	v_or_b32_e32 v90, 32, v92
	v_or_b32_e32 v91, v90, v1
	v_lshrrev_b32_e32 v101, 4, v90
	v_mul_u32_u24_e32 v90, 0x4400, v101
	v_mov_b32_e32 v101, v131
	v_mov_b32_e32 v102, v90
	v_mov_b32_e32 v103, v101
	v_lshl_add_u64 v[104:105], v[102:103], 0, v[70:71]
	v_lshlrev_b64 v[102:103], 5, v[104:105]
	v_lshl_add_u64 v[104:105], v[66:67], 0, v[102:103]
	global_load_ushort v102, v[104:105], off
	global_load_dword v103, v[86:87], off offset:128
	v_lshlrev_b32_e32 v104, 1, v91
	v_mov_b32_e32 v91, v131
	v_mov_b32_e32 v106, v104
	v_mov_b32_e32 v107, v91
	v_lshl_add_u64 v[108:109], v[84:85], 0, v[106:107]
	global_load_ushort v105, v[108:109], off
	v_mov_b32_e32 v106, v90
	v_mov_b32_e32 v107, v101
	v_lshl_add_u64 v[108:109], v[106:107], 0, v[76:77]
	v_lshlrev_b64 v[106:107], 5, v[108:109]
	v_lshl_add_u64 v[108:109], v[66:67], 0, v[106:107]
	global_load_ushort v106, v[108:109], off
	v_mov_b32_e32 v108, v104
	v_mov_b32_e32 v109, v91
	v_lshl_add_u64 v[110:111], v[82:83], 0, v[108:109]
	global_load_ushort v107, v[110:111], off
	v_mov_b32_e32 v108, v90
	v_mov_b32_e32 v109, v101
	v_lshl_add_u64 v[110:111], v[108:109], 0, v[74:75]
	v_lshlrev_b64 v[108:109], 5, v[110:111]
	v_lshl_add_u64 v[110:111], v[66:67], 0, v[108:109]
	global_load_ushort v108, v[110:111], off
	v_mov_b32_e32 v110, v104
	v_mov_b32_e32 v111, v91
	v_lshl_add_u64 v[112:113], v[80:81], 0, v[110:111]
	global_load_ushort v109, v[112:113], off
	v_mov_b32_e32 v110, v90
	v_mov_b32_e32 v111, v101
	v_lshl_add_u64 v[112:113], v[110:111], 0, v[72:73]
	v_lshlrev_b64 v[110:111], 5, v[112:113]
	v_lshl_add_u64 v[112:113], v[66:67], 0, v[110:111]
	global_load_ushort v110, v[112:113], off
	v_mov_b32_e32 v112, v104
	v_mov_b32_e32 v113, v91
	v_lshl_add_u64 v[114:115], v[78:79], 0, v[112:113]
	global_load_ushort v111, v[114:115], off
	v_or_b32_e32 v112, 48, v92
	v_or_b32_e32 v113, v112, v1
	v_lshrrev_b32_e32 v114, 4, v112
	v_mul_u32_u24_e32 v112, 0x4400, v114
	v_mov_b32_e32 v114, v131
	global_load_dword v115, v[86:87], off offset:192
	v_mov_b32_e32 v116, v112
	v_mov_b32_e32 v117, v114
	v_lshl_add_u64 v[118:119], v[116:117], 0, v[70:71]
	v_lshlrev_b64 v[116:117], 5, v[118:119]
	v_lshl_add_u64 v[118:119], v[66:67], 0, v[116:117]
	global_load_ushort v116, v[118:119], off
	v_lshlrev_b32_e32 v117, 1, v113
	v_mov_b32_e32 v118, v112
	v_mov_b32_e32 v119, v114
	v_lshl_add_u64 v[120:121], v[118:119], 0, v[76:77]
	v_lshlrev_b64 v[118:119], 5, v[120:121]
	v_lshl_add_u64 v[120:121], v[66:67], 0, v[118:119]
	v_mov_b32_e32 v113, v131
	v_mov_b32_e32 v118, v117
	v_mov_b32_e32 v119, v113
	v_lshl_add_u64 v[122:123], v[84:85], 0, v[118:119]
	global_load_ushort v118, v[122:123], off
	global_load_ushort v119, v[120:121], off
	v_mov_b32_e32 v120, v117
	v_mov_b32_e32 v121, v113
	v_lshl_add_u64 v[122:123], v[82:83], 0, v[120:121]
	global_load_ushort v120, v[122:123], off
	v_mov_b32_e32 v122, v112
	v_mov_b32_e32 v123, v114
	v_lshl_add_u64 v[124:125], v[122:123], 0, v[74:75]
	v_lshlrev_b64 v[122:123], 5, v[124:125]
	v_lshl_add_u64 v[124:125], v[66:67], 0, v[122:123]
	global_load_ushort v121, v[124:125], off
	v_mov_b32_e32 v122, v117
	v_mov_b32_e32 v123, v113
	v_lshl_add_u64 v[124:125], v[80:81], 0, v[122:123]
	global_load_ushort v122, v[124:125], off
	v_mov_b32_e32 v124, v112
	v_mov_b32_e32 v125, v114
	v_lshl_add_u64 v[126:127], v[124:125], 0, v[72:73]
	v_lshlrev_b64 v[124:125], 5, v[126:127]
	v_lshl_add_u64 v[126:127], v[66:67], 0, v[124:125]
	global_load_ushort v123, v[126:127], off
	v_mov_b32_e32 v124, v117
	v_mov_b32_e32 v125, v113
	v_lshl_add_u64 v[126:127], v[78:79], 0, v[124:125]
	global_load_ushort v113, v[126:127], off
	v_or_b32_e32 v117, 16, v70
	v_ashrrev_i32_e32 v124, 31, v117
	v_mov_b32_e32 v126, v117
	v_mov_b32_e32 v127, v124
	v_lshl_add_u64 v[128:129], v[130:131], 0, v[126:127]
	v_lshlrev_b64 v[126:127], 5, v[128:129]
	v_mov_b32_e32 v128, v117
	v_mov_b32_e32 v129, v124
	v_lshlrev_b64 v[138:139], 10, v[128:129]
	v_lshl_add_u64 v[128:129], v[66:67], 0, v[126:127]
	global_load_ushort v125, v[128:129], off
	v_lshl_add_u64 v[126:127], v[68:69], 0, v[138:139]
	global_load_ushort v128, v[126:127], off
	v_or_b32_e32 v126, 17, v70
	v_ashrrev_i32_e32 v127, 31, v126
	v_lshlrev_b64 v[140:141], 10, v[126:127]
	v_or_b32_e32 v129, 18, v70
	v_ashrrev_i32_e32 v134, 31, v129
	v_mov_b32_e32 v142, v129
	v_mov_b32_e32 v143, v134
	v_lshlrev_b64 v[144:145], 10, v[142:143]
	v_or_b32_e32 v137, 19, v70
	v_ashrrev_i32_e32 v142, 31, v137
	v_mov_b32_e32 v146, v137
	v_mov_b32_e32 v147, v142
	v_lshlrev_b64 v[148:149], 10, v[146:147]
	v_lshl_add_u64 v[146:147], v[130:131], 0, v[126:127]
	v_lshlrev_b64 v[150:151], 5, v[146:147]
	v_lshl_add_u64 v[146:147], v[66:67], 0, v[150:151]
	global_load_ushort v143, v[146:147], off
	v_lshl_add_u64 v[146:147], v[68:69], 0, v[140:141]
	global_load_ushort v150, v[146:147], off
	v_mov_b32_e32 v146, v129
	v_mov_b32_e32 v147, v134
	v_lshl_add_u64 v[152:153], v[130:131], 0, v[146:147]
	v_lshlrev_b64 v[146:147], 5, v[152:153]
	v_lshl_add_u64 v[152:153], v[66:67], 0, v[146:147]
	global_load_ushort v146, v[152:153], off
	v_lshl_add_u64 v[152:153], v[68:69], 0, v[144:145]
	global_load_ushort v147, v[152:153], off
	v_mov_b32_e32 v152, v137
	v_mov_b32_e32 v153, v142
	v_lshl_add_u64 v[154:155], v[130:131], 0, v[152:153]
	v_lshlrev_b64 v[152:153], 5, v[154:155]
	v_lshl_add_u64 v[154:155], v[66:67], 0, v[152:153]
	global_load_ushort v151, v[154:155], off
	v_lshl_add_u64 v[152:153], v[68:69], 0, v[148:149]
	global_load_ushort v154, v[152:153], off
	v_lshl_add_u64 v[152:153], s[2:3], 0, v[148:149]
	v_mov_b32_e32 v148, v117
	v_mov_b32_e32 v149, v124
	v_lshl_add_u64 v[156:157], v[64:65], 0, v[148:149]
	v_lshlrev_b64 v[148:149], 5, v[156:157]
	v_lshl_add_u64 v[156:157], v[66:67], 0, v[148:149]
	global_load_ushort v148, v[156:157], off
	v_lshl_add_u64 v[156:157], s[2:3], 0, v[138:139]
	v_lshl_add_u64 v[138:139], v[156:157], 0, v[62:63]
	global_load_ushort v149, v[138:139], off
	v_lshl_add_u64 v[138:139], v[64:65], 0, v[126:127]
	v_lshlrev_b64 v[158:159], 5, v[138:139]
	v_lshl_add_u64 v[138:139], v[66:67], 0, v[158:159]
	global_load_ushort v155, v[138:139], off
	v_lshl_add_u64 v[138:139], s[2:3], 0, v[140:141]
	v_lshl_add_u64 v[140:141], v[138:139], 0, v[62:63]
	global_load_ushort v158, v[140:141], off
	v_mov_b32_e32 v140, v129
	v_mov_b32_e32 v141, v134
	v_lshl_add_u64 v[162:163], v[64:65], 0, v[140:141]
	v_lshlrev_b64 v[140:141], 5, v[162:163]
	v_lshl_add_u64 v[162:163], v[66:67], 0, v[140:141]
	global_load_ushort v140, v[162:163], off
	v_lshl_add_u64 v[162:163], s[2:3], 0, v[144:145]
	v_lshl_add_u64 v[144:145], v[162:163], 0, v[62:63]
	global_load_ushort v141, v[144:145], off
	v_mov_b32_e32 v144, v137
	v_mov_b32_e32 v145, v142
	v_lshl_add_u64 v[164:165], v[64:65], 0, v[144:145]
	v_lshlrev_b64 v[144:145], 5, v[164:165]
	v_lshl_add_u64 v[164:165], v[66:67], 0, v[144:145]
	global_load_ushort v144, v[164:165], off
	v_lshl_add_u64 v[164:165], v[152:153], 0, v[62:63]
	global_load_ushort v145, v[164:165], off
	v_mov_b32_e32 v164, v90
	v_mov_b32_e32 v165, v101
	v_mov_b32_e32 v168, v117
	v_mov_b32_e32 v169, v124
	v_lshl_add_u64 v[170:171], v[164:165], 0, v[168:169]
	v_lshlrev_b64 v[164:165], 5, v[170:171]
	v_lshl_add_u64 v[168:169], v[66:67], 0, v[164:165]
	global_load_ushort v159, v[168:169], off
	v_mov_b32_e32 v164, v104
	v_mov_b32_e32 v165, v91
	v_lshl_add_u64 v[168:169], v[156:157], 0, v[164:165]
	global_load_ushort v156, v[168:169], off
	v_mov_b32_e32 v164, v90
	v_mov_b32_e32 v165, v101
	v_lshl_add_u64 v[168:169], v[164:165], 0, v[126:127]
	v_lshlrev_b64 v[126:127], 5, v[168:169]
	v_lshl_add_u64 v[164:165], v[66:67], 0, v[126:127]
	global_load_ushort v126, v[164:165], off
	v_mov_b32_e32 v164, v104
	v_mov_b32_e32 v165, v91
	v_lshl_add_u64 v[168:169], v[138:139], 0, v[164:165]
	global_load_ushort v127, v[168:169], off
	v_mov_b32_e32 v138, v90
	v_mov_b32_e32 v139, v101
	v_mov_b32_e32 v164, v129
	v_mov_b32_e32 v165, v134
	v_lshl_add_u64 v[168:169], v[138:139], 0, v[164:165]
	v_lshlrev_b64 v[138:139], 5, v[168:169]
	v_lshl_add_u64 v[164:165], v[66:67], 0, v[138:139]
	global_load_ushort v129, v[164:165], off
	v_mov_b32_e32 v138, v104
	v_mov_b32_e32 v139, v91
	v_lshl_add_u64 v[164:165], v[162:163], 0, v[138:139]
	global_load_ushort v134, v[164:165], off
	v_mov_b32_e32 v138, v90
	v_mov_b32_e32 v139, v101
	v_mov_b32_e32 v162, v137
	v_mov_b32_e32 v163, v142
	v_lshl_add_u64 v[164:165], v[138:139], 0, v[162:163]
	v_lshlrev_b64 v[138:139], 5, v[164:165]
	v_lshl_add_u64 v[162:163], v[66:67], 0, v[138:139]
	global_load_ushort v90, v[162:163], off
	v_mov_b32_e32 v138, v104
	v_mov_b32_e32 v139, v91
	v_lshl_add_u64 v[162:163], v[152:153], 0, v[138:139]
	global_load_ushort v91, v[162:163], off
	v_mov_b32_e32 v138, v112
	v_mov_b32_e32 v139, v114
	v_mov_b32_e32 v152, v117
	v_mov_b32_e32 v153, v124
	v_lshl_add_u64 v[162:163], v[138:139], 0, v[152:153]
	v_lshlrev_b64 v[138:139], 5, v[162:163]
	v_lshl_add_u64 v[152:153], v[66:67], 0, v[138:139]
	global_load_ushort v101, v[152:153], off
	v_div_scale_f32 v94, vcc, v88, v61, v88
	v_mul_f32_e32 v95, v94, v93
	v_fma_f32 v96, -v89, v95, v94
	v_fmac_f32_e32 v95, v96, v93
	v_fma_f32 v89, -v89, v95, v94
	v_div_fmas_f32 v89, v89, v93, v95
	v_div_fixup_f32 v61, v89, v61, v88
	v_mul_f32_e32 v60, v60, v61
	v_cvt_pk_bf16_f32 v60, v60, s0
	global_store_short v[58:59], v60, off
	v_or_b32_e32 v59, 32, v92
	v_or_b32_e32 v58, v59, v1
	v_lshrrev_b32_e32 v59, 4, v59
	v_mul_u32_u24_e32 v60, 0x4400, v59
	v_mov_b32_e32 v61, v131
	v_lshl_add_u64 v[94:95], v[60:61], 0, v[70:71]
	v_lshlrev_b64 v[94:95], 5, v[94:95]
	v_lshl_add_u64 v[94:95], v[66:67], 0, v[94:95]
	s_waitcnt vmcnt(0)
	v_mov_b32_e32 v59, v102
	v_mov_b32_e32 v88, v103
	v_lshlrev_b32_e32 v58, 1, v58
	v_lshlrev_b32_e32 v89, 16, v59
	v_mov_b32_e32 v59, v131
	v_lshl_add_u64 v[94:95], v[84:85], 0, v[58:59]
	v_mov_b32_e32 v93, v105
	v_add_f32_e32 v54, v54, v88
	v_mul_f32_e32 v54, 0xbfb8aa3b, v54
	v_exp_f32_e32 v54, v54
	v_add_f32_e32 v55, v55, v88
	v_mul_f32_e32 v55, 0xbfb8aa3b, v55
	v_exp_f32_e32 v55, v55
	v_add_f32_e32 v54, 1.0, v54
	v_div_scale_f32 v96, s[0:1], v54, v54, 1.0
	v_rcp_f32_e32 v97, v96
	v_add_f32_e32 v55, 1.0, v55
	v_add_f32_e32 v56, v56, v88
	v_mul_f32_e32 v56, 0xbfb8aa3b, v56
	v_fma_f32 v98, -v96, v97, 1.0
	v_fmac_f32_e32 v97, v98, v97
	v_div_scale_f32 v98, vcc, 1.0, v54, 1.0
	v_mul_f32_e32 v99, v98, v97
	v_fma_f32 v100, -v96, v99, v98
	v_fmac_f32_e32 v99, v100, v97
	v_fma_f32 v96, -v96, v99, v98
	v_div_fmas_f32 v96, v96, v97, v99
	v_div_fixup_f32 v54, v96, v54, 1.0
	v_mul_f32_e32 v54, v54, v89
	v_exp_f32_e32 v56, v56
	v_add_f32_e32 v57, v57, v88
	v_mul_f32_e32 v57, 0xbfb8aa3b, v57
	v_exp_f32_e32 v57, v57
	v_add_f32_e32 v56, 1.0, v56
	v_add_f32_e32 v38, v38, v88
	v_mul_f32_e32 v38, 0xbfb8aa3b, v38
	v_add_f32_e32 v57, 1.0, v57
	v_exp_f32_e32 v38, v38
	v_add_f32_e32 v39, v39, v88
	v_mul_f32_e32 v39, 0xbfb8aa3b, v39
	v_exp_f32_e32 v39, v39
	v_add_f32_e32 v38, 1.0, v38
	v_add_f32_e32 v40, v40, v88
	v_mul_f32_e32 v40, 0xbfb8aa3b, v40
	v_add_f32_e32 v39, 1.0, v39
	v_exp_f32_e32 v40, v40
	v_add_f32_e32 v41, v41, v88
	v_mul_f32_e32 v41, 0xbfb8aa3b, v41
	v_exp_f32_e32 v41, v41
	v_add_f32_e32 v40, 1.0, v40
	v_add_f32_e32 v22, v22, v88
	v_mul_f32_e32 v22, 0xbfb8aa3b, v22
	v_add_f32_e32 v41, 1.0, v41
	v_exp_f32_e32 v22, v22
	v_add_f32_e32 v23, v23, v88
	v_mul_f32_e32 v23, 0xbfb8aa3b, v23
	v_exp_f32_e32 v23, v23
	v_add_f32_e32 v22, 1.0, v22
	v_add_f32_e32 v24, v24, v88
	v_mul_f32_e32 v24, 0xbfb8aa3b, v24
	v_add_f32_e32 v23, 1.0, v23
	v_exp_f32_e32 v24, v24
	v_add_f32_e32 v25, v25, v88
	v_mul_f32_e32 v25, 0xbfb8aa3b, v25
	v_exp_f32_e32 v25, v25
	v_add_f32_e32 v24, 1.0, v24
	v_add_f32_e32 v6, v6, v88
	v_mul_f32_e32 v6, 0xbfb8aa3b, v6
	v_add_f32_e32 v25, 1.0, v25
	v_exp_f32_e32 v6, v6
	v_add_f32_e32 v7, v7, v88
	v_mul_f32_e32 v7, 0xbfb8aa3b, v7
	v_exp_f32_e32 v7, v7
	v_add_f32_e32 v6, 1.0, v6
	v_add_f32_e32 v8, v8, v88
	v_mul_f32_e32 v8, 0xbfb8aa3b, v8
	v_add_f32_e32 v7, 1.0, v7
	v_exp_f32_e32 v8, v8
	v_add_f32_e32 v9, v9, v88
	v_mul_f32_e32 v9, 0xbfb8aa3b, v9
	v_exp_f32_e32 v9, v9
	v_add_f32_e32 v8, 1.0, v8
	v_lshlrev_b32_e32 v93, 16, v93
	v_mul_f32_e32 v89, 0xbfb8aa3b, v93
	v_exp_f32_e32 v89, v89
	v_add_f32_e32 v9, 1.0, v9
	v_add_f32_e32 v89, 1.0, v89
	v_div_scale_f32 v96, s[0:1], v89, v89, v93
	v_rcp_f32_e32 v97, v96
	s_nop 0
	v_fma_f32 v98, -v96, v97, 1.0
	v_fmac_f32_e32 v97, v98, v97
	v_div_scale_f32 v98, vcc, v93, v89, v93
	v_mul_f32_e32 v99, v98, v97
	v_fma_f32 v100, -v96, v99, v98
	v_fmac_f32_e32 v99, v100, v97
	v_fma_f32 v96, -v96, v99, v98
	v_div_fmas_f32 v96, v96, v97, v99
	v_div_fixup_f32 v89, v96, v89, v93
	v_mul_f32_e32 v54, v54, v89
	v_cvt_pk_bf16_f32 v54, v54, s0
	global_store_short v[94:95], v54, off
	v_lshl_add_u64 v[94:95], v[60:61], 0, v[76:77]
	v_lshlrev_b64 v[94:95], 5, v[94:95]
	v_lshl_add_u64 v[94:95], v[66:67], 0, v[94:95]
	v_mov_b32_e32 v54, v106
	v_lshl_add_u64 v[94:95], v[82:83], 0, v[58:59]
	v_mov_b32_e32 v89, v107
	v_div_scale_f32 v93, s[0:1], v55, v55, 1.0
	v_rcp_f32_e32 v96, v93
	v_lshlrev_b32_e32 v54, 16, v54
	v_fma_f32 v97, -v93, v96, 1.0
	v_fmac_f32_e32 v96, v97, v96
	v_div_scale_f32 v97, vcc, 1.0, v55, 1.0
	v_mul_f32_e32 v98, v97, v96
	v_fma_f32 v99, -v93, v98, v97
	v_fmac_f32_e32 v98, v99, v96
	v_fma_f32 v93, -v93, v98, v97
	v_div_fmas_f32 v93, v93, v96, v98
	v_lshlrev_b32_e32 v89, 16, v89
	v_div_fixup_f32 v55, v93, v55, 1.0
	v_mul_f32_e32 v54, v55, v54
	v_mul_f32_e32 v55, 0xbfb8aa3b, v89
	v_exp_f32_e32 v55, v55
	s_nop 0
	v_add_f32_e32 v55, 1.0, v55
	v_div_scale_f32 v93, s[0:1], v55, v55, v89
	v_rcp_f32_e32 v96, v93
	s_nop 0
	v_fma_f32 v97, -v93, v96, 1.0
	v_fmac_f32_e32 v96, v97, v96
	v_div_scale_f32 v97, vcc, v89, v55, v89
	v_mul_f32_e32 v98, v97, v96
	v_fma_f32 v99, -v93, v98, v97
	v_fmac_f32_e32 v98, v99, v96
	v_fma_f32 v93, -v93, v98, v97
	v_div_fmas_f32 v93, v93, v96, v98
	v_div_fixup_f32 v55, v93, v55, v89
	v_mul_f32_e32 v54, v54, v55
	v_cvt_pk_bf16_f32 v54, v54, s0
	global_store_short v[94:95], v54, off
	v_lshl_add_u64 v[54:55], v[60:61], 0, v[74:75]
	v_lshlrev_b64 v[54:55], 5, v[54:55]
	v_lshl_add_u64 v[54:55], v[66:67], 0, v[54:55]
	v_mov_b32_e32 v54, v108
	v_div_scale_f32 v94, s[0:1], v56, v56, 1.0
	v_rcp_f32_e32 v95, v94
	v_lshlrev_b32_e32 v89, 16, v54
	v_lshl_add_u64 v[54:55], v[80:81], 0, v[58:59]
	v_mov_b32_e32 v93, v109
	v_fma_f32 v96, -v94, v95, 1.0
	v_fmac_f32_e32 v95, v96, v95
	v_div_scale_f32 v96, vcc, 1.0, v56, 1.0
	v_mul_f32_e32 v97, v96, v95
	v_fma_f32 v98, -v94, v97, v96
	v_fmac_f32_e32 v97, v98, v95
	v_fma_f32 v94, -v94, v97, v96
	v_div_fmas_f32 v94, v94, v95, v97
	v_div_fixup_f32 v56, v94, v56, 1.0
	v_mul_f32_e32 v56, v56, v89
	v_lshlrev_b32_e32 v93, 16, v93
	v_mul_f32_e32 v89, 0xbfb8aa3b, v93
	v_exp_f32_e32 v89, v89
	s_nop 0
	v_add_f32_e32 v89, 1.0, v89
	v_div_scale_f32 v94, s[0:1], v89, v89, v93
	v_rcp_f32_e32 v95, v94
	s_nop 0
	v_fma_f32 v96, -v94, v95, 1.0
	v_fmac_f32_e32 v95, v96, v95
	v_div_scale_f32 v96, vcc, v93, v89, v93
	v_mul_f32_e32 v97, v96, v95
	v_fma_f32 v98, -v94, v97, v96
	v_fmac_f32_e32 v97, v98, v95
	v_fma_f32 v94, -v94, v97, v96
	v_div_fmas_f32 v94, v94, v95, v97
	v_div_fixup_f32 v89, v94, v89, v93
	v_mul_f32_e32 v56, v56, v89
	v_cvt_pk_bf16_f32 v56, v56, s0
	global_store_short v[54:55], v56, off
	v_lshl_add_u64 v[54:55], v[60:61], 0, v[72:73]
	v_lshlrev_b64 v[54:55], 5, v[54:55]
	v_lshl_add_u64 v[54:55], v[66:67], 0, v[54:55]
	v_mov_b32_e32 v54, v110
	v_div_scale_f32 v93, s[0:1], v57, v57, 1.0
	v_rcp_f32_e32 v94, v93
	v_lshlrev_b32_e32 v56, 16, v54
	v_lshl_add_u64 v[54:55], v[78:79], 0, v[58:59]
	v_mov_b32_e32 v89, v111
	v_fma_f32 v95, -v93, v94, 1.0
	v_fmac_f32_e32 v94, v95, v94
	v_div_scale_f32 v95, vcc, 1.0, v57, 1.0
	v_mul_f32_e32 v96, v95, v94
	v_fma_f32 v97, -v93, v96, v95
	v_fmac_f32_e32 v96, v97, v94
	v_fma_f32 v93, -v93, v96, v95
	v_div_fmas_f32 v93, v93, v94, v96
	v_div_fixup_f32 v57, v93, v57, 1.0
	v_mul_f32_e32 v56, v57, v56
	v_lshlrev_b32_e32 v89, 16, v89
	v_mul_f32_e32 v57, 0xbfb8aa3b, v89
	v_exp_f32_e32 v57, v57
	s_nop 0
	v_add_f32_e32 v57, 1.0, v57
	v_div_scale_f32 v93, s[0:1], v57, v57, v89
	v_rcp_f32_e32 v94, v93
	s_nop 0
	v_fma_f32 v95, -v93, v94, 1.0
	v_fmac_f32_e32 v94, v95, v94
	v_div_scale_f32 v95, vcc, v89, v57, v89
	v_mul_f32_e32 v96, v95, v94
	v_fma_f32 v97, -v93, v96, v95
	v_fmac_f32_e32 v96, v97, v94
	v_fma_f32 v93, -v93, v96, v95
	v_div_fmas_f32 v93, v93, v94, v96
	v_div_fixup_f32 v57, v93, v57, v89
	v_mul_f32_e32 v56, v56, v57
	v_cvt_pk_bf16_f32 v56, v56, s0
	global_store_short v[54:55], v56, off
	v_or_b32_e32 v55, 48, v92
	v_or_b32_e32 v54, v55, v1
	v_lshrrev_b32_e32 v55, 4, v55
	v_mul_u32_u24_e32 v56, 0x4400, v55
	v_mov_b32_e32 v57, v131
	v_mov_b32_e32 v1, v115
	v_lshl_add_u64 v[86:87], v[56:57], 0, v[70:71]
	v_lshlrev_b64 v[86:87], 5, v[86:87]
	v_lshl_add_u64 v[86:87], v[66:67], 0, v[86:87]
	v_mov_b32_e32 v55, v116
	v_lshlrev_b32_e32 v54, 1, v54
	v_lshl_add_u64 v[76:77], v[56:57], 0, v[76:77]
	v_lshlrev_b64 v[76:77], 5, v[76:77]
	v_lshl_add_u64 v[76:77], v[66:67], 0, v[76:77]
	v_add_f32_e32 v50, v50, v1
	v_mul_f32_e32 v50, 0xbfb8aa3b, v50
	v_exp_f32_e32 v50, v50
	v_add_f32_e32 v51, v51, v1
	v_lshlrev_b32_e32 v86, 16, v55
	v_mov_b32_e32 v55, v131
	v_lshl_add_u64 v[84:85], v[84:85], 0, v[54:55]
	v_mov_b32_e32 v71, v118
	v_add_f32_e32 v50, 1.0, v50
	v_div_scale_f32 v87, s[0:1], v50, v50, 1.0
	v_rcp_f32_e32 v89, v87
	v_mul_f32_e32 v51, 0xbfb8aa3b, v51
	v_exp_f32_e32 v51, v51
	v_add_f32_e32 v52, v52, v1
	v_fma_f32 v92, -v87, v89, 1.0
	v_fmac_f32_e32 v89, v92, v89
	v_div_scale_f32 v92, vcc, 1.0, v50, 1.0
	v_mul_f32_e32 v93, v92, v89
	v_fma_f32 v94, -v87, v93, v92
	v_fmac_f32_e32 v93, v94, v89
	v_fma_f32 v87, -v87, v93, v92
	v_div_fmas_f32 v87, v87, v89, v93
	v_div_fixup_f32 v50, v87, v50, 1.0
	v_mul_f32_e32 v50, v50, v86
	v_add_f32_e32 v51, 1.0, v51
	v_mul_f32_e32 v52, 0xbfb8aa3b, v52
	v_exp_f32_e32 v52, v52
	v_add_f32_e32 v53, v53, v1
	v_mul_f32_e32 v53, 0xbfb8aa3b, v53
	v_exp_f32_e32 v53, v53
	v_add_f32_e32 v52, 1.0, v52
	v_add_f32_e32 v34, v34, v1
	v_mul_f32_e32 v34, 0xbfb8aa3b, v34
	v_add_f32_e32 v53, 1.0, v53
	v_exp_f32_e32 v34, v34
	v_add_f32_e32 v35, v35, v1
	v_mul_f32_e32 v35, 0xbfb8aa3b, v35
	v_exp_f32_e32 v35, v35
	v_add_f32_e32 v34, 1.0, v34
	v_add_f32_e32 v36, v36, v1
	v_mul_f32_e32 v36, 0xbfb8aa3b, v36
	v_add_f32_e32 v35, 1.0, v35
	v_exp_f32_e32 v36, v36
	v_add_f32_e32 v37, v37, v1
	v_mul_f32_e32 v37, 0xbfb8aa3b, v37
	v_exp_f32_e32 v37, v37
	v_add_f32_e32 v36, 1.0, v36
	v_add_f32_e32 v18, v18, v1
	v_mul_f32_e32 v18, 0xbfb8aa3b, v18
	v_add_f32_e32 v37, 1.0, v37
	v_exp_f32_e32 v18, v18
	v_add_f32_e32 v19, v19, v1
	v_mul_f32_e32 v19, 0xbfb8aa3b, v19
	v_exp_f32_e32 v19, v19
	v_add_f32_e32 v18, 1.0, v18
	v_add_f32_e32 v20, v20, v1
	v_mul_f32_e32 v20, 0xbfb8aa3b, v20
	v_add_f32_e32 v19, 1.0, v19
	v_exp_f32_e32 v20, v20
	v_add_f32_e32 v21, v21, v1
	v_mul_f32_e32 v21, 0xbfb8aa3b, v21
	v_exp_f32_e32 v21, v21
	v_add_f32_e32 v20, 1.0, v20
	v_add_f32_e32 v2, v2, v1
	v_mul_f32_e32 v2, 0xbfb8aa3b, v2
	v_add_f32_e32 v21, 1.0, v21
	v_exp_f32_e32 v2, v2
	v_add_f32_e32 v3, v3, v1
	v_mul_f32_e32 v3, 0xbfb8aa3b, v3
	v_exp_f32_e32 v3, v3
	v_add_f32_e32 v2, 1.0, v2
	v_add_f32_e32 v4, v4, v1
	v_mul_f32_e32 v4, 0xbfb8aa3b, v4
	v_add_f32_e32 v3, 1.0, v3
	v_exp_f32_e32 v4, v4
	v_add_f32_e32 v1, v5, v1
	v_mul_f32_e32 v1, 0xbfb8aa3b, v1
	v_exp_f32_e32 v1, v1
	v_add_f32_e32 v4, 1.0, v4
	v_add_f32_e32 v1, 1.0, v1
	v_lshlrev_b32_e32 v71, 16, v71
	v_mul_f32_e32 v86, 0xbfb8aa3b, v71
	v_exp_f32_e32 v86, v86
	s_nop 0
	v_add_f32_e32 v86, 1.0, v86
	v_div_scale_f32 v87, s[0:1], v86, v86, v71
	v_rcp_f32_e32 v89, v87
	s_nop 0
	v_fma_f32 v92, -v87, v89, 1.0
	v_fmac_f32_e32 v89, v92, v89
	v_div_scale_f32 v92, vcc, v71, v86, v71
	v_mul_f32_e32 v93, v92, v89
	v_fma_f32 v94, -v87, v93, v92
	v_fmac_f32_e32 v93, v94, v89
	v_fma_f32 v87, -v87, v93, v92
	v_div_fmas_f32 v87, v87, v89, v93
	v_div_fixup_f32 v71, v87, v86, v71
	v_mul_f32_e32 v50, v50, v71
	v_cvt_pk_bf16_f32 v50, v50, s0
	global_store_short v[84:85], v50, off
	v_mov_b32_e32 v50, v119
	v_lshl_add_u64 v[76:77], v[82:83], 0, v[54:55]
	v_mov_b32_e32 v71, v120
	v_div_scale_f32 v82, s[0:1], v51, v51, 1.0
	v_rcp_f32_e32 v83, v82
	v_lshlrev_b32_e32 v50, 16, v50
	v_fma_f32 v84, -v82, v83, 1.0
	v_fmac_f32_e32 v83, v84, v83
	v_div_scale_f32 v84, vcc, 1.0, v51, 1.0
	v_mul_f32_e32 v85, v84, v83
	v_fma_f32 v86, -v82, v85, v84
	v_fmac_f32_e32 v85, v86, v83
	v_fma_f32 v82, -v82, v85, v84
	v_div_fmas_f32 v82, v82, v83, v85
	v_lshlrev_b32_e32 v71, 16, v71
	v_div_fixup_f32 v51, v82, v51, 1.0
	v_mul_f32_e32 v50, v51, v50
	v_mul_f32_e32 v51, 0xbfb8aa3b, v71
	v_exp_f32_e32 v51, v51
	s_nop 0
	v_add_f32_e32 v51, 1.0, v51
	v_div_scale_f32 v82, s[0:1], v51, v51, v71
	v_rcp_f32_e32 v83, v82
	s_nop 0
	v_fma_f32 v84, -v82, v83, 1.0
	v_fmac_f32_e32 v83, v84, v83
	v_div_scale_f32 v84, vcc, v71, v51, v71
	v_mul_f32_e32 v85, v84, v83
	v_fma_f32 v86, -v82, v85, v84
	v_fmac_f32_e32 v85, v86, v83
	v_fma_f32 v82, -v82, v85, v84
	v_div_fmas_f32 v82, v82, v83, v85
	v_div_fixup_f32 v51, v82, v51, v71
	v_mul_f32_e32 v50, v50, v51
	v_cvt_pk_bf16_f32 v50, v50, s0
	global_store_short v[76:77], v50, off
	v_lshl_add_u64 v[50:51], v[56:57], 0, v[74:75]
	v_lshlrev_b64 v[50:51], 5, v[50:51]
	v_lshl_add_u64 v[50:51], v[66:67], 0, v[50:51]
	v_mov_b32_e32 v50, v121
	v_div_scale_f32 v75, s[0:1], v52, v52, 1.0
	v_rcp_f32_e32 v76, v75
	v_lshlrev_b32_e32 v71, 16, v50
	v_lshl_add_u64 v[50:51], v[80:81], 0, v[54:55]
	v_mov_b32_e32 v74, v122
	v_fma_f32 v77, -v75, v76, 1.0
	v_fmac_f32_e32 v76, v77, v76
	v_div_scale_f32 v77, vcc, 1.0, v52, 1.0
	v_mul_f32_e32 v80, v77, v76
	v_fma_f32 v81, -v75, v80, v77
	v_fmac_f32_e32 v80, v81, v76
	v_fma_f32 v75, -v75, v80, v77
	v_div_fmas_f32 v75, v75, v76, v80
	v_div_fixup_f32 v52, v75, v52, 1.0
	v_mul_f32_e32 v52, v52, v71
	v_lshlrev_b32_e32 v74, 16, v74
	v_mul_f32_e32 v71, 0xbfb8aa3b, v74
	v_exp_f32_e32 v71, v71
	s_nop 0
	v_add_f32_e32 v71, 1.0, v71
	v_div_scale_f32 v75, s[0:1], v71, v71, v74
	v_rcp_f32_e32 v76, v75
	s_nop 0
	v_fma_f32 v77, -v75, v76, 1.0
	v_fmac_f32_e32 v76, v77, v76
	v_div_scale_f32 v77, vcc, v74, v71, v74
	v_mul_f32_e32 v80, v77, v76
	v_fma_f32 v81, -v75, v80, v77
	v_fmac_f32_e32 v80, v81, v76
	v_fma_f32 v75, -v75, v80, v77
	v_div_fmas_f32 v75, v75, v76, v80
	v_div_fixup_f32 v71, v75, v71, v74
	v_mul_f32_e32 v52, v52, v71
	v_cvt_pk_bf16_f32 v52, v52, s0
	global_store_short v[50:51], v52, off
	v_lshl_add_u64 v[50:51], v[56:57], 0, v[72:73]
	v_lshlrev_b64 v[50:51], 5, v[50:51]
	v_lshl_add_u64 v[50:51], v[66:67], 0, v[50:51]
	v_mov_b32_e32 v50, v123
	v_div_scale_f32 v72, s[0:1], v53, v53, 1.0
	v_rcp_f32_e32 v73, v72
	v_lshlrev_b32_e32 v52, 16, v50
	v_lshl_add_u64 v[50:51], v[78:79], 0, v[54:55]
	v_mov_b32_e32 v71, v113
	v_fma_f32 v74, -v72, v73, 1.0
	v_fmac_f32_e32 v73, v74, v73
	v_div_scale_f32 v74, vcc, 1.0, v53, 1.0
	v_mul_f32_e32 v75, v74, v73
	v_fma_f32 v76, -v72, v75, v74
	v_fmac_f32_e32 v75, v76, v73
	v_fma_f32 v72, -v72, v75, v74
	v_div_fmas_f32 v72, v72, v73, v75
	v_div_fixup_f32 v53, v72, v53, 1.0
	v_mul_f32_e32 v52, v53, v52
	v_lshlrev_b32_e32 v71, 16, v71
	v_mul_f32_e32 v53, 0xbfb8aa3b, v71
	v_exp_f32_e32 v53, v53
	s_nop 0
	v_add_f32_e32 v53, 1.0, v53
	v_div_scale_f32 v72, s[0:1], v53, v53, v71
	v_rcp_f32_e32 v73, v72
	s_nop 0
	v_fma_f32 v74, -v72, v73, 1.0
	v_fmac_f32_e32 v73, v74, v73
	v_div_scale_f32 v74, vcc, v71, v53, v71
	v_mul_f32_e32 v75, v74, v73
	v_fma_f32 v76, -v72, v75, v74
	v_fmac_f32_e32 v75, v76, v73
	v_fma_f32 v72, -v72, v75, v74
	v_div_fmas_f32 v72, v72, v73, v75
	v_or_b32_e32 v74, 16, v70
	v_div_fixup_f32 v53, v72, v53, v71
	v_ashrrev_i32_e32 v75, 31, v74
	v_mul_f32_e32 v52, v52, v53
	v_lshl_add_u64 v[84:85], v[130:131], 0, v[74:75]
	v_cvt_pk_bf16_f32 v52, v52, s0
	v_lshlrev_b64 v[84:85], 5, v[84:85]
	global_store_short v[50:51], v52, off
	v_lshlrev_b64 v[82:83], 10, v[74:75]
	v_lshl_add_u64 v[84:85], v[66:67], 0, v[84:85]
	v_mov_b32_e32 v71, v125
	v_lshl_add_u64 v[84:85], v[68:69], 0, v[82:83]
	v_mov_b32_e32 v86, v128
	v_div_scale_f32 v87, s[0:1], v46, v46, 1.0
	v_rcp_f32_e32 v89, v87
	v_or_b32_e32 v72, 17, v70
	v_ashrrev_i32_e32 v73, 31, v72
	v_lshlrev_b64 v[80:81], 10, v[72:73]
	v_fma_f32 v92, -v87, v89, 1.0
	v_fmac_f32_e32 v89, v92, v89
	v_div_scale_f32 v92, vcc, 1.0, v46, 1.0
	v_mul_f32_e32 v93, v92, v89
	v_fma_f32 v94, -v87, v93, v92
	v_fmac_f32_e32 v93, v94, v89
	v_fma_f32 v87, -v87, v93, v92
	v_div_fmas_f32 v87, v87, v89, v93
	v_div_fixup_f32 v46, v87, v46, 1.0
	v_or_b32_e32 v52, 18, v70
	v_ashrrev_i32_e32 v53, 31, v52
	v_lshlrev_b64 v[78:79], 10, v[52:53]
	v_or_b32_e32 v50, 19, v70
	v_ashrrev_i32_e32 v51, 31, v50
	v_lshlrev_b64 v[76:77], 10, v[50:51]
	v_lshlrev_b32_e32 v71, 16, v71
	v_mul_f32_e32 v46, v46, v71
	v_lshlrev_b32_e32 v86, 16, v86
	v_mul_f32_e32 v71, 0xbfb8aa3b, v86
	v_exp_f32_e32 v71, v71
	s_nop 0
	v_add_f32_e32 v71, 1.0, v71
	v_div_scale_f32 v87, s[0:1], v71, v71, v86
	v_rcp_f32_e32 v89, v87
	s_nop 0
	v_fma_f32 v92, -v87, v89, 1.0
	v_fmac_f32_e32 v89, v92, v89
	v_div_scale_f32 v92, vcc, v86, v71, v86
	v_mul_f32_e32 v93, v92, v89
	v_fma_f32 v94, -v87, v93, v92
	v_fmac_f32_e32 v93, v94, v89
	v_fma_f32 v87, -v87, v93, v92
	v_div_fmas_f32 v87, v87, v89, v93
	v_div_fixup_f32 v71, v87, v71, v86
	v_mul_f32_e32 v46, v46, v71
	v_cvt_pk_bf16_f32 v46, v46, s0
	global_store_short v[84:85], v46, off
	v_lshl_add_u64 v[84:85], v[130:131], 0, v[72:73]
	v_lshlrev_b64 v[84:85], 5, v[84:85]
	v_lshl_add_u64 v[84:85], v[66:67], 0, v[84:85]
	v_mov_b32_e32 v46, v143
	v_lshl_add_u64 v[84:85], v[68:69], 0, v[80:81]
	v_mov_b32_e32 v71, v150
	v_div_scale_f32 v86, s[0:1], v47, v47, 1.0
	v_rcp_f32_e32 v87, v86
	v_lshlrev_b32_e32 v46, 16, v46
	v_fma_f32 v89, -v86, v87, 1.0
	v_fmac_f32_e32 v87, v89, v87
	v_div_scale_f32 v89, vcc, 1.0, v47, 1.0
	v_mul_f32_e32 v92, v89, v87
	v_fma_f32 v93, -v86, v92, v89
	v_fmac_f32_e32 v92, v93, v87
	v_fma_f32 v86, -v86, v92, v89
	v_div_fmas_f32 v86, v86, v87, v92
	v_lshlrev_b32_e32 v71, 16, v71
	v_div_fixup_f32 v47, v86, v47, 1.0
	v_mul_f32_e32 v46, v47, v46
	v_mul_f32_e32 v47, 0xbfb8aa3b, v71
	v_exp_f32_e32 v47, v47
	s_nop 0
	v_add_f32_e32 v47, 1.0, v47
	v_div_scale_f32 v86, s[0:1], v47, v47, v71
	v_rcp_f32_e32 v87, v86
	s_nop 0
	v_fma_f32 v89, -v86, v87, 1.0
	v_fmac_f32_e32 v87, v89, v87
	v_div_scale_f32 v89, vcc, v71, v47, v71
	v_mul_f32_e32 v92, v89, v87
	v_fma_f32 v93, -v86, v92, v89
	v_fmac_f32_e32 v92, v93, v87
	v_fma_f32 v86, -v86, v92, v89
	v_div_fmas_f32 v86, v86, v87, v92
	v_div_fixup_f32 v47, v86, v47, v71
	v_mul_f32_e32 v46, v46, v47
	v_cvt_pk_bf16_f32 v46, v46, s0
	global_store_short v[84:85], v46, off
	v_lshl_add_u64 v[46:47], v[130:131], 0, v[52:53]
	v_lshlrev_b64 v[46:47], 5, v[46:47]
	v_lshl_add_u64 v[46:47], v[66:67], 0, v[46:47]
	v_mov_b32_e32 v46, v146
	v_div_scale_f32 v85, s[0:1], v48, v48, 1.0
	v_rcp_f32_e32 v86, v85
	v_lshlrev_b32_e32 v71, 16, v46
	v_lshl_add_u64 v[46:47], v[68:69], 0, v[78:79]
	v_mov_b32_e32 v84, v147
	v_fma_f32 v87, -v85, v86, 1.0
	v_fmac_f32_e32 v86, v87, v86
	v_div_scale_f32 v87, vcc, 1.0, v48, 1.0
	v_mul_f32_e32 v89, v87, v86
	v_fma_f32 v92, -v85, v89, v87
	v_fmac_f32_e32 v89, v92, v86
	v_fma_f32 v85, -v85, v89, v87
	v_div_fmas_f32 v85, v85, v86, v89
	v_div_fixup_f32 v48, v85, v48, 1.0
	v_mul_f32_e32 v48, v48, v71
	v_lshlrev_b32_e32 v84, 16, v84
	v_mul_f32_e32 v71, 0xbfb8aa3b, v84
	v_exp_f32_e32 v71, v71
	s_nop 0
	v_add_f32_e32 v71, 1.0, v71
	v_div_scale_f32 v85, s[0:1], v71, v71, v84
	v_rcp_f32_e32 v86, v85
	s_nop 0
	v_fma_f32 v87, -v85, v86, 1.0
	v_fmac_f32_e32 v86, v87, v86
	v_div_scale_f32 v87, vcc, v84, v71, v84
	v_mul_f32_e32 v89, v87, v86
	v_fma_f32 v92, -v85, v89, v87
	v_fmac_f32_e32 v89, v92, v86
	v_fma_f32 v85, -v85, v89, v87
	v_div_fmas_f32 v85, v85, v86, v89
	v_div_fixup_f32 v71, v85, v71, v84
	v_mul_f32_e32 v48, v48, v71
	v_cvt_pk_bf16_f32 v48, v48, s0
	global_store_short v[46:47], v48, off
	v_lshl_add_u64 v[46:47], v[130:131], 0, v[50:51]
	v_lshlrev_b64 v[46:47], 5, v[46:47]
	v_lshl_add_u64 v[46:47], v[66:67], 0, v[46:47]
	v_mov_b32_e32 v46, v151
	v_div_scale_f32 v84, s[0:1], v49, v49, 1.0
	v_rcp_f32_e32 v85, v84
	v_lshlrev_b32_e32 v48, 16, v46
	v_lshl_add_u64 v[46:47], v[68:69], 0, v[76:77]
	v_mov_b32_e32 v71, v154
	v_fma_f32 v86, -v84, v85, 1.0
	v_fmac_f32_e32 v85, v86, v85
	v_div_scale_f32 v86, vcc, 1.0, v49, 1.0
	v_mul_f32_e32 v87, v86, v85
	v_fma_f32 v89, -v84, v87, v86
	v_fmac_f32_e32 v87, v89, v85
	v_fma_f32 v84, -v84, v87, v86
	v_div_fmas_f32 v84, v84, v85, v87
	v_div_fixup_f32 v49, v84, v49, 1.0
	v_mul_f32_e32 v48, v49, v48
	v_lshl_add_u64 v[76:77], s[2:3], 0, v[76:77]
	v_lshlrev_b32_e32 v71, 16, v71
	v_mul_f32_e32 v49, 0xbfb8aa3b, v71
	v_exp_f32_e32 v49, v49
	s_nop 0
	v_add_f32_e32 v49, 1.0, v49
	v_div_scale_f32 v84, s[0:1], v49, v49, v71
	v_rcp_f32_e32 v85, v84
	s_nop 0
	v_fma_f32 v86, -v84, v85, 1.0
	v_fmac_f32_e32 v85, v86, v85
	v_div_scale_f32 v86, vcc, v71, v49, v71
	v_mul_f32_e32 v87, v86, v85
	v_fma_f32 v89, -v84, v87, v86
	v_fmac_f32_e32 v87, v89, v85
	v_fma_f32 v84, -v84, v87, v86
	v_div_fmas_f32 v84, v84, v85, v87
	v_div_fixup_f32 v49, v84, v49, v71
	v_mul_f32_e32 v48, v48, v49
	v_cvt_pk_bf16_f32 v48, v48, s0
	global_store_short v[46:47], v48, off
	v_lshl_add_u64 v[46:47], v[64:65], 0, v[74:75]
	v_lshlrev_b64 v[46:47], 5, v[46:47]
	v_lshl_add_u64 v[46:47], v[66:67], 0, v[46:47]
	v_mov_b32_e32 v46, v148
	v_lshlrev_b32_e32 v71, 16, v46
	v_lshl_add_u64 v[46:47], s[2:3], 0, v[82:83]
	v_lshl_add_u64 v[48:49], v[46:47], 0, v[62:63]
	v_mov_b32_e32 v82, v149
	v_div_scale_f32 v83, s[0:1], v42, v42, 1.0
	v_rcp_f32_e32 v84, v83
	v_lshlrev_b32_e32 v82, 16, v82
	v_fma_f32 v85, -v83, v84, 1.0
	v_fmac_f32_e32 v84, v85, v84
	v_div_scale_f32 v85, vcc, 1.0, v42, 1.0
	v_mul_f32_e32 v86, v85, v84
	v_fma_f32 v87, -v83, v86, v85
	v_fmac_f32_e32 v86, v87, v84
	v_fma_f32 v83, -v83, v86, v85
	v_div_fmas_f32 v83, v83, v84, v86
	v_div_fixup_f32 v42, v83, v42, 1.0
	v_mul_f32_e32 v42, v42, v71
	v_mul_f32_e32 v71, 0xbfb8aa3b, v82
	v_exp_f32_e32 v71, v71
	s_nop 0
	v_add_f32_e32 v71, 1.0, v71
	v_div_scale_f32 v83, s[0:1], v71, v71, v82
	v_rcp_f32_e32 v84, v83
	s_nop 0
	v_fma_f32 v85, -v83, v84, 1.0
	v_fmac_f32_e32 v84, v85, v84
	v_div_scale_f32 v85, vcc, v82, v71, v82
	v_mul_f32_e32 v86, v85, v84
	v_fma_f32 v87, -v83, v86, v85
	v_fmac_f32_e32 v86, v87, v84
	v_fma_f32 v83, -v83, v86, v85
	v_div_fmas_f32 v83, v83, v84, v86
	v_div_fixup_f32 v71, v83, v71, v82
	v_mul_f32_e32 v42, v42, v71
	v_cvt_pk_bf16_f32 v42, v42, s0
	global_store_short v[48:49], v42, off
	v_lshl_add_u64 v[48:49], v[64:65], 0, v[72:73]
	v_lshlrev_b64 v[48:49], 5, v[48:49]
	v_lshl_add_u64 v[48:49], v[66:67], 0, v[48:49]
	v_mov_b32_e32 v42, v155
	v_lshl_add_u64 v[48:49], s[2:3], 0, v[80:81]
	v_lshl_add_u64 v[80:81], v[48:49], 0, v[62:63]
	v_mov_b32_e32 v71, v158
	v_div_scale_f32 v82, s[0:1], v43, v43, 1.0
	v_rcp_f32_e32 v83, v82
	v_lshlrev_b32_e32 v42, 16, v42
	v_fma_f32 v84, -v82, v83, 1.0
	v_fmac_f32_e32 v83, v84, v83
	v_div_scale_f32 v84, vcc, 1.0, v43, 1.0
	v_mul_f32_e32 v85, v84, v83
	v_fma_f32 v86, -v82, v85, v84
	v_fmac_f32_e32 v85, v86, v83
	v_fma_f32 v82, -v82, v85, v84
	v_div_fmas_f32 v82, v82, v83, v85
	v_lshlrev_b32_e32 v71, 16, v71
	v_div_fixup_f32 v43, v82, v43, 1.0
	v_mul_f32_e32 v42, v43, v42
	v_mul_f32_e32 v43, 0xbfb8aa3b, v71
	v_exp_f32_e32 v43, v43
	s_nop 0
	v_add_f32_e32 v43, 1.0, v43
	v_div_scale_f32 v82, s[0:1], v43, v43, v71
	v_rcp_f32_e32 v83, v82
	s_nop 0
	v_fma_f32 v84, -v82, v83, 1.0
	v_fmac_f32_e32 v83, v84, v83
	v_div_scale_f32 v84, vcc, v71, v43, v71
	v_mul_f32_e32 v85, v84, v83
	v_fma_f32 v86, -v82, v85, v84
	v_fmac_f32_e32 v85, v86, v83
	v_fma_f32 v82, -v82, v85, v84
	v_div_fmas_f32 v82, v82, v83, v85
	v_div_fixup_f32 v43, v82, v43, v71
	v_mul_f32_e32 v42, v42, v43
	v_cvt_pk_bf16_f32 v42, v42, s0
	global_store_short v[80:81], v42, off
	v_lshl_add_u64 v[42:43], v[64:65], 0, v[52:53]
	v_lshlrev_b64 v[42:43], 5, v[42:43]
	v_lshl_add_u64 v[42:43], v[66:67], 0, v[42:43]
	v_mov_b32_e32 v42, v140
	v_div_scale_f32 v81, s[0:1], v44, v44, 1.0
	v_rcp_f32_e32 v82, v81
	v_lshlrev_b32_e32 v71, 16, v42
	v_lshl_add_u64 v[42:43], s[2:3], 0, v[78:79]
	v_lshl_add_u64 v[78:79], v[42:43], 0, v[62:63]
	v_mov_b32_e32 v80, v141
	v_fma_f32 v83, -v81, v82, 1.0
	v_fmac_f32_e32 v82, v83, v82
	v_div_scale_f32 v83, vcc, 1.0, v44, 1.0
	v_mul_f32_e32 v84, v83, v82
	v_fma_f32 v85, -v81, v84, v83
	v_fmac_f32_e32 v84, v85, v82
	v_fma_f32 v81, -v81, v84, v83
	v_div_fmas_f32 v81, v81, v82, v84
	v_div_fixup_f32 v44, v81, v44, 1.0
	v_mul_f32_e32 v44, v44, v71
	v_lshlrev_b32_e32 v80, 16, v80
	v_mul_f32_e32 v71, 0xbfb8aa3b, v80
	v_exp_f32_e32 v71, v71
	s_nop 0
	v_add_f32_e32 v71, 1.0, v71
	v_div_scale_f32 v81, s[0:1], v71, v71, v80
	v_rcp_f32_e32 v82, v81
	s_nop 0
	v_fma_f32 v83, -v81, v82, 1.0
	v_fmac_f32_e32 v82, v83, v82
	v_div_scale_f32 v83, vcc, v80, v71, v80
	v_mul_f32_e32 v84, v83, v82
	v_fma_f32 v85, -v81, v84, v83
	v_fmac_f32_e32 v84, v85, v82
	v_fma_f32 v81, -v81, v84, v83
	v_div_fmas_f32 v81, v81, v82, v84
	v_div_fixup_f32 v71, v81, v71, v80
	v_mul_f32_e32 v44, v44, v71
	v_cvt_pk_bf16_f32 v44, v44, s0
	global_store_short v[78:79], v44, off
	v_lshl_add_u64 v[78:79], v[64:65], 0, v[50:51]
	v_lshlrev_b64 v[78:79], 5, v[78:79]
	v_lshl_add_u64 v[78:79], v[66:67], 0, v[78:79]
	v_mov_b32_e32 v44, v144
	v_lshl_add_u64 v[78:79], v[76:77], 0, v[62:63]
	v_mov_b32_e32 v71, v145
	v_div_scale_f32 v80, s[0:1], v45, v45, 1.0
	v_rcp_f32_e32 v81, v80
	v_lshlrev_b32_e32 v44, 16, v44
	v_fma_f32 v82, -v80, v81, 1.0
	v_fmac_f32_e32 v81, v82, v81
	v_div_scale_f32 v82, vcc, 1.0, v45, 1.0
	v_mul_f32_e32 v83, v82, v81
	v_fma_f32 v84, -v80, v83, v82
	v_fmac_f32_e32 v83, v84, v81
	v_fma_f32 v80, -v80, v83, v82
	v_div_fmas_f32 v80, v80, v81, v83
	v_lshlrev_b32_e32 v71, 16, v71
	v_div_fixup_f32 v45, v80, v45, 1.0
	v_mul_f32_e32 v44, v45, v44
	v_mul_f32_e32 v45, 0xbfb8aa3b, v71
	v_exp_f32_e32 v45, v45
	s_nop 0
	v_add_f32_e32 v45, 1.0, v45
	v_div_scale_f32 v80, s[0:1], v45, v45, v71
	v_rcp_f32_e32 v81, v80
	s_nop 0
	v_fma_f32 v82, -v80, v81, 1.0
	v_fmac_f32_e32 v81, v82, v81
	v_div_scale_f32 v82, vcc, v71, v45, v71
	v_mul_f32_e32 v83, v82, v81
	v_fma_f32 v84, -v80, v83, v82
	v_fmac_f32_e32 v83, v84, v81
	v_fma_f32 v80, -v80, v83, v82
	v_div_fmas_f32 v80, v80, v81, v83
	v_div_fixup_f32 v45, v80, v45, v71
	v_mul_f32_e32 v44, v44, v45
	v_cvt_pk_bf16_f32 v44, v44, s0
	global_store_short v[78:79], v44, off
	v_lshl_add_u64 v[44:45], v[60:61], 0, v[74:75]
	v_lshlrev_b64 v[44:45], 5, v[44:45]
	v_lshl_add_u64 v[44:45], v[66:67], 0, v[44:45]
	v_mov_b32_e32 v44, v159
	v_div_scale_f32 v79, s[0:1], v38, v38, 1.0
	v_rcp_f32_e32 v80, v79
	v_lshlrev_b32_e32 v71, 16, v44
	v_lshl_add_u64 v[44:45], v[46:47], 0, v[58:59]
	v_mov_b32_e32 v78, v156
	v_fma_f32 v81, -v79, v80, 1.0
	v_fmac_f32_e32 v80, v81, v80
	v_div_scale_f32 v81, vcc, 1.0, v38, 1.0
	v_mul_f32_e32 v82, v81, v80
	v_fma_f32 v83, -v79, v82, v81
	v_fmac_f32_e32 v82, v83, v80
	v_fma_f32 v79, -v79, v82, v81
	v_div_fmas_f32 v79, v79, v80, v82
	v_div_fixup_f32 v38, v79, v38, 1.0
	v_mul_f32_e32 v38, v38, v71
	v_lshlrev_b32_e32 v78, 16, v78
	v_mul_f32_e32 v71, 0xbfb8aa3b, v78
	v_exp_f32_e32 v71, v71
	s_nop 0
	v_add_f32_e32 v71, 1.0, v71
	v_div_scale_f32 v79, s[0:1], v71, v71, v78
	v_rcp_f32_e32 v80, v79
	s_nop 0
	v_fma_f32 v81, -v79, v80, 1.0
	v_fmac_f32_e32 v80, v81, v80
	v_div_scale_f32 v81, vcc, v78, v71, v78
	v_mul_f32_e32 v82, v81, v80
	v_fma_f32 v83, -v79, v82, v81
	v_fmac_f32_e32 v82, v83, v80
	v_fma_f32 v79, -v79, v82, v81
	v_div_fmas_f32 v79, v79, v80, v82
	v_div_fixup_f32 v71, v79, v71, v78
	v_mul_f32_e32 v38, v38, v71
	v_cvt_pk_bf16_f32 v38, v38, s0
	global_store_short v[44:45], v38, off
	v_lshl_add_u64 v[44:45], v[60:61], 0, v[72:73]
	v_lshlrev_b64 v[44:45], 5, v[44:45]
	v_lshl_add_u64 v[44:45], v[66:67], 0, v[44:45]
	v_mov_b32_e32 v38, v126
	v_lshl_add_u64 v[44:45], v[48:49], 0, v[58:59]
	v_mov_b32_e32 v71, v127
	v_div_scale_f32 v78, s[0:1], v39, v39, 1.0
	v_rcp_f32_e32 v79, v78
	v_lshlrev_b32_e32 v38, 16, v38
	v_fma_f32 v80, -v78, v79, 1.0
	v_fmac_f32_e32 v79, v80, v79
	v_div_scale_f32 v80, vcc, 1.0, v39, 1.0
	v_mul_f32_e32 v81, v80, v79
	v_fma_f32 v82, -v78, v81, v80
	v_fmac_f32_e32 v81, v82, v79
	v_fma_f32 v78, -v78, v81, v80
	v_div_fmas_f32 v78, v78, v79, v81
	v_lshlrev_b32_e32 v71, 16, v71
	v_div_fixup_f32 v39, v78, v39, 1.0
	v_mul_f32_e32 v38, v39, v38
	v_mul_f32_e32 v39, 0xbfb8aa3b, v71
	v_exp_f32_e32 v39, v39
	s_nop 0
	v_add_f32_e32 v39, 1.0, v39
	v_div_scale_f32 v78, s[0:1], v39, v39, v71
	v_rcp_f32_e32 v79, v78
	s_nop 0
	v_fma_f32 v80, -v78, v79, 1.0
	v_fmac_f32_e32 v79, v80, v79
	v_div_scale_f32 v80, vcc, v71, v39, v71
	v_mul_f32_e32 v81, v80, v79
	v_fma_f32 v82, -v78, v81, v80
	v_fmac_f32_e32 v81, v82, v79
	v_fma_f32 v78, -v78, v81, v80
	v_div_fmas_f32 v78, v78, v79, v81
	v_div_fixup_f32 v39, v78, v39, v71
	v_mul_f32_e32 v38, v38, v39
	v_cvt_pk_bf16_f32 v38, v38, s0
	global_store_short v[44:45], v38, off
	v_lshl_add_u64 v[38:39], v[60:61], 0, v[52:53]
	v_lshlrev_b64 v[38:39], 5, v[38:39]
	v_lshl_add_u64 v[38:39], v[66:67], 0, v[38:39]
	v_mov_b32_e32 v38, v129
	v_div_scale_f32 v71, s[0:1], v40, v40, 1.0
	v_rcp_f32_e32 v78, v71
	v_lshlrev_b32_e32 v44, 16, v38
	v_lshl_add_u64 v[38:39], v[42:43], 0, v[58:59]
	v_mov_b32_e32 v45, v134
	v_fma_f32 v79, -v71, v78, 1.0
	v_fmac_f32_e32 v78, v79, v78
	v_div_scale_f32 v79, vcc, 1.0, v40, 1.0
	v_mul_f32_e32 v80, v79, v78
	v_fma_f32 v81, -v71, v80, v79
	v_fmac_f32_e32 v80, v81, v78
	v_fma_f32 v71, -v71, v80, v79
	v_div_fmas_f32 v71, v71, v78, v80
	v_div_fixup_f32 v40, v71, v40, 1.0
	v_mul_f32_e32 v40, v40, v44
	v_lshlrev_b32_e32 v45, 16, v45
	v_mul_f32_e32 v44, 0xbfb8aa3b, v45
	v_exp_f32_e32 v44, v44
	s_nop 0
	v_add_f32_e32 v44, 1.0, v44
	v_div_scale_f32 v71, s[0:1], v44, v44, v45
	v_rcp_f32_e32 v78, v71
	s_nop 0
	v_fma_f32 v79, -v71, v78, 1.0
	v_fmac_f32_e32 v78, v79, v78
	v_div_scale_f32 v79, vcc, v45, v44, v45
	v_mul_f32_e32 v80, v79, v78
	v_fma_f32 v81, -v71, v80, v79
	v_fmac_f32_e32 v80, v81, v78
	v_fma_f32 v71, -v71, v80, v79
	v_div_fmas_f32 v71, v71, v78, v80
	v_div_fixup_f32 v44, v71, v44, v45
	v_mul_f32_e32 v40, v40, v44
	v_cvt_pk_bf16_f32 v40, v40, s0
	global_store_short v[38:39], v40, off
	v_lshl_add_u64 v[38:39], v[60:61], 0, v[50:51]
	v_lshlrev_b64 v[38:39], 5, v[38:39]
	v_lshl_add_u64 v[38:39], v[66:67], 0, v[38:39]
	v_mov_b32_e32 v38, v90
	v_div_scale_f32 v45, s[0:1], v41, v41, 1.0
	v_rcp_f32_e32 v71, v45
	v_lshlrev_b32_e32 v40, 16, v38
	v_lshl_add_u64 v[38:39], v[76:77], 0, v[58:59]
	v_mov_b32_e32 v44, v91
	v_fma_f32 v78, -v45, v71, 1.0
	v_fmac_f32_e32 v71, v78, v71
	v_div_scale_f32 v78, vcc, 1.0, v41, 1.0
	v_mul_f32_e32 v79, v78, v71
	v_fma_f32 v80, -v45, v79, v78
	v_fmac_f32_e32 v79, v80, v71
	v_fma_f32 v45, -v45, v79, v78
	v_div_fmas_f32 v45, v45, v71, v79
	v_div_fixup_f32 v41, v45, v41, 1.0
	v_mul_f32_e32 v40, v41, v40
	v_lshlrev_b32_e32 v44, 16, v44
	v_mul_f32_e32 v41, 0xbfb8aa3b, v44
	v_exp_f32_e32 v41, v41
	s_nop 0
	v_add_f32_e32 v41, 1.0, v41
	v_div_scale_f32 v45, s[0:1], v41, v41, v44
	v_rcp_f32_e32 v71, v45
	s_nop 0
	v_fma_f32 v78, -v45, v71, 1.0
	v_fmac_f32_e32 v71, v78, v71
	v_div_scale_f32 v78, vcc, v44, v41, v44
	v_mul_f32_e32 v79, v78, v71
	v_fma_f32 v80, -v45, v79, v78
	v_fmac_f32_e32 v79, v80, v71
	v_fma_f32 v45, -v45, v79, v78
	v_div_fmas_f32 v45, v45, v71, v79
	v_div_fixup_f32 v41, v45, v41, v44
	v_mul_f32_e32 v40, v40, v41
	v_cvt_pk_bf16_f32 v40, v40, s0
	global_store_short v[38:39], v40, off
	v_lshl_add_u64 v[38:39], v[56:57], 0, v[74:75]
	v_lshlrev_b64 v[38:39], 5, v[38:39]
	v_lshl_add_u64 v[38:39], v[66:67], 0, v[38:39]
	v_mov_b32_e32 v38, v101
	v_div_scale_f32 v44, s[0:1], v34, v34, 1.0
	v_rcp_f32_e32 v45, v44
	v_lshlrev_b32_e32 v40, 16, v38
	v_lshl_add_u64 v[38:39], v[46:47], 0, v[54:55]
	global_load_ushort v78, v[38:39], off
	v_lshl_add_u64 v[82:83], v[56:57], 0, v[72:73]
	v_lshlrev_b64 v[84:85], 5, v[82:83]
	v_lshl_add_u64 v[82:83], v[66:67], 0, v[84:85]
	global_load_ushort v84, v[82:83], off
	v_lshl_add_u64 v[82:83], v[48:49], 0, v[54:55]
	global_load_ushort v85, v[82:83], off
	v_lshl_add_u64 v[82:83], v[56:57], 0, v[52:53]
	v_lshlrev_b64 v[86:87], 5, v[82:83]
	v_lshl_add_u64 v[82:83], v[66:67], 0, v[86:87]
	global_load_ushort v86, v[82:83], off
	v_lshl_add_u64 v[82:83], v[42:43], 0, v[54:55]
	global_load_ushort v87, v[82:83], off
	v_lshl_add_u64 v[82:83], v[56:57], 0, v[50:51]
	v_lshlrev_b64 v[88:89], 5, v[82:83]
	v_lshl_add_u64 v[82:83], v[66:67], 0, v[88:89]
	global_load_ushort v88, v[82:83], off
	v_lshl_add_u64 v[82:83], v[76:77], 0, v[54:55]
	global_load_ushort v89, v[82:83], off
	v_or_b32_e32 v82, 32, v70
	v_ashrrev_i32_e32 v83, 31, v82
	v_lshl_add_u64 v[90:91], v[130:131], 0, v[82:83]
	v_lshlrev_b64 v[92:93], 5, v[90:91]
	v_lshl_add_u64 v[90:91], v[66:67], 0, v[92:93]
	global_load_ushort v92, v[90:91], off
	v_lshlrev_b64 v[90:91], 10, v[82:83]
	v_or_b32_e32 v93, 33, v70
	v_ashrrev_i32_e32 v94, 31, v93
	v_mov_b32_e32 v96, v93
	v_mov_b32_e32 v97, v94
	v_lshlrev_b64 v[98:99], 10, v[96:97]
	v_or_b32_e32 v95, 34, v70
	v_ashrrev_i32_e32 v96, 31, v95
	v_mov_b32_e32 v100, v95
	v_mov_b32_e32 v101, v96
	v_lshlrev_b64 v[102:103], 10, v[100:101]
	v_or_b32_e32 v97, 35, v70
	v_ashrrev_i32_e32 v100, 31, v97
	v_mov_b32_e32 v104, v97
	v_mov_b32_e32 v105, v100
	v_lshlrev_b64 v[106:107], 10, v[104:105]
	v_lshl_add_u64 v[104:105], v[68:69], 0, v[90:91]
	global_load_ushort v101, v[104:105], off
	v_mov_b32_e32 v104, v93
	v_mov_b32_e32 v105, v94
	v_lshl_add_u64 v[108:109], v[130:131], 0, v[104:105]
	v_lshlrev_b64 v[104:105], 5, v[108:109]
	v_lshl_add_u64 v[108:109], v[66:67], 0, v[104:105]
	global_load_ushort v104, v[108:109], off
	v_lshl_add_u64 v[108:109], v[68:69], 0, v[98:99]
	global_load_ushort v105, v[108:109], off
	v_mov_b32_e32 v108, v95
	v_mov_b32_e32 v109, v96
	v_lshl_add_u64 v[110:111], v[130:131], 0, v[108:109]
	v_lshlrev_b64 v[108:109], 5, v[110:111]
	v_lshl_add_u64 v[110:111], v[66:67], 0, v[108:109]
	global_load_ushort v108, v[110:111], off
	v_lshl_add_u64 v[110:111], v[68:69], 0, v[102:103]
	global_load_ushort v109, v[110:111], off
	v_mov_b32_e32 v110, v97
	v_mov_b32_e32 v111, v100
	v_lshl_add_u64 v[112:113], v[130:131], 0, v[110:111]
	v_lshlrev_b64 v[110:111], 5, v[112:113]
	v_lshl_add_u64 v[112:113], v[66:67], 0, v[110:111]
	global_load_ushort v110, v[112:113], off
	v_lshl_add_u64 v[112:113], v[68:69], 0, v[106:107]
	global_load_ushort v111, v[112:113], off
	v_lshl_add_u64 v[112:113], s[2:3], 0, v[106:107]
	v_lshl_add_u64 v[106:107], v[64:65], 0, v[82:83]
	v_lshlrev_b64 v[114:115], 5, v[106:107]
	v_lshl_add_u64 v[106:107], v[66:67], 0, v[114:115]
	global_load_ushort v114, v[106:107], off
	v_lshl_add_u64 v[106:107], s[2:3], 0, v[90:91]
	v_lshl_add_u64 v[90:91], v[106:107], 0, v[62:63]
	global_load_ushort v115, v[90:91], off
	v_mov_b32_e32 v90, v93
	v_mov_b32_e32 v91, v94
	v_lshl_add_u64 v[116:117], v[64:65], 0, v[90:91]
	v_lshlrev_b64 v[90:91], 5, v[116:117]
	v_lshl_add_u64 v[116:117], v[66:67], 0, v[90:91]
	global_load_ushort v90, v[116:117], off
	v_lshl_add_u64 v[116:117], s[2:3], 0, v[98:99]
	v_lshl_add_u64 v[98:99], v[116:117], 0, v[62:63]
	global_load_ushort v91, v[98:99], off
	v_mov_b32_e32 v98, v95
	v_mov_b32_e32 v99, v96
	v_lshl_add_u64 v[118:119], v[64:65], 0, v[98:99]
	v_lshlrev_b64 v[98:99], 5, v[118:119]
	v_lshl_add_u64 v[118:119], v[66:67], 0, v[98:99]
	global_load_ushort v98, v[118:119], off
	v_lshl_add_u64 v[118:119], s[2:3], 0, v[102:103]
	v_lshl_add_u64 v[102:103], v[118:119], 0, v[62:63]
	global_load_ushort v99, v[102:103], off
	v_mov_b32_e32 v102, v97
	v_mov_b32_e32 v103, v100
	v_lshl_add_u64 v[120:121], v[64:65], 0, v[102:103]
	v_lshlrev_b64 v[102:103], 5, v[120:121]
	v_lshl_add_u64 v[120:121], v[66:67], 0, v[102:103]
	global_load_ushort v102, v[120:121], off
	v_lshl_add_u64 v[120:121], v[112:113], 0, v[62:63]
	global_load_ushort v103, v[120:121], off
	v_lshl_add_u64 v[120:121], v[60:61], 0, v[82:83]
	v_lshlrev_b64 v[122:123], 5, v[120:121]
	v_lshl_add_u64 v[120:121], v[66:67], 0, v[122:123]
	v_lshl_add_u64 v[122:123], v[106:107], 0, v[58:59]
	global_load_ushort v124, v[120:121], off
	global_load_ushort v120, v[122:123], off
	v_mov_b32_e32 v122, v93
	v_mov_b32_e32 v123, v94
	v_lshl_add_u64 v[126:127], v[60:61], 0, v[122:123]
	v_lshlrev_b64 v[122:123], 5, v[126:127]
	v_lshl_add_u64 v[126:127], v[66:67], 0, v[122:123]
	global_load_ushort v121, v[126:127], off
	v_lshl_add_u64 v[122:123], v[116:117], 0, v[58:59]
	global_load_ushort v125, v[122:123], off
	v_mov_b32_e32 v122, v95
	v_mov_b32_e32 v123, v96
	v_lshl_add_u64 v[126:127], v[60:61], 0, v[122:123]
	v_lshlrev_b64 v[122:123], 5, v[126:127]
	v_lshl_add_u64 v[126:127], v[66:67], 0, v[122:123]
	global_load_ushort v122, v[126:127], off
	v_lshl_add_u64 v[126:127], v[118:119], 0, v[58:59]
	global_load_ushort v123, v[126:127], off
	v_mov_b32_e32 v126, v97
	v_mov_b32_e32 v127, v100
	v_lshl_add_u64 v[128:129], v[60:61], 0, v[126:127]
	v_lshlrev_b64 v[126:127], 5, v[128:129]
	v_lshl_add_u64 v[128:129], v[66:67], 0, v[126:127]
	global_load_ushort v126, v[128:129], off
	v_lshl_add_u64 v[128:129], v[112:113], 0, v[58:59]
	global_load_ushort v127, v[128:129], off
	v_lshl_add_u64 v[128:129], v[56:57], 0, v[82:83]
	v_lshlrev_b64 v[82:83], 5, v[128:129]
	v_lshl_add_u64 v[128:129], v[66:67], 0, v[82:83]
	global_load_ushort v82, v[128:129], off
	v_lshl_add_u64 v[128:129], v[106:107], 0, v[54:55]
	global_load_ushort v83, v[128:129], off
	v_mov_b32_e32 v106, v93
	v_mov_b32_e32 v107, v94
	v_lshl_add_u64 v[128:129], v[56:57], 0, v[106:107]
	v_lshlrev_b64 v[106:107], 5, v[128:129]
	v_lshl_add_u64 v[128:129], v[66:67], 0, v[106:107]
	global_load_ushort v93, v[128:129], off
	v_lshl_add_u64 v[106:107], v[116:117], 0, v[54:55]
	global_load_ushort v94, v[106:107], off
	v_mov_b32_e32 v106, v95
	v_mov_b32_e32 v107, v96
	v_lshl_add_u64 v[116:117], v[56:57], 0, v[106:107]
	v_lshlrev_b64 v[106:107], 5, v[116:117]
	v_lshl_add_u64 v[116:117], v[66:67], 0, v[106:107]
	global_load_ushort v95, v[116:117], off
	v_lshl_add_u64 v[106:107], v[118:119], 0, v[54:55]
	global_load_ushort v96, v[106:107], off
	v_mov_b32_e32 v106, v97
	v_mov_b32_e32 v107, v100
	v_lshl_add_u64 v[116:117], v[56:57], 0, v[106:107]
	v_lshlrev_b64 v[106:107], 5, v[116:117]
	v_lshl_add_u64 v[116:117], v[66:67], 0, v[106:107]
	global_load_ushort v97, v[116:117], off
	v_lshl_add_u64 v[106:107], v[112:113], 0, v[54:55]
	global_load_ushort v100, v[106:107], off
	v_or_b32_e32 v106, 48, v70
	v_ashrrev_i32_e32 v107, 31, v106
	v_lshl_add_u64 v[112:113], v[130:131], 0, v[106:107]
	v_lshlrev_b64 v[116:117], 5, v[112:113]
	v_lshl_add_u64 v[112:113], v[66:67], 0, v[116:117]
	global_load_ushort v116, v[112:113], off
	v_lshlrev_b64 v[112:113], 10, v[106:107]
	v_or_b32_e32 v117, 49, v70
	v_ashrrev_i32_e32 v118, 31, v117
	v_mov_b32_e32 v128, v117
	v_mov_b32_e32 v129, v118
	v_lshlrev_b64 v[138:139], 10, v[128:129]
	v_or_b32_e32 v119, 50, v70
	v_ashrrev_i32_e32 v128, 31, v119
	v_mov_b32_e32 v140, v119
	v_mov_b32_e32 v141, v128
	v_lshlrev_b64 v[142:143], 10, v[140:141]
	v_or_b32_e32 v129, 51, v70
	v_ashrrev_i32_e32 v134, 31, v129
	v_mov_b32_e32 v140, v129
	v_mov_b32_e32 v141, v134
	v_lshlrev_b64 v[144:145], 10, v[140:141]
	v_lshl_add_u64 v[140:141], v[68:69], 0, v[112:113]
	global_load_ushort v137, v[140:141], off
	v_mov_b32_e32 v140, v117
	v_mov_b32_e32 v141, v118
	v_lshl_add_u64 v[146:147], v[130:131], 0, v[140:141]
	v_lshlrev_b64 v[140:141], 5, v[146:147]
	v_lshl_add_u64 v[146:147], v[66:67], 0, v[140:141]
	global_load_ushort v140, v[146:147], off
	v_lshl_add_u64 v[146:147], v[68:69], 0, v[138:139]
	global_load_ushort v141, v[146:147], off
	v_mov_b32_e32 v146, v119
	v_mov_b32_e32 v147, v128
	v_lshl_add_u64 v[148:149], v[130:131], 0, v[146:147]
	v_lshlrev_b64 v[146:147], 5, v[148:149]
	v_lshl_add_u64 v[148:149], v[66:67], 0, v[146:147]
	global_load_ushort v146, v[148:149], off
	v_lshl_add_u64 v[148:149], v[68:69], 0, v[142:143]
	global_load_ushort v147, v[148:149], off
	v_mov_b32_e32 v148, v129
	v_mov_b32_e32 v149, v134
	v_lshl_add_u64 v[150:151], v[130:131], 0, v[148:149]
	v_lshlrev_b64 v[148:149], 5, v[150:151]
	v_lshl_add_u64 v[150:151], v[66:67], 0, v[148:149]
	global_load_ushort v148, v[150:151], off
	v_lshl_add_u64 v[150:151], v[68:69], 0, v[144:145]
	global_load_ushort v149, v[150:151], off
	v_lshl_add_u64 v[150:151], s[2:3], 0, v[144:145]
	v_lshl_add_u64 v[144:145], v[64:65], 0, v[106:107]
	v_lshlrev_b64 v[152:153], 5, v[144:145]
	v_lshl_add_u64 v[144:145], v[66:67], 0, v[152:153]
	global_load_ushort v152, v[144:145], off
	v_lshl_add_u64 v[144:145], s[2:3], 0, v[112:113]
	v_lshl_add_u64 v[112:113], v[144:145], 0, v[62:63]
	global_load_ushort v153, v[112:113], off
	v_mov_b32_e32 v112, v117
	v_mov_b32_e32 v113, v118
	v_lshl_add_u64 v[154:155], v[64:65], 0, v[112:113]
	v_lshlrev_b64 v[112:113], 5, v[154:155]
	v_lshl_add_u64 v[154:155], v[66:67], 0, v[112:113]
	global_load_ushort v112, v[154:155], off
	v_lshl_add_u64 v[154:155], s[2:3], 0, v[138:139]
	v_lshl_add_u64 v[138:139], v[154:155], 0, v[62:63]
	global_load_ushort v113, v[138:139], off
	v_mov_b32_e32 v138, v119
	v_mov_b32_e32 v139, v128
	v_lshl_add_u64 v[156:157], v[64:65], 0, v[138:139]
	v_lshlrev_b64 v[138:139], 5, v[156:157]
	v_lshl_add_u64 v[156:157], v[66:67], 0, v[138:139]
	global_load_ushort v138, v[156:157], off
	v_lshl_add_u64 v[156:157], s[2:3], 0, v[142:143]
	v_lshl_add_u64 v[142:143], v[156:157], 0, v[62:63]
	global_load_ushort v139, v[142:143], off
	v_mov_b32_e32 v142, v129
	v_mov_b32_e32 v143, v134
	v_lshl_add_u64 v[158:159], v[64:65], 0, v[142:143]
	v_lshlrev_b64 v[142:143], 5, v[158:159]
	v_lshl_add_u64 v[158:159], v[66:67], 0, v[142:143]
	global_load_ushort v142, v[158:159], off
	v_lshl_add_u64 v[158:159], v[150:151], 0, v[62:63]
	global_load_ushort v143, v[158:159], off
	v_lshl_add_u64 v[158:159], v[60:61], 0, v[106:107]
	v_lshlrev_b64 v[162:163], 5, v[158:159]
	v_lshl_add_u64 v[158:159], v[66:67], 0, v[162:163]
	global_load_ushort v160, v[158:159], off
	v_lshl_add_u64 v[158:159], v[144:145], 0, v[58:59]
	global_load_ushort v162, v[158:159], off
	v_mov_b32_e32 v158, v117
	v_mov_b32_e32 v159, v118
	v_lshl_add_u64 v[164:165], v[60:61], 0, v[158:159]
	v_lshlrev_b64 v[158:159], 5, v[164:165]
	v_lshl_add_u64 v[164:165], v[66:67], 0, v[158:159]
	global_load_ushort v158, v[164:165], off
	v_lshl_add_u64 v[164:165], v[154:155], 0, v[58:59]
	global_load_ushort v159, v[164:165], off
	v_mov_b32_e32 v164, v119
	v_mov_b32_e32 v165, v128
	v_lshl_add_u64 v[168:169], v[60:61], 0, v[164:165]
	v_lshlrev_b64 v[164:165], 5, v[168:169]
	v_lshl_add_u64 v[168:169], v[66:67], 0, v[164:165]
	global_load_ushort v163, v[168:169], off
	v_lshl_add_u64 v[164:165], v[156:157], 0, v[58:59]
	global_load_ushort v166, v[164:165], off
	v_mov_b32_e32 v164, v129
	v_mov_b32_e32 v165, v134
	v_lshl_add_u64 v[168:169], v[60:61], 0, v[164:165]
	v_lshlrev_b64 v[164:165], 5, v[168:169]
	v_lshl_add_u64 v[168:169], v[66:67], 0, v[164:165]
	global_load_ushort v164, v[168:169], off
	v_lshl_add_u64 v[168:169], v[150:151], 0, v[58:59]
	global_load_ushort v165, v[168:169], off
	v_lshl_add_u64 v[168:169], v[56:57], 0, v[106:107]
	v_lshlrev_b64 v[106:107], 5, v[168:169]
	v_lshl_add_u64 v[168:169], v[66:67], 0, v[106:107]
	global_load_ushort v106, v[168:169], off
	v_lshl_add_u64 v[168:169], v[144:145], 0, v[54:55]
	global_load_ushort v107, v[168:169], off
	v_mov_b32_e32 v144, v117
	v_mov_b32_e32 v145, v118
	v_lshl_add_u64 v[168:169], v[56:57], 0, v[144:145]
	v_lshlrev_b64 v[144:145], 5, v[168:169]
	v_lshl_add_u64 v[168:169], v[66:67], 0, v[144:145]
	global_load_ushort v117, v[168:169], off
	v_lshl_add_u64 v[144:145], v[154:155], 0, v[54:55]
	global_load_ushort v118, v[144:145], off
	v_mov_b32_e32 v144, v119
	v_mov_b32_e32 v145, v128
	v_lshl_add_u64 v[154:155], v[56:57], 0, v[144:145]
	v_lshlrev_b64 v[144:145], 5, v[154:155]
	v_lshl_add_u64 v[154:155], v[66:67], 0, v[144:145]
	global_load_ushort v119, v[154:155], off
	v_lshl_add_u64 v[144:145], v[156:157], 0, v[54:55]
	global_load_ushort v128, v[144:145], off
	v_mov_b32_e32 v144, v129
	v_mov_b32_e32 v145, v134
	v_lshl_add_u64 v[154:155], v[56:57], 0, v[144:145]
	v_lshlrev_b64 v[144:145], 5, v[154:155]
	v_lshl_add_u64 v[154:155], v[66:67], 0, v[144:145]
	global_load_ushort v129, v[154:155], off
	v_lshl_add_u64 v[144:145], v[150:151], 0, v[54:55]
	global_load_ushort v134, v[144:145], off
	s_waitcnt vmcnt(0)
	v_mov_b32_e32 v41, v78
	v_fma_f32 v46, -v44, v45, 1.0
	v_fmac_f32_e32 v45, v46, v45
	v_div_scale_f32 v46, vcc, 1.0, v34, 1.0
	v_mul_f32_e32 v47, v46, v45
	v_fma_f32 v71, -v44, v47, v46
	v_fmac_f32_e32 v47, v71, v45
	v_fma_f32 v44, -v44, v47, v46
	v_div_fmas_f32 v44, v44, v45, v47
	v_div_fixup_f32 v34, v44, v34, 1.0
	v_mul_f32_e32 v34, v34, v40
	v_lshlrev_b32_e32 v41, 16, v41
	v_mul_f32_e32 v40, 0xbfb8aa3b, v41
	v_exp_f32_e32 v40, v40
	s_nop 0
	v_add_f32_e32 v40, 1.0, v40
	v_div_scale_f32 v44, s[0:1], v40, v40, v41
	v_rcp_f32_e32 v45, v44
	s_nop 0
	v_fma_f32 v46, -v44, v45, 1.0
	v_fmac_f32_e32 v45, v46, v45
	v_div_scale_f32 v46, vcc, v41, v40, v41
	v_mul_f32_e32 v47, v46, v45
	v_fma_f32 v71, -v44, v47, v46
	v_fmac_f32_e32 v47, v71, v45
	v_fma_f32 v44, -v44, v47, v46
	v_div_fmas_f32 v44, v44, v45, v47
	v_div_fixup_f32 v40, v44, v40, v41
	v_mul_f32_e32 v34, v34, v40
	v_cvt_pk_bf16_f32 v34, v34, s0
	global_store_short v[38:39], v34, off
	v_lshl_add_u64 v[38:39], v[56:57], 0, v[72:73]
	v_lshlrev_b64 v[38:39], 5, v[38:39]
	v_lshl_add_u64 v[38:39], v[66:67], 0, v[38:39]
	v_mov_b32_e32 v34, v84
	v_lshl_add_u64 v[38:39], v[48:49], 0, v[54:55]
	v_mov_b32_e32 v40, v85
	v_div_scale_f32 v41, s[0:1], v35, v35, 1.0
	v_rcp_f32_e32 v44, v41
	v_lshlrev_b32_e32 v34, 16, v34
	v_fma_f32 v45, -v41, v44, 1.0
	v_fmac_f32_e32 v44, v45, v44
	v_div_scale_f32 v45, vcc, 1.0, v35, 1.0
	v_mul_f32_e32 v46, v45, v44
	v_fma_f32 v47, -v41, v46, v45
	v_fmac_f32_e32 v46, v47, v44
	v_fma_f32 v41, -v41, v46, v45
	v_div_fmas_f32 v41, v41, v44, v46
	v_lshlrev_b32_e32 v40, 16, v40
	v_div_fixup_f32 v35, v41, v35, 1.0
	v_mul_f32_e32 v34, v35, v34
	v_mul_f32_e32 v35, 0xbfb8aa3b, v40
	v_exp_f32_e32 v35, v35
	s_nop 0
	v_add_f32_e32 v35, 1.0, v35
	v_div_scale_f32 v41, s[0:1], v35, v35, v40
	v_rcp_f32_e32 v44, v41
	s_nop 0
	v_fma_f32 v45, -v41, v44, 1.0
	v_fmac_f32_e32 v44, v45, v44
	v_div_scale_f32 v45, vcc, v40, v35, v40
	v_mul_f32_e32 v46, v45, v44
	v_fma_f32 v47, -v41, v46, v45
	v_fmac_f32_e32 v46, v47, v44
	v_fma_f32 v41, -v41, v46, v45
	v_div_fmas_f32 v41, v41, v44, v46
	v_div_fixup_f32 v35, v41, v35, v40
	v_mul_f32_e32 v34, v34, v35
	v_cvt_pk_bf16_f32 v34, v34, s0
	global_store_short v[38:39], v34, off
	v_lshl_add_u64 v[34:35], v[56:57], 0, v[52:53]
	v_lshlrev_b64 v[34:35], 5, v[34:35]
	v_lshl_add_u64 v[34:35], v[66:67], 0, v[34:35]
	v_mov_b32_e32 v34, v86
	v_div_scale_f32 v40, s[0:1], v36, v36, 1.0
	v_rcp_f32_e32 v41, v40
	v_lshlrev_b32_e32 v38, 16, v34
	v_lshl_add_u64 v[34:35], v[42:43], 0, v[54:55]
	v_mov_b32_e32 v39, v87
	v_fma_f32 v42, -v40, v41, 1.0
	v_fmac_f32_e32 v41, v42, v41
	v_div_scale_f32 v42, vcc, 1.0, v36, 1.0
	v_mul_f32_e32 v43, v42, v41
	v_fma_f32 v44, -v40, v43, v42
	v_fmac_f32_e32 v43, v44, v41
	v_fma_f32 v40, -v40, v43, v42
	v_div_fmas_f32 v40, v40, v41, v43
	v_div_fixup_f32 v36, v40, v36, 1.0
	v_mul_f32_e32 v36, v36, v38
	v_lshlrev_b32_e32 v39, 16, v39
	v_mul_f32_e32 v38, 0xbfb8aa3b, v39
	v_exp_f32_e32 v38, v38
	s_nop 0
	v_add_f32_e32 v38, 1.0, v38
	v_div_scale_f32 v40, s[0:1], v38, v38, v39
	v_rcp_f32_e32 v41, v40
	s_nop 0
	v_fma_f32 v42, -v40, v41, 1.0
	v_fmac_f32_e32 v41, v42, v41
	v_div_scale_f32 v42, vcc, v39, v38, v39
	v_mul_f32_e32 v43, v42, v41
	v_fma_f32 v44, -v40, v43, v42
	v_fmac_f32_e32 v43, v44, v41
	v_fma_f32 v40, -v40, v43, v42
	v_div_fmas_f32 v40, v40, v41, v43
	v_div_fixup_f32 v38, v40, v38, v39
	v_mul_f32_e32 v36, v36, v38
	v_cvt_pk_bf16_f32 v36, v36, s0
	global_store_short v[34:35], v36, off
	v_lshl_add_u64 v[34:35], v[56:57], 0, v[50:51]
	v_lshlrev_b64 v[34:35], 5, v[34:35]
	v_lshl_add_u64 v[34:35], v[66:67], 0, v[34:35]
	v_mov_b32_e32 v34, v88
	v_div_scale_f32 v39, s[0:1], v37, v37, 1.0
	v_rcp_f32_e32 v40, v39
	v_lshlrev_b32_e32 v36, 16, v34
	v_lshl_add_u64 v[34:35], v[76:77], 0, v[54:55]
	v_mov_b32_e32 v38, v89
	v_fma_f32 v41, -v39, v40, 1.0
	v_fmac_f32_e32 v40, v41, v40
	v_div_scale_f32 v41, vcc, 1.0, v37, 1.0
	v_mul_f32_e32 v42, v41, v40
	v_fma_f32 v43, -v39, v42, v41
	v_fmac_f32_e32 v42, v43, v40
	v_fma_f32 v39, -v39, v42, v41
	v_div_fmas_f32 v39, v39, v40, v42
	v_div_fixup_f32 v37, v39, v37, 1.0
	v_mul_f32_e32 v36, v37, v36
	v_lshlrev_b32_e32 v38, 16, v38
	v_mul_f32_e32 v37, 0xbfb8aa3b, v38
	v_exp_f32_e32 v37, v37
	s_nop 0
	v_add_f32_e32 v37, 1.0, v37
	v_div_scale_f32 v39, s[0:1], v37, v37, v38
	v_rcp_f32_e32 v40, v39
	s_nop 0
	v_fma_f32 v41, -v39, v40, 1.0
	v_fmac_f32_e32 v40, v41, v40
	v_div_scale_f32 v41, vcc, v38, v37, v38
	v_mul_f32_e32 v42, v41, v40
	v_fma_f32 v43, -v39, v42, v41
	v_fmac_f32_e32 v42, v43, v40
	v_fma_f32 v39, -v39, v42, v41
	v_div_fmas_f32 v39, v39, v40, v42
	v_or_b32_e32 v40, 32, v70
	v_div_fixup_f32 v37, v39, v37, v38
	v_ashrrev_i32_e32 v41, 31, v40
	v_mul_f32_e32 v36, v36, v37
	v_lshl_add_u64 v[50:51], v[130:131], 0, v[40:41]
	v_cvt_pk_bf16_f32 v36, v36, s0
	v_lshlrev_b64 v[50:51], 5, v[50:51]
	global_store_short v[34:35], v36, off
	v_lshl_add_u64 v[50:51], v[66:67], 0, v[50:51]
	v_mov_b32_e32 v50, v92
	v_lshlrev_b64 v[48:49], 10, v[40:41]
	v_div_scale_f32 v71, s[0:1], v30, v30, 1.0
	v_rcp_f32_e32 v72, v71
	v_or_b32_e32 v38, 33, v70
	v_ashrrev_i32_e32 v39, 31, v38
	v_lshlrev_b64 v[46:47], 10, v[38:39]
	v_fma_f32 v73, -v71, v72, 1.0
	v_fmac_f32_e32 v72, v73, v72
	v_div_scale_f32 v73, vcc, 1.0, v30, 1.0
	v_mul_f32_e32 v74, v73, v72
	v_fma_f32 v75, -v71, v74, v73
	v_fmac_f32_e32 v74, v75, v72
	v_fma_f32 v71, -v71, v74, v73
	v_div_fmas_f32 v71, v71, v72, v74
	v_div_fixup_f32 v30, v71, v30, 1.0
	v_or_b32_e32 v36, 34, v70
	v_ashrrev_i32_e32 v37, 31, v36
	v_lshlrev_b64 v[44:45], 10, v[36:37]
	v_or_b32_e32 v34, 35, v70
	v_ashrrev_i32_e32 v35, 31, v34
	v_lshlrev_b64 v[42:43], 10, v[34:35]
	v_lshlrev_b32_e32 v52, 16, v50
	v_lshl_add_u64 v[50:51], v[68:69], 0, v[48:49]
	v_mov_b32_e32 v53, v101
	v_mul_f32_e32 v30, v30, v52
	v_lshlrev_b32_e32 v53, 16, v53
	v_mul_f32_e32 v52, 0xbfb8aa3b, v53
	v_exp_f32_e32 v52, v52
	s_nop 0
	v_add_f32_e32 v52, 1.0, v52
	v_div_scale_f32 v71, s[0:1], v52, v52, v53
	v_rcp_f32_e32 v72, v71
	s_nop 0
	v_fma_f32 v73, -v71, v72, 1.0
	v_fmac_f32_e32 v72, v73, v72
	v_div_scale_f32 v73, vcc, v53, v52, v53
	v_mul_f32_e32 v74, v73, v72
	v_fma_f32 v75, -v71, v74, v73
	v_fmac_f32_e32 v74, v75, v72
	v_fma_f32 v71, -v71, v74, v73
	v_div_fmas_f32 v71, v71, v72, v74
	v_div_fixup_f32 v52, v71, v52, v53
	v_mul_f32_e32 v30, v30, v52
	v_cvt_pk_bf16_f32 v30, v30, s0
	global_store_short v[50:51], v30, off
	v_lshl_add_u64 v[50:51], v[130:131], 0, v[38:39]
	v_lshlrev_b64 v[50:51], 5, v[50:51]
	v_lshl_add_u64 v[50:51], v[66:67], 0, v[50:51]
	v_mov_b32_e32 v30, v104
	v_lshl_add_u64 v[50:51], v[68:69], 0, v[46:47]
	v_mov_b32_e32 v52, v105
	v_div_scale_f32 v53, s[0:1], v31, v31, 1.0
	v_rcp_f32_e32 v71, v53
	v_lshlrev_b32_e32 v30, 16, v30
	v_fma_f32 v72, -v53, v71, 1.0
	v_fmac_f32_e32 v71, v72, v71
	v_div_scale_f32 v72, vcc, 1.0, v31, 1.0
	v_mul_f32_e32 v73, v72, v71
	v_fma_f32 v74, -v53, v73, v72
	v_fmac_f32_e32 v73, v74, v71
	v_fma_f32 v53, -v53, v73, v72
	v_div_fmas_f32 v53, v53, v71, v73
	v_lshlrev_b32_e32 v52, 16, v52
	v_div_fixup_f32 v31, v53, v31, 1.0
	v_mul_f32_e32 v30, v31, v30
	v_mul_f32_e32 v31, 0xbfb8aa3b, v52
	v_exp_f32_e32 v31, v31
	s_nop 0
	v_add_f32_e32 v31, 1.0, v31
	v_div_scale_f32 v53, s[0:1], v31, v31, v52
	v_rcp_f32_e32 v71, v53
	s_nop 0
	v_fma_f32 v72, -v53, v71, 1.0
	v_fmac_f32_e32 v71, v72, v71
	v_div_scale_f32 v72, vcc, v52, v31, v52
	v_mul_f32_e32 v73, v72, v71
	v_fma_f32 v74, -v53, v73, v72
	v_fmac_f32_e32 v73, v74, v71
	v_fma_f32 v53, -v53, v73, v72
	v_div_fmas_f32 v53, v53, v71, v73
	v_div_fixup_f32 v31, v53, v31, v52
	v_mul_f32_e32 v30, v30, v31
	v_cvt_pk_bf16_f32 v30, v30, s0
	global_store_short v[50:51], v30, off
	v_lshl_add_u64 v[30:31], v[130:131], 0, v[36:37]
	v_lshlrev_b64 v[30:31], 5, v[30:31]
	v_lshl_add_u64 v[30:31], v[66:67], 0, v[30:31]
	v_mov_b32_e32 v30, v108
	v_div_scale_f32 v52, s[0:1], v32, v32, 1.0
	v_rcp_f32_e32 v53, v52
	v_lshlrev_b32_e32 v50, 16, v30
	v_lshl_add_u64 v[30:31], v[68:69], 0, v[44:45]
	v_mov_b32_e32 v51, v109
	v_fma_f32 v71, -v52, v53, 1.0
	v_fmac_f32_e32 v53, v71, v53
	v_div_scale_f32 v71, vcc, 1.0, v32, 1.0
	v_mul_f32_e32 v72, v71, v53
	v_fma_f32 v73, -v52, v72, v71
	v_fmac_f32_e32 v72, v73, v53
	v_fma_f32 v52, -v52, v72, v71
	v_div_fmas_f32 v52, v52, v53, v72
	v_div_fixup_f32 v32, v52, v32, 1.0
	v_mul_f32_e32 v32, v32, v50
	v_lshlrev_b32_e32 v51, 16, v51
	v_mul_f32_e32 v50, 0xbfb8aa3b, v51
	v_exp_f32_e32 v50, v50
	s_nop 0
	v_add_f32_e32 v50, 1.0, v50
	v_div_scale_f32 v52, s[0:1], v50, v50, v51
	v_rcp_f32_e32 v53, v52
	s_nop 0
	v_fma_f32 v71, -v52, v53, 1.0
	v_fmac_f32_e32 v53, v71, v53
	v_div_scale_f32 v71, vcc, v51, v50, v51
	v_mul_f32_e32 v72, v71, v53
	v_fma_f32 v73, -v52, v72, v71
	v_fmac_f32_e32 v72, v73, v53
	v_fma_f32 v52, -v52, v72, v71
	v_div_fmas_f32 v52, v52, v53, v72
	v_div_fixup_f32 v50, v52, v50, v51
	v_mul_f32_e32 v32, v32, v50
	v_cvt_pk_bf16_f32 v32, v32, s0
	global_store_short v[30:31], v32, off
	v_lshl_add_u64 v[30:31], v[130:131], 0, v[34:35]
	v_lshlrev_b64 v[30:31], 5, v[30:31]
	v_lshl_add_u64 v[30:31], v[66:67], 0, v[30:31]
	v_mov_b32_e32 v30, v110
	v_div_scale_f32 v51, s[0:1], v33, v33, 1.0
	v_rcp_f32_e32 v52, v51
	v_lshlrev_b32_e32 v32, 16, v30
	v_lshl_add_u64 v[30:31], v[68:69], 0, v[42:43]
	v_mov_b32_e32 v50, v111
	v_fma_f32 v53, -v51, v52, 1.0
	v_fmac_f32_e32 v52, v53, v52
	v_div_scale_f32 v53, vcc, 1.0, v33, 1.0
	v_mul_f32_e32 v71, v53, v52
	v_fma_f32 v72, -v51, v71, v53
	v_fmac_f32_e32 v71, v72, v52
	v_fma_f32 v51, -v51, v71, v53
	v_div_fmas_f32 v51, v51, v52, v71
	v_div_fixup_f32 v33, v51, v33, 1.0
	v_mul_f32_e32 v32, v33, v32
	v_lshl_add_u64 v[42:43], s[2:3], 0, v[42:43]
	v_lshlrev_b32_e32 v50, 16, v50
	v_mul_f32_e32 v33, 0xbfb8aa3b, v50
	v_exp_f32_e32 v33, v33
	s_nop 0
	v_add_f32_e32 v33, 1.0, v33
	v_div_scale_f32 v51, s[0:1], v33, v33, v50
	v_rcp_f32_e32 v52, v51
	s_nop 0
	v_fma_f32 v53, -v51, v52, 1.0
	v_fmac_f32_e32 v52, v53, v52
	v_div_scale_f32 v53, vcc, v50, v33, v50
	v_mul_f32_e32 v71, v53, v52
	v_fma_f32 v72, -v51, v71, v53
	v_fmac_f32_e32 v71, v72, v52
	v_fma_f32 v51, -v51, v71, v53
	v_div_fmas_f32 v51, v51, v52, v71
	v_div_fixup_f32 v33, v51, v33, v50
	v_mul_f32_e32 v32, v32, v33
	v_cvt_pk_bf16_f32 v32, v32, s0
	global_store_short v[30:31], v32, off
	v_lshl_add_u64 v[30:31], v[64:65], 0, v[40:41]
	v_lshlrev_b64 v[30:31], 5, v[30:31]
	v_lshl_add_u64 v[30:31], v[66:67], 0, v[30:31]
	v_mov_b32_e32 v30, v114
	v_lshlrev_b32_e32 v50, 16, v30
	v_lshl_add_u64 v[30:31], s[2:3], 0, v[48:49]
	v_lshl_add_u64 v[32:33], v[30:31], 0, v[62:63]
	v_mov_b32_e32 v48, v115
	v_div_scale_f32 v49, s[0:1], v26, v26, 1.0
	v_rcp_f32_e32 v51, v49
	v_lshlrev_b32_e32 v48, 16, v48
	v_fma_f32 v52, -v49, v51, 1.0
	v_fmac_f32_e32 v51, v52, v51
	v_div_scale_f32 v52, vcc, 1.0, v26, 1.0
	v_mul_f32_e32 v53, v52, v51
	v_fma_f32 v71, -v49, v53, v52
	v_fmac_f32_e32 v53, v71, v51
	v_fma_f32 v49, -v49, v53, v52
	v_div_fmas_f32 v49, v49, v51, v53
	v_div_fixup_f32 v26, v49, v26, 1.0
	v_mul_f32_e32 v49, 0xbfb8aa3b, v48
	v_exp_f32_e32 v49, v49
	v_mul_f32_e32 v26, v26, v50
	v_add_f32_e32 v49, 1.0, v49
	v_div_scale_f32 v50, s[0:1], v49, v49, v48
	v_rcp_f32_e32 v51, v50
	s_nop 0
	v_fma_f32 v52, -v50, v51, 1.0
	v_fmac_f32_e32 v51, v52, v51
	v_div_scale_f32 v52, vcc, v48, v49, v48
	v_mul_f32_e32 v53, v52, v51
	v_fma_f32 v71, -v50, v53, v52
	v_fmac_f32_e32 v53, v71, v51
	v_fma_f32 v50, -v50, v53, v52
	v_div_fmas_f32 v50, v50, v51, v53
	v_div_fixup_f32 v48, v50, v49, v48
	v_mul_f32_e32 v26, v26, v48
	v_cvt_pk_bf16_f32 v26, v26, s0
	global_store_short v[32:33], v26, off
	v_lshl_add_u64 v[32:33], v[64:65], 0, v[38:39]
	v_lshlrev_b64 v[32:33], 5, v[32:33]
	v_lshl_add_u64 v[32:33], v[66:67], 0, v[32:33]
	v_mov_b32_e32 v26, v90
	v_lshl_add_u64 v[32:33], s[2:3], 0, v[46:47]
	v_lshl_add_u64 v[46:47], v[32:33], 0, v[62:63]
	v_mov_b32_e32 v48, v91
	v_div_scale_f32 v49, s[0:1], v27, v27, 1.0
	v_rcp_f32_e32 v50, v49
	v_lshlrev_b32_e32 v26, 16, v26
	v_fma_f32 v51, -v49, v50, 1.0
	v_fmac_f32_e32 v50, v51, v50
	v_div_scale_f32 v51, vcc, 1.0, v27, 1.0
	v_mul_f32_e32 v52, v51, v50
	v_fma_f32 v53, -v49, v52, v51
	v_fmac_f32_e32 v52, v53, v50
	v_fma_f32 v49, -v49, v52, v51
	v_div_fmas_f32 v49, v49, v50, v52
	v_lshlrev_b32_e32 v48, 16, v48
	v_div_fixup_f32 v27, v49, v27, 1.0
	v_mul_f32_e32 v26, v27, v26
	v_mul_f32_e32 v27, 0xbfb8aa3b, v48
	v_exp_f32_e32 v27, v27
	s_nop 0
	v_add_f32_e32 v27, 1.0, v27
	v_div_scale_f32 v49, s[0:1], v27, v27, v48
	v_rcp_f32_e32 v50, v49
	s_nop 0
	v_fma_f32 v51, -v49, v50, 1.0
	v_fmac_f32_e32 v50, v51, v50
	v_div_scale_f32 v51, vcc, v48, v27, v48
	v_mul_f32_e32 v52, v51, v50
	v_fma_f32 v53, -v49, v52, v51
	v_fmac_f32_e32 v52, v53, v50
	v_fma_f32 v49, -v49, v52, v51
	v_div_fmas_f32 v49, v49, v50, v52
	v_div_fixup_f32 v27, v49, v27, v48
	v_mul_f32_e32 v26, v26, v27
	v_cvt_pk_bf16_f32 v26, v26, s0
	global_store_short v[46:47], v26, off
	v_lshl_add_u64 v[26:27], v[64:65], 0, v[36:37]
	v_lshlrev_b64 v[26:27], 5, v[26:27]
	v_lshl_add_u64 v[26:27], v[66:67], 0, v[26:27]
	v_mov_b32_e32 v26, v98
	v_div_scale_f32 v48, s[0:1], v28, v28, 1.0
	v_rcp_f32_e32 v49, v48
	v_lshlrev_b32_e32 v46, 16, v26
	v_lshl_add_u64 v[26:27], s[2:3], 0, v[44:45]
	v_lshl_add_u64 v[44:45], v[26:27], 0, v[62:63]
	v_mov_b32_e32 v47, v99
	v_fma_f32 v50, -v48, v49, 1.0
	v_fmac_f32_e32 v49, v50, v49
	v_div_scale_f32 v50, vcc, 1.0, v28, 1.0
	v_mul_f32_e32 v51, v50, v49
	v_fma_f32 v52, -v48, v51, v50
	v_fmac_f32_e32 v51, v52, v49
	v_fma_f32 v48, -v48, v51, v50
	v_div_fmas_f32 v48, v48, v49, v51
	v_div_fixup_f32 v28, v48, v28, 1.0
	v_mul_f32_e32 v28, v28, v46
	v_lshlrev_b32_e32 v47, 16, v47
	v_mul_f32_e32 v46, 0xbfb8aa3b, v47
	v_exp_f32_e32 v46, v46
	s_nop 0
	v_add_f32_e32 v46, 1.0, v46
	v_div_scale_f32 v48, s[0:1], v46, v46, v47
	v_rcp_f32_e32 v49, v48
	s_nop 0
	v_fma_f32 v50, -v48, v49, 1.0
	v_fmac_f32_e32 v49, v50, v49
	v_div_scale_f32 v50, vcc, v47, v46, v47
	v_mul_f32_e32 v51, v50, v49
	v_fma_f32 v52, -v48, v51, v50
	v_fmac_f32_e32 v51, v52, v49
	v_fma_f32 v48, -v48, v51, v50
	v_div_fmas_f32 v48, v48, v49, v51
	v_div_fixup_f32 v46, v48, v46, v47
	v_mul_f32_e32 v28, v28, v46
	v_cvt_pk_bf16_f32 v28, v28, s0
	global_store_short v[44:45], v28, off
	v_lshl_add_u64 v[44:45], v[64:65], 0, v[34:35]
	v_lshlrev_b64 v[44:45], 5, v[44:45]
	v_lshl_add_u64 v[44:45], v[66:67], 0, v[44:45]
	v_mov_b32_e32 v28, v102
	v_lshl_add_u64 v[44:45], v[42:43], 0, v[62:63]
	v_mov_b32_e32 v46, v103
	v_div_scale_f32 v47, s[0:1], v29, v29, 1.0
	v_rcp_f32_e32 v48, v47
	v_lshlrev_b32_e32 v28, 16, v28
	v_fma_f32 v49, -v47, v48, 1.0
	v_fmac_f32_e32 v48, v49, v48
	v_div_scale_f32 v49, vcc, 1.0, v29, 1.0
	v_mul_f32_e32 v50, v49, v48
	v_fma_f32 v51, -v47, v50, v49
	v_fmac_f32_e32 v50, v51, v48
	v_fma_f32 v47, -v47, v50, v49
	v_div_fmas_f32 v47, v47, v48, v50
	v_lshlrev_b32_e32 v46, 16, v46
	v_div_fixup_f32 v29, v47, v29, 1.0
	v_mul_f32_e32 v28, v29, v28
	v_mul_f32_e32 v29, 0xbfb8aa3b, v46
	v_exp_f32_e32 v29, v29
	s_nop 0
	v_add_f32_e32 v29, 1.0, v29
	v_div_scale_f32 v47, s[0:1], v29, v29, v46
	v_rcp_f32_e32 v48, v47
	s_nop 0
	v_fma_f32 v49, -v47, v48, 1.0
	v_fmac_f32_e32 v48, v49, v48
	v_div_scale_f32 v49, vcc, v46, v29, v46
	v_mul_f32_e32 v50, v49, v48
	v_fma_f32 v51, -v47, v50, v49
	v_fmac_f32_e32 v50, v51, v48
	v_fma_f32 v47, -v47, v50, v49
	v_div_fmas_f32 v47, v47, v48, v50
	v_div_fixup_f32 v29, v47, v29, v46
	v_mul_f32_e32 v28, v28, v29
	v_cvt_pk_bf16_f32 v28, v28, s0
	global_store_short v[44:45], v28, off
	v_lshl_add_u64 v[28:29], v[60:61], 0, v[40:41]
	v_lshlrev_b64 v[28:29], 5, v[28:29]
	v_lshl_add_u64 v[28:29], v[66:67], 0, v[28:29]
	v_lshl_add_u64 v[44:45], v[30:31], 0, v[58:59]
	v_mov_b32_e32 v28, v124
	v_div_scale_f32 v46, s[0:1], v22, v22, 1.0
	v_mov_b32_e32 v29, v120
	v_rcp_f32_e32 v47, v46
	v_lshlrev_b32_e32 v28, 16, v28
	v_fma_f32 v48, -v46, v47, 1.0
	v_fmac_f32_e32 v47, v48, v47
	v_div_scale_f32 v48, vcc, 1.0, v22, 1.0
	v_mul_f32_e32 v49, v48, v47
	v_fma_f32 v50, -v46, v49, v48
	v_fmac_f32_e32 v49, v50, v47
	v_fma_f32 v46, -v46, v49, v48
	v_div_fmas_f32 v46, v46, v47, v49
	v_lshlrev_b32_e32 v29, 16, v29
	v_div_fixup_f32 v22, v46, v22, 1.0
	v_mul_f32_e32 v22, v22, v28
	v_mul_f32_e32 v28, 0xbfb8aa3b, v29
	v_exp_f32_e32 v28, v28
	s_nop 0
	v_add_f32_e32 v28, 1.0, v28
	v_div_scale_f32 v46, s[0:1], v28, v28, v29
	v_rcp_f32_e32 v47, v46
	s_nop 0
	v_fma_f32 v48, -v46, v47, 1.0
	v_fmac_f32_e32 v47, v48, v47
	v_div_scale_f32 v48, vcc, v29, v28, v29
	v_mul_f32_e32 v49, v48, v47
	v_fma_f32 v50, -v46, v49, v48
	v_fmac_f32_e32 v49, v50, v47
	v_fma_f32 v46, -v46, v49, v48
	v_div_fmas_f32 v46, v46, v47, v49
	v_div_fixup_f32 v28, v46, v28, v29
	v_mul_f32_e32 v22, v22, v28
	v_lshl_add_u64 v[28:29], v[60:61], 0, v[38:39]
	v_cvt_pk_bf16_f32 v22, v22, s0
	v_lshlrev_b64 v[28:29], 5, v[28:29]
	global_store_short v[44:45], v22, off
	v_lshl_add_u64 v[28:29], v[66:67], 0, v[28:29]
	v_mov_b32_e32 v22, v121
	v_lshl_add_u64 v[28:29], v[32:33], 0, v[58:59]
	v_mov_b32_e32 v44, v125
	v_div_scale_f32 v45, s[0:1], v23, v23, 1.0
	v_rcp_f32_e32 v46, v45
	v_lshlrev_b32_e32 v22, 16, v22
	v_fma_f32 v47, -v45, v46, 1.0
	v_fmac_f32_e32 v46, v47, v46
	v_div_scale_f32 v47, vcc, 1.0, v23, 1.0
	v_mul_f32_e32 v48, v47, v46
	v_fma_f32 v49, -v45, v48, v47
	v_fmac_f32_e32 v48, v49, v46
	v_fma_f32 v45, -v45, v48, v47
	v_div_fmas_f32 v45, v45, v46, v48
	v_lshlrev_b32_e32 v44, 16, v44
	v_div_fixup_f32 v23, v45, v23, 1.0
	v_mul_f32_e32 v22, v23, v22
	v_mul_f32_e32 v23, 0xbfb8aa3b, v44
	v_exp_f32_e32 v23, v23
	s_nop 0
	v_add_f32_e32 v23, 1.0, v23
	v_div_scale_f32 v45, s[0:1], v23, v23, v44
	v_rcp_f32_e32 v46, v45
	s_nop 0
	v_fma_f32 v47, -v45, v46, 1.0
	v_fmac_f32_e32 v46, v47, v46
	v_div_scale_f32 v47, vcc, v44, v23, v44
	v_mul_f32_e32 v48, v47, v46
	v_fma_f32 v49, -v45, v48, v47
	v_fmac_f32_e32 v48, v49, v46
	v_fma_f32 v45, -v45, v48, v47
	v_div_fmas_f32 v45, v45, v46, v48
	v_div_fixup_f32 v23, v45, v23, v44
	v_mul_f32_e32 v22, v22, v23
	v_cvt_pk_bf16_f32 v22, v22, s0
	global_store_short v[28:29], v22, off
	v_lshl_add_u64 v[22:23], v[60:61], 0, v[36:37]
	v_lshlrev_b64 v[22:23], 5, v[22:23]
	v_lshl_add_u64 v[22:23], v[66:67], 0, v[22:23]
	v_mov_b32_e32 v22, v122
	v_div_scale_f32 v44, s[0:1], v24, v24, 1.0
	v_rcp_f32_e32 v45, v44
	v_lshlrev_b32_e32 v28, 16, v22
	v_lshl_add_u64 v[22:23], v[26:27], 0, v[58:59]
	v_mov_b32_e32 v29, v123
	v_fma_f32 v46, -v44, v45, 1.0
	v_fmac_f32_e32 v45, v46, v45
	v_div_scale_f32 v46, vcc, 1.0, v24, 1.0
	v_mul_f32_e32 v47, v46, v45
	v_fma_f32 v48, -v44, v47, v46
	v_fmac_f32_e32 v47, v48, v45
	v_fma_f32 v44, -v44, v47, v46
	v_div_fmas_f32 v44, v44, v45, v47
	v_div_fixup_f32 v24, v44, v24, 1.0
	v_mul_f32_e32 v24, v24, v28
	v_lshlrev_b32_e32 v29, 16, v29
	v_mul_f32_e32 v28, 0xbfb8aa3b, v29
	v_exp_f32_e32 v28, v28
	s_nop 0
	v_add_f32_e32 v28, 1.0, v28
	v_div_scale_f32 v44, s[0:1], v28, v28, v29
	v_rcp_f32_e32 v45, v44
	s_nop 0
	v_fma_f32 v46, -v44, v45, 1.0
	v_fmac_f32_e32 v45, v46, v45
	v_div_scale_f32 v46, vcc, v29, v28, v29
	v_mul_f32_e32 v47, v46, v45
	v_fma_f32 v48, -v44, v47, v46
	v_fmac_f32_e32 v47, v48, v45
	v_fma_f32 v44, -v44, v47, v46
	v_div_fmas_f32 v44, v44, v45, v47
	v_div_fixup_f32 v28, v44, v28, v29
	v_mul_f32_e32 v24, v24, v28
	v_cvt_pk_bf16_f32 v24, v24, s0
	global_store_short v[22:23], v24, off
	v_lshl_add_u64 v[22:23], v[60:61], 0, v[34:35]
	v_lshlrev_b64 v[22:23], 5, v[22:23]
	v_lshl_add_u64 v[22:23], v[66:67], 0, v[22:23]
	v_mov_b32_e32 v22, v126
	v_div_scale_f32 v29, s[0:1], v25, v25, 1.0
	v_rcp_f32_e32 v44, v29
	v_lshlrev_b32_e32 v24, 16, v22
	v_lshl_add_u64 v[22:23], v[42:43], 0, v[58:59]
	v_mov_b32_e32 v28, v127
	v_fma_f32 v45, -v29, v44, 1.0
	v_fmac_f32_e32 v44, v45, v44
	v_div_scale_f32 v45, vcc, 1.0, v25, 1.0
	v_mul_f32_e32 v46, v45, v44
	v_fma_f32 v47, -v29, v46, v45
	v_fmac_f32_e32 v46, v47, v44
	v_fma_f32 v29, -v29, v46, v45
	v_div_fmas_f32 v29, v29, v44, v46
	v_div_fixup_f32 v25, v29, v25, 1.0
	v_mul_f32_e32 v24, v25, v24
	v_lshlrev_b32_e32 v28, 16, v28
	v_mul_f32_e32 v25, 0xbfb8aa3b, v28
	v_exp_f32_e32 v25, v25
	s_nop 0
	v_add_f32_e32 v25, 1.0, v25
	v_div_scale_f32 v29, s[0:1], v25, v25, v28
	v_rcp_f32_e32 v44, v29
	s_nop 0
	v_fma_f32 v45, -v29, v44, 1.0
	v_fmac_f32_e32 v44, v45, v44
	v_div_scale_f32 v45, vcc, v28, v25, v28
	v_mul_f32_e32 v46, v45, v44
	v_fma_f32 v47, -v29, v46, v45
	v_fmac_f32_e32 v46, v47, v44
	v_fma_f32 v29, -v29, v46, v45
	v_div_fmas_f32 v29, v29, v44, v46
	v_div_fixup_f32 v25, v29, v25, v28
	v_mul_f32_e32 v24, v24, v25
	v_cvt_pk_bf16_f32 v24, v24, s0
	global_store_short v[22:23], v24, off
	v_lshl_add_u64 v[22:23], v[56:57], 0, v[40:41]
	v_lshlrev_b64 v[22:23], 5, v[22:23]
	v_lshl_add_u64 v[22:23], v[66:67], 0, v[22:23]
	v_mov_b32_e32 v22, v82
	v_div_scale_f32 v28, s[0:1], v18, v18, 1.0
	v_rcp_f32_e32 v29, v28
	v_lshlrev_b32_e32 v24, 16, v22
	v_lshl_add_u64 v[22:23], v[30:31], 0, v[54:55]
	v_mov_b32_e32 v25, v83
	v_fma_f32 v30, -v28, v29, 1.0
	v_fmac_f32_e32 v29, v30, v29
	v_div_scale_f32 v30, vcc, 1.0, v18, 1.0
	v_mul_f32_e32 v31, v30, v29
	v_fma_f32 v40, -v28, v31, v30
	v_fmac_f32_e32 v31, v40, v29
	v_fma_f32 v28, -v28, v31, v30
	v_div_fmas_f32 v28, v28, v29, v31
	v_div_fixup_f32 v18, v28, v18, 1.0
	v_mul_f32_e32 v18, v18, v24
	v_lshlrev_b32_e32 v25, 16, v25
	v_mul_f32_e32 v24, 0xbfb8aa3b, v25
	v_exp_f32_e32 v24, v24
	s_nop 0
	v_add_f32_e32 v24, 1.0, v24
	v_div_scale_f32 v28, s[0:1], v24, v24, v25
	v_rcp_f32_e32 v29, v28
	s_nop 0
	v_fma_f32 v30, -v28, v29, 1.0
	v_fmac_f32_e32 v29, v30, v29
	v_div_scale_f32 v30, vcc, v25, v24, v25
	v_mul_f32_e32 v31, v30, v29
	v_fma_f32 v40, -v28, v31, v30
	v_fmac_f32_e32 v31, v40, v29
	v_fma_f32 v28, -v28, v31, v30
	v_div_fmas_f32 v28, v28, v29, v31
	v_div_fixup_f32 v24, v28, v24, v25
	v_mul_f32_e32 v18, v18, v24
	v_cvt_pk_bf16_f32 v18, v18, s0
	global_store_short v[22:23], v18, off
	v_lshl_add_u64 v[22:23], v[56:57], 0, v[38:39]
	v_lshlrev_b64 v[22:23], 5, v[22:23]
	v_lshl_add_u64 v[22:23], v[66:67], 0, v[22:23]
	v_mov_b32_e32 v18, v93
	v_lshl_add_u64 v[22:23], v[32:33], 0, v[54:55]
	v_mov_b32_e32 v24, v94
	v_div_scale_f32 v25, s[0:1], v19, v19, 1.0
	v_rcp_f32_e32 v28, v25
	v_lshlrev_b32_e32 v18, 16, v18
	v_fma_f32 v29, -v25, v28, 1.0
	v_fmac_f32_e32 v28, v29, v28
	v_div_scale_f32 v29, vcc, 1.0, v19, 1.0
	v_mul_f32_e32 v30, v29, v28
	v_fma_f32 v31, -v25, v30, v29
	v_fmac_f32_e32 v30, v31, v28
	v_fma_f32 v25, -v25, v30, v29
	v_div_fmas_f32 v25, v25, v28, v30
	v_lshlrev_b32_e32 v24, 16, v24
	v_div_fixup_f32 v19, v25, v19, 1.0
	v_mul_f32_e32 v18, v19, v18
	v_mul_f32_e32 v19, 0xbfb8aa3b, v24
	v_exp_f32_e32 v19, v19
	s_nop 0
	v_add_f32_e32 v19, 1.0, v19
	v_div_scale_f32 v25, s[0:1], v19, v19, v24
	v_rcp_f32_e32 v28, v25
	s_nop 0
	v_fma_f32 v29, -v25, v28, 1.0
	v_fmac_f32_e32 v28, v29, v28
	v_div_scale_f32 v29, vcc, v24, v19, v24
	v_mul_f32_e32 v30, v29, v28
	v_fma_f32 v31, -v25, v30, v29
	v_fmac_f32_e32 v30, v31, v28
	v_fma_f32 v25, -v25, v30, v29
	v_div_fmas_f32 v25, v25, v28, v30
	v_div_fixup_f32 v19, v25, v19, v24
	v_mul_f32_e32 v18, v18, v19
	v_cvt_pk_bf16_f32 v18, v18, s0
	global_store_short v[22:23], v18, off
	v_lshl_add_u64 v[18:19], v[56:57], 0, v[36:37]
	v_lshlrev_b64 v[18:19], 5, v[18:19]
	v_lshl_add_u64 v[18:19], v[66:67], 0, v[18:19]
	v_mov_b32_e32 v18, v95
	v_div_scale_f32 v24, s[0:1], v20, v20, 1.0
	v_rcp_f32_e32 v25, v24
	v_lshlrev_b32_e32 v22, 16, v18
	v_lshl_add_u64 v[18:19], v[26:27], 0, v[54:55]
	v_mov_b32_e32 v23, v96
	v_fma_f32 v26, -v24, v25, 1.0
	v_fmac_f32_e32 v25, v26, v25
	v_div_scale_f32 v26, vcc, 1.0, v20, 1.0
	v_mul_f32_e32 v27, v26, v25
	v_fma_f32 v28, -v24, v27, v26
	v_fmac_f32_e32 v27, v28, v25
	v_fma_f32 v24, -v24, v27, v26
	v_div_fmas_f32 v24, v24, v25, v27
	v_div_fixup_f32 v20, v24, v20, 1.0
	v_mul_f32_e32 v20, v20, v22
	v_lshlrev_b32_e32 v23, 16, v23
	v_mul_f32_e32 v22, 0xbfb8aa3b, v23
	v_exp_f32_e32 v22, v22
	s_nop 0
	v_add_f32_e32 v22, 1.0, v22
	v_div_scale_f32 v24, s[0:1], v22, v22, v23
	v_rcp_f32_e32 v25, v24
	s_nop 0
	v_fma_f32 v26, -v24, v25, 1.0
	v_fmac_f32_e32 v25, v26, v25
	v_div_scale_f32 v26, vcc, v23, v22, v23
	v_mul_f32_e32 v27, v26, v25
	v_fma_f32 v28, -v24, v27, v26
	v_fmac_f32_e32 v27, v28, v25
	v_fma_f32 v24, -v24, v27, v26
	v_div_fmas_f32 v24, v24, v25, v27
	v_div_fixup_f32 v22, v24, v22, v23
	v_mul_f32_e32 v20, v20, v22
	v_cvt_pk_bf16_f32 v20, v20, s0
	global_store_short v[18:19], v20, off
	v_lshl_add_u64 v[18:19], v[56:57], 0, v[34:35]
	v_lshlrev_b64 v[18:19], 5, v[18:19]
	v_lshl_add_u64 v[18:19], v[66:67], 0, v[18:19]
	v_mov_b32_e32 v18, v97
	v_div_scale_f32 v23, s[0:1], v21, v21, 1.0
	v_rcp_f32_e32 v24, v23
	v_lshlrev_b32_e32 v20, 16, v18
	v_lshl_add_u64 v[18:19], v[42:43], 0, v[54:55]
	v_mov_b32_e32 v22, v100
	v_fma_f32 v25, -v23, v24, 1.0
	v_fmac_f32_e32 v24, v25, v24
	v_div_scale_f32 v25, vcc, 1.0, v21, 1.0
	v_mul_f32_e32 v26, v25, v24
	v_fma_f32 v27, -v23, v26, v25
	v_fmac_f32_e32 v26, v27, v24
	v_fma_f32 v23, -v23, v26, v25
	v_div_fmas_f32 v23, v23, v24, v26
	v_div_fixup_f32 v21, v23, v21, 1.0
	v_mul_f32_e32 v20, v21, v20
	v_lshlrev_b32_e32 v22, 16, v22
	v_mul_f32_e32 v21, 0xbfb8aa3b, v22
	v_exp_f32_e32 v21, v21
	s_nop 0
	v_add_f32_e32 v21, 1.0, v21
	v_div_scale_f32 v23, s[0:1], v21, v21, v22
	v_rcp_f32_e32 v24, v23
	s_nop 0
	v_fma_f32 v25, -v23, v24, 1.0
	v_fmac_f32_e32 v24, v25, v24
	v_div_scale_f32 v25, vcc, v22, v21, v22
	v_mul_f32_e32 v26, v25, v24
	v_fma_f32 v27, -v23, v26, v25
	v_fmac_f32_e32 v26, v27, v24
	v_fma_f32 v23, -v23, v26, v25
	v_div_fmas_f32 v23, v23, v24, v26
	v_or_b32_e32 v24, 48, v70
	v_div_fixup_f32 v21, v23, v21, v22
	v_ashrrev_i32_e32 v25, 31, v24
	v_mul_f32_e32 v20, v20, v21
	v_lshl_add_u64 v[34:35], v[130:131], 0, v[24:25]
	v_cvt_pk_bf16_f32 v20, v20, s0
	v_lshlrev_b64 v[34:35], 5, v[34:35]
	global_store_short v[18:19], v20, off
	v_lshl_add_u64 v[34:35], v[66:67], 0, v[34:35]
	v_mov_b32_e32 v34, v116
	v_lshlrev_b64 v[32:33], 10, v[24:25]
	v_div_scale_f32 v38, s[0:1], v14, v14, 1.0
	v_rcp_f32_e32 v39, v38
	v_or_b32_e32 v22, 49, v70
	v_ashrrev_i32_e32 v23, 31, v22
	v_lshlrev_b64 v[30:31], 10, v[22:23]
	v_fma_f32 v40, -v38, v39, 1.0
	v_fmac_f32_e32 v39, v40, v39
	v_div_scale_f32 v40, vcc, 1.0, v14, 1.0
	v_mul_f32_e32 v41, v40, v39
	v_fma_f32 v42, -v38, v41, v40
	v_fmac_f32_e32 v41, v42, v39
	v_fma_f32 v38, -v38, v41, v40
	v_div_fmas_f32 v38, v38, v39, v41
	v_div_fixup_f32 v14, v38, v14, 1.0
	v_or_b32_e32 v20, 50, v70
	v_ashrrev_i32_e32 v21, 31, v20
	v_lshlrev_b64 v[28:29], 10, v[20:21]
	v_or_b32_e32 v18, 51, v70
	v_ashrrev_i32_e32 v19, 31, v18
	v_lshlrev_b64 v[26:27], 10, v[18:19]
	v_lshlrev_b32_e32 v36, 16, v34
	v_lshl_add_u64 v[34:35], v[68:69], 0, v[32:33]
	v_mov_b32_e32 v37, v137
	v_mul_f32_e32 v14, v14, v36
	v_lshlrev_b32_e32 v37, 16, v37
	v_mul_f32_e32 v36, 0xbfb8aa3b, v37
	v_exp_f32_e32 v36, v36
	s_nop 0
	v_add_f32_e32 v36, 1.0, v36
	v_div_scale_f32 v38, s[0:1], v36, v36, v37
	v_rcp_f32_e32 v39, v38
	s_nop 0
	v_fma_f32 v40, -v38, v39, 1.0
	v_fmac_f32_e32 v39, v40, v39
	v_div_scale_f32 v40, vcc, v37, v36, v37
	v_mul_f32_e32 v41, v40, v39
	v_fma_f32 v42, -v38, v41, v40
	v_fmac_f32_e32 v41, v42, v39
	v_fma_f32 v38, -v38, v41, v40
	v_div_fmas_f32 v38, v38, v39, v41
	v_div_fixup_f32 v36, v38, v36, v37
	v_mul_f32_e32 v14, v14, v36
	v_cvt_pk_bf16_f32 v14, v14, s0
	global_store_short v[34:35], v14, off
	v_lshl_add_u64 v[34:35], v[130:131], 0, v[22:23]
	v_lshlrev_b64 v[34:35], 5, v[34:35]
	v_lshl_add_u64 v[34:35], v[66:67], 0, v[34:35]
	v_mov_b32_e32 v14, v140
	v_lshl_add_u64 v[34:35], v[68:69], 0, v[30:31]
	v_mov_b32_e32 v36, v141
	v_div_scale_f32 v37, s[0:1], v15, v15, 1.0
	v_rcp_f32_e32 v38, v37
	v_lshlrev_b32_e32 v14, 16, v14
	v_fma_f32 v39, -v37, v38, 1.0
	v_fmac_f32_e32 v38, v39, v38
	v_div_scale_f32 v39, vcc, 1.0, v15, 1.0
	v_mul_f32_e32 v40, v39, v38
	v_fma_f32 v41, -v37, v40, v39
	v_fmac_f32_e32 v40, v41, v38
	v_fma_f32 v37, -v37, v40, v39
	v_div_fmas_f32 v37, v37, v38, v40
	v_lshlrev_b32_e32 v36, 16, v36
	v_div_fixup_f32 v15, v37, v15, 1.0
	v_mul_f32_e32 v14, v15, v14
	v_mul_f32_e32 v15, 0xbfb8aa3b, v36
	v_exp_f32_e32 v15, v15
	s_nop 0
	v_add_f32_e32 v15, 1.0, v15
	v_div_scale_f32 v37, s[0:1], v15, v15, v36
	v_rcp_f32_e32 v38, v37
	s_nop 0
	v_fma_f32 v39, -v37, v38, 1.0
	v_fmac_f32_e32 v38, v39, v38
	v_div_scale_f32 v39, vcc, v36, v15, v36
	v_mul_f32_e32 v40, v39, v38
	v_fma_f32 v41, -v37, v40, v39
	v_fmac_f32_e32 v40, v41, v38
	v_fma_f32 v37, -v37, v40, v39
	v_div_fmas_f32 v37, v37, v38, v40
	v_div_fixup_f32 v15, v37, v15, v36
	v_mul_f32_e32 v14, v14, v15
	v_cvt_pk_bf16_f32 v14, v14, s0
	global_store_short v[34:35], v14, off
	v_lshl_add_u64 v[14:15], v[130:131], 0, v[20:21]
	v_lshlrev_b64 v[14:15], 5, v[14:15]
	v_lshl_add_u64 v[14:15], v[66:67], 0, v[14:15]
	v_mov_b32_e32 v14, v146
	v_div_scale_f32 v36, s[0:1], v16, v16, 1.0
	v_rcp_f32_e32 v37, v36
	v_lshlrev_b32_e32 v34, 16, v14
	v_lshl_add_u64 v[14:15], v[68:69], 0, v[28:29]
	v_mov_b32_e32 v35, v147
	v_fma_f32 v38, -v36, v37, 1.0
	v_fmac_f32_e32 v37, v38, v37
	v_div_scale_f32 v38, vcc, 1.0, v16, 1.0
	v_mul_f32_e32 v39, v38, v37
	v_fma_f32 v40, -v36, v39, v38
	v_fmac_f32_e32 v39, v40, v37
	v_fma_f32 v36, -v36, v39, v38
	v_div_fmas_f32 v36, v36, v37, v39
	v_div_fixup_f32 v16, v36, v16, 1.0
	v_mul_f32_e32 v16, v16, v34
	v_lshlrev_b32_e32 v35, 16, v35
	v_mul_f32_e32 v34, 0xbfb8aa3b, v35
	v_exp_f32_e32 v34, v34
	s_nop 0
	v_add_f32_e32 v34, 1.0, v34
	v_div_scale_f32 v36, s[0:1], v34, v34, v35
	v_rcp_f32_e32 v37, v36
	s_nop 0
	v_fma_f32 v38, -v36, v37, 1.0
	v_fmac_f32_e32 v37, v38, v37
	v_div_scale_f32 v38, vcc, v35, v34, v35
	v_mul_f32_e32 v39, v38, v37
	v_fma_f32 v40, -v36, v39, v38
	v_fmac_f32_e32 v39, v40, v37
	v_fma_f32 v36, -v36, v39, v38
	v_div_fmas_f32 v36, v36, v37, v39
	v_div_fixup_f32 v34, v36, v34, v35
	v_mul_f32_e32 v16, v16, v34
	v_cvt_pk_bf16_f32 v16, v16, s0
	global_store_short v[14:15], v16, off
	v_lshl_add_u64 v[14:15], v[130:131], 0, v[18:19]
	v_lshlrev_b64 v[14:15], 5, v[14:15]
	v_lshl_add_u64 v[14:15], v[66:67], 0, v[14:15]
	v_mov_b32_e32 v14, v148
	v_div_scale_f32 v35, s[0:1], v17, v17, 1.0
	v_rcp_f32_e32 v36, v35
	v_lshlrev_b32_e32 v16, 16, v14
	v_lshl_add_u64 v[14:15], v[68:69], 0, v[26:27]
	v_mov_b32_e32 v34, v149
	v_fma_f32 v37, -v35, v36, 1.0
	v_fmac_f32_e32 v36, v37, v36
	v_div_scale_f32 v37, vcc, 1.0, v17, 1.0
	v_mul_f32_e32 v38, v37, v36
	v_fma_f32 v39, -v35, v38, v37
	v_fmac_f32_e32 v38, v39, v36
	v_fma_f32 v35, -v35, v38, v37
	v_div_fmas_f32 v35, v35, v36, v38
	v_div_fixup_f32 v17, v35, v17, 1.0
	v_mul_f32_e32 v16, v17, v16
	v_lshl_add_u64 v[26:27], s[2:3], 0, v[26:27]
	v_lshlrev_b32_e32 v34, 16, v34
	v_mul_f32_e32 v17, 0xbfb8aa3b, v34
	v_exp_f32_e32 v17, v17
	s_nop 0
	v_add_f32_e32 v17, 1.0, v17
	v_div_scale_f32 v35, s[0:1], v17, v17, v34
	v_rcp_f32_e32 v36, v35
	s_nop 0
	v_fma_f32 v37, -v35, v36, 1.0
	v_fmac_f32_e32 v36, v37, v36
	v_div_scale_f32 v37, vcc, v34, v17, v34
	v_mul_f32_e32 v38, v37, v36
	v_fma_f32 v39, -v35, v38, v37
	v_fmac_f32_e32 v38, v39, v36
	v_fma_f32 v35, -v35, v38, v37
	v_div_fmas_f32 v35, v35, v36, v38
	v_div_fixup_f32 v17, v35, v17, v34
	v_mul_f32_e32 v16, v16, v17
	v_cvt_pk_bf16_f32 v16, v16, s0
	global_store_short v[14:15], v16, off
	v_lshl_add_u64 v[14:15], v[64:65], 0, v[24:25]
	v_lshlrev_b64 v[14:15], 5, v[14:15]
	v_lshl_add_u64 v[14:15], v[66:67], 0, v[14:15]
	v_mov_b32_e32 v14, v152
	v_lshl_add_u64 v[16:17], s[2:3], 0, v[32:33]
	v_div_scale_f32 v33, s[0:1], v10, v10, 1.0
	v_rcp_f32_e32 v35, v33
	v_lshlrev_b32_e32 v34, 16, v14
	v_lshl_add_u64 v[14:15], v[16:17], 0, v[62:63]
	v_mov_b32_e32 v32, v153
	v_fma_f32 v36, -v33, v35, 1.0
	v_fmac_f32_e32 v35, v36, v35
	v_div_scale_f32 v36, vcc, 1.0, v10, 1.0
	v_mul_f32_e32 v37, v36, v35
	v_fma_f32 v38, -v33, v37, v36
	v_fmac_f32_e32 v37, v38, v35
	v_fma_f32 v33, -v33, v37, v36
	v_div_fmas_f32 v33, v33, v35, v37
	v_div_fixup_f32 v10, v33, v10, 1.0
	v_mul_f32_e32 v10, v10, v34
	v_lshlrev_b32_e32 v32, 16, v32
	v_mul_f32_e32 v33, 0xbfb8aa3b, v32
	v_exp_f32_e32 v33, v33
	s_nop 0
	v_add_f32_e32 v33, 1.0, v33
	v_div_scale_f32 v34, s[0:1], v33, v33, v32
	v_rcp_f32_e32 v35, v34
	s_nop 0
	v_fma_f32 v36, -v34, v35, 1.0
	v_fmac_f32_e32 v35, v36, v35
	v_div_scale_f32 v36, vcc, v32, v33, v32
	v_mul_f32_e32 v37, v36, v35
	v_fma_f32 v38, -v34, v37, v36
	v_fmac_f32_e32 v37, v38, v35
	v_fma_f32 v34, -v34, v37, v36
	v_div_fmas_f32 v34, v34, v35, v37
	v_div_fixup_f32 v32, v34, v33, v32
	v_mul_f32_e32 v10, v10, v32
	v_cvt_pk_bf16_f32 v10, v10, s0
	global_store_short v[14:15], v10, off
	v_lshl_add_u64 v[14:15], v[64:65], 0, v[22:23]
	v_lshlrev_b64 v[14:15], 5, v[14:15]
	v_lshl_add_u64 v[14:15], v[66:67], 0, v[14:15]
	v_mov_b32_e32 v10, v112
	v_lshl_add_u64 v[14:15], s[2:3], 0, v[30:31]
	v_lshl_add_u64 v[30:31], v[14:15], 0, v[62:63]
	v_mov_b32_e32 v32, v113
	v_div_scale_f32 v33, s[0:1], v11, v11, 1.0
	v_rcp_f32_e32 v34, v33
	v_lshlrev_b32_e32 v10, 16, v10
	v_fma_f32 v35, -v33, v34, 1.0
	v_fmac_f32_e32 v34, v35, v34
	v_div_scale_f32 v35, vcc, 1.0, v11, 1.0
	v_mul_f32_e32 v36, v35, v34
	v_fma_f32 v37, -v33, v36, v35
	v_fmac_f32_e32 v36, v37, v34
	v_fma_f32 v33, -v33, v36, v35
	v_div_fmas_f32 v33, v33, v34, v36
	v_lshlrev_b32_e32 v32, 16, v32
	v_div_fixup_f32 v11, v33, v11, 1.0
	v_mul_f32_e32 v10, v11, v10
	v_mul_f32_e32 v11, 0xbfb8aa3b, v32
	v_exp_f32_e32 v11, v11
	s_nop 0
	v_add_f32_e32 v11, 1.0, v11
	v_div_scale_f32 v33, s[0:1], v11, v11, v32
	v_rcp_f32_e32 v34, v33
	s_nop 0
	v_fma_f32 v35, -v33, v34, 1.0
	v_fmac_f32_e32 v34, v35, v34
	v_div_scale_f32 v35, vcc, v32, v11, v32
	v_mul_f32_e32 v36, v35, v34
	v_fma_f32 v37, -v33, v36, v35
	v_fmac_f32_e32 v36, v37, v34
	v_fma_f32 v33, -v33, v36, v35
	v_div_fmas_f32 v33, v33, v34, v36
	v_div_fixup_f32 v11, v33, v11, v32
	v_mul_f32_e32 v10, v10, v11
	v_cvt_pk_bf16_f32 v10, v10, s0
	global_store_short v[30:31], v10, off
	v_lshl_add_u64 v[10:11], v[64:65], 0, v[20:21]
	v_lshlrev_b64 v[10:11], 5, v[10:11]
	v_lshl_add_u64 v[10:11], v[66:67], 0, v[10:11]
	v_mov_b32_e32 v10, v138
	v_div_scale_f32 v32, s[0:1], v12, v12, 1.0
	v_rcp_f32_e32 v33, v32
	v_lshlrev_b32_e32 v30, 16, v10
	v_lshl_add_u64 v[10:11], s[2:3], 0, v[28:29]
	v_lshl_add_u64 v[28:29], v[10:11], 0, v[62:63]
	v_mov_b32_e32 v31, v139
	v_fma_f32 v34, -v32, v33, 1.0
	v_fmac_f32_e32 v33, v34, v33
	v_div_scale_f32 v34, vcc, 1.0, v12, 1.0
	v_mul_f32_e32 v35, v34, v33
	v_fma_f32 v36, -v32, v35, v34
	v_fmac_f32_e32 v35, v36, v33
	v_fma_f32 v32, -v32, v35, v34
	v_div_fmas_f32 v32, v32, v33, v35
	v_div_fixup_f32 v12, v32, v12, 1.0
	v_mul_f32_e32 v12, v12, v30
	v_lshlrev_b32_e32 v31, 16, v31
	v_mul_f32_e32 v30, 0xbfb8aa3b, v31
	v_exp_f32_e32 v30, v30
	s_nop 0
	v_add_f32_e32 v30, 1.0, v30
	v_div_scale_f32 v32, s[0:1], v30, v30, v31
	v_rcp_f32_e32 v33, v32
	s_nop 0
	v_fma_f32 v34, -v32, v33, 1.0
	v_fmac_f32_e32 v33, v34, v33
	v_div_scale_f32 v34, vcc, v31, v30, v31
	v_mul_f32_e32 v35, v34, v33
	v_fma_f32 v36, -v32, v35, v34
	v_fmac_f32_e32 v35, v36, v33
	v_fma_f32 v32, -v32, v35, v34
	v_div_fmas_f32 v32, v32, v33, v35
	v_div_fixup_f32 v30, v32, v30, v31
	v_mul_f32_e32 v12, v12, v30
	v_cvt_pk_bf16_f32 v12, v12, s0
	global_store_short v[28:29], v12, off
	v_lshl_add_u64 v[28:29], v[64:65], 0, v[18:19]
	v_lshlrev_b64 v[28:29], 5, v[28:29]
	v_lshl_add_u64 v[28:29], v[66:67], 0, v[28:29]
	v_mov_b32_e32 v12, v142
	v_lshl_add_u64 v[28:29], v[26:27], 0, v[62:63]
	v_mov_b32_e32 v30, v143
	v_div_scale_f32 v31, s[0:1], v13, v13, 1.0
	v_rcp_f32_e32 v32, v31
	v_lshlrev_b32_e32 v12, 16, v12
	v_fma_f32 v33, -v31, v32, 1.0
	v_fmac_f32_e32 v32, v33, v32
	v_div_scale_f32 v33, vcc, 1.0, v13, 1.0
	v_mul_f32_e32 v34, v33, v32
	v_fma_f32 v35, -v31, v34, v33
	v_fmac_f32_e32 v34, v35, v32
	v_fma_f32 v31, -v31, v34, v33
	v_div_fmas_f32 v31, v31, v32, v34
	v_lshlrev_b32_e32 v30, 16, v30
	v_div_fixup_f32 v13, v31, v13, 1.0
	v_mul_f32_e32 v12, v13, v12
	v_mul_f32_e32 v13, 0xbfb8aa3b, v30
	v_exp_f32_e32 v13, v13
	s_nop 0
	v_add_f32_e32 v13, 1.0, v13
	v_div_scale_f32 v31, s[0:1], v13, v13, v30
	v_rcp_f32_e32 v32, v31
	s_nop 0
	v_fma_f32 v33, -v31, v32, 1.0
	v_fmac_f32_e32 v32, v33, v32
	v_div_scale_f32 v33, vcc, v30, v13, v30
	v_mul_f32_e32 v34, v33, v32
	v_fma_f32 v35, -v31, v34, v33
	v_fmac_f32_e32 v34, v35, v32
	v_fma_f32 v31, -v31, v34, v33
	v_div_fmas_f32 v31, v31, v32, v34
	v_div_fixup_f32 v13, v31, v13, v30
	v_mul_f32_e32 v12, v12, v13
	v_cvt_pk_bf16_f32 v12, v12, s0
	global_store_short v[28:29], v12, off
	v_lshl_add_u64 v[12:13], v[60:61], 0, v[24:25]
	v_lshlrev_b64 v[12:13], 5, v[12:13]
	v_lshl_add_u64 v[12:13], v[66:67], 0, v[12:13]
	v_mov_b32_e32 v12, v160
	v_div_scale_f32 v30, s[0:1], v6, v6, 1.0
	v_rcp_f32_e32 v31, v30
	v_lshlrev_b32_e32 v28, 16, v12
	v_lshl_add_u64 v[12:13], v[16:17], 0, v[58:59]
	v_mov_b32_e32 v29, v162
	v_fma_f32 v32, -v30, v31, 1.0
	v_fmac_f32_e32 v31, v32, v31
	v_div_scale_f32 v32, vcc, 1.0, v6, 1.0
	v_mul_f32_e32 v33, v32, v31
	v_fma_f32 v34, -v30, v33, v32
	v_fmac_f32_e32 v33, v34, v31
	v_fma_f32 v30, -v30, v33, v32
	v_div_fmas_f32 v30, v30, v31, v33
	v_div_fixup_f32 v6, v30, v6, 1.0
	v_mul_f32_e32 v6, v6, v28
	v_lshlrev_b32_e32 v29, 16, v29
	v_mul_f32_e32 v28, 0xbfb8aa3b, v29
	v_exp_f32_e32 v28, v28
	s_nop 0
	v_add_f32_e32 v28, 1.0, v28
	v_div_scale_f32 v30, s[0:1], v28, v28, v29
	v_rcp_f32_e32 v31, v30
	s_nop 0
	v_fma_f32 v32, -v30, v31, 1.0
	v_fmac_f32_e32 v31, v32, v31
	v_div_scale_f32 v32, vcc, v29, v28, v29
	v_mul_f32_e32 v33, v32, v31
	v_fma_f32 v34, -v30, v33, v32
	v_fmac_f32_e32 v33, v34, v31
	v_fma_f32 v30, -v30, v33, v32
	v_div_fmas_f32 v30, v30, v31, v33
	v_div_fixup_f32 v28, v30, v28, v29
	v_mul_f32_e32 v6, v6, v28
	v_cvt_pk_bf16_f32 v6, v6, s0
	global_store_short v[12:13], v6, off
	v_lshl_add_u64 v[12:13], v[60:61], 0, v[22:23]
	v_lshlrev_b64 v[12:13], 5, v[12:13]
	v_lshl_add_u64 v[12:13], v[66:67], 0, v[12:13]
	v_mov_b32_e32 v6, v158
	v_lshl_add_u64 v[12:13], v[14:15], 0, v[58:59]
	v_mov_b32_e32 v28, v159
	v_div_scale_f32 v29, s[0:1], v7, v7, 1.0
	v_rcp_f32_e32 v30, v29
	v_lshlrev_b32_e32 v6, 16, v6
	v_fma_f32 v31, -v29, v30, 1.0
	v_fmac_f32_e32 v30, v31, v30
	v_div_scale_f32 v31, vcc, 1.0, v7, 1.0
	v_mul_f32_e32 v32, v31, v30
	v_fma_f32 v33, -v29, v32, v31
	v_fmac_f32_e32 v32, v33, v30
	v_fma_f32 v29, -v29, v32, v31
	v_div_fmas_f32 v29, v29, v30, v32
	v_lshlrev_b32_e32 v28, 16, v28
	v_div_fixup_f32 v7, v29, v7, 1.0
	v_mul_f32_e32 v6, v7, v6
	v_mul_f32_e32 v7, 0xbfb8aa3b, v28
	v_exp_f32_e32 v7, v7
	s_nop 0
	v_add_f32_e32 v7, 1.0, v7
	v_div_scale_f32 v29, s[0:1], v7, v7, v28
	v_rcp_f32_e32 v30, v29
	s_nop 0
	v_fma_f32 v31, -v29, v30, 1.0
	v_fmac_f32_e32 v30, v31, v30
	v_div_scale_f32 v31, vcc, v28, v7, v28
	v_mul_f32_e32 v32, v31, v30
	v_fma_f32 v33, -v29, v32, v31
	v_fmac_f32_e32 v32, v33, v30
	v_fma_f32 v29, -v29, v32, v31
	v_div_fmas_f32 v29, v29, v30, v32
	v_div_fixup_f32 v7, v29, v7, v28
	v_mul_f32_e32 v6, v6, v7
	v_cvt_pk_bf16_f32 v6, v6, s0
	global_store_short v[12:13], v6, off
	v_lshl_add_u64 v[6:7], v[60:61], 0, v[20:21]
	v_lshlrev_b64 v[6:7], 5, v[6:7]
	v_lshl_add_u64 v[6:7], v[66:67], 0, v[6:7]
	v_mov_b32_e32 v6, v163
	v_div_scale_f32 v28, s[0:1], v8, v8, 1.0
	v_rcp_f32_e32 v29, v28
	v_lshlrev_b32_e32 v12, 16, v6
	v_lshl_add_u64 v[6:7], v[10:11], 0, v[58:59]
	v_mov_b32_e32 v13, v166
	v_fma_f32 v30, -v28, v29, 1.0
	v_fmac_f32_e32 v29, v30, v29
	v_div_scale_f32 v30, vcc, 1.0, v8, 1.0
	v_mul_f32_e32 v31, v30, v29
	v_fma_f32 v32, -v28, v31, v30
	v_fmac_f32_e32 v31, v32, v29
	v_fma_f32 v28, -v28, v31, v30
	v_div_fmas_f32 v28, v28, v29, v31
	v_div_fixup_f32 v8, v28, v8, 1.0
	v_mul_f32_e32 v8, v8, v12
	v_lshlrev_b32_e32 v13, 16, v13
	v_mul_f32_e32 v12, 0xbfb8aa3b, v13
	v_exp_f32_e32 v12, v12
	s_nop 0
	v_add_f32_e32 v12, 1.0, v12
	v_div_scale_f32 v28, s[0:1], v12, v12, v13
	v_rcp_f32_e32 v29, v28
	s_nop 0
	v_fma_f32 v30, -v28, v29, 1.0
	v_fmac_f32_e32 v29, v30, v29
	v_div_scale_f32 v30, vcc, v13, v12, v13
	v_mul_f32_e32 v31, v30, v29
	v_fma_f32 v32, -v28, v31, v30
	v_fmac_f32_e32 v31, v32, v29
	v_fma_f32 v28, -v28, v31, v30
	v_div_fmas_f32 v28, v28, v29, v31
	v_div_fixup_f32 v12, v28, v12, v13
	v_mul_f32_e32 v8, v8, v12
	v_cvt_pk_bf16_f32 v8, v8, s0
	global_store_short v[6:7], v8, off
	v_lshl_add_u64 v[6:7], v[60:61], 0, v[18:19]
	v_lshlrev_b64 v[6:7], 5, v[6:7]
	v_lshl_add_u64 v[6:7], v[66:67], 0, v[6:7]
	v_mov_b32_e32 v6, v164
	v_div_scale_f32 v13, s[0:1], v9, v9, 1.0
	v_rcp_f32_e32 v28, v13
	v_lshlrev_b32_e32 v8, 16, v6
	v_lshl_add_u64 v[6:7], v[26:27], 0, v[58:59]
	v_mov_b32_e32 v12, v165
	v_fma_f32 v29, -v13, v28, 1.0
	v_fmac_f32_e32 v28, v29, v28
	v_div_scale_f32 v29, vcc, 1.0, v9, 1.0
	v_mul_f32_e32 v30, v29, v28
	v_fma_f32 v31, -v13, v30, v29
	v_fmac_f32_e32 v30, v31, v28
	v_fma_f32 v13, -v13, v30, v29
	v_div_fmas_f32 v13, v13, v28, v30
	v_div_fixup_f32 v9, v13, v9, 1.0
	v_mul_f32_e32 v8, v9, v8
	v_lshlrev_b32_e32 v12, 16, v12
	v_mul_f32_e32 v9, 0xbfb8aa3b, v12
	v_exp_f32_e32 v9, v9
	s_nop 0
	v_add_f32_e32 v9, 1.0, v9
	v_div_scale_f32 v13, s[0:1], v9, v9, v12
	v_rcp_f32_e32 v28, v13
	s_nop 0
	v_fma_f32 v29, -v13, v28, 1.0
	v_fmac_f32_e32 v28, v29, v28
	v_div_scale_f32 v29, vcc, v12, v9, v12
	v_mul_f32_e32 v30, v29, v28
	v_fma_f32 v31, -v13, v30, v29
	v_fmac_f32_e32 v30, v31, v28
	v_fma_f32 v13, -v13, v30, v29
	v_div_fmas_f32 v13, v13, v28, v30
	v_div_fixup_f32 v9, v13, v9, v12
	v_mul_f32_e32 v8, v8, v9
	v_cvt_pk_bf16_f32 v8, v8, s0
	global_store_short v[6:7], v8, off
	v_lshl_add_u64 v[6:7], v[56:57], 0, v[24:25]
	v_lshlrev_b64 v[6:7], 5, v[6:7]
	v_lshl_add_u64 v[6:7], v[66:67], 0, v[6:7]
	v_mov_b32_e32 v6, v106
	v_div_scale_f32 v12, s[0:1], v2, v2, 1.0
	v_rcp_f32_e32 v13, v12
	v_lshlrev_b32_e32 v8, 16, v6
	v_lshl_add_u64 v[6:7], v[16:17], 0, v[54:55]
	v_mov_b32_e32 v9, v107
	v_fma_f32 v16, -v12, v13, 1.0
	v_fmac_f32_e32 v13, v16, v13
	v_div_scale_f32 v16, vcc, 1.0, v2, 1.0
	v_mul_f32_e32 v17, v16, v13
	v_fma_f32 v24, -v12, v17, v16
	v_fmac_f32_e32 v17, v24, v13
	v_fma_f32 v12, -v12, v17, v16
	v_div_fmas_f32 v12, v12, v13, v17
	v_div_fixup_f32 v2, v12, v2, 1.0
	v_mul_f32_e32 v2, v2, v8
	v_lshlrev_b32_e32 v9, 16, v9
	v_mul_f32_e32 v8, 0xbfb8aa3b, v9
	v_exp_f32_e32 v8, v8
	s_nop 0
	v_add_f32_e32 v8, 1.0, v8
	v_div_scale_f32 v12, s[0:1], v8, v8, v9
	v_rcp_f32_e32 v13, v12
	s_nop 0
	v_fma_f32 v16, -v12, v13, 1.0
	v_fmac_f32_e32 v13, v16, v13
	v_div_scale_f32 v16, vcc, v9, v8, v9
	v_mul_f32_e32 v17, v16, v13
	v_fma_f32 v24, -v12, v17, v16
	v_fmac_f32_e32 v17, v24, v13
	v_fma_f32 v12, -v12, v17, v16
	v_div_fmas_f32 v12, v12, v13, v17
	v_div_fixup_f32 v8, v12, v8, v9
	v_mul_f32_e32 v2, v2, v8
	v_cvt_pk_bf16_f32 v2, v2, s0
	global_store_short v[6:7], v2, off
	v_lshl_add_u64 v[6:7], v[56:57], 0, v[22:23]
	v_lshlrev_b64 v[6:7], 5, v[6:7]
	v_lshl_add_u64 v[6:7], v[66:67], 0, v[6:7]
	v_mov_b32_e32 v2, v117
	v_lshl_add_u64 v[6:7], v[14:15], 0, v[54:55]
	v_mov_b32_e32 v8, v118
	v_div_scale_f32 v9, s[0:1], v3, v3, 1.0
	v_rcp_f32_e32 v12, v9
	v_lshlrev_b32_e32 v2, 16, v2
	v_fma_f32 v13, -v9, v12, 1.0
	v_fmac_f32_e32 v12, v13, v12
	v_div_scale_f32 v13, vcc, 1.0, v3, 1.0
	v_mul_f32_e32 v14, v13, v12
	v_fma_f32 v15, -v9, v14, v13
	v_fmac_f32_e32 v14, v15, v12
	v_fma_f32 v9, -v9, v14, v13
	v_div_fmas_f32 v9, v9, v12, v14
	v_lshlrev_b32_e32 v8, 16, v8
	v_div_fixup_f32 v3, v9, v3, 1.0
	v_mul_f32_e32 v2, v3, v2
	v_mul_f32_e32 v3, 0xbfb8aa3b, v8
	v_exp_f32_e32 v3, v3
	s_nop 0
	v_add_f32_e32 v3, 1.0, v3
	v_div_scale_f32 v9, s[0:1], v3, v3, v8
	v_rcp_f32_e32 v12, v9
	s_nop 0
	v_fma_f32 v13, -v9, v12, 1.0
	v_fmac_f32_e32 v12, v13, v12
	v_div_scale_f32 v13, vcc, v8, v3, v8
	v_mul_f32_e32 v14, v13, v12
	v_fma_f32 v15, -v9, v14, v13
	v_fmac_f32_e32 v14, v15, v12
	v_fma_f32 v9, -v9, v14, v13
	v_div_fmas_f32 v9, v9, v12, v14
	v_div_fixup_f32 v3, v9, v3, v8
	v_mul_f32_e32 v2, v2, v3
	v_cvt_pk_bf16_f32 v2, v2, s0
	global_store_short v[6:7], v2, off
	v_lshl_add_u64 v[2:3], v[56:57], 0, v[20:21]
	v_lshlrev_b64 v[2:3], 5, v[2:3]
	v_lshl_add_u64 v[2:3], v[66:67], 0, v[2:3]
	v_mov_b32_e32 v2, v119
	v_div_scale_f32 v8, s[0:1], v4, v4, 1.0
	v_rcp_f32_e32 v9, v8
	v_lshlrev_b32_e32 v6, 16, v2
	v_lshl_add_u64 v[2:3], v[10:11], 0, v[54:55]
	v_mov_b32_e32 v7, v128
	v_fma_f32 v10, -v8, v9, 1.0
	v_fmac_f32_e32 v9, v10, v9
	v_div_scale_f32 v10, vcc, 1.0, v4, 1.0
	v_mul_f32_e32 v11, v10, v9
	v_fma_f32 v12, -v8, v11, v10
	v_fmac_f32_e32 v11, v12, v9
	v_fma_f32 v8, -v8, v11, v10
	v_div_fmas_f32 v8, v8, v9, v11
	v_div_fixup_f32 v4, v8, v4, 1.0
	v_mul_f32_e32 v4, v4, v6
	v_lshlrev_b32_e32 v7, 16, v7
	v_mul_f32_e32 v6, 0xbfb8aa3b, v7
	v_exp_f32_e32 v6, v6
	s_nop 0
	v_add_f32_e32 v6, 1.0, v6
	v_div_scale_f32 v8, s[0:1], v6, v6, v7
	v_rcp_f32_e32 v9, v8
	s_nop 0
	v_fma_f32 v10, -v8, v9, 1.0
	v_fmac_f32_e32 v9, v10, v9
	v_div_scale_f32 v10, vcc, v7, v6, v7
	v_mul_f32_e32 v11, v10, v9
	v_fma_f32 v12, -v8, v11, v10
	v_fmac_f32_e32 v11, v12, v9
	v_fma_f32 v8, -v8, v11, v10
	v_div_fmas_f32 v8, v8, v9, v11
	v_div_fixup_f32 v6, v8, v6, v7
	v_mul_f32_e32 v4, v4, v6
	v_cvt_pk_bf16_f32 v4, v4, s0
	global_store_short v[2:3], v4, off
	v_lshl_add_u64 v[2:3], v[56:57], 0, v[18:19]
	v_lshlrev_b64 v[2:3], 5, v[2:3]
	v_lshl_add_u64 v[2:3], v[66:67], 0, v[2:3]
	v_mov_b32_e32 v2, v129
	v_div_scale_f32 v5, s[0:1], v1, v1, 1.0
	v_rcp_f32_e32 v7, v5
	v_lshlrev_b32_e32 v4, 16, v2
	v_lshl_add_u64 v[2:3], v[26:27], 0, v[54:55]
	v_mov_b32_e32 v6, v134
	v_fma_f32 v8, -v5, v7, 1.0
	v_fmac_f32_e32 v7, v8, v7
	v_div_scale_f32 v8, vcc, 1.0, v1, 1.0
	v_mul_f32_e32 v9, v8, v7
	v_fma_f32 v10, -v5, v9, v8
	v_fmac_f32_e32 v9, v10, v7
	v_fma_f32 v5, -v5, v9, v8
	v_div_fmas_f32 v5, v5, v7, v9
	v_div_fixup_f32 v1, v5, v1, 1.0
	v_mul_f32_e32 v1, v1, v4
	v_lshlrev_b32_e32 v6, 16, v6
	v_mul_f32_e32 v4, 0xbfb8aa3b, v6
	v_exp_f32_e32 v4, v4
	s_nop 0
	v_add_f32_e32 v4, 1.0, v4
	v_div_scale_f32 v5, s[0:1], v4, v4, v6
	v_rcp_f32_e32 v7, v5
	s_nop 0
	v_fma_f32 v8, -v5, v7, 1.0
	v_fmac_f32_e32 v7, v8, v7
	v_div_scale_f32 v8, vcc, v6, v4, v6
	v_mul_f32_e32 v9, v8, v7
	v_fma_f32 v10, -v5, v9, v8
	v_fmac_f32_e32 v9, v10, v7
	v_fma_f32 v5, -v5, v9, v8
	v_div_fmas_f32 v5, v5, v7, v9
	v_div_fixup_f32 v4, v5, v4, v6
	v_mul_f32_e32 v1, v1, v4
	v_cvt_pk_bf16_f32 v1, v1, s0
	global_store_short v[2:3], v1, off

.LBB0_192:
	v_readlane_b32 s27, v254, 63
	s_or_b32 s32, s14, s27
	s_ashr_i32 s27, s32, 31
	s_mov_b32 s64, s32
	s_mov_b32 s65, s27
	s_lshl_b64 s[98:99], s[64:65], 2
	s_add_u32 s27, s62, s98
	s_addc_u32 s32, s63, s99
	s_mov_b32 s64, s27
	s_mov_b32 s65, s32
	global_load_dword v64, v131, s[64:65]
	s_lshl_b32 s27, s15, 1
	v_readlane_b32 s32, v253, 49
	v_readlane_b32 s64, v253, 50
	s_add_u32 s65, s32, s27
	v_add_u32_e32 v65, s10, v62
	s_addc_u32 s27, s64, 0
	v_ashrrev_i32_e32 v72, 31, v65
	v_lshlrev_b32_e32 v73, 1, v219
	v_mov_b32_e32 v74, v65
	v_mov_b32_e32 v75, v72
	v_lshlrev_b64 v[82:83], 11, v[74:75]
	s_mov_b32 s98, s65
	s_mov_b32 s99, s27
	v_mov_b32_e32 v74, v73
	v_mov_b32_e32 v75, v131
	v_lshl_add_u64 v[84:85], s[98:99], 0, v[74:75]
	v_lshl_add_u64 v[72:73], v[84:85], 0, v[82:83]
	global_load_ushort v74, v[72:73], off
	v_or_b32_e32 v75, 1, v65
	v_ashrrev_i32_e32 v76, 31, v75
	v_mov_b32_e32 v82, v75
	v_mov_b32_e32 v83, v76
	v_lshlrev_b64 v[86:87], 11, v[82:83]
	v_lshl_add_u64 v[82:83], v[84:85], 0, v[86:87]
	global_load_ushort v75, v[82:83], off
	v_or_b32_e32 v76, 2, v65
	v_ashrrev_i32_e32 v78, 31, v76
	v_mov_b32_e32 v86, v76
	v_mov_b32_e32 v87, v78
	v_lshlrev_b64 v[88:89], 11, v[86:87]
	v_lshl_add_u64 v[86:87], v[84:85], 0, v[88:89]
	global_load_ushort v76, v[86:87], off
	v_or_b32_e32 v78, 3, v65
	v_ashrrev_i32_e32 v65, 31, v78
	v_mov_b32_e32 v88, v78
	v_mov_b32_e32 v89, v65
	v_lshlrev_b64 v[90:91], 11, v[88:89]
	v_lshl_add_u64 v[88:89], v[84:85], 0, v[90:91]
	global_load_ushort v65, v[88:89], off
	global_load_ushort v78, v[72:73], off offset:32
	global_load_ushort v90, v[82:83], off offset:32
	global_load_ushort v91, v[86:87], off offset:32
	global_load_ushort v92, v[88:89], off offset:32
	global_load_ushort v93, v[72:73], off offset:64
	global_load_ushort v94, v[82:83], off offset:64
	global_load_ushort v95, v[86:87], off offset:64
	global_load_ushort v96, v[88:89], off offset:64
	global_load_ushort v97, v[72:73], off offset:96
	global_load_ushort v72, v[82:83], off offset:96
	global_load_ushort v73, v[86:87], off offset:96
	global_load_ushort v82, v[88:89], off offset:96
	v_add_u32_e32 v83, s10, v218
	v_ashrrev_i32_e32 v86, 31, v83
	v_mov_b32_e32 v88, v83
	v_mov_b32_e32 v89, v86
	v_lshlrev_b64 v[98:99], 11, v[88:89]
	v_lshl_add_u64 v[86:87], v[84:85], 0, v[98:99]
	global_load_ushort v88, v[86:87], off
	v_or_b32_e32 v89, 1, v83
	v_ashrrev_i32_e32 v98, 31, v89
	v_mov_b32_e32 v100, v89
	v_mov_b32_e32 v101, v98
	v_lshlrev_b64 v[102:103], 11, v[100:101]
	v_lshl_add_u64 v[98:99], v[84:85], 0, v[102:103]
	global_load_ushort v89, v[98:99], off
	v_or_b32_e32 v100, 2, v83
	v_ashrrev_i32_e32 v101, 31, v100
	v_lshlrev_b64 v[102:103], 11, v[100:101]
	v_lshl_add_u64 v[100:101], v[84:85], 0, v[102:103]
	global_load_ushort v102, v[100:101], off
	v_or_b32_e32 v103, 3, v83
	v_ashrrev_i32_e32 v83, 31, v103
	v_mov_b32_e32 v104, v103
	v_mov_b32_e32 v105, v83
	v_lshlrev_b64 v[106:107], 11, v[104:105]
	v_lshl_add_u64 v[104:105], v[84:85], 0, v[106:107]
	global_load_ushort v83, v[104:105], off
	global_load_ushort v84, v[86:87], off offset:32
	global_load_ushort v85, v[98:99], off offset:32
	global_load_ushort v103, v[100:101], off offset:32
	global_load_ushort v106, v[104:105], off offset:32
	global_load_ushort v107, v[86:87], off offset:64
	global_load_ushort v108, v[98:99], off offset:64
	global_load_ushort v109, v[100:101], off offset:64
	global_load_ushort v110, v[104:105], off offset:64
	global_load_ushort v111, v[86:87], off offset:96
	global_load_ushort v86, v[98:99], off offset:96
	global_load_ushort v87, v[100:101], off offset:96
	global_load_ushort v98, v[104:105], off offset:96
	v_cmp_lt_i32_e32 vcc, v203, v200
	v_readlane_b32 s0, v254, 63
	s_or_b32 s0, s14, s0
	v_cndmask_b32_e32 v1, v198, v203, vcc
	v_cmp_lt_i32_e32 vcc, v204, v200
	s_ashr_i32 s1, s0, 31
	s_lshl_b64 s[0:1], s[0:1], 2
	v_cndmask_b32_e32 v34, v198, v204, vcc
	v_cmp_lt_i32_e32 vcc, v205, v200
	v_lshlrev_b32_e32 v44, 2, v34
	s_add_u32 s0, s62, s0
	v_cndmask_b32_e32 v34, v198, v205, vcc
	v_cmp_lt_i32_e32 vcc, v206, v200
	v_lshlrev_b32_e32 v45, 2, v34
	s_addc_u32 s1, s63, s1
	v_cndmask_b32_e32 v34, v198, v206, vcc
	v_lshlrev_b32_e32 v46, 2, v34
	ds_read_b64 v[34:35], v155 offset:34816
	s_waitcnt vmcnt(0)
	v_mov_b32_e32 v47, v64
	s_lshl_b32 s0, s15, 1
	v_readlane_b32 s2, v253, 49
	v_readlane_b32 s3, v253, 50
	s_add_u32 s4, s2, s0
	v_add_u32_e32 v42, s10, v62
	s_addc_u32 s5, s3, 0
	v_ashrrev_i32_e32 v43, 31, v42
	v_lshlrev_b32_e32 v130, 1, v219
	v_lshlrev_b64 v[36:37], 11, v[42:43]
	s_waitcnt lgkmcnt(0)
	v_lshlrev_b32_e32 v38, 16, v34
	v_and_b32_e32 v39, 0xffff0000, v34
	v_lshlrev_b32_e32 v48, 16, v35
	v_and_b32_e32 v49, 0xffff0000, v35
	v_lshl_add_u64 v[34:35], s[4:5], 0, v[130:131]
	v_lshl_add_u64 v[40:41], v[34:35], 0, v[36:37]
	v_mov_b32_e32 v36, v74
	s_lshl_b64 s[0:1], s[10:11], 2
	v_readlane_b32 s6, v253, 51
	v_readlane_b32 s7, v253, 52
	s_add_u32 s0, s6, s0
	s_addc_u32 s1, s7, s1
	s_mul_i32 s14, s14, 0x11000
	s_add_u32 s0, s0, s14
	v_lshlrev_b32_e32 v1, 2, v1
	s_addc_u32 s1, s1, 0
	v_ashrrev_i32_e32 v63, 31, v62
	v_cmp_eq_u32_e64 s[2:3], 0, v219
	v_fma_f32 v30, v47, v38, v30
	v_fma_f32 v31, v47, v39, v31
	v_fmac_f32_e32 v33, v47, v49
	v_lshlrev_b32_e32 v36, 16, v36
	v_mul_f32_e32 v37, 0xbfb8aa3b, v36
	v_exp_f32_e32 v37, v37
	s_nop 0
	v_add_f32_e32 v37, 1.0, v37
	v_div_scale_f32 v38, s[4:5], v37, v37, v36
	v_rcp_f32_e32 v43, v38
	s_nop 0
	v_fma_f32 v50, -v38, v43, 1.0
	v_fmac_f32_e32 v43, v50, v43
	v_div_scale_f32 v50, vcc, v36, v37, v36
	v_mul_f32_e32 v51, v50, v43
	v_fma_f32 v52, -v38, v51, v50
	v_fmac_f32_e32 v51, v52, v43
	v_fma_f32 v38, -v38, v51, v50
	v_div_fmas_f32 v38, v38, v43, v51
	v_div_fixup_f32 v36, v38, v37, v36
	v_mul_f32_e32 v50, v30, v36
	v_or_b32_e32 v36, 1, v42
	v_ashrrev_i32_e32 v37, 31, v36
	v_lshlrev_b64 v[36:37], 11, v[36:37]
	v_cvt_pk_bf16_f32 v30, v50, s0
	v_lshl_add_u64 v[36:37], v[34:35], 0, v[36:37]
	global_store_short v[40:41], v30, off
	v_mov_b32_e32 v30, v75
	v_lshlrev_b32_e32 v30, 16, v30
	v_mul_f32_e32 v38, 0xbfb8aa3b, v30
	v_exp_f32_e32 v38, v38
	s_nop 0
	v_add_f32_e32 v38, 1.0, v38
	v_div_scale_f32 v39, s[4:5], v38, v38, v30
	v_rcp_f32_e32 v43, v39
	s_nop 0
	v_fma_f32 v51, -v39, v43, 1.0
	v_fmac_f32_e32 v43, v51, v43
	v_div_scale_f32 v51, vcc, v30, v38, v30
	v_mul_f32_e32 v52, v51, v43
	v_fma_f32 v53, -v39, v52, v51
	v_fmac_f32_e32 v52, v53, v43
	v_fma_f32 v39, -v39, v52, v51
	v_div_fmas_f32 v39, v39, v43, v52
	v_div_fixup_f32 v30, v39, v38, v30
	v_mul_f32_e32 v43, v31, v30
	v_cvt_pk_bf16_f32 v30, v43, s0
	global_store_short v[36:37], v30, off
	v_or_b32_e32 v30, 2, v42
	v_ashrrev_i32_e32 v31, 31, v30
	v_lshlrev_b64 v[30:31], 11, v[30:31]
	v_lshl_add_u64 v[38:39], v[34:35], 0, v[30:31]
	v_mov_b32_e32 v30, v76
	v_fma_f32 v31, v47, v48, v32
	v_lshlrev_b32_e32 v30, 16, v30
	v_mul_f32_e32 v32, 0xbfb8aa3b, v30
	v_exp_f32_e32 v32, v32
	s_nop 0
	v_add_f32_e32 v32, 1.0, v32
	v_div_scale_f32 v48, s[4:5], v32, v32, v30
	v_rcp_f32_e32 v51, v48
	s_nop 0
	v_fma_f32 v52, -v48, v51, 1.0
	v_fmac_f32_e32 v51, v52, v51
	v_div_scale_f32 v52, vcc, v30, v32, v30
	v_mul_f32_e32 v53, v52, v51
	v_fma_f32 v54, -v48, v53, v52
	v_fmac_f32_e32 v53, v54, v51
	v_fma_f32 v48, -v48, v53, v52
	v_div_fmas_f32 v48, v48, v51, v53
	v_div_fixup_f32 v30, v48, v32, v30
	v_mul_f32_e32 v32, v31, v30
	v_cvt_pk_bf16_f32 v30, v32, s0
	global_store_short v[38:39], v30, off
	v_or_b32_e32 v30, 3, v42
	v_ashrrev_i32_e32 v31, 31, v30
	v_lshlrev_b64 v[30:31], 11, v[30:31]
	v_lshl_add_u64 v[30:31], v[34:35], 0, v[30:31]
	v_mov_b32_e32 v42, v65
	v_lshlrev_b32_e32 v42, 16, v42
	v_mul_f32_e32 v48, 0xbfb8aa3b, v42
	v_exp_f32_e32 v48, v48
	s_nop 0
	v_add_f32_e32 v48, 1.0, v48
	v_div_scale_f32 v49, s[4:5], v48, v48, v42
	v_rcp_f32_e32 v51, v49
	s_nop 0
	v_fma_f32 v52, -v49, v51, 1.0
	v_fmac_f32_e32 v51, v52, v51
	v_div_scale_f32 v52, vcc, v42, v48, v42
	v_mul_f32_e32 v53, v52, v51
	v_fma_f32 v54, -v49, v53, v52
	v_fmac_f32_e32 v53, v54, v51
	v_fma_f32 v49, -v49, v53, v52
	v_div_fmas_f32 v49, v49, v51, v53
	v_div_fixup_f32 v42, v49, v48, v42
	ds_read_b64 v[48:49], v155 offset:39168
	v_mul_f32_e32 v33, v33, v42
	v_cvt_pk_bf16_f32 v42, v33, s0
	global_store_short v[30:31], v42, off
	s_waitcnt lgkmcnt(0)
	v_lshlrev_b32_e32 v42, 16, v48
	v_and_b32_e32 v51, 0xffff0000, v48
	v_mov_b32_e32 v48, v78
	v_fma_f32 v26, v47, v42, v26
	v_fma_f32 v27, v47, v51, v27
	v_lshlrev_b32_e32 v52, 16, v49
	v_and_b32_e32 v49, 0xffff0000, v49
	v_fmac_f32_e32 v29, v47, v49
	v_lshlrev_b32_e32 v48, 16, v48
	v_mul_f32_e32 v42, 0xbfb8aa3b, v48
	v_exp_f32_e32 v42, v42
	s_nop 0
	v_add_f32_e32 v42, 1.0, v42
	v_div_scale_f32 v53, s[4:5], v42, v42, v48
	v_rcp_f32_e32 v54, v53
	s_nop 0
	v_fma_f32 v55, -v53, v54, 1.0
	v_fmac_f32_e32 v54, v55, v54
	v_div_scale_f32 v55, vcc, v48, v42, v48
	v_mul_f32_e32 v56, v55, v54
	v_fma_f32 v57, -v53, v56, v55
	v_fmac_f32_e32 v56, v57, v54
	v_fma_f32 v53, -v53, v56, v55
	v_div_fmas_f32 v53, v53, v54, v56
	v_div_fixup_f32 v42, v53, v42, v48
	v_mul_f32_e32 v26, v26, v42
	v_cvt_pk_bf16_f32 v42, v26, s0
	v_mul_f32_e32 v48, v26, v26
	v_mov_b32_e32 v26, v90
	v_fmac_f32_e32 v48, v50, v50
	global_store_short v[40:41], v42, off offset:32
	v_lshlrev_b32_e32 v26, 16, v26
	v_mul_f32_e32 v42, 0xbfb8aa3b, v26
	v_exp_f32_e32 v42, v42
	s_nop 0
	v_add_f32_e32 v42, 1.0, v42
	v_div_scale_f32 v50, s[4:5], v42, v42, v26
	v_rcp_f32_e32 v51, v50
	s_nop 0
	v_fma_f32 v53, -v50, v51, 1.0
	v_fmac_f32_e32 v51, v53, v51
	v_div_scale_f32 v53, vcc, v26, v42, v26
	v_mul_f32_e32 v54, v53, v51
	v_fma_f32 v55, -v50, v54, v53
	v_fmac_f32_e32 v54, v55, v51
	v_fma_f32 v50, -v50, v54, v53
	v_div_fmas_f32 v50, v50, v51, v54
	v_div_fixup_f32 v26, v50, v42, v26
	v_mul_f32_e32 v42, v27, v26
	v_cvt_pk_bf16_f32 v26, v42, s0
	global_store_short v[36:37], v26, off offset:32
	v_mov_b32_e32 v26, v91
	v_fma_f32 v27, v47, v52, v28
	v_lshlrev_b32_e32 v26, 16, v26
	v_mul_f32_e32 v28, 0xbfb8aa3b, v26
	v_exp_f32_e32 v28, v28
	s_nop 0
	v_add_f32_e32 v28, 1.0, v28
	v_div_scale_f32 v50, s[4:5], v28, v28, v26
	v_rcp_f32_e32 v51, v50
	s_nop 0
	v_fma_f32 v52, -v50, v51, 1.0
	v_fmac_f32_e32 v51, v52, v51
	v_div_scale_f32 v52, vcc, v26, v28, v26
	v_mul_f32_e32 v53, v52, v51
	v_fma_f32 v54, -v50, v53, v52
	v_fmac_f32_e32 v53, v54, v51
	v_fma_f32 v50, -v50, v53, v52
	v_div_fmas_f32 v50, v50, v51, v53
	v_div_fixup_f32 v26, v50, v28, v26
	v_mul_f32_e32 v27, v27, v26
	v_cvt_pk_bf16_f32 v26, v27, s0
	global_store_short v[38:39], v26, off offset:32
	v_mov_b32_e32 v26, v92
	v_lshlrev_b32_e32 v26, 16, v26
	v_mul_f32_e32 v28, 0xbfb8aa3b, v26
	v_exp_f32_e32 v28, v28
	s_nop 0
	v_add_f32_e32 v28, 1.0, v28
	v_div_scale_f32 v49, s[4:5], v28, v28, v26
	v_rcp_f32_e32 v50, v49
	s_nop 0
	v_fma_f32 v51, -v49, v50, 1.0
	v_fmac_f32_e32 v50, v51, v50
	v_div_scale_f32 v51, vcc, v26, v28, v26
	v_mul_f32_e32 v52, v51, v50
	v_fma_f32 v53, -v49, v52, v51
	v_fmac_f32_e32 v52, v53, v50
	v_fma_f32 v49, -v49, v52, v51
	v_mov_b32_e32 v51, v93
	v_div_fmas_f32 v49, v49, v50, v52
	v_div_fixup_f32 v26, v49, v28, v26
	v_mul_f32_e32 v26, v29, v26
	v_cvt_pk_bf16_f32 v28, v26, s0
	global_store_short v[30:31], v28, off offset:32
	ds_read_b64 v[28:29], v155 offset:43520
	s_waitcnt lgkmcnt(0)
	v_lshlrev_b32_e32 v49, 16, v28
	v_fma_f32 v22, v47, v49, v22
	v_and_b32_e32 v28, 0xffff0000, v28
	v_fma_f32 v23, v47, v28, v23
	v_lshlrev_b32_e32 v50, 16, v29
	v_and_b32_e32 v29, 0xffff0000, v29
	v_fmac_f32_e32 v25, v47, v29
	v_lshlrev_b32_e32 v51, 16, v51
	v_mul_f32_e32 v49, 0xbfb8aa3b, v51
	v_exp_f32_e32 v49, v49
	s_nop 0
	v_add_f32_e32 v49, 1.0, v49
	v_div_scale_f32 v52, s[4:5], v49, v49, v51
	v_rcp_f32_e32 v53, v52
	s_nop 0
	v_fma_f32 v54, -v52, v53, 1.0
	v_fmac_f32_e32 v53, v54, v53
	v_div_scale_f32 v54, vcc, v51, v49, v51
	v_mul_f32_e32 v55, v54, v53
	v_fma_f32 v56, -v52, v55, v54
	v_fmac_f32_e32 v55, v56, v53
	v_fma_f32 v52, -v52, v55, v54
	v_div_fmas_f32 v52, v52, v53, v55
	v_div_fixup_f32 v49, v52, v49, v51
	v_mul_f32_e32 v22, v22, v49
	v_cvt_pk_bf16_f32 v49, v22, s0
	v_fmac_f32_e32 v48, v22, v22
	v_mov_b32_e32 v22, v94
	v_lshlrev_b32_e32 v22, 16, v22
	v_mul_f32_e32 v28, 0xbfb8aa3b, v22
	v_exp_f32_e32 v28, v28
	global_store_short v[40:41], v49, off offset:64
	v_add_f32_e32 v28, 1.0, v28
	v_div_scale_f32 v49, s[4:5], v28, v28, v22
	v_rcp_f32_e32 v51, v49
	s_nop 0
	v_fma_f32 v52, -v49, v51, 1.0
	v_fmac_f32_e32 v51, v52, v51
	v_div_scale_f32 v52, vcc, v22, v28, v22
	v_mul_f32_e32 v53, v52, v51
	v_fma_f32 v54, -v49, v53, v52
	v_fmac_f32_e32 v53, v54, v51
	v_fma_f32 v49, -v49, v53, v52
	v_div_fmas_f32 v49, v49, v51, v53
	v_div_fixup_f32 v22, v49, v28, v22
	v_mul_f32_e32 v28, v23, v22
	v_cvt_pk_bf16_f32 v22, v28, s0
	global_store_short v[36:37], v22, off offset:64
	v_mov_b32_e32 v22, v95
	v_fma_f32 v23, v47, v50, v24
	v_lshlrev_b32_e32 v22, 16, v22
	v_mul_f32_e32 v24, 0xbfb8aa3b, v22
	v_exp_f32_e32 v24, v24
	s_nop 0
	v_add_f32_e32 v24, 1.0, v24
	v_div_scale_f32 v49, s[4:5], v24, v24, v22
	v_rcp_f32_e32 v50, v49
	s_nop 0
	v_fma_f32 v51, -v49, v50, 1.0
	v_fmac_f32_e32 v50, v51, v50
	v_div_scale_f32 v51, vcc, v22, v24, v22
	v_mul_f32_e32 v52, v51, v50
	v_fma_f32 v53, -v49, v52, v51
	v_fmac_f32_e32 v52, v53, v50
	v_fma_f32 v49, -v49, v52, v51
	v_div_fmas_f32 v49, v49, v50, v52
	v_div_fixup_f32 v22, v49, v24, v22
	v_mul_f32_e32 v23, v23, v22
	v_cvt_pk_bf16_f32 v22, v23, s0
	global_store_short v[38:39], v22, off offset:64
	v_mov_b32_e32 v22, v96
	v_lshlrev_b32_e32 v22, 16, v22
	v_mul_f32_e32 v24, 0xbfb8aa3b, v22
	v_exp_f32_e32 v24, v24
	s_nop 0
	v_add_f32_e32 v24, 1.0, v24
	v_div_scale_f32 v29, s[4:5], v24, v24, v22
	v_rcp_f32_e32 v49, v29
	s_nop 0
	v_fma_f32 v50, -v29, v49, 1.0
	v_fmac_f32_e32 v49, v50, v49
	v_div_scale_f32 v50, vcc, v22, v24, v22
	v_mul_f32_e32 v51, v50, v49
	v_fma_f32 v52, -v29, v51, v50
	v_fmac_f32_e32 v51, v52, v49
	v_fma_f32 v29, -v29, v51, v50
	v_div_fmas_f32 v29, v29, v49, v51
	v_div_fixup_f32 v22, v29, v24, v22
	v_mul_f32_e32 v22, v25, v22
	v_cvt_pk_bf16_f32 v24, v22, s0
	global_store_short v[30:31], v24, off offset:64
	ds_read_b64 v[24:25], v155 offset:47872
	s_waitcnt lgkmcnt(0)
	v_lshlrev_b32_e32 v29, 16, v24
	v_and_b32_e32 v49, 0xffff0000, v24
	v_lshlrev_b32_e32 v50, 16, v25
	v_and_b32_e32 v24, 0xffff0000, v25
	v_mov_b32_e32 v25, v97
	v_fma_f32 v18, v47, v29, v18
	v_fma_f32 v19, v47, v49, v19
	v_fmac_f32_e32 v21, v47, v24
	v_lshlrev_b32_e32 v25, 16, v25
	v_mul_f32_e32 v29, 0xbfb8aa3b, v25
	v_exp_f32_e32 v29, v29
	s_nop 0
	v_add_f32_e32 v29, 1.0, v29
	v_div_scale_f32 v51, s[4:5], v29, v29, v25
	v_rcp_f32_e32 v52, v51
	s_nop 0
	v_fma_f32 v53, -v51, v52, 1.0
	v_fmac_f32_e32 v52, v53, v52
	v_div_scale_f32 v53, vcc, v25, v29, v25
	v_mul_f32_e32 v54, v53, v52
	v_fma_f32 v55, -v51, v54, v53
	v_fmac_f32_e32 v54, v55, v52
	v_fma_f32 v51, -v51, v54, v53
	v_div_fmas_f32 v51, v51, v52, v54
	v_div_fixup_f32 v25, v51, v29, v25
	v_mul_f32_e32 v18, v18, v25
	v_cvt_pk_bf16_f32 v25, v18, s0
	v_fmac_f32_e32 v48, v18, v18
	v_mov_b32_e32 v18, v72
	v_lshlrev_b32_e32 v18, 16, v18
	global_store_short v[40:41], v25, off offset:96
	v_mul_f32_e32 v25, 0xbfb8aa3b, v18
	v_exp_f32_e32 v25, v25
	s_nop 0
	v_add_f32_e32 v25, 1.0, v25
	v_div_scale_f32 v29, s[4:5], v25, v25, v18
	v_rcp_f32_e32 v40, v29
	s_nop 0
	v_fma_f32 v41, -v29, v40, 1.0
	v_fmac_f32_e32 v40, v41, v40
	v_div_scale_f32 v41, vcc, v18, v25, v18
	v_mul_f32_e32 v49, v41, v40
	v_fma_f32 v51, -v29, v49, v41
	v_fmac_f32_e32 v49, v51, v40
	v_fma_f32 v29, -v29, v49, v41
	v_div_fmas_f32 v29, v29, v40, v49
	v_div_fixup_f32 v18, v29, v25, v18
	v_mul_f32_e32 v25, v19, v18
	v_cvt_pk_bf16_f32 v18, v25, s0
	global_store_short v[36:37], v18, off offset:96
	v_mov_b32_e32 v18, v73
	v_fma_f32 v19, v47, v50, v20
	v_lshlrev_b32_e32 v18, 16, v18
	v_mul_f32_e32 v20, 0xbfb8aa3b, v18
	v_exp_f32_e32 v20, v20
	s_nop 0
	v_add_f32_e32 v20, 1.0, v20
	v_div_scale_f32 v29, s[4:5], v20, v20, v18
	v_rcp_f32_e32 v36, v29
	s_nop 0
	v_fma_f32 v37, -v29, v36, 1.0
	v_fmac_f32_e32 v36, v37, v36
	v_div_scale_f32 v37, vcc, v18, v20, v18
	v_mul_f32_e32 v40, v37, v36
	v_fma_f32 v41, -v29, v40, v37
	v_fmac_f32_e32 v40, v41, v36
	v_fma_f32 v29, -v29, v40, v37
	v_div_fmas_f32 v29, v29, v36, v40
	v_div_fixup_f32 v18, v29, v20, v18
	v_mul_f32_e32 v20, v19, v18
	v_cvt_pk_bf16_f32 v18, v20, s0
	global_store_short v[38:39], v18, off offset:96
	v_mov_b32_e32 v18, v82
	v_lshlrev_b32_e32 v18, 16, v18
	v_mul_f32_e32 v19, 0xbfb8aa3b, v18
	v_exp_f32_e32 v19, v19
	s_nop 0
	v_add_f32_e32 v19, 1.0, v19
	v_div_scale_f32 v24, s[4:5], v19, v19, v18
	v_rcp_f32_e32 v29, v24
	s_nop 0
	v_fma_f32 v36, -v24, v29, 1.0
	v_fmac_f32_e32 v29, v36, v29
	v_div_scale_f32 v36, vcc, v18, v19, v18
	v_mul_f32_e32 v37, v36, v29
	v_fma_f32 v38, -v24, v37, v36
	v_fmac_f32_e32 v37, v38, v29
	v_fma_f32 v24, -v24, v37, v36
	v_div_fmas_f32 v24, v24, v29, v37
	v_div_fixup_f32 v18, v24, v19, v18
	ds_bpermute_b32 v24, v1, v48
	v_mul_f32_e32 v21, v21, v18
	v_cvt_pk_bf16_f32 v18, v21, s0
	global_store_short v[30:31], v18, off offset:96
	v_lshl_add_u64 v[18:19], v[62:63], 2, s[0:1]
	s_waitcnt lgkmcnt(0)
	v_add_f32_e32 v24, v48, v24
	ds_bpermute_b32 v29, v44, v24
	s_waitcnt lgkmcnt(0)
	v_add_f32_e32 v24, v24, v29
	ds_bpermute_b32 v29, v45, v24
	s_waitcnt lgkmcnt(0)
	v_add_f32_e32 v24, v24, v29
	ds_bpermute_b32 v29, v46, v24
	s_and_saveexec_b64 s[0:1], s[2:3]
	s_cbranch_execz .LBB0_194
	s_waitcnt lgkmcnt(0)
	v_add_f32_e32 v24, v24, v29
	global_store_dword v[18:19], v24, off

.LBB0_200:
	s_or_b64 exec, exec, s[0:1]
	v_add_u32_e32 v26, s10, v218
	v_ashrrev_i32_e32 v27, 31, v26
	s_waitcnt lgkmcnt(0)
	v_lshlrev_b64 v[20:21], 11, v[26:27]
	v_lshl_add_u64 v[24:25], v[34:35], 0, v[20:21]
	v_mov_b32_e32 v20, v88
	ds_read_b64 v[22:23], v155 offset:34848
	s_waitcnt lgkmcnt(0)
	v_lshlrev_b32_e32 v27, 16, v22
	v_lshlrev_b32_e32 v28, 16, v23
	v_and_b32_e32 v29, 0xffff0000, v23
	v_fma_f32 v14, v47, v27, v14
	v_and_b32_e32 v22, 0xffff0000, v22
	v_fma_f32 v15, v47, v22, v15
	v_fmac_f32_e32 v17, v47, v29
	v_lshlrev_b32_e32 v20, 16, v20
	v_mul_f32_e32 v21, 0xbfb8aa3b, v20
	v_exp_f32_e32 v21, v21
	s_nop 0
	v_add_f32_e32 v21, 1.0, v21
	v_div_scale_f32 v23, s[0:1], v21, v21, v20
	v_rcp_f32_e32 v27, v23
	s_nop 0
	v_fma_f32 v30, -v23, v27, 1.0
	v_fmac_f32_e32 v27, v30, v27
	v_div_scale_f32 v30, vcc, v20, v21, v20
	v_mul_f32_e32 v31, v30, v27
	v_fma_f32 v32, -v23, v31, v30
	v_fmac_f32_e32 v31, v32, v27
	v_fma_f32 v23, -v23, v31, v30
	v_div_fmas_f32 v23, v23, v27, v31
	v_div_fixup_f32 v20, v23, v21, v20
	v_mul_f32_e32 v30, v14, v20
	v_or_b32_e32 v20, 1, v26
	v_ashrrev_i32_e32 v21, 31, v20
	v_lshlrev_b64 v[20:21], 11, v[20:21]
	v_cvt_pk_bf16_f32 v14, v30, s0
	v_lshl_add_u64 v[20:21], v[34:35], 0, v[20:21]
	global_store_short v[24:25], v14, off
	v_mov_b32_e32 v14, v89
	v_lshlrev_b32_e32 v14, 16, v14
	v_mul_f32_e32 v22, 0xbfb8aa3b, v14
	v_exp_f32_e32 v22, v22
	s_nop 0
	v_add_f32_e32 v22, 1.0, v22
	v_div_scale_f32 v23, s[0:1], v22, v22, v14
	v_rcp_f32_e32 v27, v23
	s_nop 0
	v_fma_f32 v31, -v23, v27, 1.0
	v_fmac_f32_e32 v27, v31, v27
	v_div_scale_f32 v31, vcc, v14, v22, v14
	v_mul_f32_e32 v32, v31, v27
	v_fma_f32 v33, -v23, v32, v31
	v_fmac_f32_e32 v32, v33, v27
	v_fma_f32 v23, -v23, v32, v31
	v_div_fmas_f32 v23, v23, v27, v32
	v_div_fixup_f32 v14, v23, v22, v14
	v_mul_f32_e32 v27, v15, v14
	v_cvt_pk_bf16_f32 v14, v27, s0
	global_store_short v[20:21], v14, off
	v_or_b32_e32 v14, 2, v26
	v_ashrrev_i32_e32 v15, 31, v14
	v_lshlrev_b64 v[14:15], 11, v[14:15]
	v_lshl_add_u64 v[22:23], v[34:35], 0, v[14:15]
	v_mov_b32_e32 v14, v102
	v_fma_f32 v15, v47, v28, v16
	v_lshlrev_b32_e32 v14, 16, v14
	v_mul_f32_e32 v16, 0xbfb8aa3b, v14
	v_exp_f32_e32 v16, v16
	s_nop 0
	v_add_f32_e32 v16, 1.0, v16
	v_div_scale_f32 v28, s[0:1], v16, v16, v14
	v_rcp_f32_e32 v31, v28
	s_nop 0
	v_fma_f32 v32, -v28, v31, 1.0
	v_fmac_f32_e32 v31, v32, v31
	v_div_scale_f32 v32, vcc, v14, v16, v14
	v_mul_f32_e32 v33, v32, v31
	v_fma_f32 v36, -v28, v33, v32
	v_fmac_f32_e32 v33, v36, v31
	v_fma_f32 v28, -v28, v33, v32
	v_div_fmas_f32 v28, v28, v31, v33
	v_div_fixup_f32 v14, v28, v16, v14
	v_mul_f32_e32 v16, v15, v14
	v_cvt_pk_bf16_f32 v14, v16, s0
	global_store_short v[22:23], v14, off
	v_or_b32_e32 v14, 3, v26
	v_ashrrev_i32_e32 v15, 31, v14
	v_lshlrev_b64 v[14:15], 11, v[14:15]
	v_lshl_add_u64 v[14:15], v[34:35], 0, v[14:15]
	v_mov_b32_e32 v26, v83
	v_lshlrev_b32_e32 v26, 16, v26
	v_mul_f32_e32 v28, 0xbfb8aa3b, v26
	v_exp_f32_e32 v28, v28
	s_nop 0
	v_add_f32_e32 v28, 1.0, v28
	v_div_scale_f32 v29, s[0:1], v28, v28, v26
	v_rcp_f32_e32 v31, v29
	s_nop 0
	v_fma_f32 v32, -v29, v31, 1.0
	v_fmac_f32_e32 v31, v32, v31
	v_div_scale_f32 v32, vcc, v26, v28, v26
	v_mul_f32_e32 v33, v32, v31
	v_fma_f32 v34, -v29, v33, v32
	v_fmac_f32_e32 v33, v34, v31
	v_fma_f32 v29, -v29, v33, v32
	v_div_fmas_f32 v29, v29, v31, v33
	v_div_fixup_f32 v26, v29, v28, v26
	ds_read_b64 v[28:29], v155 offset:39200
	v_mul_f32_e32 v17, v17, v26
	v_cvt_pk_bf16_f32 v26, v17, s0
	global_store_short v[14:15], v26, off
	s_waitcnt lgkmcnt(0)
	v_lshlrev_b32_e32 v26, 16, v28
	v_and_b32_e32 v31, 0xffff0000, v28
	v_mov_b32_e32 v28, v84
	v_fma_f32 v10, v47, v26, v10
	v_fma_f32 v11, v47, v31, v11
	v_lshlrev_b32_e32 v32, 16, v29
	v_and_b32_e32 v29, 0xffff0000, v29
	v_fmac_f32_e32 v13, v47, v29
	v_lshlrev_b32_e32 v28, 16, v28
	v_mul_f32_e32 v26, 0xbfb8aa3b, v28
	v_exp_f32_e32 v26, v26
	s_nop 0
	v_add_f32_e32 v26, 1.0, v26
	v_div_scale_f32 v33, s[0:1], v26, v26, v28
	v_rcp_f32_e32 v34, v33
	s_nop 0
	v_fma_f32 v35, -v33, v34, 1.0
	v_fmac_f32_e32 v34, v35, v34
	v_div_scale_f32 v35, vcc, v28, v26, v28
	v_mul_f32_e32 v36, v35, v34
	v_fma_f32 v37, -v33, v36, v35
	v_fmac_f32_e32 v36, v37, v34
	v_fma_f32 v33, -v33, v36, v35
	v_div_fmas_f32 v33, v33, v34, v36
	v_div_fixup_f32 v26, v33, v26, v28
	v_mul_f32_e32 v10, v10, v26
	v_cvt_pk_bf16_f32 v26, v10, s0
	v_mul_f32_e32 v28, v10, v10
	v_mov_b32_e32 v10, v85
	v_fmac_f32_e32 v28, v30, v30
	global_store_short v[24:25], v26, off offset:32
	v_lshlrev_b32_e32 v10, 16, v10
	v_mul_f32_e32 v26, 0xbfb8aa3b, v10
	v_exp_f32_e32 v26, v26
	s_nop 0
	v_add_f32_e32 v26, 1.0, v26
	v_div_scale_f32 v30, s[0:1], v26, v26, v10
	v_rcp_f32_e32 v31, v30
	s_nop 0
	v_fma_f32 v33, -v30, v31, 1.0
	v_fmac_f32_e32 v31, v33, v31
	v_div_scale_f32 v33, vcc, v10, v26, v10
	v_mul_f32_e32 v34, v33, v31
	v_fma_f32 v35, -v30, v34, v33
	v_fmac_f32_e32 v34, v35, v31
	v_fma_f32 v30, -v30, v34, v33
	v_div_fmas_f32 v30, v30, v31, v34
	v_div_fixup_f32 v10, v30, v26, v10
	v_mul_f32_e32 v26, v11, v10
	v_cvt_pk_bf16_f32 v10, v26, s0
	global_store_short v[20:21], v10, off offset:32
	v_mov_b32_e32 v10, v103
	v_fma_f32 v11, v47, v32, v12
	v_lshlrev_b32_e32 v10, 16, v10
	v_mul_f32_e32 v12, 0xbfb8aa3b, v10
	v_exp_f32_e32 v12, v12
	s_nop 0
	v_add_f32_e32 v12, 1.0, v12
	v_div_scale_f32 v30, s[0:1], v12, v12, v10
	v_rcp_f32_e32 v31, v30
	s_nop 0
	v_fma_f32 v32, -v30, v31, 1.0
	v_fmac_f32_e32 v31, v32, v31
	v_div_scale_f32 v32, vcc, v10, v12, v10
	v_mul_f32_e32 v33, v32, v31
	v_fma_f32 v34, -v30, v33, v32
	v_fmac_f32_e32 v33, v34, v31
	v_fma_f32 v30, -v30, v33, v32
	v_div_fmas_f32 v30, v30, v31, v33
	v_div_fixup_f32 v10, v30, v12, v10
	v_mul_f32_e32 v11, v11, v10
	v_cvt_pk_bf16_f32 v10, v11, s0
	global_store_short v[22:23], v10, off offset:32
	v_mov_b32_e32 v10, v106
	v_lshlrev_b32_e32 v10, 16, v10
	v_mul_f32_e32 v12, 0xbfb8aa3b, v10
	v_exp_f32_e32 v12, v12
	s_nop 0
	v_add_f32_e32 v12, 1.0, v12
	v_div_scale_f32 v29, s[0:1], v12, v12, v10
	v_rcp_f32_e32 v30, v29
	s_nop 0
	v_fma_f32 v31, -v29, v30, 1.0
	v_fmac_f32_e32 v30, v31, v30
	v_div_scale_f32 v31, vcc, v10, v12, v10
	v_mul_f32_e32 v32, v31, v30
	v_fma_f32 v33, -v29, v32, v31
	v_fmac_f32_e32 v32, v33, v30
	v_fma_f32 v29, -v29, v32, v31
	v_mov_b32_e32 v31, v107
	v_div_fmas_f32 v29, v29, v30, v32
	v_div_fixup_f32 v10, v29, v12, v10
	v_mul_f32_e32 v10, v13, v10
	v_cvt_pk_bf16_f32 v12, v10, s0
	global_store_short v[14:15], v12, off offset:32
	ds_read_b64 v[12:13], v155 offset:43552
	s_waitcnt lgkmcnt(0)
	v_lshlrev_b32_e32 v29, 16, v12
	v_fma_f32 v6, v47, v29, v6
	v_and_b32_e32 v12, 0xffff0000, v12
	v_fma_f32 v7, v47, v12, v7
	v_lshlrev_b32_e32 v30, 16, v13
	v_and_b32_e32 v13, 0xffff0000, v13
	v_fmac_f32_e32 v9, v47, v13
	v_lshlrev_b32_e32 v31, 16, v31
	v_mul_f32_e32 v29, 0xbfb8aa3b, v31
	v_exp_f32_e32 v29, v29
	s_nop 0
	v_add_f32_e32 v29, 1.0, v29
	v_div_scale_f32 v32, s[0:1], v29, v29, v31
	v_rcp_f32_e32 v33, v32
	s_nop 0
	v_fma_f32 v34, -v32, v33, 1.0
	v_fmac_f32_e32 v33, v34, v33
	v_div_scale_f32 v34, vcc, v31, v29, v31
	v_mul_f32_e32 v35, v34, v33
	v_fma_f32 v36, -v32, v35, v34
	v_fmac_f32_e32 v35, v36, v33
	v_fma_f32 v32, -v32, v35, v34
	v_div_fmas_f32 v32, v32, v33, v35
	v_div_fixup_f32 v29, v32, v29, v31
	v_mul_f32_e32 v6, v6, v29
	v_cvt_pk_bf16_f32 v29, v6, s0
	v_fmac_f32_e32 v28, v6, v6
	v_mov_b32_e32 v6, v108
	v_lshlrev_b32_e32 v6, 16, v6
	v_mul_f32_e32 v12, 0xbfb8aa3b, v6
	v_exp_f32_e32 v12, v12
	global_store_short v[24:25], v29, off offset:64
	v_add_f32_e32 v12, 1.0, v12
	v_div_scale_f32 v29, s[0:1], v12, v12, v6
	v_rcp_f32_e32 v31, v29
	s_nop 0
	v_fma_f32 v32, -v29, v31, 1.0
	v_fmac_f32_e32 v31, v32, v31
	v_div_scale_f32 v32, vcc, v6, v12, v6
	v_mul_f32_e32 v33, v32, v31
	v_fma_f32 v34, -v29, v33, v32
	v_fmac_f32_e32 v33, v34, v31
	v_fma_f32 v29, -v29, v33, v32
	v_div_fmas_f32 v29, v29, v31, v33
	v_div_fixup_f32 v6, v29, v12, v6
	v_mul_f32_e32 v12, v7, v6
	v_cvt_pk_bf16_f32 v6, v12, s0
	global_store_short v[20:21], v6, off offset:64
	v_mov_b32_e32 v6, v109
	v_fma_f32 v7, v47, v30, v8
	v_lshlrev_b32_e32 v6, 16, v6
	v_mul_f32_e32 v8, 0xbfb8aa3b, v6
	v_exp_f32_e32 v8, v8
	s_nop 0
	v_add_f32_e32 v8, 1.0, v8
	v_div_scale_f32 v29, s[0:1], v8, v8, v6
	v_rcp_f32_e32 v30, v29
	s_nop 0
	v_fma_f32 v31, -v29, v30, 1.0
	v_fmac_f32_e32 v30, v31, v30
	v_div_scale_f32 v31, vcc, v6, v8, v6
	v_mul_f32_e32 v32, v31, v30
	v_fma_f32 v33, -v29, v32, v31
	v_fmac_f32_e32 v32, v33, v30
	v_fma_f32 v29, -v29, v32, v31
	v_div_fmas_f32 v29, v29, v30, v32
	v_div_fixup_f32 v6, v29, v8, v6
	v_mul_f32_e32 v7, v7, v6
	v_cvt_pk_bf16_f32 v6, v7, s0
	global_store_short v[22:23], v6, off offset:64
	v_mov_b32_e32 v6, v110
	v_lshlrev_b32_e32 v6, 16, v6
	v_mul_f32_e32 v8, 0xbfb8aa3b, v6
	v_exp_f32_e32 v8, v8
	s_nop 0
	v_add_f32_e32 v8, 1.0, v8
	v_div_scale_f32 v13, s[0:1], v8, v8, v6
	v_rcp_f32_e32 v29, v13
	s_nop 0
	v_fma_f32 v30, -v13, v29, 1.0
	v_fmac_f32_e32 v29, v30, v29
	v_div_scale_f32 v30, vcc, v6, v8, v6
	v_mul_f32_e32 v31, v30, v29
	v_fma_f32 v32, -v13, v31, v30
	v_fmac_f32_e32 v31, v32, v29
	v_fma_f32 v13, -v13, v31, v30
	v_div_fmas_f32 v13, v13, v29, v31
	v_div_fixup_f32 v6, v13, v8, v6
	v_mul_f32_e32 v6, v9, v6
	v_cvt_pk_bf16_f32 v8, v6, s0
	global_store_short v[14:15], v8, off offset:64
	ds_read_b64 v[8:9], v155 offset:47904
	s_waitcnt lgkmcnt(0)
	v_lshlrev_b32_e32 v13, 16, v8
	v_and_b32_e32 v29, 0xffff0000, v8
	v_lshlrev_b32_e32 v30, 16, v9
	v_and_b32_e32 v8, 0xffff0000, v9
	v_mov_b32_e32 v9, v111
	v_fma_f32 v2, v47, v13, v2
	v_fma_f32 v3, v47, v29, v3
	v_fma_f32 v4, v47, v30, v4
	v_fmac_f32_e32 v5, v47, v8
	v_lshlrev_b32_e32 v9, 16, v9
	v_mul_f32_e32 v13, 0xbfb8aa3b, v9
	v_exp_f32_e32 v13, v13
	s_nop 0
	v_add_f32_e32 v13, 1.0, v13
	v_div_scale_f32 v31, s[0:1], v13, v13, v9
	v_rcp_f32_e32 v32, v31
	s_nop 0
	v_fma_f32 v33, -v31, v32, 1.0
	v_fmac_f32_e32 v32, v33, v32
	v_div_scale_f32 v33, vcc, v9, v13, v9
	v_mul_f32_e32 v34, v33, v32
	v_fma_f32 v35, -v31, v34, v33
	v_fmac_f32_e32 v34, v35, v32
	v_fma_f32 v31, -v31, v34, v33
	v_div_fmas_f32 v31, v31, v32, v34
	v_div_fixup_f32 v9, v31, v13, v9
	v_mul_f32_e32 v2, v2, v9
	v_cvt_pk_bf16_f32 v9, v2, s0
	v_fmac_f32_e32 v28, v2, v2
	v_mov_b32_e32 v2, v86
	v_lshlrev_b32_e32 v2, 16, v2
	global_store_short v[24:25], v9, off offset:96
	v_mul_f32_e32 v9, 0xbfb8aa3b, v2
	v_exp_f32_e32 v9, v9
	s_nop 0
	v_add_f32_e32 v9, 1.0, v9
	v_div_scale_f32 v13, s[0:1], v9, v9, v2
	v_rcp_f32_e32 v24, v13
	s_nop 0
	v_fma_f32 v25, -v13, v24, 1.0
	v_fmac_f32_e32 v24, v25, v24
	v_div_scale_f32 v25, vcc, v2, v9, v2
	v_mul_f32_e32 v29, v25, v24
	v_fma_f32 v31, -v13, v29, v25
	v_fmac_f32_e32 v29, v31, v24
	v_fma_f32 v13, -v13, v29, v25
	v_div_fmas_f32 v13, v13, v24, v29
	v_div_fixup_f32 v2, v13, v9, v2
	v_mul_f32_e32 v3, v3, v2
	v_cvt_pk_bf16_f32 v2, v3, s0
	global_store_short v[20:21], v2, off offset:96
	v_mov_b32_e32 v2, v87
	v_lshlrev_b32_e32 v2, 16, v2
	v_mul_f32_e32 v9, 0xbfb8aa3b, v2
	v_exp_f32_e32 v9, v9
	s_nop 0
	v_add_f32_e32 v9, 1.0, v9
	v_div_scale_f32 v13, s[0:1], v9, v9, v2
	v_rcp_f32_e32 v20, v13
	s_nop 0
	v_fma_f32 v21, -v13, v20, 1.0
	v_fmac_f32_e32 v20, v21, v20
	v_div_scale_f32 v21, vcc, v2, v9, v2
	v_mul_f32_e32 v24, v21, v20
	v_fma_f32 v25, -v13, v24, v21
	v_fmac_f32_e32 v24, v25, v20
	v_fma_f32 v13, -v13, v24, v21
	v_div_fmas_f32 v13, v13, v20, v24
	v_div_fixup_f32 v2, v13, v9, v2
	v_mul_f32_e32 v2, v4, v2
	v_cvt_pk_bf16_f32 v4, v2, s0
	global_store_short v[22:23], v4, off offset:96
	v_mov_b32_e32 v4, v98
	v_lshlrev_b32_e32 v4, 16, v4
	v_mul_f32_e32 v8, 0xbfb8aa3b, v4
	v_exp_f32_e32 v8, v8
	s_nop 0
	v_add_f32_e32 v8, 1.0, v8
	v_div_scale_f32 v9, s[0:1], v8, v8, v4
	v_rcp_f32_e32 v13, v9
	s_nop 0
	v_fma_f32 v20, -v9, v13, 1.0
	v_fmac_f32_e32 v13, v20, v13
	v_div_scale_f32 v20, vcc, v4, v8, v4
	v_mul_f32_e32 v21, v20, v13
	v_fma_f32 v22, -v9, v21, v20
	v_fmac_f32_e32 v21, v22, v13
	v_fma_f32 v9, -v9, v21, v20
	v_div_fmas_f32 v9, v9, v13, v21
	v_div_fixup_f32 v4, v9, v8, v4
	v_mul_f32_e32 v4, v5, v4
	v_cvt_pk_bf16_f32 v5, v4, s0
	global_store_short v[14:15], v5, off offset:96
	ds_bpermute_b32 v5, v1, v28
	s_waitcnt lgkmcnt(0)
	v_add_f32_e32 v5, v28, v5
	ds_bpermute_b32 v8, v44, v5
	s_waitcnt lgkmcnt(0)
	v_add_f32_e32 v5, v5, v8
	ds_bpermute_b32 v8, v45, v5
	s_waitcnt lgkmcnt(0)
	v_add_f32_e32 v5, v5, v8
	ds_bpermute_b32 v8, v46, v5
	s_and_saveexec_b64 s[0:1], s[2:3]
	s_cbranch_execz .LBB0_202
	s_waitcnt lgkmcnt(0)
	v_add_f32_e32 v5, v5, v8
	global_store_dword v[18:19], v5, off offset:64

.LBB0_328:
	s_andn2_b64 vcc, exec, s[2:3]
	s_cbranch_vccnz .LBB0_395
	s_ashr_i32 s2, s14, 2
	s_cmpk_gt_i32 s2, 0x7f
	v_readlane_b32 s0, v254, 47
	s_cselect_b64 s[4:5], -1, 0
	v_readlane_b32 s1, v254, 48
	s_and_b64 s[4:5], s[0:1], s[4:5]
	s_and_b64 vcc, exec, s[4:5]
	s_cbranch_vccnz .LBB0_395
	v_mov_b32_e32 v29, v0
	s_lshl_b32 s3, s2, 7
	s_lshl_b32 s2, s14, 7
	s_and_b32 s2, s2, 0x180
	v_ashrrev_i32_e32 v27, 3, v29
	s_waitcnt vmcnt(0)
	v_add_u32_e32 v2, s2, v27
	v_ashrrev_i32_e32 v3, 31, v2
	v_readlane_b32 s0, v253, 31
	v_lshlrev_b64 v[2:3], 11, v[2:3]
	v_add_u32_e32 v4, s3, v27
	v_readlane_b32 s1, v253, 32
	v_ashrrev_i32_e32 v5, 31, v4
	v_lshlrev_b32_e32 v1, 4, v29
	v_lshl_add_u64 v[2:3], s[0:1], 0, v[2:3]
	v_readlane_b32 s0, v253, 53
	v_lshlrev_b64 v[10:11], 10, v[4:5]
	v_readlane_b32 s1, v253, 54
	s_mov_b64 s[4:5], 0x8000
	v_and_b32_e32 v130, 0x70, v1
	v_lshl_add_u64 v[4:5], s[0:1], 0, v[10:11]
	v_lshl_add_u64 v[12:13], v[10:11], 0, s[4:5]
	s_mov_b64 s[4:5], 0x10000
	v_lshl_add_u64 v[18:19], v[4:5], 0, v[130:131]
	v_lshl_add_u64 v[4:5], s[0:1], 0, v[12:13]
	v_lshl_add_u64 v[14:15], v[10:11], 0, s[4:5]
	s_mov_b64 s[4:5], 0x18000
	v_lshl_add_u64 v[20:21], v[4:5], 0, v[130:131]
	v_lshl_add_u64 v[4:5], s[0:1], 0, v[14:15]
	v_lshl_add_u64 v[16:17], v[10:11], 0, s[4:5]
	v_lshl_add_u64 v[2:3], v[2:3], 0, v[130:131]
	v_lshl_add_u64 v[22:23], v[4:5], 0, v[130:131]
	v_lshl_add_u64 v[4:5], s[0:1], 0, v[16:17]
	s_mov_b32 s0, 0x10000
	v_lshl_add_u64 v[24:25], v[4:5], 0, v[130:131]
	v_add_co_u32_e32 v4, vcc, s0, v2
	s_mov_b32 s0, 0x20000
	s_nop 0
	v_addc_co_u32_e32 v5, vcc, 0, v3, vcc
	v_add_co_u32_e32 v6, vcc, s0, v2
	global_load_dwordx4 v[32:35], v[2:3], off
	global_load_dwordx4 v[36:39], v[4:5], off
	v_addc_co_u32_e32 v7, vcc, 0, v3, vcc
	global_load_dwordx4 v[40:43], v[6:7], off
	global_load_dwordx4 v[44:47], v[18:19], off
	global_load_dwordx4 v[48:51], v[20:21], off
	global_load_dwordx4 v[52:55], v[22:23], off
	global_load_dwordx4 v[56:59], v[24:25], off
	s_mov_b32 s0, 0x30000
	v_add_co_u32_e32 v8, vcc, s0, v2
	v_lshrrev_b32_e32 v28, 4, v29
	s_nop 0
	v_addc_co_u32_e32 v9, vcc, 0, v3, vcc
	global_load_dwordx4 v[60:63], v[8:9], off
	global_load_dwordx4 v[64:67], v[2:3], off offset:128
	global_load_dwordx4 v[68:71], v[18:19], off offset:128
	global_load_dwordx4 v[72:75], v[20:21], off offset:128
	global_load_dwordx4 v[76:79], v[22:23], off offset:128
	global_load_dwordx4 v[80:83], v[24:25], off offset:128
	global_load_dwordx4 v[84:87], v[4:5], off offset:128
	global_load_dwordx4 v[88:91], v[6:7], off offset:128
	global_load_dwordx4 v[92:95], v[8:9], off offset:128
	v_and_b32_e32 v26, 15, v29
	v_bfe_u32 v128, v29, 1, 3
	v_xor_b32_e32 v30, v28, v29
	v_ashrrev_i32_e32 v1, 7, v29
	v_bitop3_b32 v28, v28, v128, 3 bitop3:0x6c
	v_lshlrev_b32_e32 v31, 7, v26
	v_lshlrev_b32_e32 v30, 4, v30
	v_lshlrev_b32_e32 v96, 4, v28
	v_lshl_or_b32 v129, v1, 13, v31
	v_and_b32_e32 v30, 0x70, v30
	v_or_b32_e32 v28, v96, v129
	v_lshl_or_b32 v30, v27, 7, v30
	s_waitcnt vmcnt(63) expcnt(7) lgkmcnt(15)
	s_barrier
	v_bfe_u32 v27, v29, 6, 1
	v_lshl_or_b32 v133, v27, 13, v31
	v_or_b32_e32 v31, v96, v133
	v_bfe_u32 v29, v29, 4, 2
	v_lshl_add_u64 v[10:11], s[86:87], 0, v[10:11]
	v_lshl_add_u64 v[10:11], v[10:11], 0, v[130:131]
	s_mov_b32 s0, 0x5ef1000
	v_lshl_add_u64 v[12:13], s[86:87], 0, v[12:13]
	v_add_co_u32_e32 v10, vcc, s0, v10
	v_lshl_add_u64 v[12:13], v[12:13], 0, v[130:131]
	s_nop 0
	v_addc_co_u32_e32 v11, vcc, 0, v11, vcc
	v_lshl_add_u64 v[14:15], s[86:87], 0, v[14:15]
	v_add_co_u32_e32 v12, vcc, s0, v12
	v_lshl_add_u64 v[14:15], v[14:15], 0, v[130:131]
	s_nop 0
	v_addc_co_u32_e32 v13, vcc, 0, v13, vcc
	v_lshl_add_u64 v[16:17], s[86:87], 0, v[16:17]
	v_add_co_u32_e32 v14, vcc, s0, v14
	v_lshl_add_u64 v[16:17], v[16:17], 0, v[130:131]
	s_nop 0
	v_addc_co_u32_e32 v15, vcc, 0, v15, vcc
	s_waitcnt vmcnt(12)
	ds_write_b128 v30, v[44:47]
	ds_write_b128 v30, v[32:35] offset:32768
	s_waitcnt vmcnt(11)
	ds_write_b128 v30, v[48:51] offset:4096
	s_waitcnt vmcnt(10)
	ds_write_b128 v30, v[52:55] offset:8192
	s_waitcnt vmcnt(9)
	ds_write_b128 v30, v[56:59] offset:12288
	ds_write_b128 v30, v[36:39] offset:36864
	ds_write_b128 v30, v[40:43] offset:40960
	s_waitcnt vmcnt(8)
	ds_write_b128 v30, v[60:63] offset:45056
	s_waitcnt lgkmcnt(0)
	s_barrier
	ds_read_b128 v[32:35], v28
	ds_read_b128 v[142:145], v28 offset:6144
	ds_read_b128 v[36:39], v31 offset:32768
	ds_read_b128 v[44:47], v31 offset:34816
	ds_read_b128 v[52:55], v31 offset:36864
	ds_read_b128 v[60:63], v31 offset:38912
	s_waitcnt lgkmcnt(3)
	v_mfma_f32_16x16x32_bf16 v[40:43], v[32:35], v[36:39], 0
	v_add_co_u32_e32 v16, vcc, s0, v16
	v_lshl_add_u32 v1, v1, 6, s3
	s_waitcnt lgkmcnt(2)
	v_mfma_f32_16x16x32_bf16 v[48:51], v[32:35], v[44:47], 0
	v_addc_co_u32_e32 v17, vcc, 0, v17, vcc
	s_movk_i32 s0, 0x4000
	s_waitcnt lgkmcnt(1)
	v_mfma_f32_16x16x32_bf16 v[56:59], v[32:35], v[52:55], 0
	v_readlane_b32 s4, v253, 4
	v_readlane_b32 s8, v253, 8
	v_readlane_b32 s9, v253, 9
	s_waitcnt lgkmcnt(0)
	v_mfma_f32_16x16x32_bf16 v[96:99], v[32:35], v[60:63], 0
	ds_read_b128 v[32:35], v28 offset:2048
	v_readlane_b32 s5, v253, 5
	v_readlane_b32 s6, v253, 6
	s_waitcnt lgkmcnt(0)
	v_mfma_f32_16x16x32_bf16 v[100:103], v[32:35], v[36:39], 0
	v_readlane_b32 s7, v253, 7
	v_readlane_b32 s10, v253, 10
	v_readlane_b32 s11, v253, 11
	v_mfma_f32_16x16x32_bf16 v[104:107], v[32:35], v[44:47], 0
	v_mfma_f32_16x16x32_bf16 v[108:111], v[32:35], v[52:55], 0
	v_mfma_f32_16x16x32_bf16 v[112:115], v[32:35], v[60:63], 0
	ds_read_b128 v[32:35], v28 offset:4096
	s_waitcnt lgkmcnt(0)
	v_mfma_f32_16x16x32_bf16 v[116:119], v[32:35], v[36:39], 0
	v_mfma_f32_16x16x32_bf16 v[120:123], v[32:35], v[44:47], 0
	v_mfma_f32_16x16x32_bf16 v[124:127], v[32:35], v[52:55], 0
	v_mfma_f32_16x16x32_bf16 v[138:141], v[32:35], v[60:63], 0
	v_bitop3_b32 v32, v29, v128, 4 bitop3:0x36
	v_lshlrev_b32_e32 v32, 4, v32
	v_or_b32_e32 v33, v32, v129
	ds_read_b128 v[146:149], v33
	v_or_b32_e32 v32, v32, v133
	v_mfma_f32_16x16x32_bf16 v[34:37], v[142:145], v[36:39], 0
	ds_read_b128 v[150:153], v32 offset:34816
	ds_read_b128 v[154:157], v32 offset:36864
	ds_read_b128 v[162:165], v32 offset:38912
	v_mfma_f32_16x16x32_bf16 v[44:47], v[142:145], v[44:47], 0
	v_mfma_f32_16x16x32_bf16 v[52:55], v[142:145], v[52:55], 0
	v_mfma_f32_16x16x32_bf16 v[60:63], v[142:145], v[60:63], 0
	ds_read_b128 v[142:145], v32 offset:32768
	s_waitcnt lgkmcnt(0)
	v_mfma_f32_16x16x32_bf16 v[38:41], v[146:149], v[142:145], v[40:43]
	v_mfma_f32_16x16x32_bf16 v[48:51], v[146:149], v[150:153], v[48:51]
	v_mfma_f32_16x16x32_bf16 v[56:59], v[146:149], v[154:157], v[56:59]
	v_mfma_f32_16x16x32_bf16 v[96:99], v[146:149], v[162:165], v[96:99]
	ds_read_b128 v[146:149], v33 offset:2048
	s_waitcnt lgkmcnt(0)
	v_mfma_f32_16x16x32_bf16 v[100:103], v[146:149], v[142:145], v[100:103]
	v_mfma_f32_16x16x32_bf16 v[104:107], v[146:149], v[150:153], v[104:107]
	v_mfma_f32_16x16x32_bf16 v[108:111], v[146:149], v[154:157], v[108:111]
	v_mfma_f32_16x16x32_bf16 v[112:115], v[146:149], v[162:165], v[112:115]
	ds_read_b128 v[146:149], v33 offset:4096
	s_waitcnt lgkmcnt(0)
	v_mfma_f32_16x16x32_bf16 v[116:119], v[146:149], v[142:145], v[116:119]
	v_mfma_f32_16x16x32_bf16 v[120:123], v[146:149], v[150:153], v[120:123]
	v_mfma_f32_16x16x32_bf16 v[124:127], v[146:149], v[154:157], v[124:127]
	v_mfma_f32_16x16x32_bf16 v[138:141], v[146:149], v[162:165], v[138:141]
	ds_read_b128 v[146:149], v33 offset:6144
	s_waitcnt lgkmcnt(0)
	v_mfma_f32_16x16x32_bf16 v[34:37], v[146:149], v[142:145], v[34:37]
	v_mfma_f32_16x16x32_bf16 v[42:45], v[146:149], v[150:153], v[44:47]
	global_load_dwordx4 v[142:145], v[6:7], off offset:256
	global_load_dwordx4 v[150:153], v[8:9], off offset:256
	s_waitcnt vmcnt(8)
	ds_write_b128 v30, v[68:71] offset:16384
	s_waitcnt vmcnt(7)
	ds_write_b128 v30, v[72:75] offset:20480
	s_waitcnt vmcnt(6)
	ds_write_b128 v30, v[76:79] offset:24576
	s_waitcnt vmcnt(5)
	ds_write_b128 v30, v[80:83] offset:28672
	ds_write_b128 v30, v[64:67] offset:49152
	s_waitcnt vmcnt(4)
	ds_write_b128 v30, v[84:87] offset:53248
	s_waitcnt vmcnt(3)
	ds_write_b128 v30, v[88:91] offset:57344
	s_waitcnt vmcnt(2)
	ds_write_b128 v30, v[92:95] offset:61440
	global_load_dwordx4 v[64:67], v[2:3], off offset:256
	global_load_dwordx4 v[68:71], v[18:19], off offset:256
	global_load_dwordx4 v[72:75], v[20:21], off offset:256
	global_load_dwordx4 v[76:79], v[22:23], off offset:256
	global_load_dwordx4 v[80:83], v[4:5], off offset:256
	global_load_dwordx4 v[84:87], v[24:25], off offset:256
	s_waitcnt lgkmcnt(0)
	s_barrier
	ds_read_b128 v[88:91], v28 offset:16384
	ds_read_b128 v[92:95], v31 offset:49152
	v_mfma_f32_16x16x32_bf16 v[52:55], v[146:149], v[154:157], v[52:55]
	ds_read_b128 v[154:157], v31 offset:53248
	v_mfma_f32_16x16x32_bf16 v[60:63], v[146:149], v[162:165], v[60:63]
	ds_read_b128 v[146:149], v31 offset:51200
	ds_read_b128 v[162:165], v31 offset:55296
	s_waitcnt lgkmcnt(3)
	v_mfma_f32_16x16x32_bf16 v[38:41], v[88:91], v[92:95], v[38:41]
	s_waitcnt lgkmcnt(1)
	v_mfma_f32_16x16x32_bf16 v[46:49], v[88:91], v[146:149], v[48:51]
	v_mfma_f32_16x16x32_bf16 v[56:59], v[88:91], v[154:157], v[56:59]
	s_waitcnt lgkmcnt(0)
	v_mfma_f32_16x16x32_bf16 v[88:91], v[88:91], v[162:165], v[96:99]
	s_nop 2
	ds_read_b128 v[96:99], v28 offset:18432
	s_waitcnt lgkmcnt(0)
	v_mfma_f32_16x16x32_bf16 v[100:103], v[96:99], v[92:95], v[100:103]
	v_mfma_f32_16x16x32_bf16 v[104:107], v[96:99], v[146:149], v[104:107]
	v_mfma_f32_16x16x32_bf16 v[108:111], v[96:99], v[154:157], v[108:111]
	v_mfma_f32_16x16x32_bf16 v[96:99], v[96:99], v[162:165], v[112:115]
	s_nop 2
	ds_read_b128 v[112:115], v28 offset:20480
	s_waitcnt lgkmcnt(0)
	v_mfma_f32_16x16x32_bf16 v[116:119], v[112:115], v[92:95], v[116:119]
	v_mfma_f32_16x16x32_bf16 v[120:123], v[112:115], v[146:149], v[120:123]
	v_mfma_f32_16x16x32_bf16 v[124:127], v[112:115], v[154:157], v[124:127]
	v_mfma_f32_16x16x32_bf16 v[112:115], v[112:115], v[162:165], v[138:141]
	s_nop 2
	ds_read_b128 v[138:141], v28 offset:22528
	s_waitcnt lgkmcnt(0)
	v_mfma_f32_16x16x32_bf16 v[34:37], v[138:141], v[92:95], v[34:37]
	ds_read_b128 v[92:95], v33 offset:16384
	v_mfma_f32_16x16x32_bf16 v[42:45], v[138:141], v[146:149], v[42:45]
	ds_read_b128 v[146:149], v32 offset:51200
	v_mfma_f32_16x16x32_bf16 v[50:53], v[138:141], v[154:157], v[52:55]
	ds_read_b128 v[154:157], v32 offset:53248
	v_mfma_f32_16x16x32_bf16 v[60:63], v[138:141], v[162:165], v[60:63]
	ds_read_b128 v[138:141], v32 offset:49152
	ds_read_b128 v[162:165], v32 offset:55296
	s_waitcnt lgkmcnt(1)
	v_mfma_f32_16x16x32_bf16 v[38:41], v[92:95], v[138:141], v[38:41]
	v_mfma_f32_16x16x32_bf16 v[46:49], v[92:95], v[146:149], v[46:49]
	v_mfma_f32_16x16x32_bf16 v[54:57], v[92:95], v[154:157], v[56:59]
	s_waitcnt lgkmcnt(0)
	v_mfma_f32_16x16x32_bf16 v[88:91], v[92:95], v[162:165], v[88:91]
	ds_read_b128 v[92:95], v33 offset:18432
	s_waitcnt lgkmcnt(0)
	v_mfma_f32_16x16x32_bf16 v[100:103], v[92:95], v[138:141], v[100:103]
	v_mfma_f32_16x16x32_bf16 v[104:107], v[92:95], v[146:149], v[104:107]
	v_mfma_f32_16x16x32_bf16 v[108:111], v[92:95], v[154:157], v[108:111]
	v_mfma_f32_16x16x32_bf16 v[92:95], v[92:95], v[162:165], v[96:99]
	s_nop 2
	ds_read_b128 v[96:99], v33 offset:20480
	s_waitcnt lgkmcnt(0)
	v_mfma_f32_16x16x32_bf16 v[116:119], v[96:99], v[138:141], v[116:119]
	v_mfma_f32_16x16x32_bf16 v[120:123], v[96:99], v[146:149], v[120:123]
	v_mfma_f32_16x16x32_bf16 v[124:127], v[96:99], v[154:157], v[124:127]
	v_mfma_f32_16x16x32_bf16 v[96:99], v[96:99], v[162:165], v[112:115]
	s_nop 2
	ds_read_b128 v[112:115], v33 offset:22528
	s_waitcnt lgkmcnt(0)
	v_mfma_f32_16x16x32_bf16 v[34:37], v[112:115], v[138:141], v[34:37]
	v_mfma_f32_16x16x32_bf16 v[42:45], v[112:115], v[146:149], v[42:45]
	global_load_dwordx4 v[138:141], v[6:7], off offset:384
	global_load_dwordx4 v[146:149], v[8:9], off offset:384
	s_waitcnt vmcnt(6)
	ds_write_b128 v30, v[68:71]
	s_waitcnt vmcnt(5)
	ds_write_b128 v30, v[72:75] offset:4096
	s_waitcnt vmcnt(4)
	ds_write_b128 v30, v[76:79] offset:8192
	s_waitcnt vmcnt(2)
	ds_write_b128 v30, v[84:87] offset:12288
	ds_write_b128 v30, v[64:67] offset:32768
	ds_write_b128 v30, v[80:83] offset:36864
	ds_write_b128 v30, v[142:145] offset:40960
	ds_write_b128 v30, v[150:153] offset:45056
	global_load_dwordx4 v[64:67], v[2:3], off offset:384
	global_load_dwordx4 v[68:71], v[18:19], off offset:384
	global_load_dwordx4 v[72:75], v[20:21], off offset:384
	global_load_dwordx4 v[76:79], v[22:23], off offset:384
	global_load_dwordx4 v[80:83], v[4:5], off offset:384
	global_load_dwordx4 v[84:87], v[24:25], off offset:384
	s_waitcnt lgkmcnt(0)
	s_barrier
	ds_read_b128 v[142:145], v28
	v_mfma_f32_16x16x32_bf16 v[50:53], v[112:115], v[154:157], v[50:53]
	ds_read_b128 v[150:153], v31 offset:34816
	ds_read_b128 v[154:157], v31 offset:36864
	v_mfma_f32_16x16x32_bf16 v[58:61], v[112:115], v[162:165], v[60:63]
	ds_read_b128 v[112:115], v31 offset:32768
	ds_read_b128 v[162:165], v31 offset:38912
	s_waitcnt lgkmcnt(1)
	v_mfma_f32_16x16x32_bf16 v[38:41], v[142:145], v[112:115], v[38:41]
	v_mfma_f32_16x16x32_bf16 v[46:49], v[142:145], v[150:153], v[46:49]
	v_mfma_f32_16x16x32_bf16 v[54:57], v[142:145], v[154:157], v[54:57]
	s_waitcnt lgkmcnt(0)
	v_mfma_f32_16x16x32_bf16 v[88:91], v[142:145], v[162:165], v[88:91]
	ds_read_b128 v[142:145], v28 offset:2048
	s_waitcnt lgkmcnt(0)
	v_mfma_f32_16x16x32_bf16 v[100:103], v[142:145], v[112:115], v[100:103]
	v_mfma_f32_16x16x32_bf16 v[104:107], v[142:145], v[150:153], v[104:107]
	v_mfma_f32_16x16x32_bf16 v[108:111], v[142:145], v[154:157], v[108:111]
	v_mfma_f32_16x16x32_bf16 v[92:95], v[142:145], v[162:165], v[92:95]
	ds_read_b128 v[142:145], v28 offset:4096
	s_waitcnt lgkmcnt(0)
	v_mfma_f32_16x16x32_bf16 v[116:119], v[142:145], v[112:115], v[116:119]
	v_mfma_f32_16x16x32_bf16 v[120:123], v[142:145], v[150:153], v[120:123]
	v_mfma_f32_16x16x32_bf16 v[124:127], v[142:145], v[154:157], v[124:127]
	v_mfma_f32_16x16x32_bf16 v[96:99], v[142:145], v[162:165], v[96:99]
	ds_read_b128 v[142:145], v28 offset:6144
	s_waitcnt lgkmcnt(0)
	v_mfma_f32_16x16x32_bf16 v[34:37], v[142:145], v[112:115], v[34:37]
	ds_read_b128 v[112:115], v33
	v_mfma_f32_16x16x32_bf16 v[42:45], v[142:145], v[150:153], v[42:45]
	ds_read_b128 v[150:153], v32 offset:34816
	v_mfma_f32_16x16x32_bf16 v[50:53], v[142:145], v[154:157], v[50:53]
	ds_read_b128 v[154:157], v32 offset:36864
	v_mfma_f32_16x16x32_bf16 v[58:61], v[142:145], v[162:165], v[58:61]
	ds_read_b128 v[142:145], v32 offset:32768
	ds_read_b128 v[162:165], v32 offset:38912
	s_waitcnt lgkmcnt(1)
	v_mfma_f32_16x16x32_bf16 v[38:41], v[112:115], v[142:145], v[38:41]
	v_mfma_f32_16x16x32_bf16 v[46:49], v[112:115], v[150:153], v[46:49]
	v_mfma_f32_16x16x32_bf16 v[54:57], v[112:115], v[154:157], v[54:57]
	s_waitcnt lgkmcnt(0)
	v_mfma_f32_16x16x32_bf16 v[88:91], v[112:115], v[162:165], v[88:91]
	ds_read_b128 v[112:115], v33 offset:2048
	s_waitcnt lgkmcnt(0)
	v_mfma_f32_16x16x32_bf16 v[100:103], v[112:115], v[142:145], v[100:103]
	v_mfma_f32_16x16x32_bf16 v[104:107], v[112:115], v[150:153], v[104:107]
	v_mfma_f32_16x16x32_bf16 v[108:111], v[112:115], v[154:157], v[108:111]
	v_mfma_f32_16x16x32_bf16 v[92:95], v[112:115], v[162:165], v[92:95]
	ds_read_b128 v[112:115], v33 offset:4096
	s_waitcnt lgkmcnt(0)
	v_mfma_f32_16x16x32_bf16 v[116:119], v[112:115], v[142:145], v[116:119]
	v_mfma_f32_16x16x32_bf16 v[120:123], v[112:115], v[150:153], v[120:123]
	v_mfma_f32_16x16x32_bf16 v[124:127], v[112:115], v[154:157], v[124:127]
	v_mfma_f32_16x16x32_bf16 v[96:99], v[112:115], v[162:165], v[96:99]
	ds_read_b128 v[112:115], v33 offset:6144
	s_waitcnt lgkmcnt(0)
	v_mfma_f32_16x16x32_bf16 v[34:37], v[112:115], v[142:145], v[34:37]
	v_mfma_f32_16x16x32_bf16 v[42:45], v[112:115], v[150:153], v[42:45]
	global_load_dwordx4 v[142:145], v[6:7], off offset:512
	global_load_dwordx4 v[150:153], v[8:9], off offset:512
	s_waitcnt vmcnt(6)
	ds_write_b128 v30, v[68:71] offset:16384
	s_waitcnt vmcnt(5)
	ds_write_b128 v30, v[72:75] offset:20480
	s_waitcnt vmcnt(4)
	ds_write_b128 v30, v[76:79] offset:24576
	s_waitcnt vmcnt(2)
	ds_write_b128 v30, v[84:87] offset:28672
	ds_write_b128 v30, v[64:67] offset:49152
	ds_write_b128 v30, v[80:83] offset:53248
	ds_write_b128 v30, v[138:141] offset:57344
	ds_write_b128 v30, v[146:149] offset:61440
	global_load_dwordx4 v[62:65], v[2:3], off offset:512
	global_load_dwordx4 v[66:69], v[18:19], off offset:512
	global_load_dwordx4 v[70:73], v[20:21], off offset:512
	global_load_dwordx4 v[74:77], v[22:23], off offset:512
	global_load_dwordx4 v[78:81], v[4:5], off offset:512
	global_load_dwordx4 v[82:85], v[24:25], off offset:512
	s_waitcnt lgkmcnt(0)
	s_barrier
	ds_read_b128 v[138:141], v28 offset:16384
	v_mfma_f32_16x16x32_bf16 v[50:53], v[112:115], v[154:157], v[50:53]
	ds_read_b128 v[146:149], v31 offset:51200
	ds_read_b128 v[154:157], v31 offset:53248
	v_mfma_f32_16x16x32_bf16 v[58:61], v[112:115], v[162:165], v[58:61]
	ds_read_b128 v[112:115], v31 offset:49152
	ds_read_b128 v[162:165], v31 offset:55296
	s_waitcnt lgkmcnt(1)
	v_mfma_f32_16x16x32_bf16 v[38:41], v[138:141], v[112:115], v[38:41]
	v_mfma_f32_16x16x32_bf16 v[46:49], v[138:141], v[146:149], v[46:49]
	v_mfma_f32_16x16x32_bf16 v[54:57], v[138:141], v[154:157], v[54:57]
	s_waitcnt lgkmcnt(0)
	v_mfma_f32_16x16x32_bf16 v[86:89], v[138:141], v[162:165], v[88:91]
	ds_read_b128 v[138:141], v28 offset:18432
	s_waitcnt lgkmcnt(0)
	v_mfma_f32_16x16x32_bf16 v[100:103], v[138:141], v[112:115], v[100:103]
	v_mfma_f32_16x16x32_bf16 v[104:107], v[138:141], v[146:149], v[104:107]
	v_mfma_f32_16x16x32_bf16 v[108:111], v[138:141], v[154:157], v[108:111]
	v_mfma_f32_16x16x32_bf16 v[90:93], v[138:141], v[162:165], v[92:95]
	ds_read_b128 v[138:141], v28 offset:20480
	s_waitcnt lgkmcnt(0)
	v_mfma_f32_16x16x32_bf16 v[116:119], v[138:141], v[112:115], v[116:119]
	v_mfma_f32_16x16x32_bf16 v[120:123], v[138:141], v[146:149], v[120:123]
	v_mfma_f32_16x16x32_bf16 v[124:127], v[138:141], v[154:157], v[124:127]
	v_mfma_f32_16x16x32_bf16 v[94:97], v[138:141], v[162:165], v[96:99]
	ds_read_b128 v[138:141], v28 offset:22528
	s_waitcnt lgkmcnt(0)
	v_mfma_f32_16x16x32_bf16 v[34:37], v[138:141], v[112:115], v[34:37]
	ds_read_b128 v[112:115], v33 offset:16384
	v_mfma_f32_16x16x32_bf16 v[42:45], v[138:141], v[146:149], v[42:45]
	ds_read_b128 v[146:149], v32 offset:51200
	v_mfma_f32_16x16x32_bf16 v[50:53], v[138:141], v[154:157], v[50:53]
	ds_read_b128 v[154:157], v32 offset:53248
	v_mfma_f32_16x16x32_bf16 v[58:61], v[138:141], v[162:165], v[58:61]
	ds_read_b128 v[138:141], v32 offset:49152
	ds_read_b128 v[162:165], v32 offset:55296
	s_waitcnt lgkmcnt(1)
	v_mfma_f32_16x16x32_bf16 v[38:41], v[112:115], v[138:141], v[38:41]
	v_mfma_f32_16x16x32_bf16 v[46:49], v[112:115], v[146:149], v[46:49]
	v_mfma_f32_16x16x32_bf16 v[54:57], v[112:115], v[154:157], v[54:57]
	s_waitcnt lgkmcnt(0)
	v_mfma_f32_16x16x32_bf16 v[86:89], v[112:115], v[162:165], v[86:89]
	ds_read_b128 v[112:115], v33 offset:18432
	s_waitcnt lgkmcnt(0)
	v_mfma_f32_16x16x32_bf16 v[98:101], v[112:115], v[138:141], v[100:103]
	v_mfma_f32_16x16x32_bf16 v[102:105], v[112:115], v[146:149], v[104:107]
	v_mfma_f32_16x16x32_bf16 v[106:109], v[112:115], v[154:157], v[108:111]
	v_mfma_f32_16x16x32_bf16 v[90:93], v[112:115], v[162:165], v[90:93]
	s_nop 1
	ds_read_b128 v[110:113], v33 offset:20480
	s_waitcnt lgkmcnt(0)
	v_mfma_f32_16x16x32_bf16 v[114:117], v[110:113], v[138:141], v[116:119]
	v_mfma_f32_16x16x32_bf16 v[118:121], v[110:113], v[146:149], v[120:123]
	v_mfma_f32_16x16x32_bf16 v[122:125], v[110:113], v[154:157], v[124:127]
	v_mfma_f32_16x16x32_bf16 v[94:97], v[110:113], v[162:165], v[94:97]
	ds_read_b128 v[110:113], v33 offset:22528
	s_waitcnt lgkmcnt(0)
	v_mfma_f32_16x16x32_bf16 v[34:37], v[110:113], v[138:141], v[34:37]
	global_load_dwordx4 v[126:129], v[6:7], off offset:640
	global_load_dwordx4 v[138:141], v[8:9], off offset:640
	s_waitcnt vmcnt(6)
	ds_write_b128 v30, v[66:69]
	s_waitcnt vmcnt(5)
	ds_write_b128 v30, v[70:73] offset:4096
	s_waitcnt vmcnt(4)
	ds_write_b128 v30, v[74:77] offset:8192
	s_waitcnt vmcnt(2)
	ds_write_b128 v30, v[82:85] offset:12288
	ds_write_b128 v30, v[62:65] offset:32768
	ds_write_b128 v30, v[78:81] offset:36864
	ds_write_b128 v30, v[142:145] offset:40960
	ds_write_b128 v30, v[150:153] offset:45056
	global_load_dwordx4 v[62:65], v[2:3], off offset:640
	global_load_dwordx4 v[66:69], v[18:19], off offset:640
	global_load_dwordx4 v[70:73], v[20:21], off offset:640
	global_load_dwordx4 v[74:77], v[22:23], off offset:640
	global_load_dwordx4 v[78:81], v[4:5], off offset:640
	global_load_dwordx4 v[82:85], v[24:25], off offset:640
	s_waitcnt lgkmcnt(0)
	s_barrier
	ds_read_b128 v[142:145], v28
	v_mfma_f32_16x16x32_bf16 v[42:45], v[110:113], v[146:149], v[42:45]
	ds_read_b128 v[146:149], v31 offset:34816
	ds_read_b128 v[150:153], v31 offset:36864
	v_mfma_f32_16x16x32_bf16 v[50:53], v[110:113], v[154:157], v[50:53]
	ds_read_b128 v[154:157], v31 offset:38912
	v_mfma_f32_16x16x32_bf16 v[58:61], v[110:113], v[162:165], v[58:61]
	ds_read_b128 v[110:113], v31 offset:32768
	s_waitcnt lgkmcnt(0)
	v_mfma_f32_16x16x32_bf16 v[38:41], v[142:145], v[110:113], v[38:41]
	v_mfma_f32_16x16x32_bf16 v[46:49], v[142:145], v[146:149], v[46:49]
	v_mfma_f32_16x16x32_bf16 v[54:57], v[142:145], v[150:153], v[54:57]
	v_mfma_f32_16x16x32_bf16 v[86:89], v[142:145], v[154:157], v[86:89]
	ds_read_b128 v[142:145], v28 offset:2048
	s_waitcnt lgkmcnt(0)
	v_mfma_f32_16x16x32_bf16 v[98:101], v[142:145], v[110:113], v[98:101]
	v_mfma_f32_16x16x32_bf16 v[102:105], v[142:145], v[146:149], v[102:105]
	v_mfma_f32_16x16x32_bf16 v[106:109], v[142:145], v[150:153], v[106:109]
	v_mfma_f32_16x16x32_bf16 v[90:93], v[142:145], v[154:157], v[90:93]
	ds_read_b128 v[142:145], v28 offset:4096
	s_waitcnt lgkmcnt(0)
	v_mfma_f32_16x16x32_bf16 v[114:117], v[142:145], v[110:113], v[114:117]
	v_mfma_f32_16x16x32_bf16 v[118:121], v[142:145], v[146:149], v[118:121]
	v_mfma_f32_16x16x32_bf16 v[122:125], v[142:145], v[150:153], v[122:125]
	v_mfma_f32_16x16x32_bf16 v[94:97], v[142:145], v[154:157], v[94:97]
	ds_read_b128 v[142:145], v28 offset:6144
	s_waitcnt lgkmcnt(0)
	v_mfma_f32_16x16x32_bf16 v[34:37], v[142:145], v[110:113], v[34:37]
	ds_read_b128 v[110:113], v33
	v_mfma_f32_16x16x32_bf16 v[42:45], v[142:145], v[146:149], v[42:45]
	ds_read_b128 v[146:149], v32 offset:34816
	v_mfma_f32_16x16x32_bf16 v[50:53], v[142:145], v[150:153], v[50:53]
	ds_read_b128 v[150:153], v32 offset:36864
	v_mfma_f32_16x16x32_bf16 v[58:61], v[142:145], v[154:157], v[58:61]
	ds_read_b128 v[142:145], v32 offset:32768
	ds_read_b128 v[154:157], v32 offset:38912
	s_waitcnt lgkmcnt(1)
	v_mfma_f32_16x16x32_bf16 v[38:41], v[110:113], v[142:145], v[38:41]
	v_mfma_f32_16x16x32_bf16 v[46:49], v[110:113], v[146:149], v[46:49]
	v_mfma_f32_16x16x32_bf16 v[54:57], v[110:113], v[150:153], v[54:57]
	s_waitcnt lgkmcnt(0)
	v_mfma_f32_16x16x32_bf16 v[86:89], v[110:113], v[154:157], v[86:89]
	ds_read_b128 v[110:113], v33 offset:2048
	s_waitcnt lgkmcnt(0)
	v_mfma_f32_16x16x32_bf16 v[98:101], v[110:113], v[142:145], v[98:101]
	v_mfma_f32_16x16x32_bf16 v[102:105], v[110:113], v[146:149], v[102:105]
	v_mfma_f32_16x16x32_bf16 v[106:109], v[110:113], v[150:153], v[106:109]
	v_mfma_f32_16x16x32_bf16 v[90:93], v[110:113], v[154:157], v[90:93]
	ds_read_b128 v[110:113], v33 offset:4096
	s_waitcnt lgkmcnt(0)
	v_mfma_f32_16x16x32_bf16 v[114:117], v[110:113], v[142:145], v[114:117]
	v_mfma_f32_16x16x32_bf16 v[118:121], v[110:113], v[146:149], v[118:121]
	v_mfma_f32_16x16x32_bf16 v[122:125], v[110:113], v[150:153], v[122:125]
	v_mfma_f32_16x16x32_bf16 v[94:97], v[110:113], v[154:157], v[94:97]
	ds_read_b128 v[110:113], v33 offset:6144
	s_waitcnt lgkmcnt(0)
	v_mfma_f32_16x16x32_bf16 v[34:37], v[110:113], v[142:145], v[34:37]
	v_mfma_f32_16x16x32_bf16 v[42:45], v[110:113], v[146:149], v[42:45]
	global_load_dwordx4 v[142:145], v[6:7], off offset:768
	global_load_dwordx4 v[146:149], v[8:9], off offset:768
	s_waitcnt vmcnt(6)
	ds_write_b128 v30, v[66:69] offset:16384
	s_waitcnt vmcnt(5)
	ds_write_b128 v30, v[70:73] offset:20480
	s_waitcnt vmcnt(4)
	ds_write_b128 v30, v[74:77] offset:24576
	s_waitcnt vmcnt(2)
	ds_write_b128 v30, v[82:85] offset:28672
	ds_write_b128 v30, v[62:65] offset:49152
	ds_write_b128 v30, v[78:81] offset:53248
	ds_write_b128 v30, v[126:129] offset:57344
	ds_write_b128 v30, v[138:141] offset:61440
	global_load_dwordx4 v[62:65], v[2:3], off offset:768
	global_load_dwordx4 v[66:69], v[18:19], off offset:768
	global_load_dwordx4 v[70:73], v[20:21], off offset:768
	global_load_dwordx4 v[74:77], v[22:23], off offset:768
	global_load_dwordx4 v[78:81], v[4:5], off offset:768
	global_load_dwordx4 v[82:85], v[24:25], off offset:768
	s_waitcnt lgkmcnt(0)
	s_barrier
	ds_read_b128 v[126:129], v28 offset:16384
	v_mfma_f32_16x16x32_bf16 v[50:53], v[110:113], v[150:153], v[50:53]
	ds_read_b128 v[138:141], v31 offset:51200
	ds_read_b128 v[150:153], v31 offset:53248
	v_mfma_f32_16x16x32_bf16 v[58:61], v[110:113], v[154:157], v[58:61]
	ds_read_b128 v[110:113], v31 offset:49152
	ds_read_b128 v[154:157], v31 offset:55296
	s_waitcnt lgkmcnt(1)
	v_mfma_f32_16x16x32_bf16 v[38:41], v[126:129], v[110:113], v[38:41]
	v_mfma_f32_16x16x32_bf16 v[46:49], v[126:129], v[138:141], v[46:49]
	v_mfma_f32_16x16x32_bf16 v[54:57], v[126:129], v[150:153], v[54:57]
	s_waitcnt lgkmcnt(0)
	v_mfma_f32_16x16x32_bf16 v[86:89], v[126:129], v[154:157], v[86:89]
	ds_read_b128 v[126:129], v28 offset:18432
	s_waitcnt lgkmcnt(0)
	v_mfma_f32_16x16x32_bf16 v[98:101], v[126:129], v[110:113], v[98:101]
	v_mfma_f32_16x16x32_bf16 v[102:105], v[126:129], v[138:141], v[102:105]
	v_mfma_f32_16x16x32_bf16 v[106:109], v[126:129], v[150:153], v[106:109]
	v_mfma_f32_16x16x32_bf16 v[90:93], v[126:129], v[154:157], v[90:93]
	ds_read_b128 v[126:129], v28 offset:20480
	s_waitcnt lgkmcnt(0)
	v_mfma_f32_16x16x32_bf16 v[114:117], v[126:129], v[110:113], v[114:117]
	v_mfma_f32_16x16x32_bf16 v[118:121], v[126:129], v[138:141], v[118:121]
	v_mfma_f32_16x16x32_bf16 v[122:125], v[126:129], v[150:153], v[122:125]
	v_mfma_f32_16x16x32_bf16 v[94:97], v[126:129], v[154:157], v[94:97]
	ds_read_b128 v[126:129], v28 offset:22528
	s_waitcnt lgkmcnt(0)
	v_mfma_f32_16x16x32_bf16 v[34:37], v[126:129], v[110:113], v[34:37]
	ds_read_b128 v[110:113], v33 offset:16384
	v_mfma_f32_16x16x32_bf16 v[42:45], v[126:129], v[138:141], v[42:45]
	ds_read_b128 v[138:141], v32 offset:51200
	v_mfma_f32_16x16x32_bf16 v[50:53], v[126:129], v[150:153], v[50:53]
	ds_read_b128 v[150:153], v32 offset:53248
	v_mfma_f32_16x16x32_bf16 v[58:61], v[126:129], v[154:157], v[58:61]
	ds_read_b128 v[126:129], v32 offset:49152
	ds_read_b128 v[154:157], v32 offset:55296
	s_waitcnt lgkmcnt(1)
	v_mfma_f32_16x16x32_bf16 v[38:41], v[110:113], v[126:129], v[38:41]
	v_mfma_f32_16x16x32_bf16 v[46:49], v[110:113], v[138:141], v[46:49]
	v_mfma_f32_16x16x32_bf16 v[54:57], v[110:113], v[150:153], v[54:57]
	s_waitcnt lgkmcnt(0)
	v_mfma_f32_16x16x32_bf16 v[86:89], v[110:113], v[154:157], v[86:89]
	ds_read_b128 v[110:113], v33 offset:18432
	s_waitcnt lgkmcnt(0)
	v_mfma_f32_16x16x32_bf16 v[98:101], v[110:113], v[126:129], v[98:101]
	v_mfma_f32_16x16x32_bf16 v[102:105], v[110:113], v[138:141], v[102:105]
	v_mfma_f32_16x16x32_bf16 v[106:109], v[110:113], v[150:153], v[106:109]
	v_mfma_f32_16x16x32_bf16 v[90:93], v[110:113], v[154:157], v[90:93]
	ds_read_b128 v[110:113], v33 offset:20480
	s_waitcnt lgkmcnt(0)
	v_mfma_f32_16x16x32_bf16 v[114:117], v[110:113], v[126:129], v[114:117]
	v_mfma_f32_16x16x32_bf16 v[118:121], v[110:113], v[138:141], v[118:121]
	v_mfma_f32_16x16x32_bf16 v[122:125], v[110:113], v[150:153], v[122:125]
	v_mfma_f32_16x16x32_bf16 v[94:97], v[110:113], v[154:157], v[94:97]
	ds_read_b128 v[110:113], v33 offset:22528
	s_waitcnt lgkmcnt(0)
	v_mfma_f32_16x16x32_bf16 v[34:37], v[110:113], v[126:129], v[34:37]
	v_mfma_f32_16x16x32_bf16 v[42:45], v[110:113], v[138:141], v[42:45]
	global_load_dwordx4 v[126:129], v[6:7], off offset:896
	global_load_dwordx4 v[138:141], v[8:9], off offset:896
	s_waitcnt vmcnt(6)
	ds_write_b128 v30, v[66:69]
	s_waitcnt vmcnt(5)
	ds_write_b128 v30, v[70:73] offset:4096
	s_waitcnt vmcnt(4)
	ds_write_b128 v30, v[74:77] offset:8192
	s_waitcnt vmcnt(2)
	ds_write_b128 v30, v[82:85] offset:12288
	ds_write_b128 v30, v[62:65] offset:32768
	ds_write_b128 v30, v[78:81] offset:36864
	ds_write_b128 v30, v[142:145] offset:40960
	ds_write_b128 v30, v[146:149] offset:45056
	global_load_dwordx4 v[62:65], v[2:3], off offset:896
	global_load_dwordx4 v[66:69], v[18:19], off offset:896
	s_nop 0
	global_load_dwordx4 v[18:21], v[20:21], off offset:896
	s_nop 0
	global_load_dwordx4 v[70:73], v[22:23], off offset:896
	global_load_dwordx4 v[74:77], v[4:5], off offset:896
	s_nop 0
	global_load_dwordx4 v[22:25], v[24:25], off offset:896
	s_waitcnt lgkmcnt(0)
	s_barrier
	ds_read_b128 v[78:81], v28
	ds_read_b128 v[82:85], v31 offset:32768
	v_mfma_f32_16x16x32_bf16 v[50:53], v[110:113], v[150:153], v[50:53]
	ds_read_b128 v[142:145], v31 offset:36864
	ds_read_b128 v[146:149], v31 offset:38912
	ds_read_b128 v[150:153], v33 offset:6144
	v_mfma_f32_16x16x32_bf16 v[58:61], v[110:113], v[154:157], v[58:61]
	ds_read_b128 v[110:113], v31 offset:34816
	s_waitcnt lgkmcnt(4)
	v_mfma_f32_16x16x32_bf16 v[38:41], v[78:81], v[82:85], v[38:41]
	s_waitcnt lgkmcnt(0)
	v_mfma_f32_16x16x32_bf16 v[46:49], v[78:81], v[110:113], v[46:49]
	v_mfma_f32_16x16x32_bf16 v[54:57], v[78:81], v[142:145], v[54:57]
	v_mfma_f32_16x16x32_bf16 v[78:81], v[78:81], v[146:149], v[86:89]
	s_nop 2
	ds_read_b128 v[86:89], v28 offset:2048
	s_waitcnt lgkmcnt(0)
	v_mfma_f32_16x16x32_bf16 v[98:101], v[86:89], v[82:85], v[98:101]
	v_mfma_f32_16x16x32_bf16 v[102:105], v[86:89], v[110:113], v[102:105]
	v_mfma_f32_16x16x32_bf16 v[106:109], v[86:89], v[142:145], v[106:109]
	v_mfma_f32_16x16x32_bf16 v[86:89], v[86:89], v[146:149], v[90:93]
	s_nop 2
	ds_read_b128 v[90:93], v28 offset:4096
	s_waitcnt lgkmcnt(0)
	v_mfma_f32_16x16x32_bf16 v[114:117], v[90:93], v[82:85], v[114:117]
	v_mfma_f32_16x16x32_bf16 v[118:121], v[90:93], v[110:113], v[118:121]
	v_mfma_f32_16x16x32_bf16 v[122:125], v[90:93], v[142:145], v[122:125]
	v_mfma_f32_16x16x32_bf16 v[90:93], v[90:93], v[146:149], v[94:97]
	s_nop 2
	ds_read_b128 v[94:97], v28 offset:6144
	s_waitcnt lgkmcnt(0)
	v_mfma_f32_16x16x32_bf16 v[34:37], v[94:97], v[82:85], v[34:37]
	ds_read_b128 v[82:85], v33
	v_mfma_f32_16x16x32_bf16 v[42:45], v[94:97], v[110:113], v[42:45]
	ds_read_b128 v[110:113], v32 offset:34816
	v_mfma_f32_16x16x32_bf16 v[50:53], v[94:97], v[142:145], v[50:53]
	ds_read_b128 v[142:145], v32 offset:36864
	v_mfma_f32_16x16x32_bf16 v[58:61], v[94:97], v[146:149], v[58:61]
	ds_read_b128 v[94:97], v32 offset:32768
	ds_read_b128 v[146:149], v32 offset:38912
	s_waitcnt lgkmcnt(1)
	v_mfma_f32_16x16x32_bf16 v[38:41], v[82:85], v[94:97], v[38:41]
	v_mfma_f32_16x16x32_bf16 v[46:49], v[82:85], v[110:113], v[46:49]
	v_mfma_f32_16x16x32_bf16 v[54:57], v[82:85], v[142:145], v[54:57]
	s_waitcnt lgkmcnt(0)
	v_mfma_f32_16x16x32_bf16 v[78:81], v[82:85], v[146:149], v[78:81]
	ds_read_b128 v[82:85], v33 offset:2048
	s_waitcnt lgkmcnt(0)
	v_mfma_f32_16x16x32_bf16 v[98:101], v[82:85], v[94:97], v[98:101]
	v_mfma_f32_16x16x32_bf16 v[102:105], v[82:85], v[110:113], v[102:105]
	v_mfma_f32_16x16x32_bf16 v[106:109], v[82:85], v[142:145], v[106:109]
	v_mfma_f32_16x16x32_bf16 v[82:85], v[82:85], v[146:149], v[86:89]
	s_nop 2
	ds_read_b128 v[86:89], v33 offset:4096
	s_waitcnt lgkmcnt(0)
	v_mfma_f32_16x16x32_bf16 v[114:117], v[86:89], v[94:97], v[114:117]
	v_mfma_f32_16x16x32_bf16 v[118:121], v[86:89], v[110:113], v[118:121]
	v_mfma_f32_16x16x32_bf16 v[122:125], v[86:89], v[142:145], v[122:125]
	v_mfma_f32_16x16x32_bf16 v[86:89], v[86:89], v[146:149], v[90:93]
	v_mfma_f32_16x16x32_bf16 v[34:37], v[150:153], v[94:97], v[34:37]
	v_mfma_f32_16x16x32_bf16 v[42:45], v[150:153], v[110:113], v[42:45]
	s_nop 0
	global_load_dwordx4 v[90:93], v[2:3], off offset:1024
	global_load_dwordx4 v[94:97], v[4:5], off offset:1024
	global_load_dwordx4 v[110:113], v[6:7], off offset:1024
	global_load_dwordx4 v[154:157], v[8:9], off offset:1024
	s_waitcnt vmcnt(8)
	ds_write_b128 v30, v[66:69] offset:16384
	s_waitcnt vmcnt(7)
	ds_write_b128 v30, v[18:21] offset:20480
	s_waitcnt vmcnt(6)
	ds_write_b128 v30, v[70:73] offset:24576
	s_waitcnt vmcnt(4)
	ds_write_b128 v30, v[22:25] offset:28672
	ds_write_b128 v30, v[62:65] offset:49152
	ds_write_b128 v30, v[74:77] offset:53248
	ds_write_b128 v30, v[126:129] offset:57344
	ds_write_b128 v30, v[138:141] offset:61440
	global_load_dwordx4 v[18:21], v[10:11], off offset:256
	global_load_dwordx4 v[22:25], v[12:13], off offset:256
	global_load_dwordx4 v[62:65], v[14:15], off offset:256
	global_load_dwordx4 v[66:69], v[16:17], off offset:256
	s_waitcnt lgkmcnt(0)
	s_barrier
	ds_read_b128 v[70:73], v28 offset:16384
	ds_read_b128 v[74:77], v31 offset:49152
	v_mfma_f32_16x16x32_bf16 v[50:53], v[150:153], v[142:145], v[50:53]
	ds_read_b128 v[126:129], v31 offset:51200
	ds_read_b128 v[138:141], v31 offset:53248
	ds_read_b128 v[142:145], v31 offset:55296
	s_waitcnt lgkmcnt(3)
	v_mfma_f32_16x16x32_bf16 v[38:41], v[70:73], v[74:77], v[38:41]
	s_waitcnt lgkmcnt(2)
	v_mfma_f32_16x16x32_bf16 v[46:49], v[70:73], v[126:129], v[46:49]
	s_waitcnt lgkmcnt(1)
	v_mfma_f32_16x16x32_bf16 v[54:57], v[70:73], v[138:141], v[54:57]
	s_waitcnt lgkmcnt(0)
	v_mfma_f32_16x16x32_bf16 v[70:73], v[70:73], v[142:145], v[78:81]
	s_nop 2
	ds_read_b128 v[78:81], v28 offset:18432
	s_waitcnt lgkmcnt(0)
	v_mfma_f32_16x16x32_bf16 v[98:101], v[78:81], v[74:77], v[98:101]
	v_mfma_f32_16x16x32_bf16 v[102:105], v[78:81], v[126:129], v[102:105]
	v_mfma_f32_16x16x32_bf16 v[106:109], v[78:81], v[138:141], v[106:109]
	v_mfma_f32_16x16x32_bf16 v[78:81], v[78:81], v[142:145], v[82:85]
	s_nop 2
	ds_read_b128 v[82:85], v28 offset:20480
	s_waitcnt lgkmcnt(0)
	v_mfma_f32_16x16x32_bf16 v[114:117], v[82:85], v[74:77], v[114:117]
	v_mfma_f32_16x16x32_bf16 v[118:121], v[82:85], v[126:129], v[118:121]
	v_mfma_f32_16x16x32_bf16 v[122:125], v[82:85], v[138:141], v[122:125]
	v_mfma_f32_16x16x32_bf16 v[82:85], v[82:85], v[142:145], v[86:89]
	s_nop 2
	ds_read_b128 v[86:89], v28 offset:22528
	v_mfma_f32_16x16x32_bf16 v[58:61], v[150:153], v[146:149], v[58:61]
	s_waitcnt lgkmcnt(0)
	v_mfma_f32_16x16x32_bf16 v[34:37], v[86:89], v[74:77], v[34:37]
	ds_read_b128 v[74:77], v33 offset:16384
	v_mfma_f32_16x16x32_bf16 v[42:45], v[86:89], v[126:129], v[42:45]
	ds_read_b128 v[126:129], v32 offset:51200
	v_mfma_f32_16x16x32_bf16 v[50:53], v[86:89], v[138:141], v[50:53]
	ds_read_b128 v[138:141], v32 offset:53248
	v_mfma_f32_16x16x32_bf16 v[58:61], v[86:89], v[142:145], v[58:61]
	ds_read_b128 v[86:89], v32 offset:49152
	ds_read_b128 v[142:145], v32 offset:55296
	s_waitcnt lgkmcnt(1)
	v_mfma_f32_16x16x32_bf16 v[38:41], v[74:77], v[86:89], v[38:41]
	v_mfma_f32_16x16x32_bf16 v[46:49], v[74:77], v[126:129], v[46:49]
	v_mfma_f32_16x16x32_bf16 v[54:57], v[74:77], v[138:141], v[54:57]
	s_waitcnt lgkmcnt(0)
	v_mfma_f32_16x16x32_bf16 v[70:73], v[74:77], v[142:145], v[70:73]
	ds_read_b128 v[74:77], v33 offset:18432
	s_waitcnt lgkmcnt(0)
	v_mfma_f32_16x16x32_bf16 v[98:101], v[74:77], v[86:89], v[98:101]
	v_mfma_f32_16x16x32_bf16 v[102:105], v[74:77], v[126:129], v[102:105]
	v_mfma_f32_16x16x32_bf16 v[106:109], v[74:77], v[138:141], v[106:109]
	v_mfma_f32_16x16x32_bf16 v[74:77], v[74:77], v[142:145], v[78:81]
	s_nop 2
	ds_read_b128 v[78:81], v33 offset:20480
	s_waitcnt lgkmcnt(0)
	v_mfma_f32_16x16x32_bf16 v[114:117], v[78:81], v[86:89], v[114:117]
	v_mfma_f32_16x16x32_bf16 v[118:121], v[78:81], v[126:129], v[118:121]
	v_mfma_f32_16x16x32_bf16 v[122:125], v[78:81], v[138:141], v[122:125]
	v_mfma_f32_16x16x32_bf16 v[78:81], v[78:81], v[142:145], v[82:85]
	s_nop 2
	ds_read_b128 v[82:85], v33 offset:22528
	s_waitcnt lgkmcnt(0)
	v_mfma_f32_16x16x32_bf16 v[34:37], v[82:85], v[86:89], v[34:37]
	v_mfma_f32_16x16x32_bf16 v[42:45], v[82:85], v[126:129], v[42:45]
	global_load_dwordx4 v[86:89], v[2:3], off offset:1152
	global_load_dwordx4 v[126:129], v[4:5], off offset:1152
	global_load_dwordx4 v[146:149], v[6:7], off offset:1152
	global_load_dwordx4 v[150:153], v[8:9], off offset:1152
	s_waitcnt vmcnt(7)
	ds_write_b128 v30, v[18:21]
	s_waitcnt vmcnt(6)
	ds_write_b128 v30, v[22:25] offset:4096
	s_waitcnt vmcnt(5)
	ds_write_b128 v30, v[62:65] offset:8192
	s_waitcnt vmcnt(4)
	ds_write_b128 v30, v[66:69] offset:12288
	ds_write_b128 v30, v[90:93] offset:32768
	ds_write_b128 v30, v[94:97] offset:36864
	ds_write_b128 v30, v[110:113] offset:40960
	ds_write_b128 v30, v[154:157] offset:45056
	global_load_dwordx4 v[18:21], v[10:11], off offset:384
	global_load_dwordx4 v[22:25], v[12:13], off offset:384
	global_load_dwordx4 v[62:65], v[14:15], off offset:384
	global_load_dwordx4 v[66:69], v[16:17], off offset:384
	s_waitcnt lgkmcnt(0)
	s_barrier
	ds_read_b128 v[90:93], v28
	v_mfma_f32_16x16x32_bf16 v[50:53], v[82:85], v[138:141], v[50:53]
	ds_read_b128 v[94:97], v31 offset:34816
	ds_read_b128 v[110:113], v31 offset:36864
	ds_read_b128 v[138:141], v31 offset:38912
	v_mfma_f32_16x16x32_bf16 v[58:61], v[82:85], v[142:145], v[58:61]
	ds_read_b128 v[82:85], v31 offset:32768
	s_waitcnt lgkmcnt(0)
	v_mfma_f32_16x16x32_bf16 v[38:41], v[90:93], v[82:85], v[38:41]
	v_mfma_f32_16x16x32_bf16 v[46:49], v[90:93], v[94:97], v[46:49]
	v_mfma_f32_16x16x32_bf16 v[54:57], v[90:93], v[110:113], v[54:57]
	v_mfma_f32_16x16x32_bf16 v[70:73], v[90:93], v[138:141], v[70:73]
	ds_read_b128 v[90:93], v28 offset:2048
	s_waitcnt lgkmcnt(0)
	v_mfma_f32_16x16x32_bf16 v[98:101], v[90:93], v[82:85], v[98:101]
	v_mfma_f32_16x16x32_bf16 v[102:105], v[90:93], v[94:97], v[102:105]
	v_mfma_f32_16x16x32_bf16 v[106:109], v[90:93], v[110:113], v[106:109]
	v_mfma_f32_16x16x32_bf16 v[74:77], v[90:93], v[138:141], v[74:77]
	ds_read_b128 v[90:93], v28 offset:4096
	s_waitcnt lgkmcnt(0)
	v_mfma_f32_16x16x32_bf16 v[114:117], v[90:93], v[82:85], v[114:117]
	v_mfma_f32_16x16x32_bf16 v[118:121], v[90:93], v[94:97], v[118:121]
	v_mfma_f32_16x16x32_bf16 v[122:125], v[90:93], v[110:113], v[122:125]
	v_mfma_f32_16x16x32_bf16 v[78:81], v[90:93], v[138:141], v[78:81]
	ds_read_b128 v[90:93], v28 offset:6144
	s_waitcnt lgkmcnt(0)
	v_mfma_f32_16x16x32_bf16 v[34:37], v[90:93], v[82:85], v[34:37]
	ds_read_b128 v[82:85], v33
	v_mfma_f32_16x16x32_bf16 v[42:45], v[90:93], v[94:97], v[42:45]
	ds_read_b128 v[94:97], v32 offset:34816
	v_mfma_f32_16x16x32_bf16 v[50:53], v[90:93], v[110:113], v[50:53]
	ds_read_b128 v[110:113], v32 offset:36864
	v_mfma_f32_16x16x32_bf16 v[58:61], v[90:93], v[138:141], v[58:61]
	ds_read_b128 v[90:93], v32 offset:32768
	ds_read_b128 v[138:141], v32 offset:38912
	s_waitcnt lgkmcnt(1)
	v_mfma_f32_16x16x32_bf16 v[38:41], v[82:85], v[90:93], v[38:41]
	v_mfma_f32_16x16x32_bf16 v[46:49], v[82:85], v[94:97], v[46:49]
	v_mfma_f32_16x16x32_bf16 v[54:57], v[82:85], v[110:113], v[54:57]
	s_waitcnt lgkmcnt(0)
	v_mfma_f32_16x16x32_bf16 v[70:73], v[82:85], v[138:141], v[70:73]
	ds_read_b128 v[82:85], v33 offset:2048
	s_waitcnt lgkmcnt(0)
	v_mfma_f32_16x16x32_bf16 v[98:101], v[82:85], v[90:93], v[98:101]
	v_mfma_f32_16x16x32_bf16 v[102:105], v[82:85], v[94:97], v[102:105]
	v_mfma_f32_16x16x32_bf16 v[106:109], v[82:85], v[110:113], v[106:109]
	v_mfma_f32_16x16x32_bf16 v[74:77], v[82:85], v[138:141], v[74:77]
	ds_read_b128 v[82:85], v33 offset:4096
	s_waitcnt lgkmcnt(0)
	v_mfma_f32_16x16x32_bf16 v[114:117], v[82:85], v[90:93], v[114:117]
	v_mfma_f32_16x16x32_bf16 v[118:121], v[82:85], v[94:97], v[118:121]
	v_mfma_f32_16x16x32_bf16 v[122:125], v[82:85], v[110:113], v[122:125]
	v_mfma_f32_16x16x32_bf16 v[78:81], v[82:85], v[138:141], v[78:81]
	ds_read_b128 v[82:85], v33 offset:6144
	s_waitcnt lgkmcnt(0)
	v_mfma_f32_16x16x32_bf16 v[34:37], v[82:85], v[90:93], v[34:37]
	v_mfma_f32_16x16x32_bf16 v[42:45], v[82:85], v[94:97], v[42:45]
	global_load_dwordx4 v[90:93], v[2:3], off offset:1280
	global_load_dwordx4 v[94:97], v[4:5], off offset:1280
	global_load_dwordx4 v[142:145], v[6:7], off offset:1280
	global_load_dwordx4 v[154:157], v[8:9], off offset:1280
	s_waitcnt vmcnt(7)
	ds_write_b128 v30, v[18:21] offset:16384
	s_waitcnt vmcnt(6)
	ds_write_b128 v30, v[22:25] offset:20480
	s_waitcnt vmcnt(5)
	ds_write_b128 v30, v[62:65] offset:24576
	s_waitcnt vmcnt(4)
	ds_write_b128 v30, v[66:69] offset:28672
	ds_write_b128 v30, v[86:89] offset:49152
	ds_write_b128 v30, v[126:129] offset:53248
	ds_write_b128 v30, v[146:149] offset:57344
	ds_write_b128 v30, v[150:153] offset:61440
	global_load_dwordx4 v[18:21], v[10:11], off offset:512
	global_load_dwordx4 v[22:25], v[12:13], off offset:512
	global_load_dwordx4 v[62:65], v[14:15], off offset:512
	global_load_dwordx4 v[66:69], v[16:17], off offset:512
	s_waitcnt lgkmcnt(0)
	s_barrier
	ds_read_b128 v[86:89], v28 offset:16384
	v_mfma_f32_16x16x32_bf16 v[50:53], v[82:85], v[110:113], v[50:53]
	ds_read_b128 v[110:113], v31 offset:51200
	ds_read_b128 v[126:129], v31 offset:53248
	v_mfma_f32_16x16x32_bf16 v[58:61], v[82:85], v[138:141], v[58:61]
	ds_read_b128 v[82:85], v31 offset:49152
	ds_read_b128 v[138:141], v31 offset:55296
	s_waitcnt lgkmcnt(1)
	v_mfma_f32_16x16x32_bf16 v[38:41], v[86:89], v[82:85], v[38:41]
	v_mfma_f32_16x16x32_bf16 v[46:49], v[86:89], v[110:113], v[46:49]
	v_mfma_f32_16x16x32_bf16 v[54:57], v[86:89], v[126:129], v[54:57]
	s_waitcnt lgkmcnt(0)
	v_mfma_f32_16x16x32_bf16 v[70:73], v[86:89], v[138:141], v[70:73]
	ds_read_b128 v[86:89], v28 offset:18432
	s_waitcnt lgkmcnt(0)
	v_mfma_f32_16x16x32_bf16 v[98:101], v[86:89], v[82:85], v[98:101]
	v_mfma_f32_16x16x32_bf16 v[102:105], v[86:89], v[110:113], v[102:105]
	v_mfma_f32_16x16x32_bf16 v[106:109], v[86:89], v[126:129], v[106:109]
	v_mfma_f32_16x16x32_bf16 v[74:77], v[86:89], v[138:141], v[74:77]
	ds_read_b128 v[86:89], v28 offset:20480
	s_waitcnt lgkmcnt(0)
	v_mfma_f32_16x16x32_bf16 v[114:117], v[86:89], v[82:85], v[114:117]
	v_mfma_f32_16x16x32_bf16 v[118:121], v[86:89], v[110:113], v[118:121]
	v_mfma_f32_16x16x32_bf16 v[122:125], v[86:89], v[126:129], v[122:125]
	v_mfma_f32_16x16x32_bf16 v[78:81], v[86:89], v[138:141], v[78:81]
	ds_read_b128 v[86:89], v28 offset:22528
	s_waitcnt lgkmcnt(0)
	v_mfma_f32_16x16x32_bf16 v[34:37], v[86:89], v[82:85], v[34:37]
	ds_read_b128 v[82:85], v33 offset:16384
	v_mfma_f32_16x16x32_bf16 v[42:45], v[86:89], v[110:113], v[42:45]
	ds_read_b128 v[110:113], v32 offset:51200
	v_mfma_f32_16x16x32_bf16 v[50:53], v[86:89], v[126:129], v[50:53]
	ds_read_b128 v[126:129], v32 offset:53248
	v_mfma_f32_16x16x32_bf16 v[58:61], v[86:89], v[138:141], v[58:61]
	ds_read_b128 v[86:89], v32 offset:49152
	ds_read_b128 v[138:141], v32 offset:55296
	s_waitcnt lgkmcnt(1)
	v_mfma_f32_16x16x32_bf16 v[38:41], v[82:85], v[86:89], v[38:41]
	v_mfma_f32_16x16x32_bf16 v[46:49], v[82:85], v[110:113], v[46:49]
	v_mfma_f32_16x16x32_bf16 v[54:57], v[82:85], v[126:129], v[54:57]
	s_waitcnt lgkmcnt(0)
	v_mfma_f32_16x16x32_bf16 v[70:73], v[82:85], v[138:141], v[70:73]
	ds_read_b128 v[82:85], v33 offset:18432
	s_waitcnt lgkmcnt(0)
	v_mfma_f32_16x16x32_bf16 v[98:101], v[82:85], v[86:89], v[98:101]
	v_mfma_f32_16x16x32_bf16 v[102:105], v[82:85], v[110:113], v[102:105]
	v_mfma_f32_16x16x32_bf16 v[106:109], v[82:85], v[126:129], v[106:109]
	v_mfma_f32_16x16x32_bf16 v[74:77], v[82:85], v[138:141], v[74:77]
	ds_read_b128 v[82:85], v33 offset:20480
	s_waitcnt lgkmcnt(0)
	v_mfma_f32_16x16x32_bf16 v[114:117], v[82:85], v[86:89], v[114:117]
	v_mfma_f32_16x16x32_bf16 v[118:121], v[82:85], v[110:113], v[118:121]
	v_mfma_f32_16x16x32_bf16 v[122:125], v[82:85], v[126:129], v[122:125]
	v_mfma_f32_16x16x32_bf16 v[78:81], v[82:85], v[138:141], v[78:81]
	ds_read_b128 v[82:85], v33 offset:22528
	s_waitcnt lgkmcnt(0)
	v_mfma_f32_16x16x32_bf16 v[34:37], v[82:85], v[86:89], v[34:37]
	v_mfma_f32_16x16x32_bf16 v[42:45], v[82:85], v[110:113], v[42:45]
	global_load_dwordx4 v[86:89], v[2:3], off offset:1408
	global_load_dwordx4 v[110:113], v[4:5], off offset:1408
	global_load_dwordx4 v[146:149], v[6:7], off offset:1408
	global_load_dwordx4 v[150:153], v[8:9], off offset:1408
	s_waitcnt vmcnt(7)
	ds_write_b128 v30, v[18:21]
	s_waitcnt vmcnt(6)
	ds_write_b128 v30, v[22:25] offset:4096
	s_waitcnt vmcnt(5)
	ds_write_b128 v30, v[62:65] offset:8192
	s_waitcnt vmcnt(4)
	ds_write_b128 v30, v[66:69] offset:12288
	ds_write_b128 v30, v[90:93] offset:32768
	ds_write_b128 v30, v[94:97] offset:36864
	ds_write_b128 v30, v[142:145] offset:40960
	ds_write_b128 v30, v[154:157] offset:45056
	global_load_dwordx4 v[18:21], v[10:11], off offset:640
	global_load_dwordx4 v[22:25], v[12:13], off offset:640
	global_load_dwordx4 v[62:65], v[14:15], off offset:640
	global_load_dwordx4 v[66:69], v[16:17], off offset:640
	s_waitcnt lgkmcnt(0)
	s_barrier
	ds_read_b128 v[90:93], v28
	v_mfma_f32_16x16x32_bf16 v[50:53], v[82:85], v[126:129], v[50:53]
	ds_read_b128 v[94:97], v31 offset:34816
	ds_read_b128 v[126:129], v31 offset:36864
	v_mfma_f32_16x16x32_bf16 v[58:61], v[82:85], v[138:141], v[58:61]
	ds_read_b128 v[82:85], v31 offset:32768
	ds_read_b128 v[138:141], v31 offset:38912
	s_waitcnt lgkmcnt(1)
	v_mfma_f32_16x16x32_bf16 v[38:41], v[90:93], v[82:85], v[38:41]
	v_mfma_f32_16x16x32_bf16 v[46:49], v[90:93], v[94:97], v[46:49]
	v_mfma_f32_16x16x32_bf16 v[54:57], v[90:93], v[126:129], v[54:57]
	s_waitcnt lgkmcnt(0)
	v_mfma_f32_16x16x32_bf16 v[70:73], v[90:93], v[138:141], v[70:73]
	ds_read_b128 v[90:93], v28 offset:2048
	s_waitcnt lgkmcnt(0)
	v_mfma_f32_16x16x32_bf16 v[98:101], v[90:93], v[82:85], v[98:101]
	v_mfma_f32_16x16x32_bf16 v[102:105], v[90:93], v[94:97], v[102:105]
	v_mfma_f32_16x16x32_bf16 v[106:109], v[90:93], v[126:129], v[106:109]
	v_mfma_f32_16x16x32_bf16 v[74:77], v[90:93], v[138:141], v[74:77]
	ds_read_b128 v[90:93], v28 offset:4096
	s_waitcnt lgkmcnt(0)
	v_mfma_f32_16x16x32_bf16 v[114:117], v[90:93], v[82:85], v[114:117]
	v_mfma_f32_16x16x32_bf16 v[118:121], v[90:93], v[94:97], v[118:121]
	v_mfma_f32_16x16x32_bf16 v[122:125], v[90:93], v[126:129], v[122:125]
	v_mfma_f32_16x16x32_bf16 v[78:81], v[90:93], v[138:141], v[78:81]
	ds_read_b128 v[90:93], v28 offset:6144
	s_waitcnt lgkmcnt(0)
	v_mfma_f32_16x16x32_bf16 v[34:37], v[90:93], v[82:85], v[34:37]
	ds_read_b128 v[82:85], v33
	v_mfma_f32_16x16x32_bf16 v[42:45], v[90:93], v[94:97], v[42:45]
	ds_read_b128 v[94:97], v32 offset:34816
	v_mfma_f32_16x16x32_bf16 v[50:53], v[90:93], v[126:129], v[50:53]
	ds_read_b128 v[126:129], v32 offset:36864
	v_mfma_f32_16x16x32_bf16 v[58:61], v[90:93], v[138:141], v[58:61]
	ds_read_b128 v[90:93], v32 offset:32768
	ds_read_b128 v[138:141], v32 offset:38912
	s_waitcnt lgkmcnt(1)
	v_mfma_f32_16x16x32_bf16 v[38:41], v[82:85], v[90:93], v[38:41]
	v_mfma_f32_16x16x32_bf16 v[46:49], v[82:85], v[94:97], v[46:49]
	v_mfma_f32_16x16x32_bf16 v[54:57], v[82:85], v[126:129], v[54:57]
	s_waitcnt lgkmcnt(0)
	v_mfma_f32_16x16x32_bf16 v[70:73], v[82:85], v[138:141], v[70:73]
	ds_read_b128 v[82:85], v33 offset:2048
	s_waitcnt lgkmcnt(0)
	v_mfma_f32_16x16x32_bf16 v[98:101], v[82:85], v[90:93], v[98:101]
	v_mfma_f32_16x16x32_bf16 v[102:105], v[82:85], v[94:97], v[102:105]
	v_mfma_f32_16x16x32_bf16 v[106:109], v[82:85], v[126:129], v[106:109]
	v_mfma_f32_16x16x32_bf16 v[74:77], v[82:85], v[138:141], v[74:77]
	ds_read_b128 v[82:85], v33 offset:4096
	s_waitcnt lgkmcnt(0)
	v_mfma_f32_16x16x32_bf16 v[114:117], v[82:85], v[90:93], v[114:117]
	v_mfma_f32_16x16x32_bf16 v[118:121], v[82:85], v[94:97], v[118:121]
	v_mfma_f32_16x16x32_bf16 v[122:125], v[82:85], v[126:129], v[122:125]
	v_mfma_f32_16x16x32_bf16 v[78:81], v[82:85], v[138:141], v[78:81]
	ds_read_b128 v[82:85], v33 offset:6144
	s_waitcnt lgkmcnt(0)
	v_mfma_f32_16x16x32_bf16 v[34:37], v[82:85], v[90:93], v[34:37]
	v_mfma_f32_16x16x32_bf16 v[42:45], v[82:85], v[94:97], v[42:45]
	global_load_dwordx4 v[90:93], v[2:3], off offset:1536
	global_load_dwordx4 v[94:97], v[4:5], off offset:1536
	global_load_dwordx4 v[142:145], v[6:7], off offset:1536
	global_load_dwordx4 v[154:157], v[8:9], off offset:1536
	s_waitcnt vmcnt(7)
	ds_write_b128 v30, v[18:21] offset:16384
	s_waitcnt vmcnt(6)
	ds_write_b128 v30, v[22:25] offset:20480
	s_waitcnt vmcnt(5)
	ds_write_b128 v30, v[62:65] offset:24576
	s_waitcnt vmcnt(4)
	ds_write_b128 v30, v[66:69] offset:28672
	ds_write_b128 v30, v[86:89] offset:49152
	ds_write_b128 v30, v[110:113] offset:53248
	ds_write_b128 v30, v[146:149] offset:57344
	ds_write_b128 v30, v[150:153] offset:61440
	global_load_dwordx4 v[18:21], v[10:11], off offset:768
	global_load_dwordx4 v[22:25], v[12:13], off offset:768
	global_load_dwordx4 v[62:65], v[14:15], off offset:768
	global_load_dwordx4 v[66:69], v[16:17], off offset:768
	s_waitcnt lgkmcnt(0)
	s_barrier
	ds_read_b128 v[86:89], v28 offset:16384
	v_mfma_f32_16x16x32_bf16 v[50:53], v[82:85], v[126:129], v[50:53]
	ds_read_b128 v[110:113], v31 offset:51200
	ds_read_b128 v[126:129], v31 offset:53248
	v_mfma_f32_16x16x32_bf16 v[58:61], v[82:85], v[138:141], v[58:61]
	ds_read_b128 v[82:85], v31 offset:49152
	ds_read_b128 v[138:141], v31 offset:55296
	s_waitcnt lgkmcnt(1)
	v_mfma_f32_16x16x32_bf16 v[38:41], v[86:89], v[82:85], v[38:41]
	v_mfma_f32_16x16x32_bf16 v[46:49], v[86:89], v[110:113], v[46:49]
	v_mfma_f32_16x16x32_bf16 v[54:57], v[86:89], v[126:129], v[54:57]
	s_waitcnt lgkmcnt(0)
	v_mfma_f32_16x16x32_bf16 v[70:73], v[86:89], v[138:141], v[70:73]
	ds_read_b128 v[86:89], v28 offset:18432
	s_waitcnt lgkmcnt(0)
	v_mfma_f32_16x16x32_bf16 v[98:101], v[86:89], v[82:85], v[98:101]
	v_mfma_f32_16x16x32_bf16 v[102:105], v[86:89], v[110:113], v[102:105]
	v_mfma_f32_16x16x32_bf16 v[106:109], v[86:89], v[126:129], v[106:109]
	v_mfma_f32_16x16x32_bf16 v[74:77], v[86:89], v[138:141], v[74:77]
	ds_read_b128 v[86:89], v28 offset:20480
	s_waitcnt lgkmcnt(0)
	v_mfma_f32_16x16x32_bf16 v[114:117], v[86:89], v[82:85], v[114:117]
	v_mfma_f32_16x16x32_bf16 v[118:121], v[86:89], v[110:113], v[118:121]
	v_mfma_f32_16x16x32_bf16 v[122:125], v[86:89], v[126:129], v[122:125]
	v_mfma_f32_16x16x32_bf16 v[78:81], v[86:89], v[138:141], v[78:81]
	ds_read_b128 v[86:89], v28 offset:22528
	s_waitcnt lgkmcnt(0)
	v_mfma_f32_16x16x32_bf16 v[34:37], v[86:89], v[82:85], v[34:37]
	ds_read_b128 v[82:85], v33 offset:16384
	v_mfma_f32_16x16x32_bf16 v[42:45], v[86:89], v[110:113], v[42:45]
	ds_read_b128 v[110:113], v32 offset:51200
	v_mfma_f32_16x16x32_bf16 v[50:53], v[86:89], v[126:129], v[50:53]
	ds_read_b128 v[126:129], v32 offset:53248
	v_mfma_f32_16x16x32_bf16 v[58:61], v[86:89], v[138:141], v[58:61]
	ds_read_b128 v[86:89], v32 offset:49152
	ds_read_b128 v[138:141], v32 offset:55296
	s_waitcnt lgkmcnt(1)
	v_mfma_f32_16x16x32_bf16 v[38:41], v[82:85], v[86:89], v[38:41]
	v_mfma_f32_16x16x32_bf16 v[46:49], v[82:85], v[110:113], v[46:49]
	v_mfma_f32_16x16x32_bf16 v[54:57], v[82:85], v[126:129], v[54:57]
	s_waitcnt lgkmcnt(0)
	v_mfma_f32_16x16x32_bf16 v[70:73], v[82:85], v[138:141], v[70:73]
	ds_read_b128 v[82:85], v33 offset:18432
	s_waitcnt lgkmcnt(0)
	v_mfma_f32_16x16x32_bf16 v[98:101], v[82:85], v[86:89], v[98:101]
	v_mfma_f32_16x16x32_bf16 v[102:105], v[82:85], v[110:113], v[102:105]
	v_mfma_f32_16x16x32_bf16 v[106:109], v[82:85], v[126:129], v[106:109]
	v_mfma_f32_16x16x32_bf16 v[74:77], v[82:85], v[138:141], v[74:77]
	ds_read_b128 v[82:85], v33 offset:20480
	s_waitcnt lgkmcnt(0)
	v_mfma_f32_16x16x32_bf16 v[114:117], v[82:85], v[86:89], v[114:117]
	v_mfma_f32_16x16x32_bf16 v[118:121], v[82:85], v[110:113], v[118:121]
	v_mfma_f32_16x16x32_bf16 v[122:125], v[82:85], v[126:129], v[122:125]
	v_mfma_f32_16x16x32_bf16 v[78:81], v[82:85], v[138:141], v[78:81]
	ds_read_b128 v[82:85], v33 offset:22528
	s_waitcnt lgkmcnt(0)
	v_mfma_f32_16x16x32_bf16 v[34:37], v[82:85], v[86:89], v[34:37]
	v_mfma_f32_16x16x32_bf16 v[42:45], v[82:85], v[110:113], v[42:45]
	global_load_dwordx4 v[86:89], v[2:3], off offset:1664
	global_load_dwordx4 v[110:113], v[4:5], off offset:1664
	global_load_dwordx4 v[146:149], v[6:7], off offset:1664
	global_load_dwordx4 v[150:153], v[8:9], off offset:1664
	s_waitcnt vmcnt(7)
	ds_write_b128 v30, v[18:21]
	s_waitcnt vmcnt(6)
	ds_write_b128 v30, v[22:25] offset:4096
	s_waitcnt vmcnt(5)
	ds_write_b128 v30, v[62:65] offset:8192
	s_waitcnt vmcnt(4)
	ds_write_b128 v30, v[66:69] offset:12288
	ds_write_b128 v30, v[90:93] offset:32768
	ds_write_b128 v30, v[94:97] offset:36864
	ds_write_b128 v30, v[142:145] offset:40960
	ds_write_b128 v30, v[154:157] offset:45056
	global_load_dwordx4 v[18:21], v[10:11], off offset:896
	global_load_dwordx4 v[22:25], v[12:13], off offset:896
	global_load_dwordx4 v[62:65], v[14:15], off offset:896
	global_load_dwordx4 v[66:69], v[16:17], off offset:896
	s_waitcnt lgkmcnt(0)
	s_barrier
	ds_read_b128 v[90:93], v28
	v_mfma_f32_16x16x32_bf16 v[50:53], v[82:85], v[126:129], v[50:53]
	ds_read_b128 v[94:97], v31 offset:34816
	ds_read_b128 v[126:129], v31 offset:36864
	v_mfma_f32_16x16x32_bf16 v[58:61], v[82:85], v[138:141], v[58:61]
	ds_read_b128 v[82:85], v31 offset:32768
	ds_read_b128 v[138:141], v31 offset:38912
	s_waitcnt lgkmcnt(1)
	v_mfma_f32_16x16x32_bf16 v[38:41], v[90:93], v[82:85], v[38:41]
	v_mfma_f32_16x16x32_bf16 v[46:49], v[90:93], v[94:97], v[46:49]
	v_mfma_f32_16x16x32_bf16 v[54:57], v[90:93], v[126:129], v[54:57]
	s_waitcnt lgkmcnt(0)
	v_mfma_f32_16x16x32_bf16 v[70:73], v[90:93], v[138:141], v[70:73]
	ds_read_b128 v[90:93], v28 offset:2048
	s_waitcnt lgkmcnt(0)
	v_mfma_f32_16x16x32_bf16 v[98:101], v[90:93], v[82:85], v[98:101]
	v_mfma_f32_16x16x32_bf16 v[102:105], v[90:93], v[94:97], v[102:105]
	v_mfma_f32_16x16x32_bf16 v[106:109], v[90:93], v[126:129], v[106:109]
	v_mfma_f32_16x16x32_bf16 v[74:77], v[90:93], v[138:141], v[74:77]
	ds_read_b128 v[90:93], v28 offset:4096
	s_waitcnt lgkmcnt(0)
	v_mfma_f32_16x16x32_bf16 v[114:117], v[90:93], v[82:85], v[114:117]
	v_mfma_f32_16x16x32_bf16 v[118:121], v[90:93], v[94:97], v[118:121]
	v_mfma_f32_16x16x32_bf16 v[122:125], v[90:93], v[126:129], v[122:125]
	v_mfma_f32_16x16x32_bf16 v[78:81], v[90:93], v[138:141], v[78:81]
	ds_read_b128 v[90:93], v28 offset:6144
	s_waitcnt lgkmcnt(0)
	v_mfma_f32_16x16x32_bf16 v[34:37], v[90:93], v[82:85], v[34:37]
	ds_read_b128 v[82:85], v33
	v_mfma_f32_16x16x32_bf16 v[42:45], v[90:93], v[94:97], v[42:45]
	ds_read_b128 v[94:97], v32 offset:34816
	v_mfma_f32_16x16x32_bf16 v[50:53], v[90:93], v[126:129], v[50:53]
	ds_read_b128 v[126:129], v32 offset:36864
	v_mfma_f32_16x16x32_bf16 v[58:61], v[90:93], v[138:141], v[58:61]
	ds_read_b128 v[90:93], v32 offset:32768
	ds_read_b128 v[138:141], v32 offset:38912
	s_waitcnt lgkmcnt(1)
	v_mfma_f32_16x16x32_bf16 v[38:41], v[82:85], v[90:93], v[38:41]
	v_mfma_f32_16x16x32_bf16 v[46:49], v[82:85], v[94:97], v[46:49]
	v_mfma_f32_16x16x32_bf16 v[54:57], v[82:85], v[126:129], v[54:57]
	s_waitcnt lgkmcnt(0)
	v_mfma_f32_16x16x32_bf16 v[70:73], v[82:85], v[138:141], v[70:73]
	ds_read_b128 v[82:85], v33 offset:2048
	s_waitcnt lgkmcnt(0)
	v_mfma_f32_16x16x32_bf16 v[98:101], v[82:85], v[90:93], v[98:101]
	v_mfma_f32_16x16x32_bf16 v[102:105], v[82:85], v[94:97], v[102:105]
	v_mfma_f32_16x16x32_bf16 v[106:109], v[82:85], v[126:129], v[106:109]
	v_mfma_f32_16x16x32_bf16 v[74:77], v[82:85], v[138:141], v[74:77]
	ds_read_b128 v[82:85], v33 offset:4096
	s_waitcnt lgkmcnt(0)
	v_mfma_f32_16x16x32_bf16 v[114:117], v[82:85], v[90:93], v[114:117]
	v_mfma_f32_16x16x32_bf16 v[118:121], v[82:85], v[94:97], v[118:121]
	v_mfma_f32_16x16x32_bf16 v[122:125], v[82:85], v[126:129], v[122:125]
	v_mfma_f32_16x16x32_bf16 v[78:81], v[82:85], v[138:141], v[78:81]
	ds_read_b128 v[82:85], v33 offset:6144
	s_waitcnt lgkmcnt(0)
	v_mfma_f32_16x16x32_bf16 v[34:37], v[82:85], v[90:93], v[34:37]
	v_mfma_f32_16x16x32_bf16 v[42:45], v[82:85], v[94:97], v[42:45]
	global_load_dwordx4 v[90:93], v[2:3], off offset:1792
	global_load_dwordx4 v[94:97], v[4:5], off offset:1792
	global_load_dwordx4 v[142:145], v[6:7], off offset:1792
	global_load_dwordx4 v[154:157], v[8:9], off offset:1792
	s_waitcnt vmcnt(7)
	ds_write_b128 v30, v[18:21] offset:16384
	s_waitcnt vmcnt(6)
	ds_write_b128 v30, v[22:25] offset:20480
	s_waitcnt vmcnt(5)
	ds_write_b128 v30, v[62:65] offset:24576
	s_waitcnt vmcnt(4)
	ds_write_b128 v30, v[66:69] offset:28672
	ds_write_b128 v30, v[86:89] offset:49152
	ds_write_b128 v30, v[110:113] offset:53248
	ds_write_b128 v30, v[146:149] offset:57344
	ds_write_b128 v30, v[150:153] offset:61440
	global_load_dwordx4 v[18:21], v[10:11], off offset:1024
	global_load_dwordx4 v[22:25], v[12:13], off offset:1024
	global_load_dwordx4 v[62:65], v[14:15], off offset:1024
	global_load_dwordx4 v[66:69], v[16:17], off offset:1024
	s_waitcnt lgkmcnt(0)
	s_barrier
	ds_read_b128 v[86:89], v28 offset:16384
	v_mfma_f32_16x16x32_bf16 v[50:53], v[82:85], v[126:129], v[50:53]
	ds_read_b128 v[110:113], v31 offset:51200
	ds_read_b128 v[126:129], v31 offset:53248
	v_mfma_f32_16x16x32_bf16 v[58:61], v[82:85], v[138:141], v[58:61]
	ds_read_b128 v[82:85], v31 offset:49152
	ds_read_b128 v[138:141], v31 offset:55296
	s_waitcnt lgkmcnt(1)
	v_mfma_f32_16x16x32_bf16 v[38:41], v[86:89], v[82:85], v[38:41]
	v_mfma_f32_16x16x32_bf16 v[46:49], v[86:89], v[110:113], v[46:49]
	v_mfma_f32_16x16x32_bf16 v[54:57], v[86:89], v[126:129], v[54:57]
	s_waitcnt lgkmcnt(0)
	v_mfma_f32_16x16x32_bf16 v[70:73], v[86:89], v[138:141], v[70:73]
	ds_read_b128 v[86:89], v28 offset:18432
	s_waitcnt lgkmcnt(0)
	v_mfma_f32_16x16x32_bf16 v[98:101], v[86:89], v[82:85], v[98:101]
	v_mfma_f32_16x16x32_bf16 v[102:105], v[86:89], v[110:113], v[102:105]
	v_mfma_f32_16x16x32_bf16 v[106:109], v[86:89], v[126:129], v[106:109]
	v_mfma_f32_16x16x32_bf16 v[74:77], v[86:89], v[138:141], v[74:77]
	ds_read_b128 v[86:89], v28 offset:20480
	s_waitcnt lgkmcnt(0)
	v_mfma_f32_16x16x32_bf16 v[114:117], v[86:89], v[82:85], v[114:117]
	v_mfma_f32_16x16x32_bf16 v[118:121], v[86:89], v[110:113], v[118:121]
	v_mfma_f32_16x16x32_bf16 v[122:125], v[86:89], v[126:129], v[122:125]
	v_mfma_f32_16x16x32_bf16 v[78:81], v[86:89], v[138:141], v[78:81]
	ds_read_b128 v[86:89], v28 offset:22528
	s_waitcnt lgkmcnt(0)
	v_mfma_f32_16x16x32_bf16 v[34:37], v[86:89], v[82:85], v[34:37]
	ds_read_b128 v[82:85], v33 offset:16384
	v_mfma_f32_16x16x32_bf16 v[42:45], v[86:89], v[110:113], v[42:45]
	ds_read_b128 v[110:113], v32 offset:51200
	v_mfma_f32_16x16x32_bf16 v[50:53], v[86:89], v[126:129], v[50:53]
	ds_read_b128 v[126:129], v32 offset:53248
	v_mfma_f32_16x16x32_bf16 v[58:61], v[86:89], v[138:141], v[58:61]
	ds_read_b128 v[86:89], v32 offset:49152
	ds_read_b128 v[138:141], v32 offset:55296
	s_waitcnt lgkmcnt(1)
	v_mfma_f32_16x16x32_bf16 v[38:41], v[82:85], v[86:89], v[38:41]
	v_mfma_f32_16x16x32_bf16 v[46:49], v[82:85], v[110:113], v[46:49]
	v_mfma_f32_16x16x32_bf16 v[54:57], v[82:85], v[126:129], v[54:57]
	s_waitcnt lgkmcnt(0)
	v_mfma_f32_16x16x32_bf16 v[70:73], v[82:85], v[138:141], v[70:73]
	ds_read_b128 v[82:85], v33 offset:18432
	s_waitcnt lgkmcnt(0)
	v_mfma_f32_16x16x32_bf16 v[98:101], v[82:85], v[86:89], v[98:101]
	v_mfma_f32_16x16x32_bf16 v[102:105], v[82:85], v[110:113], v[102:105]
	v_mfma_f32_16x16x32_bf16 v[106:109], v[82:85], v[126:129], v[106:109]
	v_mfma_f32_16x16x32_bf16 v[74:77], v[82:85], v[138:141], v[74:77]
	ds_read_b128 v[82:85], v33 offset:20480
	s_waitcnt lgkmcnt(0)
	v_mfma_f32_16x16x32_bf16 v[114:117], v[82:85], v[86:89], v[114:117]
	v_mfma_f32_16x16x32_bf16 v[118:121], v[82:85], v[110:113], v[118:121]
	v_mfma_f32_16x16x32_bf16 v[122:125], v[82:85], v[126:129], v[122:125]
	v_mfma_f32_16x16x32_bf16 v[78:81], v[82:85], v[138:141], v[78:81]
	ds_read_b128 v[82:85], v33 offset:22528
	s_waitcnt lgkmcnt(0)
	v_mfma_f32_16x16x32_bf16 v[34:37], v[82:85], v[86:89], v[34:37]
	v_mfma_f32_16x16x32_bf16 v[42:45], v[82:85], v[110:113], v[42:45]
	global_load_dwordx4 v[86:89], v[2:3], off offset:1920
	s_nop 0
	global_load_dwordx4 v[2:5], v[4:5], off offset:1920
	s_nop 0
	global_load_dwordx4 v[110:113], v[6:7], off offset:1920
	s_nop 0
	global_load_dwordx4 v[6:9], v[8:9], off offset:1920
	s_waitcnt vmcnt(7)
	ds_write_b128 v30, v[18:21]
	s_waitcnt vmcnt(6)
	ds_write_b128 v30, v[22:25] offset:4096
	s_waitcnt vmcnt(5)
	ds_write_b128 v30, v[62:65] offset:8192
	s_waitcnt vmcnt(4)
	ds_write_b128 v30, v[66:69] offset:12288
	ds_write_b128 v30, v[90:93] offset:32768
	ds_write_b128 v30, v[94:97] offset:36864
	ds_write_b128 v30, v[142:145] offset:40960
	ds_write_b128 v30, v[154:157] offset:45056
	global_load_dwordx4 v[18:21], v[10:11], off offset:1152
	s_nop 0
	global_load_dwordx4 v[10:13], v[12:13], off offset:1152
	s_nop 0
	global_load_dwordx4 v[22:25], v[14:15], off offset:1152
	s_nop 0
	global_load_dwordx4 v[14:17], v[16:17], off offset:1152
	s_waitcnt lgkmcnt(0)
	s_barrier
	ds_read_b128 v[62:65], v28
	ds_read_b128 v[66:69], v31 offset:32768
	v_mfma_f32_16x16x32_bf16 v[50:53], v[82:85], v[126:129], v[50:53]
	ds_read_b128 v[90:93], v31 offset:36864
	ds_read_b128 v[94:97], v31 offset:38912
	v_mfma_f32_16x16x32_bf16 v[58:61], v[82:85], v[138:141], v[58:61]
	ds_read_b128 v[82:85], v31 offset:34816
	s_waitcnt lgkmcnt(3)
	v_mfma_f32_16x16x32_bf16 v[38:41], v[62:65], v[66:69], v[38:41]
	s_waitcnt lgkmcnt(0)
	v_mfma_f32_16x16x32_bf16 v[46:49], v[62:65], v[82:85], v[46:49]
	v_mfma_f32_16x16x32_bf16 v[54:57], v[62:65], v[90:93], v[54:57]
	v_mfma_f32_16x16x32_bf16 v[62:65], v[62:65], v[94:97], v[70:73]
	s_nop 2
	ds_read_b128 v[70:73], v28 offset:2048
	s_waitcnt lgkmcnt(0)
	v_mfma_f32_16x16x32_bf16 v[98:101], v[70:73], v[66:69], v[98:101]
	v_mfma_f32_16x16x32_bf16 v[102:105], v[70:73], v[82:85], v[102:105]
	v_mfma_f32_16x16x32_bf16 v[106:109], v[70:73], v[90:93], v[106:109]
	v_mfma_f32_16x16x32_bf16 v[70:73], v[70:73], v[94:97], v[74:77]
	s_nop 2
	ds_read_b128 v[74:77], v28 offset:4096
	s_waitcnt lgkmcnt(0)
	v_mfma_f32_16x16x32_bf16 v[114:117], v[74:77], v[66:69], v[114:117]
	v_mfma_f32_16x16x32_bf16 v[118:121], v[74:77], v[82:85], v[118:121]
	v_mfma_f32_16x16x32_bf16 v[122:125], v[74:77], v[90:93], v[122:125]
	v_mfma_f32_16x16x32_bf16 v[74:77], v[74:77], v[94:97], v[78:81]
	s_nop 2
	ds_read_b128 v[78:81], v28 offset:6144
	s_waitcnt lgkmcnt(0)
	v_mfma_f32_16x16x32_bf16 v[34:37], v[78:81], v[66:69], v[34:37]
	ds_read_b128 v[66:69], v33
	v_mfma_f32_16x16x32_bf16 v[42:45], v[78:81], v[82:85], v[42:45]
	ds_read_b128 v[82:85], v32 offset:34816
	v_mfma_f32_16x16x32_bf16 v[50:53], v[78:81], v[90:93], v[50:53]
	ds_read_b128 v[90:93], v32 offset:36864
	v_mfma_f32_16x16x32_bf16 v[58:61], v[78:81], v[94:97], v[58:61]
	ds_read_b128 v[78:81], v32 offset:32768
	ds_read_b128 v[94:97], v32 offset:38912
	s_waitcnt lgkmcnt(1)
	v_mfma_f32_16x16x32_bf16 v[38:41], v[66:69], v[78:81], v[38:41]
	v_mfma_f32_16x16x32_bf16 v[46:49], v[66:69], v[82:85], v[46:49]
	v_mfma_f32_16x16x32_bf16 v[54:57], v[66:69], v[90:93], v[54:57]
	s_waitcnt lgkmcnt(0)
	v_mfma_f32_16x16x32_bf16 v[62:65], v[66:69], v[94:97], v[62:65]
	ds_read_b128 v[66:69], v33 offset:2048
	s_waitcnt lgkmcnt(0)
	v_mfma_f32_16x16x32_bf16 v[98:101], v[66:69], v[78:81], v[98:101]
	v_mfma_f32_16x16x32_bf16 v[102:105], v[66:69], v[82:85], v[102:105]
	v_mfma_f32_16x16x32_bf16 v[106:109], v[66:69], v[90:93], v[106:109]
	v_mfma_f32_16x16x32_bf16 v[66:69], v[66:69], v[94:97], v[70:73]
	s_nop 2
	ds_read_b128 v[70:73], v33 offset:4096
	s_waitcnt lgkmcnt(0)
	v_mfma_f32_16x16x32_bf16 v[114:117], v[70:73], v[78:81], v[114:117]
	v_mfma_f32_16x16x32_bf16 v[118:121], v[70:73], v[82:85], v[118:121]
	v_mfma_f32_16x16x32_bf16 v[122:125], v[70:73], v[90:93], v[122:125]
	v_mfma_f32_16x16x32_bf16 v[70:73], v[70:73], v[94:97], v[74:77]
	s_nop 2
	ds_read_b128 v[74:77], v33 offset:6144
	s_waitcnt vmcnt(3)
	ds_write_b128 v30, v[18:21] offset:16384
	s_waitcnt vmcnt(2)
	ds_write_b128 v30, v[10:13] offset:20480
	s_waitcnt vmcnt(1)
	ds_write_b128 v30, v[22:25] offset:24576
	s_waitcnt vmcnt(0)
	ds_write_b128 v30, v[14:17] offset:28672
	ds_write_b128 v30, v[86:89] offset:49152
	ds_write_b128 v30, v[2:5] offset:53248
	ds_write_b128 v30, v[110:113] offset:57344
	ds_write_b128 v30, v[6:9] offset:61440
	s_waitcnt lgkmcnt(0)
	s_barrier
	ds_read_b128 v[2:5], v28 offset:16384
	ds_read_b128 v[10:13], v31 offset:49152
	ds_read_b128 v[18:21], v31 offset:51200
	v_mfma_f32_16x16x32_bf16 v[6:9], v[74:77], v[94:97], v[58:61]
	s_nop 2
	ds_read_b128 v[58:61], v28 offset:18432
	s_waitcnt lgkmcnt(2)
	v_mfma_f32_16x16x32_bf16 v[14:17], v[2:5], v[10:13], v[38:41]
	s_nop 2
	ds_read_b128 v[38:41], v31 offset:53248
	s_waitcnt lgkmcnt(2)
	v_mfma_f32_16x16x32_bf16 v[22:25], v[2:5], v[18:21], v[46:49]
	s_waitcnt lgkmcnt(0)
	v_mfma_f32_16x16x32_bf16 v[46:49], v[2:5], v[38:41], v[54:57]
	s_nop 2
	ds_read_b128 v[54:57], v31 offset:55296
	v_mfma_f32_16x16x32_bf16 v[42:45], v[74:77], v[82:85], v[42:45]
	v_mfma_f32_16x16x32_bf16 v[50:53], v[74:77], v[90:93], v[50:53]
	s_waitcnt lgkmcnt(0)
	v_mfma_f32_16x16x32_bf16 v[2:5], v[2:5], v[54:57], v[62:65]
	v_mfma_f32_16x16x32_bf16 v[82:85], v[58:61], v[10:13], v[98:101]
	s_nop 1
	ds_read_b128 v[62:65], v28 offset:22528
	v_mfma_f32_16x16x32_bf16 v[86:89], v[58:61], v[18:21], v[102:105]
	v_mfma_f32_16x16x32_bf16 v[90:93], v[58:61], v[38:41], v[106:109]
	v_mfma_f32_16x16x32_bf16 v[94:97], v[58:61], v[54:57], v[66:69]
	ds_read_b128 v[58:61], v28 offset:20480
	s_nop 1
	ds_read_b128 v[66:69], v33 offset:16384
	ds_read_b128 v[106:109], v33 offset:18432
	ds_read_b128 v[110:113], v32 offset:49152
	v_mfma_f32_16x16x32_bf16 v[34:37], v[74:77], v[78:81], v[34:37]
	v_lshl_or_b32 v77, v29, 2, v1
	v_cmp_gt_i32_e32 vcc, s0, v77
	v_bfrev_b32_e32 v81, 0.5
	s_waitcnt lgkmcnt(3)
	v_mfma_f32_16x16x32_bf16 v[98:101], v[58:61], v[10:13], v[114:117]
	v_lshrrev_b32_e32 v76, 6, v1
	v_readlane_b32 s0, v254, 5
	v_readlane_b32 s1, v254, 6
	v_mfma_f32_16x16x32_bf16 v[102:105], v[58:61], v[18:21], v[118:121]
	v_mov_b32_e32 v80, 3
	v_mov_b32_e32 v79, 2
	v_mfma_f32_16x16x32_bf16 v[114:117], v[58:61], v[38:41], v[122:125]
	ds_read_b128 v[118:121], v32 offset:51200
	s_nop 1
	ds_read_b128 v[122:125], v33 offset:20480
	ds_read_b128 v[126:129], v33 offset:22528
	ds_read_b128 v[142:145], v32 offset:53248
	ds_read_b128 v[146:149], v32 offset:55296
	s_waitcnt lgkmcnt(0)
	v_mfma_f32_16x16x32_bf16 v[138:141], v[58:61], v[54:57], v[70:73]
	s_barrier
	s_nop 1
	v_mov_b32_e32 v71, 0x7fffff00
	v_mfma_f32_16x16x32_bf16 v[162:165], v[62:65], v[54:57], v[6:9]
	s_nop 2
	v_cndmask_b32_e64 v8, 2, 6, vcc
	v_cndmask_b32_e32 v6, v71, v207, vcc
	v_cndmask_b32_e64 v7, 3, 63, vcc
	v_cndmask_b32_e32 v9, v81, v216, vcc
	v_mov_b32_e32 v137, v79
	v_mov_b32_e32 v158, v80
	v_mov_b32_e32 v159, v81
	v_mov_b32_e32 v160, v71
	v_lshlrev_b32_e32 v166, v8, v77
	v_lshlrev_b32_e32 v168, 6, v27
	v_and_b32_e32 v169, v6, v1
	v_and_b32_e32 v170, v7, v76
	v_and_b32_e32 v171, v166, v9
	v_or3_b32 v166, v168, s2, v26
	v_or3_b32 v168, v170, v169, v171
	v_ashrrev_i32_e32 v169, 31, v168
	v_lshlrev_b32_e32 v170, 1, v166
	v_lshlrev_b64 v[174:175], 10, v[168:169]
	v_mov_b32_e32 v168, 2
	v_mov_b32_e32 v176, v170
	v_mov_b32_e32 v177, v131
	v_lshl_add_u64 v[180:181], s[0:1], 0, v[176:177]
	s_movk_i32 s19, 0x3fff
	v_cmp_gt_i32_e64 s[62:63], s19, v77
	v_lshl_add_u64 v[170:171], v[180:181], 0, v[174:175]
	global_load_ushort v169, v[170:171], off
	v_or_b32_e32 v170, s90, v166
	v_ashrrev_i32_e32 v171, 31, v170
	v_lshl_add_u64 v[176:177], v[170:171], 2, s[8:9]
	global_load_dword v170, v[176:177], off
	v_mov_b32_e32 v171, 3
	v_mov_b32_e32 v172, 0x7fffff00
	v_bfrev_b32_e32 v176, 0.5
	s_and_saveexec_b64 s[64:65], s[62:63]
	v_mov_b32_e32 v176, 0xfc0
	v_mov_b32_e32 v137, 6
	v_mov_b32_e32 v158, 63
	v_mov_b32_e32 v172, 0xfffff000
	s_or_b64 exec, exec, s[64:65]
	s_movk_i32 s19, 0x3ffe
	v_cmp_gt_i32_e32 vcc, s19, v77
	v_or_b32_e32 v177, 1, v77
	v_or_b32_e32 v178, 2, v77
	v_cndmask_b32_e64 v182, 2, 6, vcc
	v_cndmask_b32_e32 v183, v71, v207, vcc
	v_cndmask_b32_e64 v184, 3, 63, vcc
	v_cndmask_b32_e32 v185, v81, v216, vcc
	v_lshlrev_b32_e32 v186, v182, v178
	v_lshlrev_b32_e32 v178, v137, v177
	v_and_b32_e32 v137, v183, v1
	v_and_b32_e32 v177, v184, v76
	v_and_b32_e32 v182, v186, v185
	v_and_b32_e32 v183, v172, v1
	v_and_b32_e32 v172, v158, v76
	v_and_b32_e32 v158, v178, v176
	v_or3_b32 v176, v177, v137, v182
	v_or3_b32 v137, v172, v183, v158
	v_ashrrev_i32_e32 v158, 31, v137
	v_mov_b32_e32 v182, v137
	v_mov_b32_e32 v183, v158
	v_lshlrev_b64 v[184:185], 10, v[182:183]
	v_lshl_add_u64 v[182:183], v[180:181], 0, v[184:185]
	global_load_ushort v137, v[182:183], off
	v_ashrrev_i32_e32 v158, 31, v176
	s_movk_i32 s19, 0x3ffd
	v_mov_b32_e32 v182, v176
	v_mov_b32_e32 v183, v158
	v_lshlrev_b64 v[184:185], 10, v[182:183]
	v_cmp_gt_i32_e64 s[62:63], s19, v77
	v_lshl_add_u64 v[176:177], v[180:181], 0, v[184:185]
	global_load_ushort v158, v[176:177], off
	s_and_saveexec_b64 s[64:65], s[62:63]
	v_mov_b32_e32 v159, 0xfc0
	v_mov_b32_e32 v168, 6
	v_mov_b32_e32 v171, 63
	v_mov_b32_e32 v160, 0xfffff000
	s_or_b64 exec, exec, s[64:65]
	v_or_b32_e32 v172, 3, v77
	v_lshlrev_b32_e32 v176, v168, v172
	v_and_b32_e32 v168, v160, v1
	v_and_b32_e32 v160, v171, v76
	v_and_b32_e32 v171, v176, v159
	v_or3_b32 v159, v160, v168, v171
	v_ashrrev_i32_e32 v160, 31, v159
	v_mov_b32_e32 v176, v159
	v_mov_b32_e32 v177, v160
	v_lshlrev_b64 v[182:183], 10, v[176:177]
	v_lshl_add_u64 v[176:177], v[180:181], 0, v[182:183]
	global_load_ushort v159, v[176:177], off
	v_readlane_b32 s19, v254, 5
	v_or_b32_e32 v160, 16, v166
	v_readlane_b32 s27, v254, 6
	v_lshlrev_b32_e32 v168, 1, v160
	s_mov_b32 s62, s19
	s_mov_b32 s63, s27
	v_lshl_add_u64 v[176:177], s[62:63], 0, v[174:175]
	v_mov_b32_e32 v174, v168
	v_mov_b32_e32 v175, v131
	v_lshl_add_u64 v[180:181], v[176:177], 0, v[174:175]
	global_load_ushort v160, v[180:181], off
	v_mov_b32_e32 v168, v131
	v_mov_b32_e32 v174, v166
	v_mov_b32_e32 v175, v168
	v_lshl_add_u64 v[176:177], v[174:175], 0, s[90:91]
	v_readlane_b32 s19, v253, 8
	v_readlane_b32 s27, v253, 9
	s_mov_b32 s62, s19
	s_mov_b32 s63, s27
	v_lshl_add_u64 v[174:175], v[176:177], 2, s[62:63]
	global_load_dword v166, v[174:175], off offset:64
	v_lshlrev_b32_e32 v8, v8, v77
	v_mfma_f32_16x16x32_bf16 v[150:153], v[62:65], v[18:21], v[42:45]
	v_lshlrev_b32_e32 v18, 6, v27
	v_and_b32_e32 v6, v6, v1
	v_and_b32_e32 v7, v7, v76
	v_and_b32_e32 v8, v8, v9
	v_or3_b32 v70, v18, s2, v26
	v_or3_b32 v6, v7, v6, v8
	v_ashrrev_i32_e32 v7, 31, v6
	v_lshlrev_b32_e32 v130, 1, v70
	v_mfma_f32_16x16x32_bf16 v[10:13], v[62:65], v[10:13], v[34:37]
	v_lshlrev_b64 v[74:75], 10, v[6:7]
	v_mfma_f32_16x16x32_bf16 v[154:157], v[62:65], v[38:41], v[50:53]
	v_mfma_f32_16x16x32_bf16 v[62:65], v[66:69], v[110:113], v[14:17]
	v_mfma_f32_16x16x32_bf16 v[58:61], v[66:69], v[118:121], v[22:25]
	v_mfma_f32_16x16x32_bf16 v[54:57], v[66:69], v[142:145], v[46:49]
	s_nop 5
	v_mov_b32_e32 v134, v62
	v_mov_b32_e32 v62, 2
	v_mfma_f32_16x16x32_bf16 v[50:53], v[66:69], v[146:149], v[2:5]
	v_lshl_add_u64 v[66:67], s[0:1], 0, v[130:131]
	s_movk_i32 s0, 0x3fff
	v_cmp_gt_i32_e64 s[14:15], s0, v77
	v_lshl_add_u64 v[2:3], v[66:67], 0, v[74:75]
	s_waitcnt vmcnt(0)
	v_mov_b32_e32 v6, v169
	v_or_b32_e32 v4, s90, v70
	v_ashrrev_i32_e32 v5, 31, v4
	v_lshl_add_u64 v[4:5], v[4:5], 2, s[8:9]
	v_mov_b32_e32 v68, v170
	v_mfma_f32_16x16x32_bf16 v[46:49], v[106:109], v[110:113], v[82:85]
	v_lshlrev_b32_e32 v6, 16, v6
	v_mul_f32_e32 v4, 0xbfb8aa3b, v6
	v_exp_f32_e32 v69, v4
	v_mfma_f32_16x16x32_bf16 v[42:45], v[106:109], v[118:121], v[86:89]
	v_mov_b32_e32 v82, 3
	v_mov_b32_e32 v83, 0x7fffff00
	v_pk_add_f32 v[4:5], v[134:135], v[68:69]
	v_mfma_f32_16x16x32_bf16 v[38:41], v[106:109], v[142:145], v[90:93]
	v_div_scale_f32 v7, s[2:3], v5, v5, v6
	v_rcp_f32_e32 v8, v7
	v_mfma_f32_16x16x32_bf16 v[34:37], v[106:109], v[146:149], v[94:97]
	v_fma_f32 v9, -v7, v8, 1.0
	v_fmac_f32_e32 v8, v9, v8
	v_div_scale_f32 v9, vcc, v6, v5, v6
	v_mul_f32_e32 v69, v9, v8
	v_fma_f32 v14, -v7, v69, v9
	v_fmac_f32_e32 v69, v14, v8
	v_fma_f32 v7, -v7, v69, v9
	v_div_fmas_f32 v7, v7, v8, v69
	v_div_fixup_f32 v5, v7, v5, v6
	v_mul_f32_e32 v4, v4, v5
	v_cvt_pk_bf16_f32 v4, v4, s0
	v_mfma_f32_16x16x32_bf16 v[30:33], v[122:125], v[110:113], v[98:101]
	global_store_short v[2:3], v4, off
	v_bfrev_b32_e32 v69, 0.5
	v_mfma_f32_16x16x32_bf16 v[26:29], v[122:125], v[118:121], v[102:105]
	v_mfma_f32_16x16x32_bf16 v[22:25], v[122:125], v[142:145], v[114:117]
	v_mfma_f32_16x16x32_bf16 v[18:21], v[122:125], v[146:149], v[138:141]
	v_mfma_f32_16x16x32_bf16 v[14:17], v[126:129], v[110:113], v[10:13]
	v_mfma_f32_16x16x32_bf16 v[10:13], v[126:129], v[118:121], v[150:153]
	v_mfma_f32_16x16x32_bf16 v[6:9], v[126:129], v[142:145], v[154:157]
	v_mfma_f32_16x16x32_bf16 v[2:5], v[126:129], v[146:149], v[162:165]
	s_and_saveexec_b64 s[2:3], s[14:15]
	v_mov_b32_e32 v69, 0xfc0
	v_mov_b32_e32 v79, 6
	v_mov_b32_e32 v80, 63
	v_mov_b32_e32 v83, 0xfffff000
	s_or_b64 exec, exec, s[2:3]
	s_movk_i32 s0, 0x3ffe
	v_cmp_gt_i32_e32 vcc, s0, v77
	v_or_b32_e32 v78, 1, v77
	v_or_b32_e32 v72, 2, v77
	v_cndmask_b32_e64 v85, 2, 6, vcc
	v_cndmask_b32_e32 v73, v71, v207, vcc
	v_cndmask_b32_e64 v84, 3, 63, vcc
	v_cndmask_b32_e32 v86, v81, v216, vcc
	v_lshlrev_b32_e32 v72, v85, v72
	v_lshlrev_b32_e32 v79, v79, v78
	v_and_b32_e32 v73, v73, v1
	v_and_b32_e32 v84, v84, v76
	v_and_b32_e32 v72, v72, v86
	v_and_b32_e32 v83, v83, v1
	v_and_b32_e32 v80, v80, v76
	v_and_b32_e32 v69, v79, v69
	v_or3_b32 v72, v84, v73, v72
	v_or3_b32 v84, v80, v83, v69
	v_ashrrev_i32_e32 v85, 31, v84
	v_lshlrev_b64 v[84:85], 10, v[84:85]
	v_lshl_add_u64 v[84:85], v[66:67], 0, v[84:85]
	v_mov_b32_e32 v69, v137
	v_add_f32_e32 v63, v63, v68
	v_ashrrev_i32_e32 v73, 31, v72
	s_movk_i32 s0, 0x3ffd
	v_lshlrev_b64 v[72:73], 10, v[72:73]
	v_add_f32_e32 v64, v64, v68
	v_cmp_gt_i32_e64 s[10:11], s0, v77
	v_lshlrev_b32_e32 v69, 16, v69
	v_mul_f32_e32 v79, 0xbfb8aa3b, v69
	v_exp_f32_e32 v79, v79
	s_nop 0
	v_add_f32_e32 v79, 1.0, v79
	v_div_scale_f32 v80, s[6:7], v79, v79, v69
	v_rcp_f32_e32 v83, v80
	s_nop 0
	v_fma_f32 v86, -v80, v83, 1.0
	v_fmac_f32_e32 v83, v86, v83
	v_div_scale_f32 v86, vcc, v69, v79, v69
	v_mul_f32_e32 v87, v86, v83
	v_fma_f32 v88, -v80, v87, v86
	v_fmac_f32_e32 v87, v88, v83
	v_fma_f32 v80, -v80, v87, v86
	v_div_fmas_f32 v80, v80, v83, v87
	v_div_fixup_f32 v69, v80, v79, v69
	v_mul_f32_e32 v63, v63, v69
	v_cvt_pk_bf16_f32 v63, v63, s0
	global_store_short v[84:85], v63, off
	v_lshl_add_u64 v[84:85], v[66:67], 0, v[72:73]
	v_mov_b32_e32 v63, v158
	v_lshlrev_b32_e32 v63, 16, v63
	v_mul_f32_e32 v69, 0xbfb8aa3b, v63
	v_exp_f32_e32 v69, v69
	s_nop 0
	v_add_f32_e32 v69, 1.0, v69
	v_div_scale_f32 v79, s[6:7], v69, v69, v63
	v_rcp_f32_e32 v80, v79
	s_nop 0
	v_fma_f32 v83, -v79, v80, 1.0
	v_fmac_f32_e32 v80, v83, v80
	v_div_scale_f32 v83, vcc, v63, v69, v63
	v_mul_f32_e32 v86, v83, v80
	v_fma_f32 v87, -v79, v86, v83
	v_fmac_f32_e32 v86, v87, v80
	v_fma_f32 v79, -v79, v86, v83
	v_div_fmas_f32 v79, v79, v80, v86
	v_div_fixup_f32 v63, v79, v69, v63
	v_mul_f32_e32 v63, v64, v63
	v_cvt_pk_bf16_f32 v63, v63, s0
	global_store_short v[84:85], v63, off
	s_and_saveexec_b64 s[6:7], s[10:11]
	v_mov_b32_e32 v81, 0xfc0
	v_mov_b32_e32 v62, 6
	v_mov_b32_e32 v82, 63
	v_mov_b32_e32 v71, 0xfffff000
	s_or_b64 exec, exec, s[6:7]
	v_or_b32_e32 v79, 3, v77
	v_lshlrev_b32_e32 v62, v62, v79
	v_and_b32_e32 v63, v71, v1
	v_and_b32_e32 v64, v82, v76
	v_and_b32_e32 v62, v62, v81
	v_or3_b32 v62, v64, v63, v62
	v_ashrrev_i32_e32 v63, 31, v62
	v_lshlrev_b64 v[62:63], 10, v[62:63]
	v_lshl_add_u64 v[62:63], v[66:67], 0, v[62:63]
	v_mov_b32_e32 v64, v159
	v_add_f32_e32 v65, v65, v68
	v_mov_b32_e32 v80, 3
	v_lshlrev_b32_e32 v64, 16, v64
	v_mul_f32_e32 v69, 0xbfb8aa3b, v64
	v_exp_f32_e32 v69, v69
	s_nop 0
	v_add_f32_e32 v69, 1.0, v69
	v_div_scale_f32 v71, s[6:7], v69, v69, v64
	v_rcp_f32_e32 v81, v71
	s_nop 0
	v_fma_f32 v82, -v71, v81, 1.0
	v_fmac_f32_e32 v81, v82, v81
	v_div_scale_f32 v82, vcc, v64, v69, v64
	v_mul_f32_e32 v83, v82, v81
	v_fma_f32 v84, -v71, v83, v82
	v_fmac_f32_e32 v83, v84, v81
	v_fma_f32 v71, -v71, v83, v82
	v_div_fmas_f32 v71, v71, v81, v83
	v_div_fixup_f32 v64, v71, v69, v64
	v_mul_f32_e32 v64, v65, v64
	v_cvt_pk_bf16_f32 v64, v64, s0
	v_readlane_b32 s0, v253, 4
	v_readlane_b32 s1, v253, 5
	v_readlane_b32 s0, v254, 5
	v_or_b32_e32 v81, 16, v70
	v_readlane_b32 s1, v254, 6
	global_store_short v[62:63], v64, off
	v_lshlrev_b32_e32 v130, 1, v81
	v_lshl_add_u64 v[64:65], s[0:1], 0, v[74:75]
	v_lshl_add_u64 v[74:75], v[64:65], 0, v[130:131]
	v_mov_b32_e32 v81, v160
	v_mov_b32_e32 v71, v131
	v_lshl_add_u64 v[62:63], v[70:71], 0, s[90:91]
	v_readlane_b32 s4, v253, 8
	v_readlane_b32 s5, v253, 9
	v_readlane_b32 s6, v253, 10
	v_readlane_b32 s7, v253, 11
	v_lshl_add_u64 v[62:63], v[62:63], 2, s[4:5]
	v_mov_b32_e32 v69, v166
	v_mov_b32_e32 v71, 2
	v_readlane_b32 s2, v253, 6
	v_readlane_b32 s3, v253, 7
	v_lshlrev_b32_e32 v81, 16, v81
	v_mul_f32_e32 v82, 0xbfb8aa3b, v81
	v_mov_b32_e32 v89, v71
	v_mov_b32_e32 v90, v80
	v_bfrev_b32_e32 v91, 0.5
	v_mov_b32_e32 v92, 0x7fffff00
	v_mov_b32_e32 v93, 0x7fffff00
	v_mov_b32_e32 v94, 3
	v_mov_b32_e32 v95, 2
	v_bfrev_b32_e32 v96, 0.5
	s_and_saveexec_b64 s[62:63], s[14:15]
	v_mov_b32_e32 v96, 0xfc0
	v_mov_b32_e32 v95, 6
	v_mov_b32_e32 v94, 63
	v_mov_b32_e32 v93, 0xfffff000
	s_or_b64 exec, exec, s[62:63]
	v_lshlrev_b32_e32 v97, v95, v78
	v_and_b32_e32 v95, v93, v1
	v_and_b32_e32 v93, v94, v76
	v_and_b32_e32 v94, v97, v96
	v_or3_b32 v96, v93, v95, v94
	v_ashrrev_i32_e32 v93, 31, v96
	v_mov_b32_e32 v94, v96
	v_mov_b32_e32 v95, v93
	v_lshlrev_b64 v[98:99], 10, v[94:95]
	v_lshl_add_u64 v[94:95], s[0:1], 0, v[98:99]
	v_lshl_add_u64 v[96:97], v[94:95], 0, v[130:131]
	global_load_ushort v93, v[96:97], off
	v_lshl_add_u64 v[94:95], s[0:1], 0, v[72:73]
	v_lshl_add_u64 v[96:97], v[94:95], 0, v[130:131]
	global_load_ushort v98, v[96:97], off
	s_and_saveexec_b64 s[62:63], s[10:11]
	v_mov_b32_e32 v91, 0xfc0
	v_mov_b32_e32 v89, 6
	v_mov_b32_e32 v90, 63
	v_mov_b32_e32 v92, 0xfffff000
	s_or_b64 exec, exec, s[62:63]
	v_lshlrev_b32_e32 v96, v89, v79
	v_and_b32_e32 v89, v92, v1
	v_and_b32_e32 v92, v90, v76
	v_and_b32_e32 v90, v96, v91
	v_or3_b32 v91, v92, v89, v90
	v_ashrrev_i32_e32 v89, 31, v91
	v_mov_b32_e32 v96, v91
	v_mov_b32_e32 v97, v89
	v_lshlrev_b64 v[100:101], 10, v[96:97]
	v_lshl_add_u64 v[90:91], s[0:1], 0, v[100:101]
	v_lshl_add_u64 v[96:97], v[90:91], 0, v[130:131]
	global_load_ushort v89, v[96:97], off
	v_or_b32_e32 v90, 32, v70
	v_lshlrev_b32_e32 v91, 1, v90
	v_mov_b32_e32 v90, v131
	v_mov_b32_e32 v96, v91
	v_mov_b32_e32 v97, v90
	v_lshl_add_u64 v[100:101], v[64:65], 0, v[96:97]
	global_load_ushort v92, v[100:101], off
	global_load_dword v96, v[62:63], off offset:128
	v_bfrev_b32_e32 v97, 0.5
	v_mov_b32_e32 v99, 2
	v_mov_b32_e32 v100, 3
	v_mov_b32_e32 v101, 0x7fffff00
	v_mov_b32_e32 v102, 0x7fffff00
	v_mov_b32_e32 v103, 3
	v_mov_b32_e32 v104, 2
	v_bfrev_b32_e32 v105, 0.5
	s_and_saveexec_b64 s[62:63], s[14:15]
	v_mov_b32_e32 v105, 0xfc0
	v_mov_b32_e32 v104, 6
	v_mov_b32_e32 v103, 63
	v_mov_b32_e32 v102, 0xfffff000
	s_or_b64 exec, exec, s[62:63]
	v_lshlrev_b32_e32 v106, v104, v78
	v_and_b32_e32 v104, v102, v1
	v_and_b32_e32 v102, v103, v76
	v_and_b32_e32 v103, v106, v105
	v_or3_b32 v105, v102, v104, v103
	v_ashrrev_i32_e32 v102, 31, v105
	v_mov_b32_e32 v106, v105
	v_mov_b32_e32 v107, v102
	v_lshlrev_b64 v[108:109], 10, v[106:107]
	v_lshl_add_u64 v[102:103], s[0:1], 0, v[108:109]
	v_mov_b32_e32 v104, v91
	v_mov_b32_e32 v105, v90
	v_lshl_add_u64 v[106:107], v[102:103], 0, v[104:105]
	global_load_ushort v102, v[106:107], off
	v_mov_b32_e32 v104, v91
	v_mov_b32_e32 v105, v90
	v_lshl_add_u64 v[106:107], v[94:95], 0, v[104:105]
	global_load_ushort v90, v[106:107], off
	s_and_saveexec_b64 s[62:63], s[10:11]
	v_mov_b32_e32 v97, 0xfc0
	v_mov_b32_e32 v99, 6
	v_mov_b32_e32 v100, 63
	v_mov_b32_e32 v101, 0xfffff000
	s_or_b64 exec, exec, s[62:63]
	v_lshlrev_b32_e32 v103, v99, v79
	v_and_b32_e32 v99, v101, v1
	v_and_b32_e32 v101, v100, v76
	v_and_b32_e32 v100, v103, v97
	v_or3_b32 v97, v101, v99, v100
	v_ashrrev_i32_e32 v99, 31, v97
	v_mov_b32_e32 v100, v97
	v_mov_b32_e32 v101, v99
	v_lshlrev_b64 v[104:105], 10, v[100:101]
	v_lshl_add_u64 v[100:101], s[0:1], 0, v[104:105]
	v_mov_b32_e32 v97, v131
	v_mov_b32_e32 v104, v91
	v_mov_b32_e32 v105, v97
	v_lshl_add_u64 v[106:107], v[100:101], 0, v[104:105]
	global_load_ushort v97, v[106:107], off
	v_or_b32_e32 v99, 48, v70
	v_lshlrev_b32_e32 v100, 1, v99
	v_mov_b32_e32 v99, v131
	global_load_dword v101, v[62:63], off offset:192
	v_mov_b32_e32 v104, v100
	v_mov_b32_e32 v105, v99
	v_lshl_add_u64 v[106:107], v[64:65], 0, v[104:105]
	global_load_ushort v103, v[106:107], off
	v_bfrev_b32_e32 v104, 0.5
	v_mov_b32_e32 v105, 2
	v_mov_b32_e32 v106, 3
	v_mov_b32_e32 v107, 0x7fffff00
	v_mov_b32_e32 v108, 0x7fffff00
	v_mov_b32_e32 v109, 3
	v_mov_b32_e32 v110, 2
	v_bfrev_b32_e32 v111, 0.5
	s_and_saveexec_b64 s[62:63], s[14:15]
	v_mov_b32_e32 v111, 0xfc0
	v_mov_b32_e32 v110, 6
	v_mov_b32_e32 v109, 63
	v_mov_b32_e32 v108, 0xfffff000
	s_or_b64 exec, exec, s[62:63]
	v_lshlrev_b32_e32 v112, v110, v78
	v_and_b32_e32 v110, v108, v1
	v_and_b32_e32 v108, v109, v76
	v_and_b32_e32 v109, v112, v111
	v_or3_b32 v111, v108, v110, v109
	v_ashrrev_i32_e32 v108, 31, v111
	v_mov_b32_e32 v112, v111
	v_mov_b32_e32 v113, v108
	v_lshlrev_b64 v[114:115], 10, v[112:113]
	v_lshl_add_u64 v[108:109], s[0:1], 0, v[114:115]
	v_mov_b32_e32 v110, v100
	v_mov_b32_e32 v111, v99
	v_lshl_add_u64 v[112:113], v[108:109], 0, v[110:111]
	global_load_ushort v108, v[112:113], off
	v_mov_b32_e32 v110, v100
	v_mov_b32_e32 v111, v99
	v_lshl_add_u64 v[112:113], v[94:95], 0, v[110:111]
	global_load_ushort v94, v[112:113], off
	s_and_saveexec_b64 s[62:63], s[10:11]
	v_mov_b32_e32 v104, 0xfc0
	v_mov_b32_e32 v105, 6
	v_mov_b32_e32 v106, 63
	v_mov_b32_e32 v107, 0xfffff000
	s_or_b64 exec, exec, s[62:63]
	v_lshlrev_b32_e32 v95, v105, v79
	v_and_b32_e32 v99, v107, v1
	v_and_b32_e32 v105, v106, v76
	v_and_b32_e32 v106, v95, v104
	v_or3_b32 v95, v105, v99, v106
	v_ashrrev_i32_e32 v99, 31, v95
	v_mov_b32_e32 v104, v95
	v_mov_b32_e32 v105, v99
	v_lshlrev_b64 v[106:107], 10, v[104:105]
	v_lshl_add_u64 v[104:105], s[0:1], 0, v[106:107]
	v_mov_b32_e32 v95, v131
	v_mov_b32_e32 v106, v100
	v_mov_b32_e32 v107, v95
	v_lshl_add_u64 v[110:111], v[104:105], 0, v[106:107]
	global_load_ushort v95, v[110:111], off
	s_movk_i32 s19, 0x4000
	v_or_b32_e32 v99, 16, v77
	v_cmp_gt_i32_e32 vcc, s19, v99
	v_mov_b32_e32 v104, 0x7fffff00
	s_nop 0
	v_cndmask_b32_e64 v105, 2, 6, vcc
	v_bfrev_b32_e32 v106, 0.5
	v_cndmask_b32_e32 v107, v104, v207, vcc
	v_cndmask_b32_e64 v109, 3, 63, vcc
	v_cndmask_b32_e32 v110, v106, v216, vcc
	v_lshlrev_b32_e32 v111, v105, v99
	v_and_b32_e32 v105, v107, v1
	v_and_b32_e32 v107, v109, v76
	v_and_b32_e32 v109, v111, v110
	v_or3_b32 v110, v107, v105, v109
	v_ashrrev_i32_e32 v105, 31, v110
	v_mov_b32_e32 v112, v110
	v_mov_b32_e32 v113, v105
	v_lshlrev_b64 v[114:115], 10, v[112:113]
	v_lshl_add_u64 v[110:111], v[66:67], 0, v[114:115]
	global_load_ushort v105, v[110:111], off
	s_movk_i32 s19, 0x3fff
	v_mov_b32_e32 v107, 3
	v_mov_b32_e32 v109, 2
	v_cmp_gt_i32_e64 s[62:63], s19, v99
	v_mov_b32_e32 v110, 0x7fffff00
	v_mov_b32_e32 v111, 3
	v_mov_b32_e32 v112, 2
	v_bfrev_b32_e32 v113, 0.5
	s_and_saveexec_b64 s[64:65], s[62:63]
	v_mov_b32_e32 v113, 0xfc0
	v_mov_b32_e32 v112, 6
	v_mov_b32_e32 v111, 63
	v_mov_b32_e32 v110, 0xfffff000
	s_or_b64 exec, exec, s[64:65]
	v_or_b32_e32 v116, 17, v77
	s_movk_i32 s19, 0x3ffe
	v_cmp_gt_i32_e32 vcc, s19, v99
	s_movk_i32 s19, 0x3ffd
	v_lshlrev_b32_e32 v117, v112, v116
	v_cmp_gt_i32_e64 s[64:65], s19, v99
	v_and_b32_e32 v99, v110, v1
	v_and_b32_e32 v110, v111, v76
	v_and_b32_e32 v111, v117, v113
	v_or3_b32 v112, v110, v99, v111
	v_ashrrev_i32_e32 v99, 31, v112
	v_mov_b32_e32 v110, v112
	v_mov_b32_e32 v111, v99
	v_lshlrev_b64 v[118:119], 10, v[110:111]
	v_lshl_add_u64 v[110:111], v[66:67], 0, v[118:119]
	global_load_ushort v99, v[110:111], off
	v_or_b32_e32 v110, 18, v77
	v_cndmask_b32_e64 v111, 2, 6, vcc
	v_cndmask_b32_e32 v112, v104, v207, vcc
	v_cndmask_b32_e64 v113, 3, 63, vcc
	v_cndmask_b32_e32 v117, v106, v216, vcc
	v_lshlrev_b32_e32 v118, v111, v110
	v_and_b32_e32 v110, v112, v1
	v_and_b32_e32 v111, v113, v76
	v_and_b32_e32 v112, v118, v117
	v_or3_b32 v113, v111, v110, v112
	v_ashrrev_i32_e32 v110, 31, v113
	v_mov_b32_e32 v118, v113
	v_mov_b32_e32 v119, v110
	v_lshlrev_b64 v[120:121], 10, v[118:119]
	v_lshl_add_u64 v[110:111], v[66:67], 0, v[120:121]
	global_load_ushort v112, v[110:111], off
	s_and_saveexec_b64 s[98:99], s[64:65]
	v_mov_b32_e32 v106, 0xfc0
	v_mov_b32_e32 v109, 6
	v_mov_b32_e32 v107, 63
	v_mov_b32_e32 v104, 0xfffff000
	s_or_b64 exec, exec, s[98:99]
	v_or_b32_e32 v110, 19, v77
	v_and_b32_e32 v111, v104, v1
	v_lshlrev_b32_e32 v104, v109, v110
	v_and_b32_e32 v109, v107, v76
	v_and_b32_e32 v107, v104, v106
	v_or3_b32 v104, v109, v111, v107
	v_ashrrev_i32_e32 v106, 31, v104
	v_mov_b32_e32 v118, v104
	v_mov_b32_e32 v119, v106
	v_lshlrev_b64 v[122:123], 10, v[118:119]
	v_lshl_add_u64 v[106:107], v[66:67], 0, v[122:123]
	global_load_ushort v104, v[106:107], off
	v_lshl_add_u64 v[106:107], s[0:1], 0, v[114:115]
	v_lshl_add_u64 v[114:115], v[106:107], 0, v[130:131]
	global_load_ushort v109, v[114:115], off
	v_bfrev_b32_e32 v111, 0.5
	v_mov_b32_e32 v113, 2
	v_mov_b32_e32 v114, 3
	v_mov_b32_e32 v115, 0x7fffff00
	v_mov_b32_e32 v117, 0x7fffff00
	v_mov_b32_e32 v118, 3
	v_mov_b32_e32 v119, 2
	v_bfrev_b32_e32 v122, 0.5
	s_and_saveexec_b64 s[98:99], s[62:63]
	v_mov_b32_e32 v122, 0xfc0
	v_mov_b32_e32 v119, 6
	v_mov_b32_e32 v118, 63
	v_mov_b32_e32 v117, 0xfffff000
	s_or_b64 exec, exec, s[98:99]
	v_lshlrev_b32_e32 v123, v119, v116
	v_and_b32_e32 v119, v117, v1
	v_and_b32_e32 v117, v118, v76
	v_and_b32_e32 v118, v123, v122
	v_or3_b32 v122, v117, v119, v118
	v_ashrrev_i32_e32 v117, 31, v122
	v_mov_b32_e32 v118, v122
	v_mov_b32_e32 v119, v117
	v_lshlrev_b64 v[124:125], 10, v[118:119]
	v_lshl_add_u64 v[118:119], s[0:1], 0, v[124:125]
	v_lshl_add_u64 v[122:123], v[118:119], 0, v[130:131]
	global_load_ushort v117, v[122:123], off
	v_lshl_add_u64 v[118:119], s[0:1], 0, v[120:121]
	v_lshl_add_u64 v[120:121], v[118:119], 0, v[130:131]
	global_load_ushort v122, v[120:121], off
	s_and_saveexec_b64 s[98:99], s[64:65]
	v_mov_b32_e32 v111, 0xfc0
	v_mov_b32_e32 v113, 6
	v_mov_b32_e32 v114, 63
	v_mov_b32_e32 v115, 0xfffff000
	s_or_b64 exec, exec, s[98:99]
	v_lshlrev_b32_e32 v120, v113, v110
	v_and_b32_e32 v113, v115, v1
	v_and_b32_e32 v115, v114, v76
	v_and_b32_e32 v114, v120, v111
	v_or3_b32 v111, v115, v113, v114
	v_ashrrev_i32_e32 v113, 31, v111
	v_mov_b32_e32 v114, v111
	v_mov_b32_e32 v115, v113
	v_lshlrev_b64 v[120:121], 10, v[114:115]
	v_lshl_add_u64 v[114:115], s[0:1], 0, v[120:121]
	v_lshl_add_u64 v[120:121], v[114:115], 0, v[130:131]
	global_load_ushort v111, v[120:121], off
	v_mov_b32_e32 v113, v131
	v_mov_b32_e32 v114, v91
	v_mov_b32_e32 v115, v113
	v_lshl_add_u64 v[120:121], v[106:107], 0, v[114:115]
	global_load_ushort v114, v[120:121], off
	v_bfrev_b32_e32 v115, 0.5
	v_mov_b32_e32 v120, 2
	v_mov_b32_e32 v121, 3
	v_mov_b32_e32 v123, 0x7fffff00
	v_mov_b32_e32 v124, 0x7fffff00
	v_mov_b32_e32 v125, 3
	v_mov_b32_e32 v126, 2
	v_bfrev_b32_e32 v127, 0.5
	s_and_saveexec_b64 s[98:99], s[62:63]
	v_mov_b32_e32 v127, 0xfc0
	v_mov_b32_e32 v126, 6
	v_mov_b32_e32 v125, 63
	v_mov_b32_e32 v124, 0xfffff000
	s_or_b64 exec, exec, s[98:99]
	v_lshlrev_b32_e32 v128, v126, v116
	v_and_b32_e32 v126, v124, v1
	v_and_b32_e32 v124, v125, v76
	v_and_b32_e32 v125, v128, v127
	v_or3_b32 v127, v124, v126, v125
	v_ashrrev_i32_e32 v124, 31, v127
	v_mov_b32_e32 v128, v127
	v_mov_b32_e32 v129, v124
	v_lshlrev_b64 v[138:139], 10, v[128:129]
	v_lshl_add_u64 v[124:125], s[0:1], 0, v[138:139]
	v_mov_b32_e32 v126, v91
	v_mov_b32_e32 v127, v113
	v_lshl_add_u64 v[128:129], v[124:125], 0, v[126:127]
	global_load_ushort v124, v[128:129], off
	v_mov_b32_e32 v126, v91
	v_mov_b32_e32 v127, v113
	v_lshl_add_u64 v[128:129], v[118:119], 0, v[126:127]
	global_load_ushort v113, v[128:129], off
	s_and_saveexec_b64 s[98:99], s[64:65]
	v_mov_b32_e32 v115, 0xfc0
	v_mov_b32_e32 v120, 6
	v_mov_b32_e32 v121, 63
	v_mov_b32_e32 v123, 0xfffff000
	s_or_b64 exec, exec, s[98:99]
	v_lshlrev_b32_e32 v125, v120, v110
	v_and_b32_e32 v120, v123, v1
	v_and_b32_e32 v123, v121, v76
	v_and_b32_e32 v121, v125, v115
	v_or3_b32 v115, v123, v120, v121
	v_ashrrev_i32_e32 v120, 31, v115
	v_mov_b32_e32 v126, v115
	v_mov_b32_e32 v127, v120
	v_lshlrev_b64 v[128:129], 10, v[126:127]
	v_lshl_add_u64 v[120:121], s[0:1], 0, v[128:129]
	v_mov_b32_e32 v115, v131
	v_mov_b32_e32 v126, v91
	v_mov_b32_e32 v127, v115
	v_lshl_add_u64 v[128:129], v[120:121], 0, v[126:127]
	global_load_ushort v115, v[128:129], off
	v_mov_b32_e32 v120, v131
	v_mov_b32_e32 v126, v100
	v_mov_b32_e32 v127, v120
	v_lshl_add_u64 v[128:129], v[106:107], 0, v[126:127]
	global_load_ushort v106, v[128:129], off
	v_bfrev_b32_e32 v107, 0.5
	v_mov_b32_e32 v121, 2
	v_mov_b32_e32 v123, 3
	v_mov_b32_e32 v125, 0x7fffff00
	v_mov_b32_e32 v126, 0x7fffff00
	v_mov_b32_e32 v127, 3
	v_mov_b32_e32 v128, 2
	v_bfrev_b32_e32 v129, 0.5
	s_and_saveexec_b64 s[98:99], s[62:63]
	v_mov_b32_e32 v129, 0xfc0
	v_mov_b32_e32 v128, 6
	v_mov_b32_e32 v127, 63
	v_mov_b32_e32 v126, 0xfffff000
	s_or_b64 exec, exec, s[98:99]
	v_lshlrev_b32_e32 v137, v128, v116
	v_and_b32_e32 v116, v126, v1
	v_and_b32_e32 v126, v127, v76
	v_and_b32_e32 v127, v137, v129
	v_or3_b32 v128, v126, v116, v127
	v_ashrrev_i32_e32 v116, 31, v128
	v_mov_b32_e32 v126, v128
	v_mov_b32_e32 v127, v116
	v_lshlrev_b64 v[138:139], 10, v[126:127]
	v_lshl_add_u64 v[126:127], s[0:1], 0, v[138:139]
	v_mov_b32_e32 v128, v100
	v_mov_b32_e32 v129, v120
	v_lshl_add_u64 v[138:139], v[126:127], 0, v[128:129]
	global_load_ushort v116, v[138:139], off
	v_mov_b32_e32 v126, v100
	v_mov_b32_e32 v127, v120
	v_lshl_add_u64 v[128:129], v[118:119], 0, v[126:127]
	global_load_ushort v118, v[128:129], off
	s_and_saveexec_b64 s[62:63], s[64:65]
	v_mov_b32_e32 v107, 0xfc0
	v_mov_b32_e32 v121, 6
	v_mov_b32_e32 v123, 63
	v_mov_b32_e32 v125, 0xfffff000
	s_or_b64 exec, exec, s[62:63]
	v_lshlrev_b32_e32 v119, v121, v110
	v_and_b32_e32 v110, v125, v1
	v_and_b32_e32 v120, v123, v76
	v_and_b32_e32 v121, v119, v107
	v_or3_b32 v107, v120, v110, v121
	v_ashrrev_i32_e32 v110, 31, v107
	v_mov_b32_e32 v120, v107
	v_mov_b32_e32 v121, v110
	v_lshlrev_b64 v[126:127], 10, v[120:121]
	v_lshl_add_u64 v[120:121], s[0:1], 0, v[126:127]
	v_mov_b32_e32 v107, v131
	v_mov_b32_e32 v126, v100
	v_mov_b32_e32 v127, v107
	v_lshl_add_u64 v[128:129], v[120:121], 0, v[126:127]
	global_load_ushort v107, v[128:129], off
	s_movk_i32 s19, 0x4000
	v_or_b32_e32 v110, 32, v77
	v_cmp_gt_i32_e32 vcc, s19, v110
	v_mov_b32_e32 v119, 0x7fffff00
	s_nop 0
	v_cndmask_b32_e64 v120, 2, 6, vcc
	v_bfrev_b32_e32 v121, 0.5
	v_cndmask_b32_e32 v123, v119, v207, vcc
	v_cndmask_b32_e64 v125, 3, 63, vcc
	v_cndmask_b32_e32 v126, v121, v216, vcc
	v_lshlrev_b32_e32 v127, v120, v110
	v_and_b32_e32 v120, v123, v1
	v_and_b32_e32 v123, v125, v76
	v_and_b32_e32 v125, v127, v126
	v_or3_b32 v126, v123, v120, v125
	v_ashrrev_i32_e32 v120, 31, v126
	v_mov_b32_e32 v128, v126
	v_mov_b32_e32 v129, v120
	v_lshlrev_b64 v[138:139], 10, v[128:129]
	v_lshl_add_u64 v[126:127], v[66:67], 0, v[138:139]
	global_load_ushort v120, v[126:127], off
	s_movk_i32 s19, 0x3fff
	v_mov_b32_e32 v123, 3
	v_mov_b32_e32 v125, 2
	v_cmp_gt_i32_e64 s[62:63], s19, v110
	v_mov_b32_e32 v126, 0x7fffff00
	v_mov_b32_e32 v127, 3
	v_mov_b32_e32 v128, 2
	v_bfrev_b32_e32 v129, 0.5
	s_and_saveexec_b64 s[64:65], s[62:63]
	v_mov_b32_e32 v129, 0xfc0
	v_mov_b32_e32 v128, 6
	v_mov_b32_e32 v127, 63
	v_mov_b32_e32 v126, 0xfffff000
	s_or_b64 exec, exec, s[64:65]
	v_or_b32_e32 v137, 33, v77
	s_movk_i32 s19, 0x3ffe
	v_cmp_gt_i32_e32 vcc, s19, v110
	s_movk_i32 s19, 0x3ffd
	v_lshlrev_b32_e32 v140, v128, v137
	v_cmp_gt_i32_e64 s[64:65], s19, v110
	v_and_b32_e32 v110, v126, v1
	v_and_b32_e32 v126, v127, v76
	v_and_b32_e32 v127, v140, v129
	v_or3_b32 v128, v126, v110, v127
	v_ashrrev_i32_e32 v110, 31, v128
	v_mov_b32_e32 v126, v128
	v_mov_b32_e32 v127, v110
	v_lshlrev_b64 v[140:141], 10, v[126:127]
	v_lshl_add_u64 v[126:127], v[66:67], 0, v[140:141]
	global_load_ushort v110, v[126:127], off
	v_or_b32_e32 v126, 34, v77
	v_cndmask_b32_e64 v127, 2, 6, vcc
	v_cndmask_b32_e32 v128, v119, v207, vcc
	v_cndmask_b32_e64 v129, 3, 63, vcc
	v_cndmask_b32_e32 v140, v121, v216, vcc
	v_lshlrev_b32_e32 v141, v127, v126
	v_and_b32_e32 v126, v128, v1
	v_and_b32_e32 v127, v129, v76
	v_and_b32_e32 v128, v141, v140
	v_or3_b32 v129, v127, v126, v128
	v_ashrrev_i32_e32 v126, 31, v129
	v_mov_b32_e32 v140, v129
	v_mov_b32_e32 v141, v126
	v_lshlrev_b64 v[142:143], 10, v[140:141]
	v_lshl_add_u64 v[126:127], v[66:67], 0, v[142:143]
	global_load_ushort v128, v[126:127], off
	s_and_saveexec_b64 s[98:99], s[64:65]
	v_mov_b32_e32 v121, 0xfc0
	v_mov_b32_e32 v125, 6
	v_mov_b32_e32 v123, 63
	v_mov_b32_e32 v119, 0xfffff000
	s_or_b64 exec, exec, s[98:99]
	v_or_b32_e32 v126, 35, v77
	v_and_b32_e32 v127, v119, v1
	v_lshlrev_b32_e32 v119, v125, v126
	v_and_b32_e32 v125, v123, v76
	v_and_b32_e32 v123, v119, v121
	v_or3_b32 v119, v125, v127, v123
	v_ashrrev_i32_e32 v121, 31, v119
	v_mov_b32_e32 v140, v119
	v_mov_b32_e32 v141, v121
	v_lshlrev_b64 v[144:145], 10, v[140:141]
	v_lshl_add_u64 v[140:141], v[66:67], 0, v[144:145]
	global_load_ushort v119, v[140:141], off
	v_lshl_add_u64 v[140:141], s[0:1], 0, v[138:139]
	v_lshl_add_u64 v[138:139], v[140:141], 0, v[130:131]
	global_load_ushort v121, v[138:139], off
	v_bfrev_b32_e32 v123, 0.5
	v_mov_b32_e32 v125, 2
	v_mov_b32_e32 v127, 3
	v_mov_b32_e32 v129, 0x7fffff00
	v_mov_b32_e32 v138, 0x7fffff00
	v_mov_b32_e32 v139, 3
	v_mov_b32_e32 v144, 2
	v_bfrev_b32_e32 v145, 0.5
	s_and_saveexec_b64 s[98:99], s[62:63]
	v_mov_b32_e32 v145, 0xfc0
	v_mov_b32_e32 v144, 6
	v_mov_b32_e32 v139, 63
	v_mov_b32_e32 v138, 0xfffff000
	s_or_b64 exec, exec, s[98:99]
	v_lshlrev_b32_e32 v146, v144, v137
	v_and_b32_e32 v144, v138, v1
	v_and_b32_e32 v138, v139, v76
	v_and_b32_e32 v139, v146, v145
	v_or3_b32 v145, v138, v144, v139
	v_ashrrev_i32_e32 v138, 31, v145
	v_mov_b32_e32 v146, v145
	v_mov_b32_e32 v147, v138
	v_lshlrev_b64 v[148:149], 10, v[146:147]
	v_lshl_add_u64 v[138:139], s[0:1], 0, v[148:149]
	v_lshl_add_u64 v[144:145], v[138:139], 0, v[130:131]
	global_load_ushort v138, v[144:145], off
	v_lshl_add_u64 v[144:145], s[0:1], 0, v[142:143]
	v_lshl_add_u64 v[142:143], v[144:145], 0, v[130:131]
	global_load_ushort v139, v[142:143], off
	s_and_saveexec_b64 s[98:99], s[64:65]
	v_mov_b32_e32 v123, 0xfc0
	v_mov_b32_e32 v125, 6
	v_mov_b32_e32 v127, 63
	v_mov_b32_e32 v129, 0xfffff000
	s_or_b64 exec, exec, s[98:99]
	v_lshlrev_b32_e32 v142, v125, v126
	v_and_b32_e32 v125, v129, v1
	v_and_b32_e32 v129, v127, v76
	v_and_b32_e32 v127, v142, v123
	v_or3_b32 v123, v129, v125, v127
	v_ashrrev_i32_e32 v125, 31, v123
	v_mov_b32_e32 v142, v123
	v_mov_b32_e32 v143, v125
	v_lshlrev_b64 v[146:147], 10, v[142:143]
	v_lshl_add_u64 v[142:143], s[0:1], 0, v[146:147]
	v_lshl_add_u64 v[146:147], v[142:143], 0, v[130:131]
	global_load_ushort v123, v[146:147], off
	v_mov_b32_e32 v125, v131
	v_mov_b32_e32 v142, v91
	v_mov_b32_e32 v143, v125
	v_lshl_add_u64 v[146:147], v[140:141], 0, v[142:143]
	global_load_ushort v127, v[146:147], off
	v_bfrev_b32_e32 v129, 0.5
	v_mov_b32_e32 v142, 2
	v_mov_b32_e32 v143, 3
	v_mov_b32_e32 v146, 0x7fffff00
	v_mov_b32_e32 v147, 0x7fffff00
	v_mov_b32_e32 v148, 3
	v_mov_b32_e32 v149, 2
	v_bfrev_b32_e32 v150, 0.5
	s_and_saveexec_b64 s[98:99], s[62:63]
	v_mov_b32_e32 v150, 0xfc0
	v_mov_b32_e32 v149, 6
	v_mov_b32_e32 v148, 63
	v_mov_b32_e32 v147, 0xfffff000
	s_or_b64 exec, exec, s[98:99]
	v_lshlrev_b32_e32 v151, v149, v137
	v_and_b32_e32 v149, v147, v1
	v_and_b32_e32 v147, v148, v76
	v_and_b32_e32 v148, v151, v150
	v_or3_b32 v150, v147, v149, v148
	v_ashrrev_i32_e32 v147, 31, v150
	v_mov_b32_e32 v148, v150
	v_mov_b32_e32 v149, v147
	v_lshlrev_b64 v[152:153], 10, v[148:149]
	v_lshl_add_u64 v[148:149], s[0:1], 0, v[152:153]
	v_mov_b32_e32 v150, v91
	v_mov_b32_e32 v151, v125
	v_lshl_add_u64 v[152:153], v[148:149], 0, v[150:151]
	global_load_ushort v147, v[152:153], off
	v_mov_b32_e32 v148, v91
	v_mov_b32_e32 v149, v125
	v_lshl_add_u64 v[150:151], v[144:145], 0, v[148:149]
	global_load_ushort v125, v[150:151], off
	s_and_saveexec_b64 s[98:99], s[64:65]
	v_mov_b32_e32 v129, 0xfc0
	v_mov_b32_e32 v142, 6
	v_mov_b32_e32 v143, 63
	v_mov_b32_e32 v146, 0xfffff000
	s_or_b64 exec, exec, s[98:99]
	v_lshlrev_b32_e32 v148, v142, v126
	v_and_b32_e32 v142, v146, v1
	v_and_b32_e32 v146, v143, v76
	v_and_b32_e32 v143, v148, v129
	v_or3_b32 v129, v146, v142, v143
	v_ashrrev_i32_e32 v142, 31, v129
	v_mov_b32_e32 v148, v129
	v_mov_b32_e32 v149, v142
	v_lshlrev_b64 v[150:151], 10, v[148:149]
	v_lshl_add_u64 v[142:143], s[0:1], 0, v[150:151]
	v_mov_b32_e32 v129, v131
	v_mov_b32_e32 v148, v91
	v_mov_b32_e32 v149, v129
	v_lshl_add_u64 v[150:151], v[142:143], 0, v[148:149]
	global_load_ushort v129, v[150:151], off
	v_mov_b32_e32 v142, v131
	v_mov_b32_e32 v148, v100
	v_mov_b32_e32 v149, v142
	v_lshl_add_u64 v[150:151], v[140:141], 0, v[148:149]
	global_load_ushort v140, v[150:151], off
	v_bfrev_b32_e32 v141, 0.5
	v_mov_b32_e32 v143, 2
	v_mov_b32_e32 v146, 3
	v_mov_b32_e32 v148, 0x7fffff00
	v_mov_b32_e32 v149, 0x7fffff00
	v_mov_b32_e32 v150, 3
	v_mov_b32_e32 v151, 2
	v_bfrev_b32_e32 v152, 0.5
	s_and_saveexec_b64 s[98:99], s[62:63]
	v_mov_b32_e32 v152, 0xfc0
	v_mov_b32_e32 v151, 6
	v_mov_b32_e32 v150, 63
	v_mov_b32_e32 v149, 0xfffff000
	s_or_b64 exec, exec, s[98:99]
	v_lshlrev_b32_e32 v153, v151, v137
	v_and_b32_e32 v137, v149, v1
	v_and_b32_e32 v149, v150, v76
	v_and_b32_e32 v150, v153, v152
	v_or3_b32 v151, v149, v137, v150
	v_ashrrev_i32_e32 v137, 31, v151
	v_mov_b32_e32 v152, v151
	v_mov_b32_e32 v153, v137
	v_lshlrev_b64 v[154:155], 10, v[152:153]
	v_lshl_add_u64 v[150:151], s[0:1], 0, v[154:155]
	v_mov_b32_e32 v152, v100
	v_mov_b32_e32 v153, v142
	v_lshl_add_u64 v[154:155], v[150:151], 0, v[152:153]
	global_load_ushort v137, v[154:155], off
	v_mov_b32_e32 v150, v100
	v_mov_b32_e32 v151, v142
	v_lshl_add_u64 v[152:153], v[144:145], 0, v[150:151]
	global_load_ushort v142, v[152:153], off
	s_and_saveexec_b64 s[62:63], s[64:65]
	v_mov_b32_e32 v141, 0xfc0
	v_mov_b32_e32 v143, 6
	v_mov_b32_e32 v146, 63
	v_mov_b32_e32 v148, 0xfffff000
	s_or_b64 exec, exec, s[62:63]
	v_lshlrev_b32_e32 v144, v143, v126
	v_and_b32_e32 v126, v148, v1
	v_and_b32_e32 v143, v146, v76
	v_and_b32_e32 v145, v144, v141
	v_or3_b32 v141, v143, v126, v145
	v_ashrrev_i32_e32 v126, 31, v141
	v_mov_b32_e32 v144, v141
	v_mov_b32_e32 v145, v126
	v_lshlrev_b64 v[148:149], 10, v[144:145]
	v_lshl_add_u64 v[144:145], s[0:1], 0, v[148:149]
	v_mov_b32_e32 v126, v131
	v_mov_b32_e32 v148, v100
	v_mov_b32_e32 v149, v126
	v_lshl_add_u64 v[150:151], v[144:145], 0, v[148:149]
	global_load_ushort v126, v[150:151], off
	s_movk_i32 s19, 0x4000
	v_or_b32_e32 v141, 48, v77
	v_cmp_gt_i32_e32 vcc, s19, v141
	v_mov_b32_e32 v143, 0x7fffff00
	s_nop 0
	v_cndmask_b32_e64 v144, 2, 6, vcc
	v_bfrev_b32_e32 v145, 0.5
	v_cndmask_b32_e32 v146, v143, v207, vcc
	v_cndmask_b32_e64 v148, 3, 63, vcc
	v_cndmask_b32_e32 v149, v145, v216, vcc
	v_lshlrev_b32_e32 v150, v144, v141
	v_and_b32_e32 v144, v146, v1
	v_and_b32_e32 v146, v148, v76
	v_and_b32_e32 v148, v150, v149
	v_or3_b32 v149, v146, v144, v148
	v_ashrrev_i32_e32 v144, 31, v149
	v_mov_b32_e32 v150, v149
	v_mov_b32_e32 v151, v144
	v_lshlrev_b64 v[152:153], 10, v[150:151]
	v_lshl_add_u64 v[148:149], v[66:67], 0, v[152:153]
	global_load_ushort v144, v[148:149], off
	s_movk_i32 s19, 0x3fff
	v_mov_b32_e32 v146, 3
	v_mov_b32_e32 v148, 2
	v_cmp_gt_i32_e64 s[62:63], s19, v141
	v_mov_b32_e32 v149, 0x7fffff00
	v_mov_b32_e32 v150, 3
	v_mov_b32_e32 v151, 2
	v_bfrev_b32_e32 v154, 0.5
	s_and_saveexec_b64 s[64:65], s[62:63]
	v_mov_b32_e32 v154, 0xfc0
	v_mov_b32_e32 v151, 6
	v_mov_b32_e32 v150, 63
	v_mov_b32_e32 v149, 0xfffff000
	s_or_b64 exec, exec, s[64:65]
	v_or_b32_e32 v155, 49, v77
	s_movk_i32 s19, 0x3ffe
	v_cmp_gt_i32_e32 vcc, s19, v141
	s_movk_i32 s19, 0x3ffd
	v_lshlrev_b32_e32 v156, v151, v155
	v_cmp_gt_i32_e64 s[64:65], s19, v141
	v_and_b32_e32 v141, v149, v1
	v_and_b32_e32 v149, v150, v76
	v_and_b32_e32 v150, v156, v154
	v_or3_b32 v151, v149, v141, v150
	v_ashrrev_i32_e32 v141, 31, v151
	v_mov_b32_e32 v156, v151
	v_mov_b32_e32 v157, v141
	v_lshlrev_b64 v[158:159], 10, v[156:157]
	v_lshl_add_u64 v[150:151], v[66:67], 0, v[158:159]
	global_load_ushort v141, v[150:151], off
	v_or_b32_e32 v149, 50, v77
	v_cndmask_b32_e64 v150, 2, 6, vcc
	v_cndmask_b32_e32 v151, v143, v207, vcc
	v_cndmask_b32_e64 v154, 3, 63, vcc
	v_cndmask_b32_e32 v156, v145, v216, vcc
	v_lshlrev_b32_e32 v157, v150, v149
	v_and_b32_e32 v149, v151, v1
	v_and_b32_e32 v150, v154, v76
	v_and_b32_e32 v151, v157, v156
	v_or3_b32 v154, v150, v149, v151
	v_ashrrev_i32_e32 v149, 31, v154
	v_mov_b32_e32 v150, v154
	v_mov_b32_e32 v151, v149
	v_lshlrev_b64 v[156:157], 10, v[150:151]
	v_lshl_add_u64 v[150:151], v[66:67], 0, v[156:157]
	global_load_ushort v149, v[150:151], off
	s_and_saveexec_b64 s[98:99], s[64:65]
	v_mov_b32_e32 v145, 0xfc0
	v_mov_b32_e32 v148, 6
	v_mov_b32_e32 v146, 63
	v_mov_b32_e32 v143, 0xfffff000
	s_or_b64 exec, exec, s[98:99]
	v_or_b32_e32 v150, 51, v77
	v_and_b32_e32 v151, v143, v1
	v_lshlrev_b32_e32 v143, v148, v150
	v_and_b32_e32 v148, v146, v76
	v_and_b32_e32 v146, v143, v145
	v_or3_b32 v143, v148, v151, v146
	v_ashrrev_i32_e32 v145, 31, v143
	v_mov_b32_e32 v158, v143
	v_mov_b32_e32 v159, v145
	v_lshlrev_b64 v[162:163], 10, v[158:159]
	v_lshl_add_u64 v[158:159], v[66:67], 0, v[162:163]
	global_load_ushort v143, v[158:159], off
	v_lshl_add_u64 v[158:159], s[0:1], 0, v[152:153]
	v_lshl_add_u64 v[152:153], v[158:159], 0, v[130:131]
	global_load_ushort v145, v[152:153], off
	v_bfrev_b32_e32 v146, 0.5
	v_mov_b32_e32 v148, 2
	v_mov_b32_e32 v151, 3
	v_mov_b32_e32 v152, 0x7fffff00
	v_mov_b32_e32 v153, 0x7fffff00
	v_mov_b32_e32 v154, 3
	v_mov_b32_e32 v160, 2
	v_bfrev_b32_e32 v162, 0.5
	s_and_saveexec_b64 s[98:99], s[62:63]
	v_mov_b32_e32 v162, 0xfc0
	v_mov_b32_e32 v160, 6
	v_mov_b32_e32 v154, 63
	v_mov_b32_e32 v153, 0xfffff000
	s_or_b64 exec, exec, s[98:99]
	v_lshlrev_b32_e32 v163, v160, v155
	v_and_b32_e32 v160, v153, v1
	v_and_b32_e32 v153, v154, v76
	v_and_b32_e32 v154, v163, v162
	v_or3_b32 v162, v153, v160, v154
	v_ashrrev_i32_e32 v153, 31, v162
	v_mov_b32_e32 v164, v162
	v_mov_b32_e32 v165, v153
	v_lshlrev_b64 v[168:169], 10, v[164:165]
	v_lshl_add_u64 v[162:163], s[0:1], 0, v[168:169]
	v_lshl_add_u64 v[164:165], v[162:163], 0, v[130:131]
	global_load_ushort v153, v[164:165], off
	v_lshl_add_u64 v[162:163], s[0:1], 0, v[156:157]
	v_lshl_add_u64 v[156:157], v[162:163], 0, v[130:131]
	global_load_ushort v154, v[156:157], off
	s_and_saveexec_b64 s[98:99], s[64:65]
	v_mov_b32_e32 v146, 0xfc0
	v_mov_b32_e32 v148, 6
	v_mov_b32_e32 v151, 63
	v_mov_b32_e32 v152, 0xfffff000
	s_or_b64 exec, exec, s[98:99]
	v_lshlrev_b32_e32 v156, v148, v150
	v_and_b32_e32 v148, v152, v1
	v_and_b32_e32 v152, v151, v76
	v_and_b32_e32 v151, v156, v146
	v_or3_b32 v146, v152, v148, v151
	v_ashrrev_i32_e32 v148, 31, v146
	v_mov_b32_e32 v156, v146
	v_mov_b32_e32 v157, v148
	v_lshlrev_b64 v[164:165], 10, v[156:157]
	v_lshl_add_u64 v[156:157], s[0:1], 0, v[164:165]
	v_lshl_add_u64 v[164:165], v[156:157], 0, v[130:131]
	global_load_ushort v146, v[164:165], off
	v_mov_b32_e32 v148, v131
	v_mov_b32_e32 v156, v91
	v_mov_b32_e32 v157, v148
	v_lshl_add_u64 v[164:165], v[158:159], 0, v[156:157]
	global_load_ushort v151, v[164:165], off
	v_bfrev_b32_e32 v152, 0.5
	v_mov_b32_e32 v156, 2
	v_mov_b32_e32 v157, 3
	v_mov_b32_e32 v160, 0x7fffff00
	v_mov_b32_e32 v164, 0x7fffff00
	v_mov_b32_e32 v165, 3
	v_mov_b32_e32 v166, 2
	v_bfrev_b32_e32 v168, 0.5
	s_and_saveexec_b64 s[98:99], s[62:63]
	v_mov_b32_e32 v168, 0xfc0
	v_mov_b32_e32 v166, 6
	v_mov_b32_e32 v165, 63
	v_mov_b32_e32 v164, 0xfffff000
	s_or_b64 exec, exec, s[98:99]
	v_lshlrev_b32_e32 v169, v166, v155
	v_and_b32_e32 v166, v164, v1
	v_and_b32_e32 v164, v165, v76
	v_and_b32_e32 v165, v169, v168
	v_or3_b32 v168, v164, v166, v165
	v_ashrrev_i32_e32 v164, 31, v168
	v_mov_b32_e32 v170, v168
	v_mov_b32_e32 v171, v164
	v_lshlrev_b64 v[174:175], 10, v[170:171]
	v_lshl_add_u64 v[164:165], s[0:1], 0, v[174:175]
	v_mov_b32_e32 v168, v91
	v_mov_b32_e32 v169, v148
	v_lshl_add_u64 v[170:171], v[164:165], 0, v[168:169]
	global_load_ushort v164, v[170:171], off
	v_mov_b32_e32 v168, v91
	v_mov_b32_e32 v169, v148
	v_lshl_add_u64 v[170:171], v[162:163], 0, v[168:169]
	global_load_ushort v148, v[170:171], off
	s_and_saveexec_b64 s[98:99], s[64:65]
	v_mov_b32_e32 v152, 0xfc0
	v_mov_b32_e32 v156, 6
	v_mov_b32_e32 v157, 63
	v_mov_b32_e32 v160, 0xfffff000
	s_or_b64 exec, exec, s[98:99]
	v_lshlrev_b32_e32 v165, v156, v150
	v_and_b32_e32 v156, v160, v1
	v_and_b32_e32 v160, v157, v76
	v_and_b32_e32 v157, v165, v152
	v_or3_b32 v152, v160, v156, v157
	v_ashrrev_i32_e32 v156, 31, v152
	v_mov_b32_e32 v168, v152
	v_mov_b32_e32 v169, v156
	v_lshlrev_b64 v[170:171], 10, v[168:169]
	v_lshl_add_u64 v[156:157], s[0:1], 0, v[170:171]
	v_mov_b32_e32 v152, v131
	v_mov_b32_e32 v168, v91
	v_mov_b32_e32 v169, v152
	v_lshl_add_u64 v[170:171], v[156:157], 0, v[168:169]
	global_load_ushort v91, v[170:171], off
	v_mov_b32_e32 v152, v131
	v_mov_b32_e32 v156, v100
	v_mov_b32_e32 v157, v152
	v_lshl_add_u64 v[168:169], v[158:159], 0, v[156:157]
	global_load_ushort v156, v[168:169], off
	v_bfrev_b32_e32 v157, 0.5
	v_mov_b32_e32 v158, 2
	v_mov_b32_e32 v159, 3
	v_mov_b32_e32 v160, 0x7fffff00
	v_mov_b32_e32 v165, 0x7fffff00
	v_mov_b32_e32 v166, 3
	v_mov_b32_e32 v168, 2
	v_bfrev_b32_e32 v169, 0.5
	s_and_saveexec_b64 s[98:99], s[62:63]
	v_mov_b32_e32 v169, 0xfc0
	v_mov_b32_e32 v168, 6
	v_mov_b32_e32 v166, 63
	v_mov_b32_e32 v165, 0xfffff000
	s_or_b64 exec, exec, s[98:99]
	v_lshlrev_b32_e32 v170, v168, v155
	v_and_b32_e32 v155, v165, v1
	v_and_b32_e32 v165, v166, v76
	v_and_b32_e32 v166, v170, v169
	v_or3_b32 v168, v165, v155, v166
	v_ashrrev_i32_e32 v155, 31, v168
	v_mov_b32_e32 v170, v168
	v_mov_b32_e32 v171, v155
	v_lshlrev_b64 v[174:175], 10, v[170:171]
	v_lshl_add_u64 v[168:169], s[0:1], 0, v[174:175]
	v_mov_b32_e32 v170, v100
	v_mov_b32_e32 v171, v152
	v_lshl_add_u64 v[174:175], v[168:169], 0, v[170:171]
	global_load_ushort v155, v[174:175], off
	v_mov_b32_e32 v168, v100
	v_mov_b32_e32 v169, v152
	v_lshl_add_u64 v[170:171], v[162:163], 0, v[168:169]
	global_load_ushort v152, v[170:171], off
	s_and_saveexec_b64 s[62:63], s[64:65]
	v_mov_b32_e32 v157, 0xfc0
	v_mov_b32_e32 v158, 6
	v_mov_b32_e32 v159, 63
	v_mov_b32_e32 v160, 0xfffff000
	s_or_b64 exec, exec, s[62:63]
	v_lshlrev_b32_e32 v162, v158, v150
	v_and_b32_e32 v150, v160, v1
	v_and_b32_e32 v158, v159, v76
	v_and_b32_e32 v159, v162, v157
	v_or3_b32 v157, v158, v150, v159
	v_ashrrev_i32_e32 v150, 31, v157
	v_mov_b32_e32 v158, v157
	v_mov_b32_e32 v159, v150
	v_lshlrev_b64 v[162:163], 10, v[158:159]
	v_lshl_add_u64 v[158:159], s[0:1], 0, v[162:163]
	v_mov_b32_e32 v150, v131
	v_mov_b32_e32 v162, v100
	v_mov_b32_e32 v163, v150
	v_lshl_add_u64 v[168:169], v[158:159], 0, v[162:163]
	global_load_ushort v100, v[168:169], off
	v_exp_f32_e32 v82, v82
	v_add_f32_e32 v58, v58, v69
	v_add_f32_e32 v82, 1.0, v82
	v_div_scale_f32 v83, s[6:7], v82, v82, v81
	v_rcp_f32_e32 v84, v83
	s_nop 0
	v_fma_f32 v85, -v83, v84, 1.0
	v_fmac_f32_e32 v84, v85, v84
	v_div_scale_f32 v85, vcc, v81, v82, v81
	v_mul_f32_e32 v86, v85, v84
	v_fma_f32 v87, -v83, v86, v85
	v_fmac_f32_e32 v86, v87, v84
	v_fma_f32 v83, -v83, v86, v85
	v_div_fmas_f32 v83, v83, v84, v86
	v_div_fixup_f32 v81, v83, v82, v81
	v_mul_f32_e32 v58, v58, v81
	v_cvt_pk_bf16_f32 v58, v58, s0
	global_store_short v[74:75], v58, off
	v_bfrev_b32_e32 v58, 0.5
	v_mov_b32_e32 v74, 0x7fffff00
	v_mov_b32_e32 v81, 0x7fffff00
	v_mov_b32_e32 v75, 3
	v_mov_b32_e32 v82, 2
	v_bfrev_b32_e32 v83, 0.5
	s_and_saveexec_b64 s[6:7], s[14:15]
	v_mov_b32_e32 v83, 0xfc0
	v_mov_b32_e32 v82, 6
	v_mov_b32_e32 v75, 63
	v_mov_b32_e32 v81, 0xfffff000
	s_or_b64 exec, exec, s[6:7]
	v_lshlrev_b32_e32 v82, v82, v78
	v_and_b32_e32 v81, v81, v1
	v_and_b32_e32 v75, v75, v76
	v_and_b32_e32 v82, v82, v83
	v_or3_b32 v82, v75, v81, v82
	v_ashrrev_i32_e32 v83, 31, v82
	v_lshlrev_b64 v[82:83], 10, v[82:83]
	v_lshl_add_u64 v[82:83], s[0:1], 0, v[82:83]
	v_lshl_add_u64 v[82:83], v[82:83], 0, v[130:131]
	s_waitcnt vmcnt(0)
	v_mov_b32_e32 v75, v93
	v_add_f32_e32 v59, v59, v69
	v_lshl_add_u64 v[72:73], s[0:1], 0, v[72:73]
	v_add_f32_e32 v60, v60, v69
	v_lshlrev_b32_e32 v75, 16, v75
	v_mul_f32_e32 v81, 0xbfb8aa3b, v75
	v_exp_f32_e32 v81, v81
	s_nop 0
	v_add_f32_e32 v81, 1.0, v81
	v_div_scale_f32 v84, s[6:7], v81, v81, v75
	v_rcp_f32_e32 v85, v84
	s_nop 0
	v_fma_f32 v86, -v84, v85, 1.0
	v_fmac_f32_e32 v85, v86, v85
	v_div_scale_f32 v86, vcc, v75, v81, v75
	v_mul_f32_e32 v87, v86, v85
	v_fma_f32 v88, -v84, v87, v86
	v_fmac_f32_e32 v87, v88, v85
	v_fma_f32 v84, -v84, v87, v86
	v_div_fmas_f32 v84, v84, v85, v87
	v_div_fixup_f32 v75, v84, v81, v75
	v_mul_f32_e32 v59, v59, v75
	v_cvt_pk_bf16_f32 v59, v59, s0
	global_store_short v[82:83], v59, off
	v_lshl_add_u64 v[82:83], v[72:73], 0, v[130:131]
	v_mov_b32_e32 v59, v98
	v_lshlrev_b32_e32 v59, 16, v59
	v_mul_f32_e32 v75, 0xbfb8aa3b, v59
	v_exp_f32_e32 v75, v75
	s_nop 0
	v_add_f32_e32 v75, 1.0, v75
	v_div_scale_f32 v81, s[6:7], v75, v75, v59
	v_rcp_f32_e32 v84, v81
	s_nop 0
	v_fma_f32 v85, -v81, v84, 1.0
	v_fmac_f32_e32 v84, v85, v84
	v_div_scale_f32 v85, vcc, v59, v75, v59
	v_mul_f32_e32 v86, v85, v84
	v_fma_f32 v87, -v81, v86, v85
	v_fmac_f32_e32 v86, v87, v84
	v_fma_f32 v81, -v81, v86, v85
	v_div_fmas_f32 v81, v81, v84, v86
	v_div_fixup_f32 v59, v81, v75, v59
	v_mul_f32_e32 v59, v60, v59
	v_cvt_pk_bf16_f32 v59, v59, s0
	global_store_short v[82:83], v59, off
	s_and_saveexec_b64 s[6:7], s[10:11]
	v_mov_b32_e32 v58, 0xfc0
	v_mov_b32_e32 v71, 6
	v_mov_b32_e32 v80, 63
	v_mov_b32_e32 v74, 0xfffff000
	s_or_b64 exec, exec, s[6:7]
	v_lshlrev_b32_e32 v71, v71, v79
	v_and_b32_e32 v59, v74, v1
	v_and_b32_e32 v60, v80, v76
	v_and_b32_e32 v58, v71, v58
	v_or3_b32 v58, v60, v59, v58
	v_ashrrev_i32_e32 v59, 31, v58
	v_lshlrev_b64 v[58:59], 10, v[58:59]
	v_lshl_add_u64 v[58:59], s[0:1], 0, v[58:59]
	v_lshl_add_u64 v[58:59], v[58:59], 0, v[130:131]
	v_mov_b32_e32 v60, v89
	v_add_f32_e32 v61, v61, v69
	v_lshlrev_b32_e32 v60, 16, v60
	v_mul_f32_e32 v71, 0xbfb8aa3b, v60
	v_exp_f32_e32 v71, v71
	s_nop 0
	v_add_f32_e32 v71, 1.0, v71
	v_div_scale_f32 v74, s[6:7], v71, v71, v60
	v_rcp_f32_e32 v75, v74
	s_nop 0
	v_fma_f32 v80, -v74, v75, 1.0
	v_fmac_f32_e32 v75, v80, v75
	v_div_scale_f32 v80, vcc, v60, v71, v60
	v_mul_f32_e32 v81, v80, v75
	v_fma_f32 v82, -v74, v81, v80
	v_fmac_f32_e32 v81, v82, v75
	v_fma_f32 v74, -v74, v81, v80
	v_div_fmas_f32 v74, v74, v75, v81
	v_div_fixup_f32 v60, v74, v71, v60
	v_mul_f32_e32 v60, v61, v60
	v_cvt_pk_bf16_f32 v60, v60, s0
	global_store_short v[58:59], v60, off
	v_or_b32_e32 v58, 32, v70
	v_lshlrev_b32_e32 v58, 1, v58
	v_mov_b32_e32 v59, v131
	v_lshl_add_u64 v[74:75], v[64:65], 0, v[58:59]
	v_mov_b32_e32 v61, v92
	v_mov_b32_e32 v60, v96
	v_lshlrev_b32_e32 v61, 16, v61
	v_mul_f32_e32 v71, 0xbfb8aa3b, v61
	v_exp_f32_e32 v71, v71
	v_add_f32_e32 v54, v54, v60
	v_add_f32_e32 v71, 1.0, v71
	v_div_scale_f32 v80, s[6:7], v71, v71, v61
	v_rcp_f32_e32 v81, v80
	s_nop 0
	v_fma_f32 v82, -v80, v81, 1.0
	v_fmac_f32_e32 v81, v82, v81
	v_div_scale_f32 v82, vcc, v61, v71, v61
	v_mul_f32_e32 v83, v82, v81
	v_fma_f32 v84, -v80, v83, v82
	v_fmac_f32_e32 v83, v84, v81
	v_fma_f32 v80, -v80, v83, v82
	v_div_fmas_f32 v80, v80, v81, v83
	v_div_fixup_f32 v61, v80, v71, v61
	v_mul_f32_e32 v54, v54, v61
	v_cvt_pk_bf16_f32 v54, v54, s0
	global_store_short v[74:75], v54, off
	v_bfrev_b32_e32 v54, 0.5
	v_mov_b32_e32 v61, 2
	v_mov_b32_e32 v71, 3
	v_mov_b32_e32 v74, 0x7fffff00
	v_mov_b32_e32 v80, 0x7fffff00
	v_mov_b32_e32 v75, 3
	v_mov_b32_e32 v81, 2
	v_bfrev_b32_e32 v82, 0.5
	s_and_saveexec_b64 s[6:7], s[14:15]
	v_mov_b32_e32 v82, 0xfc0
	v_mov_b32_e32 v81, 6
	v_mov_b32_e32 v75, 63
	v_mov_b32_e32 v80, 0xfffff000
	s_or_b64 exec, exec, s[6:7]
	v_lshlrev_b32_e32 v81, v81, v78
	v_and_b32_e32 v80, v80, v1
	v_and_b32_e32 v75, v75, v76
	v_and_b32_e32 v81, v81, v82
	v_or3_b32 v80, v75, v80, v81
	v_ashrrev_i32_e32 v81, 31, v80
	v_lshlrev_b64 v[80:81], 10, v[80:81]
	v_lshl_add_u64 v[80:81], s[0:1], 0, v[80:81]
	v_lshl_add_u64 v[80:81], v[80:81], 0, v[58:59]
	v_mov_b32_e32 v75, v102
	v_add_f32_e32 v55, v55, v60
	v_add_f32_e32 v56, v56, v60
	v_lshlrev_b32_e32 v75, 16, v75
	v_mul_f32_e32 v82, 0xbfb8aa3b, v75
	v_exp_f32_e32 v82, v82
	s_nop 0
	v_add_f32_e32 v82, 1.0, v82
	v_div_scale_f32 v83, s[6:7], v82, v82, v75
	v_rcp_f32_e32 v84, v83
	s_nop 0
	v_fma_f32 v85, -v83, v84, 1.0
	v_fmac_f32_e32 v84, v85, v84
	v_div_scale_f32 v85, vcc, v75, v82, v75
	v_mul_f32_e32 v86, v85, v84
	v_fma_f32 v87, -v83, v86, v85
	v_fmac_f32_e32 v86, v87, v84
	v_fma_f32 v83, -v83, v86, v85
	v_div_fmas_f32 v83, v83, v84, v86
	v_div_fixup_f32 v75, v83, v82, v75
	v_mul_f32_e32 v55, v55, v75
	v_cvt_pk_bf16_f32 v55, v55, s0
	global_store_short v[80:81], v55, off
	v_lshl_add_u64 v[80:81], v[72:73], 0, v[58:59]
	v_mov_b32_e32 v55, v90
	v_lshlrev_b32_e32 v55, 16, v55
	v_mul_f32_e32 v59, 0xbfb8aa3b, v55
	v_exp_f32_e32 v59, v59
	s_nop 0
	v_add_f32_e32 v59, 1.0, v59
	v_div_scale_f32 v75, s[6:7], v59, v59, v55
	v_rcp_f32_e32 v82, v75
	s_nop 0
	v_fma_f32 v83, -v75, v82, 1.0
	v_fmac_f32_e32 v82, v83, v82
	v_div_scale_f32 v83, vcc, v55, v59, v55
	v_mul_f32_e32 v84, v83, v82
	v_fma_f32 v85, -v75, v84, v83
	v_fmac_f32_e32 v84, v85, v82
	v_fma_f32 v75, -v75, v84, v83
	v_div_fmas_f32 v75, v75, v82, v84
	v_div_fixup_f32 v55, v75, v59, v55
	v_mul_f32_e32 v55, v56, v55
	v_cvt_pk_bf16_f32 v55, v55, s0
	global_store_short v[80:81], v55, off
	s_and_saveexec_b64 s[6:7], s[10:11]
	v_mov_b32_e32 v54, 0xfc0
	v_mov_b32_e32 v61, 6
	v_mov_b32_e32 v71, 63
	v_mov_b32_e32 v74, 0xfffff000
	s_or_b64 exec, exec, s[6:7]
	v_lshlrev_b32_e32 v59, v61, v79
	v_and_b32_e32 v55, v74, v1
	v_and_b32_e32 v56, v71, v76
	v_and_b32_e32 v54, v59, v54
	v_or3_b32 v54, v56, v55, v54
	v_ashrrev_i32_e32 v55, 31, v54
	v_lshlrev_b64 v[54:55], 10, v[54:55]
	v_lshl_add_u64 v[54:55], s[0:1], 0, v[54:55]
	v_mov_b32_e32 v59, v131
	v_lshl_add_u64 v[54:55], v[54:55], 0, v[58:59]
	v_mov_b32_e32 v56, v97
	v_add_f32_e32 v57, v57, v60
	v_lshlrev_b32_e32 v56, 16, v56
	v_mul_f32_e32 v59, 0xbfb8aa3b, v56
	v_exp_f32_e32 v59, v59
	s_nop 0
	v_add_f32_e32 v59, 1.0, v59
	v_div_scale_f32 v61, s[6:7], v59, v59, v56
	v_rcp_f32_e32 v71, v61
	s_nop 0
	v_fma_f32 v74, -v61, v71, 1.0
	v_fmac_f32_e32 v71, v74, v71
	v_div_scale_f32 v74, vcc, v56, v59, v56
	v_mul_f32_e32 v75, v74, v71
	v_fma_f32 v80, -v61, v75, v74
	v_fmac_f32_e32 v75, v80, v71
	v_fma_f32 v61, -v61, v75, v74
	v_div_fmas_f32 v61, v61, v71, v75
	v_div_fixup_f32 v56, v61, v59, v56
	v_mul_f32_e32 v56, v57, v56
	v_cvt_pk_bf16_f32 v56, v56, s0
	global_store_short v[54:55], v56, off
	v_or_b32_e32 v55, 48, v70
	v_lshlrev_b32_e32 v56, 1, v55
	v_mov_b32_e32 v57, v131
	v_mov_b32_e32 v54, v101
	v_lshl_add_u64 v[62:63], v[64:65], 0, v[56:57]
	v_mov_b32_e32 v55, v103
	v_add_f32_e32 v50, v50, v54
	v_lshlrev_b32_e32 v55, 16, v55
	v_mul_f32_e32 v59, 0xbfb8aa3b, v55
	v_exp_f32_e32 v59, v59
	s_nop 0
	v_add_f32_e32 v59, 1.0, v59
	v_div_scale_f32 v61, s[6:7], v59, v59, v55
	v_rcp_f32_e32 v64, v61
	s_nop 0
	v_fma_f32 v65, -v61, v64, 1.0
	v_fmac_f32_e32 v64, v65, v64
	v_div_scale_f32 v65, vcc, v55, v59, v55
	v_mul_f32_e32 v70, v65, v64
	v_fma_f32 v71, -v61, v70, v65
	v_fmac_f32_e32 v70, v71, v64
	v_fma_f32 v61, -v61, v70, v65
	v_div_fmas_f32 v61, v61, v64, v70
	v_div_fixup_f32 v55, v61, v59, v55
	v_mul_f32_e32 v50, v50, v55
	v_cvt_pk_bf16_f32 v50, v50, s0
	global_store_short v[62:63], v50, off
	v_bfrev_b32_e32 v50, 0.5
	v_mov_b32_e32 v55, 2
	v_mov_b32_e32 v59, 3
	v_mov_b32_e32 v61, 0x7fffff00
	v_mov_b32_e32 v63, 0x7fffff00
	v_mov_b32_e32 v62, 3
	v_mov_b32_e32 v64, 2
	v_bfrev_b32_e32 v65, 0.5
	s_and_saveexec_b64 s[6:7], s[14:15]
	v_mov_b32_e32 v65, 0xfc0
	v_mov_b32_e32 v64, 6
	v_mov_b32_e32 v62, 63
	v_mov_b32_e32 v63, 0xfffff000
	s_or_b64 exec, exec, s[6:7]
	v_lshlrev_b32_e32 v64, v64, v78
	v_and_b32_e32 v63, v63, v1
	v_and_b32_e32 v62, v62, v76
	v_and_b32_e32 v64, v64, v65
	v_or3_b32 v62, v62, v63, v64
	v_ashrrev_i32_e32 v63, 31, v62
	v_lshlrev_b64 v[62:63], 10, v[62:63]
	v_lshl_add_u64 v[62:63], s[0:1], 0, v[62:63]
	v_lshl_add_u64 v[62:63], v[62:63], 0, v[56:57]
	v_mov_b32_e32 v64, v108
	v_add_f32_e32 v51, v51, v54
	v_add_f32_e32 v52, v52, v54
	v_lshlrev_b32_e32 v70, 16, v64
	v_mul_f32_e32 v64, 0xbfb8aa3b, v70
	v_exp_f32_e32 v64, v64
	s_nop 0
	v_add_f32_e32 v71, 1.0, v64
	v_div_scale_f32 v74, s[4:5], v71, v71, v70
	v_rcp_f32_e32 v75, v74
	v_lshl_add_u64 v[64:65], v[72:73], 0, v[56:57]
	v_div_scale_f32 v57, vcc, v70, v71, v70
	v_fma_f32 v72, -v74, v75, 1.0
	v_fmac_f32_e32 v75, v72, v75
	v_mul_f32_e32 v72, v57, v75
	v_fma_f32 v73, -v74, v72, v57
	v_fmac_f32_e32 v72, v73, v75
	v_fma_f32 v57, -v74, v72, v57
	v_div_fmas_f32 v57, v57, v75, v72
	v_div_fixup_f32 v57, v57, v71, v70
	v_mul_f32_e32 v51, v51, v57
	v_cvt_pk_bf16_f32 v51, v51, s0
	global_store_short v[62:63], v51, off
	v_mov_b32_e32 v51, v94
	v_lshlrev_b32_e32 v51, 16, v51
	v_mul_f32_e32 v57, 0xbfb8aa3b, v51
	v_exp_f32_e32 v57, v57
	s_nop 0
	v_add_f32_e32 v57, 1.0, v57
	v_div_scale_f32 v62, s[4:5], v57, v57, v51
	v_rcp_f32_e32 v63, v62
	v_div_scale_f32 v70, vcc, v51, v57, v51
	v_fma_f32 v71, -v62, v63, 1.0
	v_fmac_f32_e32 v63, v71, v63
	v_mul_f32_e32 v71, v70, v63
	v_fma_f32 v72, -v62, v71, v70
	v_fmac_f32_e32 v71, v72, v63
	v_fma_f32 v62, -v62, v71, v70
	v_div_fmas_f32 v62, v62, v63, v71
	v_div_fixup_f32 v51, v62, v57, v51
	v_mul_f32_e32 v51, v52, v51
	v_cvt_pk_bf16_f32 v51, v51, s0
	global_store_short v[64:65], v51, off
	s_and_saveexec_b64 s[4:5], s[10:11]
	v_mov_b32_e32 v50, 0xfc0
	v_mov_b32_e32 v55, 6
	v_mov_b32_e32 v59, 63
	v_mov_b32_e32 v61, 0xfffff000
	s_or_b64 exec, exec, s[4:5]
	v_lshlrev_b32_e32 v55, v55, v79
	v_and_b32_e32 v51, v61, v1
	v_and_b32_e32 v52, v59, v76
	v_and_b32_e32 v50, v55, v50
	v_or3_b32 v50, v52, v51, v50
	v_ashrrev_i32_e32 v51, 31, v50
	v_lshlrev_b64 v[50:51], 10, v[50:51]
	v_lshl_add_u64 v[50:51], s[0:1], 0, v[50:51]
	v_mov_b32_e32 v57, v131
	v_lshl_add_u64 v[50:51], v[50:51], 0, v[56:57]
	v_mov_b32_e32 v52, v95
	v_add_f32_e32 v53, v53, v54
	v_add_f32_e32 v46, v46, v68
	v_lshlrev_b32_e32 v52, 16, v52
	v_mul_f32_e32 v55, 0xbfb8aa3b, v52
	v_exp_f32_e32 v55, v55
	s_nop 0
	v_add_f32_e32 v55, 1.0, v55
	v_div_scale_f32 v57, s[2:3], v55, v55, v52
	v_rcp_f32_e32 v59, v57
	s_movk_i32 s2, 0x4000
	v_fma_f32 v61, -v57, v59, 1.0
	v_fmac_f32_e32 v59, v61, v59
	v_div_scale_f32 v61, vcc, v52, v55, v52
	v_mul_f32_e32 v62, v61, v59
	v_fma_f32 v63, -v57, v62, v61
	v_fmac_f32_e32 v62, v63, v59
	v_fma_f32 v57, -v57, v62, v61
	v_div_fmas_f32 v57, v57, v59, v62
	v_div_fixup_f32 v52, v57, v55, v52
	v_mul_f32_e32 v52, v53, v52
	v_or_b32_e32 v63, 16, v77
	v_cvt_pk_bf16_f32 v52, v52, s0
	v_cmp_gt_i32_e32 vcc, s2, v63
	global_store_short v[50:51], v52, off
	v_mov_b32_e32 v57, 0x7fffff00
	v_cndmask_b32_e64 v52, 2, 6, vcc
	v_bfrev_b32_e32 v62, 0.5
	v_cndmask_b32_e32 v50, v57, v207, vcc
	v_cndmask_b32_e64 v51, 3, 63, vcc
	v_cndmask_b32_e32 v53, v62, v216, vcc
	v_lshlrev_b32_e32 v52, v52, v63
	v_and_b32_e32 v50, v50, v1
	v_and_b32_e32 v51, v51, v76
	v_and_b32_e32 v52, v52, v53
	v_or3_b32 v50, v51, v50, v52
	v_ashrrev_i32_e32 v51, 31, v50
	v_lshlrev_b64 v[52:53], 10, v[50:51]
	v_lshl_add_u64 v[50:51], v[66:67], 0, v[52:53]
	v_mov_b32_e32 v55, v105
	s_movk_i32 s2, 0x3fff
	v_mov_b32_e32 v59, 3
	v_mov_b32_e32 v61, 2
	v_cmp_gt_i32_e64 s[2:3], s2, v63
	v_lshlrev_b32_e32 v55, 16, v55
	v_mul_f32_e32 v64, 0xbfb8aa3b, v55
	v_exp_f32_e32 v64, v64
	s_nop 0
	v_add_f32_e32 v64, 1.0, v64
	v_div_scale_f32 v65, s[4:5], v64, v64, v55
	v_rcp_f32_e32 v70, v65
	s_nop 0
	v_fma_f32 v71, -v65, v70, 1.0
	v_fmac_f32_e32 v70, v71, v70
	v_div_scale_f32 v71, vcc, v55, v64, v55
	v_mul_f32_e32 v72, v71, v70
	v_fma_f32 v73, -v65, v72, v71
	v_fmac_f32_e32 v72, v73, v70
	v_fma_f32 v65, -v65, v72, v71
	v_div_fmas_f32 v65, v65, v70, v72
	v_div_fixup_f32 v55, v65, v64, v55
	v_mul_f32_e32 v46, v46, v55
	v_cvt_pk_bf16_f32 v46, v46, s0
	global_store_short v[50:51], v46, off
	v_mov_b32_e32 v65, 0x7fffff00
	v_mov_b32_e32 v64, 3
	v_mov_b32_e32 v46, 2
	v_bfrev_b32_e32 v70, 0.5
	s_and_saveexec_b64 s[4:5], s[2:3]
	v_mov_b32_e32 v70, 0xfc0
	v_mov_b32_e32 v46, 6
	v_mov_b32_e32 v64, 63
	v_mov_b32_e32 v65, 0xfffff000
	s_or_b64 exec, exec, s[4:5]
	v_or_b32_e32 v55, 17, v77
	s_movk_i32 s4, 0x3ffe
	v_cmp_gt_i32_e32 vcc, s4, v63
	s_movk_i32 s4, 0x3ffd
	v_lshlrev_b32_e32 v46, v46, v55
	v_cmp_gt_i32_e64 s[4:5], s4, v63
	v_and_b32_e32 v63, v65, v1
	v_and_b32_e32 v64, v64, v76
	v_and_b32_e32 v46, v46, v70
	v_or3_b32 v64, v64, v63, v46
	v_ashrrev_i32_e32 v65, 31, v64
	v_lshlrev_b64 v[64:65], 10, v[64:65]
	v_lshl_add_u64 v[64:65], v[66:67], 0, v[64:65]
	v_mov_b32_e32 v46, v99
	v_or_b32_e32 v50, 18, v77
	v_cndmask_b32_e64 v72, 2, 6, vcc
	v_cndmask_b32_e32 v51, v57, v207, vcc
	v_cndmask_b32_e64 v71, 3, 63, vcc
	v_cndmask_b32_e32 v73, v62, v216, vcc
	v_lshlrev_b32_e32 v50, v72, v50
	v_and_b32_e32 v51, v51, v1
	v_and_b32_e32 v71, v71, v76
	v_and_b32_e32 v50, v50, v73
	v_or3_b32 v50, v71, v51, v50
	v_add_f32_e32 v47, v47, v68
	v_ashrrev_i32_e32 v51, 31, v50
	v_lshlrev_b64 v[50:51], 10, v[50:51]
	v_add_f32_e32 v48, v48, v68
	v_lshlrev_b32_e32 v46, 16, v46
	v_mul_f32_e32 v63, 0xbfb8aa3b, v46
	v_exp_f32_e32 v63, v63
	s_nop 0
	v_add_f32_e32 v63, 1.0, v63
	v_div_scale_f32 v70, s[6:7], v63, v63, v46
	v_rcp_f32_e32 v71, v70
	s_nop 0
	v_fma_f32 v72, -v70, v71, 1.0
	v_fmac_f32_e32 v71, v72, v71
	v_div_scale_f32 v72, vcc, v46, v63, v46
	v_mul_f32_e32 v73, v72, v71
	v_fma_f32 v74, -v70, v73, v72
	v_fmac_f32_e32 v73, v74, v71
	v_fma_f32 v70, -v70, v73, v72
	v_div_fmas_f32 v70, v70, v71, v73
	v_div_fixup_f32 v46, v70, v63, v46
	v_mul_f32_e32 v46, v47, v46
	v_cvt_pk_bf16_f32 v46, v46, s0
	global_store_short v[64:65], v46, off
	v_lshl_add_u64 v[46:47], v[66:67], 0, v[50:51]
	v_mov_b32_e32 v63, v112
	v_lshlrev_b32_e32 v63, 16, v63
	v_mul_f32_e32 v64, 0xbfb8aa3b, v63
	v_exp_f32_e32 v64, v64
	s_nop 0
	v_add_f32_e32 v64, 1.0, v64
	v_div_scale_f32 v65, s[6:7], v64, v64, v63
	v_rcp_f32_e32 v70, v65
	s_nop 0
	v_fma_f32 v71, -v65, v70, 1.0
	v_fmac_f32_e32 v70, v71, v70
	v_div_scale_f32 v71, vcc, v63, v64, v63
	v_mul_f32_e32 v72, v71, v70
	v_fma_f32 v73, -v65, v72, v71
	v_fmac_f32_e32 v72, v73, v70
	v_fma_f32 v65, -v65, v72, v71
	v_div_fmas_f32 v65, v65, v70, v72
	v_div_fixup_f32 v63, v65, v64, v63
	v_mul_f32_e32 v48, v48, v63
	v_cvt_pk_bf16_f32 v48, v48, s0
	global_store_short v[46:47], v48, off
	s_and_saveexec_b64 s[6:7], s[4:5]
	v_mov_b32_e32 v62, 0xfc0
	v_mov_b32_e32 v61, 6
	v_mov_b32_e32 v59, 63
	v_mov_b32_e32 v57, 0xfffff000
	s_or_b64 exec, exec, s[6:7]
	v_or_b32_e32 v48, 19, v77
	v_and_b32_e32 v46, v57, v1
	v_lshlrev_b32_e32 v57, v61, v48
	v_and_b32_e32 v47, v59, v76
	v_and_b32_e32 v57, v57, v62
	v_or3_b32 v46, v47, v46, v57
	v_ashrrev_i32_e32 v47, 31, v46
	v_lshlrev_b64 v[46:47], 10, v[46:47]
	v_lshl_add_u64 v[46:47], v[66:67], 0, v[46:47]
	v_mov_b32_e32 v57, v104
	v_add_f32_e32 v49, v49, v68
	v_add_f32_e32 v42, v42, v69
	v_lshlrev_b32_e32 v57, 16, v57
	v_mul_f32_e32 v59, 0xbfb8aa3b, v57
	v_exp_f32_e32 v59, v59
	s_nop 0
	v_add_f32_e32 v59, 1.0, v59
	v_div_scale_f32 v61, s[6:7], v59, v59, v57
	v_rcp_f32_e32 v62, v61
	s_nop 0
	v_fma_f32 v63, -v61, v62, 1.0
	v_fmac_f32_e32 v62, v63, v62
	v_div_scale_f32 v63, vcc, v57, v59, v57
	v_mul_f32_e32 v64, v63, v62
	v_fma_f32 v65, -v61, v64, v63
	v_fmac_f32_e32 v64, v65, v62
	v_fma_f32 v61, -v61, v64, v63
	v_div_fmas_f32 v61, v61, v62, v64
	v_div_fixup_f32 v57, v61, v59, v57
	v_mul_f32_e32 v49, v49, v57
	v_cvt_pk_bf16_f32 v49, v49, s0
	global_store_short v[46:47], v49, off
	v_lshl_add_u64 v[46:47], s[0:1], 0, v[52:53]
	v_lshl_add_u64 v[52:53], v[46:47], 0, v[130:131]
	v_mov_b32_e32 v49, v109
	v_lshlrev_b32_e32 v49, 16, v49
	v_mul_f32_e32 v57, 0xbfb8aa3b, v49
	v_exp_f32_e32 v57, v57
	s_nop 0
	v_add_f32_e32 v57, 1.0, v57
	v_div_scale_f32 v59, s[6:7], v57, v57, v49
	v_rcp_f32_e32 v61, v59
	s_nop 0
	v_fma_f32 v62, -v59, v61, 1.0
	v_fmac_f32_e32 v61, v62, v61
	v_div_scale_f32 v62, vcc, v49, v57, v49
	v_mul_f32_e32 v63, v62, v61
	v_fma_f32 v64, -v59, v63, v62
	v_fmac_f32_e32 v63, v64, v61
	v_fma_f32 v59, -v59, v63, v62
	v_div_fmas_f32 v59, v59, v61, v63
	v_div_fixup_f32 v49, v59, v57, v49
	v_mul_f32_e32 v42, v42, v49
	v_cvt_pk_bf16_f32 v42, v42, s0
	global_store_short v[52:53], v42, off
	v_bfrev_b32_e32 v49, 0.5
	v_mov_b32_e32 v52, 2
	v_mov_b32_e32 v53, 3
	v_mov_b32_e32 v57, 0x7fffff00
	v_mov_b32_e32 v42, 0x7fffff00
	v_mov_b32_e32 v59, 3
	v_mov_b32_e32 v61, 2
	v_bfrev_b32_e32 v62, 0.5
	s_and_saveexec_b64 s[6:7], s[2:3]
	v_mov_b32_e32 v62, 0xfc0
	v_mov_b32_e32 v61, 6
	v_mov_b32_e32 v59, 63
	v_mov_b32_e32 v42, 0xfffff000
	s_or_b64 exec, exec, s[6:7]
	v_lshlrev_b32_e32 v61, v61, v55
	v_and_b32_e32 v42, v42, v1
	v_and_b32_e32 v59, v59, v76
	v_and_b32_e32 v61, v61, v62
	v_or3_b32 v62, v59, v42, v61
	v_ashrrev_i32_e32 v63, 31, v62
	v_lshlrev_b64 v[62:63], 10, v[62:63]
	v_lshl_add_u64 v[62:63], s[0:1], 0, v[62:63]
	v_lshl_add_u64 v[62:63], v[62:63], 0, v[130:131]
	v_mov_b32_e32 v42, v117
	v_add_f32_e32 v43, v43, v69
	v_add_f32_e32 v44, v44, v69
	v_lshlrev_b32_e32 v42, 16, v42
	v_mul_f32_e32 v59, 0xbfb8aa3b, v42
	v_exp_f32_e32 v59, v59
	s_nop 0
	v_add_f32_e32 v59, 1.0, v59
	v_div_scale_f32 v61, s[6:7], v59, v59, v42
	v_rcp_f32_e32 v64, v61
	s_nop 0
	v_fma_f32 v65, -v61, v64, 1.0
	v_fmac_f32_e32 v64, v65, v64
	v_div_scale_f32 v65, vcc, v42, v59, v42
	v_mul_f32_e32 v70, v65, v64
	v_fma_f32 v71, -v61, v70, v65
	v_fmac_f32_e32 v70, v71, v64
	v_fma_f32 v61, -v61, v70, v65
	v_div_fmas_f32 v61, v61, v64, v70
	v_div_fixup_f32 v42, v61, v59, v42
	v_mul_f32_e32 v42, v43, v42
	v_cvt_pk_bf16_f32 v42, v42, s0
	global_store_short v[62:63], v42, off
	v_lshl_add_u64 v[42:43], s[0:1], 0, v[50:51]
	v_lshl_add_u64 v[50:51], v[42:43], 0, v[130:131]
	v_mov_b32_e32 v59, v122
	v_lshlrev_b32_e32 v59, 16, v59
	v_mul_f32_e32 v61, 0xbfb8aa3b, v59
	v_exp_f32_e32 v61, v61
	s_nop 0
	v_add_f32_e32 v61, 1.0, v61
	v_div_scale_f32 v62, s[6:7], v61, v61, v59
	v_rcp_f32_e32 v63, v62
	s_nop 0
	v_fma_f32 v64, -v62, v63, 1.0
	v_fmac_f32_e32 v63, v64, v63
	v_div_scale_f32 v64, vcc, v59, v61, v59
	v_mul_f32_e32 v65, v64, v63
	v_fma_f32 v70, -v62, v65, v64
	v_fmac_f32_e32 v65, v70, v63
	v_fma_f32 v62, -v62, v65, v64
	v_div_fmas_f32 v62, v62, v63, v65
	v_div_fixup_f32 v59, v62, v61, v59
	v_mul_f32_e32 v44, v44, v59
	v_cvt_pk_bf16_f32 v44, v44, s0
	global_store_short v[50:51], v44, off
	s_and_saveexec_b64 s[6:7], s[4:5]
	v_mov_b32_e32 v49, 0xfc0
	v_mov_b32_e32 v52, 6
	v_mov_b32_e32 v53, 63
	v_mov_b32_e32 v57, 0xfffff000
	s_or_b64 exec, exec, s[6:7]
	v_lshlrev_b32_e32 v51, v52, v48
	v_and_b32_e32 v44, v57, v1
	v_and_b32_e32 v50, v53, v76
	v_and_b32_e32 v49, v51, v49
	v_or3_b32 v50, v50, v44, v49
	v_ashrrev_i32_e32 v51, 31, v50
	v_lshlrev_b64 v[50:51], 10, v[50:51]
	v_lshl_add_u64 v[50:51], s[0:1], 0, v[50:51]
	v_lshl_add_u64 v[50:51], v[50:51], 0, v[130:131]
	v_mov_b32_e32 v44, v111
	v_add_f32_e32 v45, v45, v69
	v_add_f32_e32 v38, v38, v60
	v_lshlrev_b32_e32 v44, 16, v44
	v_mul_f32_e32 v49, 0xbfb8aa3b, v44
	v_exp_f32_e32 v49, v49
	s_nop 0
	v_add_f32_e32 v49, 1.0, v49
	v_div_scale_f32 v52, s[6:7], v49, v49, v44
	v_rcp_f32_e32 v53, v52
	s_nop 0
	v_fma_f32 v57, -v52, v53, 1.0
	v_fmac_f32_e32 v53, v57, v53
	v_div_scale_f32 v57, vcc, v44, v49, v44
	v_mul_f32_e32 v59, v57, v53
	v_fma_f32 v61, -v52, v59, v57
	v_fmac_f32_e32 v59, v61, v53
	v_fma_f32 v52, -v52, v59, v57
	v_div_fmas_f32 v52, v52, v53, v59
	v_div_fixup_f32 v44, v52, v49, v44
	v_mul_f32_e32 v44, v45, v44
	v_cvt_pk_bf16_f32 v44, v44, s0
	v_mov_b32_e32 v59, v131
	global_store_short v[50:51], v44, off
	v_lshl_add_u64 v[44:45], v[46:47], 0, v[58:59]
	v_mov_b32_e32 v49, v114
	v_lshlrev_b32_e32 v49, 16, v49
	v_mul_f32_e32 v50, 0xbfb8aa3b, v49
	v_exp_f32_e32 v50, v50
	s_nop 0
	v_add_f32_e32 v50, 1.0, v50
	v_div_scale_f32 v51, s[6:7], v50, v50, v49
	v_rcp_f32_e32 v52, v51
	s_nop 0
	v_fma_f32 v53, -v51, v52, 1.0
	v_fmac_f32_e32 v52, v53, v52
	v_div_scale_f32 v53, vcc, v49, v50, v49
	v_mul_f32_e32 v57, v53, v52
	v_fma_f32 v61, -v51, v57, v53
	v_fmac_f32_e32 v57, v61, v52
	v_fma_f32 v51, -v51, v57, v53
	v_div_fmas_f32 v51, v51, v52, v57
	v_div_fixup_f32 v49, v51, v50, v49
	v_mul_f32_e32 v38, v38, v49
	v_cvt_pk_bf16_f32 v38, v38, s0
	global_store_short v[44:45], v38, off
	v_bfrev_b32_e32 v38, 0.5
	v_mov_b32_e32 v44, 2
	v_mov_b32_e32 v45, 3
	v_mov_b32_e32 v49, 0x7fffff00
	v_mov_b32_e32 v50, 0x7fffff00
	v_mov_b32_e32 v51, 3
	v_mov_b32_e32 v52, 2
	v_bfrev_b32_e32 v53, 0.5
	s_and_saveexec_b64 s[6:7], s[2:3]
	v_mov_b32_e32 v53, 0xfc0
	v_mov_b32_e32 v52, 6
	v_mov_b32_e32 v51, 63
	v_mov_b32_e32 v50, 0xfffff000
	s_or_b64 exec, exec, s[6:7]
	v_lshlrev_b32_e32 v52, v52, v55
	v_and_b32_e32 v50, v50, v1
	v_and_b32_e32 v51, v51, v76
	v_and_b32_e32 v52, v52, v53
	v_or3_b32 v50, v51, v50, v52
	v_ashrrev_i32_e32 v51, 31, v50
	v_lshlrev_b64 v[50:51], 10, v[50:51]
	v_lshl_add_u64 v[50:51], s[0:1], 0, v[50:51]
	v_lshl_add_u64 v[50:51], v[50:51], 0, v[58:59]
	v_mov_b32_e32 v52, v124
	v_add_f32_e32 v39, v39, v60
	v_add_f32_e32 v40, v40, v60
	v_lshlrev_b32_e32 v52, 16, v52
	v_mul_f32_e32 v53, 0xbfb8aa3b, v52
	v_exp_f32_e32 v53, v53
	s_nop 0
	v_add_f32_e32 v53, 1.0, v53
	v_div_scale_f32 v57, s[6:7], v53, v53, v52
	v_rcp_f32_e32 v61, v57
	s_nop 0
	v_fma_f32 v62, -v57, v61, 1.0
	v_fmac_f32_e32 v61, v62, v61
	v_div_scale_f32 v62, vcc, v52, v53, v52
	v_mul_f32_e32 v63, v62, v61
	v_fma_f32 v64, -v57, v63, v62
	v_fmac_f32_e32 v63, v64, v61
	v_fma_f32 v57, -v57, v63, v62
	v_div_fmas_f32 v57, v57, v61, v63
	v_div_fixup_f32 v52, v57, v53, v52
	v_mul_f32_e32 v39, v39, v52
	v_cvt_pk_bf16_f32 v39, v39, s0
	global_store_short v[50:51], v39, off
	v_lshl_add_u64 v[50:51], v[42:43], 0, v[58:59]
	v_mov_b32_e32 v39, v113
	v_lshlrev_b32_e32 v39, 16, v39
	v_mul_f32_e32 v52, 0xbfb8aa3b, v39
	v_exp_f32_e32 v52, v52
	s_nop 0
	v_add_f32_e32 v52, 1.0, v52
	v_div_scale_f32 v53, s[6:7], v52, v52, v39
	v_rcp_f32_e32 v57, v53
	s_nop 0
	v_fma_f32 v59, -v53, v57, 1.0
	v_fmac_f32_e32 v57, v59, v57
	v_div_scale_f32 v59, vcc, v39, v52, v39
	v_mul_f32_e32 v61, v59, v57
	v_fma_f32 v62, -v53, v61, v59
	v_fmac_f32_e32 v61, v62, v57
	v_fma_f32 v53, -v53, v61, v59
	v_div_fmas_f32 v53, v53, v57, v61
	v_div_fixup_f32 v39, v53, v52, v39
	v_mul_f32_e32 v39, v40, v39
	v_cvt_pk_bf16_f32 v39, v39, s0
	global_store_short v[50:51], v39, off
	s_and_saveexec_b64 s[6:7], s[4:5]
	v_mov_b32_e32 v38, 0xfc0
	v_mov_b32_e32 v44, 6
	v_mov_b32_e32 v45, 63
	v_mov_b32_e32 v49, 0xfffff000
	s_or_b64 exec, exec, s[6:7]
	v_lshlrev_b32_e32 v44, v44, v48
	v_and_b32_e32 v39, v49, v1
	v_and_b32_e32 v40, v45, v76
	v_and_b32_e32 v38, v44, v38
	v_or3_b32 v38, v40, v39, v38
	v_ashrrev_i32_e32 v39, 31, v38
	v_lshlrev_b64 v[38:39], 10, v[38:39]
	v_lshl_add_u64 v[38:39], s[0:1], 0, v[38:39]
	v_mov_b32_e32 v59, v131
	v_lshl_add_u64 v[38:39], v[38:39], 0, v[58:59]
	v_mov_b32_e32 v40, v115
	v_add_f32_e32 v41, v41, v60
	v_mov_b32_e32 v57, v131
	v_add_f32_e32 v34, v34, v54
	v_lshlrev_b32_e32 v40, 16, v40
	v_mul_f32_e32 v44, 0xbfb8aa3b, v40
	v_exp_f32_e32 v44, v44
	s_nop 0
	v_add_f32_e32 v44, 1.0, v44
	v_div_scale_f32 v45, s[6:7], v44, v44, v40
	v_rcp_f32_e32 v49, v45
	s_nop 0
	v_fma_f32 v50, -v45, v49, 1.0
	v_fmac_f32_e32 v49, v50, v49
	v_div_scale_f32 v50, vcc, v40, v44, v40
	v_mul_f32_e32 v51, v50, v49
	v_fma_f32 v52, -v45, v51, v50
	v_fmac_f32_e32 v51, v52, v49
	v_fma_f32 v45, -v45, v51, v50
	v_div_fmas_f32 v45, v45, v49, v51
	v_div_fixup_f32 v40, v45, v44, v40
	v_mul_f32_e32 v40, v41, v40
	v_cvt_pk_bf16_f32 v40, v40, s0
	global_store_short v[38:39], v40, off
	v_lshl_add_u64 v[38:39], v[46:47], 0, v[56:57]
	v_mov_b32_e32 v40, v106
	v_lshlrev_b32_e32 v40, 16, v40
	v_mul_f32_e32 v41, 0xbfb8aa3b, v40
	v_exp_f32_e32 v41, v41
	s_nop 0
	v_add_f32_e32 v41, 1.0, v41
	v_div_scale_f32 v44, s[6:7], v41, v41, v40
	v_rcp_f32_e32 v45, v44
	s_nop 0
	v_fma_f32 v46, -v44, v45, 1.0
	v_fmac_f32_e32 v45, v46, v45
	v_div_scale_f32 v46, vcc, v40, v41, v40
	v_mul_f32_e32 v47, v46, v45
	v_fma_f32 v49, -v44, v47, v46
	v_fmac_f32_e32 v47, v49, v45
	v_fma_f32 v44, -v44, v47, v46
	v_div_fmas_f32 v44, v44, v45, v47
	v_div_fixup_f32 v40, v44, v41, v40
	v_mul_f32_e32 v34, v34, v40
	v_cvt_pk_bf16_f32 v34, v34, s0
	global_store_short v[38:39], v34, off
	v_bfrev_b32_e32 v34, 0.5
	v_mov_b32_e32 v38, 2
	v_mov_b32_e32 v39, 3
	v_mov_b32_e32 v40, 0x7fffff00
	v_mov_b32_e32 v41, 0x7fffff00
	v_mov_b32_e32 v44, 3
	v_mov_b32_e32 v45, 2
	v_bfrev_b32_e32 v46, 0.5
	s_and_saveexec_b64 s[6:7], s[2:3]
	v_mov_b32_e32 v46, 0xfc0
	v_mov_b32_e32 v45, 6
	v_mov_b32_e32 v44, 63
	v_mov_b32_e32 v41, 0xfffff000
	s_or_b64 exec, exec, s[6:7]
	v_lshlrev_b32_e32 v45, v45, v55
	v_and_b32_e32 v41, v41, v1
	v_and_b32_e32 v44, v44, v76
	v_and_b32_e32 v45, v45, v46
	v_or3_b32 v44, v44, v41, v45
	v_ashrrev_i32_e32 v45, 31, v44
	v_lshlrev_b64 v[44:45], 10, v[44:45]
	v_lshl_add_u64 v[44:45], s[0:1], 0, v[44:45]
	v_lshl_add_u64 v[44:45], v[44:45], 0, v[56:57]
	v_mov_b32_e32 v41, v116
	v_add_f32_e32 v35, v35, v54
	v_lshl_add_u64 v[42:43], v[42:43], 0, v[56:57]
	v_add_f32_e32 v36, v36, v54
	v_lshlrev_b32_e32 v41, 16, v41
	v_mul_f32_e32 v46, 0xbfb8aa3b, v41
	v_exp_f32_e32 v46, v46
	s_nop 0
	v_add_f32_e32 v46, 1.0, v46
	v_div_scale_f32 v47, s[2:3], v46, v46, v41
	v_rcp_f32_e32 v49, v47
	v_div_scale_f32 v50, vcc, v41, v46, v41
	v_fma_f32 v51, -v47, v49, 1.0
	v_fmac_f32_e32 v49, v51, v49
	v_mul_f32_e32 v51, v50, v49
	v_fma_f32 v52, -v47, v51, v50
	v_fmac_f32_e32 v51, v52, v49
	v_fma_f32 v47, -v47, v51, v50
	v_div_fmas_f32 v47, v47, v49, v51
	v_div_fixup_f32 v41, v47, v46, v41
	v_mul_f32_e32 v35, v35, v41
	v_cvt_pk_bf16_f32 v35, v35, s0
	global_store_short v[44:45], v35, off
	v_mov_b32_e32 v35, v118
	v_lshlrev_b32_e32 v35, 16, v35
	v_mul_f32_e32 v41, 0xbfb8aa3b, v35
	v_exp_f32_e32 v41, v41
	s_nop 0
	v_add_f32_e32 v41, 1.0, v41
	v_div_scale_f32 v44, s[2:3], v41, v41, v35
	v_rcp_f32_e32 v45, v44
	v_div_scale_f32 v46, vcc, v35, v41, v35
	v_fma_f32 v47, -v44, v45, 1.0
	v_fmac_f32_e32 v45, v47, v45
	v_mul_f32_e32 v47, v46, v45
	v_fma_f32 v49, -v44, v47, v46
	v_fmac_f32_e32 v47, v49, v45
	v_fma_f32 v44, -v44, v47, v46
	v_div_fmas_f32 v44, v44, v45, v47
	v_div_fixup_f32 v35, v44, v41, v35
	v_mul_f32_e32 v35, v36, v35
	v_cvt_pk_bf16_f32 v35, v35, s0
	global_store_short v[42:43], v35, off
	s_and_saveexec_b64 s[2:3], s[4:5]
	v_mov_b32_e32 v34, 0xfc0
	v_mov_b32_e32 v38, 6
	v_mov_b32_e32 v39, 63
	v_mov_b32_e32 v40, 0xfffff000
	s_or_b64 exec, exec, s[2:3]
	v_lshlrev_b32_e32 v38, v38, v48
	v_and_b32_e32 v35, v40, v1
	v_and_b32_e32 v36, v39, v76
	v_and_b32_e32 v34, v38, v34
	v_or3_b32 v34, v36, v35, v34
	v_ashrrev_i32_e32 v35, 31, v34
	v_lshlrev_b64 v[34:35], 10, v[34:35]
	v_lshl_add_u64 v[34:35], s[0:1], 0, v[34:35]
	v_mov_b32_e32 v57, v131
	v_lshl_add_u64 v[34:35], v[34:35], 0, v[56:57]
	v_mov_b32_e32 v36, v107
	v_add_f32_e32 v37, v37, v54
	v_add_f32_e32 v30, v30, v68
	v_lshlrev_b32_e32 v36, 16, v36
	v_mul_f32_e32 v38, 0xbfb8aa3b, v36
	v_exp_f32_e32 v38, v38
	s_nop 0
	v_add_f32_e32 v38, 1.0, v38
	v_div_scale_f32 v39, s[2:3], v38, v38, v36
	v_rcp_f32_e32 v40, v39
	s_movk_i32 s2, 0x4000
	v_fma_f32 v41, -v39, v40, 1.0
	v_fmac_f32_e32 v40, v41, v40
	v_div_scale_f32 v41, vcc, v36, v38, v36
	v_mul_f32_e32 v42, v41, v40
	v_fma_f32 v43, -v39, v42, v41
	v_fmac_f32_e32 v42, v43, v40
	v_fma_f32 v39, -v39, v42, v41
	v_div_fmas_f32 v39, v39, v40, v42
	v_div_fixup_f32 v36, v39, v38, v36
	v_mul_f32_e32 v36, v37, v36
	v_or_b32_e32 v43, 32, v77
	v_cvt_pk_bf16_f32 v36, v36, s0
	v_cmp_gt_i32_e32 vcc, s2, v43
	global_store_short v[34:35], v36, off
	v_mov_b32_e32 v39, 0x7fffff00
	v_cndmask_b32_e64 v36, 2, 6, vcc
	v_bfrev_b32_e32 v42, 0.5
	v_cndmask_b32_e32 v34, v39, v207, vcc
	v_cndmask_b32_e64 v35, 3, 63, vcc
	v_cndmask_b32_e32 v37, v42, v216, vcc
	v_lshlrev_b32_e32 v36, v36, v43
	v_and_b32_e32 v34, v34, v1
	v_and_b32_e32 v35, v35, v76
	v_and_b32_e32 v36, v36, v37
	v_or3_b32 v34, v35, v34, v36
	v_ashrrev_i32_e32 v35, 31, v34
	v_lshlrev_b64 v[36:37], 10, v[34:35]
	v_lshl_add_u64 v[34:35], v[66:67], 0, v[36:37]
	v_mov_b32_e32 v38, v120
	s_movk_i32 s2, 0x3fff
	v_mov_b32_e32 v40, 3
	v_mov_b32_e32 v41, 2
	v_cmp_gt_i32_e64 s[2:3], s2, v43
	v_lshlrev_b32_e32 v38, 16, v38
	v_mul_f32_e32 v44, 0xbfb8aa3b, v38
	v_exp_f32_e32 v44, v44
	s_nop 0
	v_add_f32_e32 v44, 1.0, v44
	v_div_scale_f32 v45, s[4:5], v44, v44, v38
	v_rcp_f32_e32 v46, v45
	s_nop 0
	v_fma_f32 v47, -v45, v46, 1.0
	v_fmac_f32_e32 v46, v47, v46
	v_div_scale_f32 v47, vcc, v38, v44, v38
	v_mul_f32_e32 v48, v47, v46
	v_fma_f32 v49, -v45, v48, v47
	v_fmac_f32_e32 v48, v49, v46
	v_fma_f32 v45, -v45, v48, v47
	v_div_fmas_f32 v45, v45, v46, v48
	v_div_fixup_f32 v38, v45, v44, v38
	v_mul_f32_e32 v30, v30, v38
	v_cvt_pk_bf16_f32 v30, v30, s0
	global_store_short v[34:35], v30, off
	v_mov_b32_e32 v45, 0x7fffff00
	v_mov_b32_e32 v44, 3
	v_mov_b32_e32 v30, 2
	v_bfrev_b32_e32 v46, 0.5
	s_and_saveexec_b64 s[4:5], s[2:3]
	v_mov_b32_e32 v46, 0xfc0
	v_mov_b32_e32 v30, 6
	v_mov_b32_e32 v44, 63
	v_mov_b32_e32 v45, 0xfffff000
	s_or_b64 exec, exec, s[4:5]
	v_or_b32_e32 v38, 33, v77
	s_movk_i32 s4, 0x3ffe
	v_cmp_gt_i32_e32 vcc, s4, v43
	s_movk_i32 s4, 0x3ffd
	v_lshlrev_b32_e32 v30, v30, v38
	v_cmp_gt_i32_e64 s[4:5], s4, v43
	v_and_b32_e32 v43, v45, v1
	v_and_b32_e32 v44, v44, v76
	v_and_b32_e32 v30, v30, v46
	v_or3_b32 v44, v44, v43, v30
	v_ashrrev_i32_e32 v45, 31, v44
	v_lshlrev_b64 v[44:45], 10, v[44:45]
	v_lshl_add_u64 v[44:45], v[66:67], 0, v[44:45]
	v_mov_b32_e32 v30, v110
	v_or_b32_e32 v34, 34, v77
	v_cndmask_b32_e64 v48, 2, 6, vcc
	v_cndmask_b32_e32 v35, v39, v207, vcc
	v_cndmask_b32_e64 v47, 3, 63, vcc
	v_cndmask_b32_e32 v49, v42, v216, vcc
	v_lshlrev_b32_e32 v34, v48, v34
	v_and_b32_e32 v35, v35, v1
	v_and_b32_e32 v47, v47, v76
	v_and_b32_e32 v34, v34, v49
	v_or3_b32 v34, v47, v35, v34
	v_add_f32_e32 v31, v31, v68
	v_ashrrev_i32_e32 v35, 31, v34
	v_lshlrev_b64 v[34:35], 10, v[34:35]
	v_add_f32_e32 v32, v32, v68
	v_lshlrev_b32_e32 v30, 16, v30
	v_mul_f32_e32 v43, 0xbfb8aa3b, v30
	v_exp_f32_e32 v43, v43
	s_nop 0
	v_add_f32_e32 v43, 1.0, v43
	v_div_scale_f32 v46, s[6:7], v43, v43, v30
	v_rcp_f32_e32 v47, v46
	s_nop 0
	v_fma_f32 v48, -v46, v47, 1.0
	v_fmac_f32_e32 v47, v48, v47
	v_div_scale_f32 v48, vcc, v30, v43, v30
	v_mul_f32_e32 v49, v48, v47
	v_fma_f32 v50, -v46, v49, v48
	v_fmac_f32_e32 v49, v50, v47
	v_fma_f32 v46, -v46, v49, v48
	v_div_fmas_f32 v46, v46, v47, v49
	v_div_fixup_f32 v30, v46, v43, v30
	v_mul_f32_e32 v30, v31, v30
	v_cvt_pk_bf16_f32 v30, v30, s0
	global_store_short v[44:45], v30, off
	v_lshl_add_u64 v[30:31], v[66:67], 0, v[34:35]
	v_mov_b32_e32 v43, v128
	v_lshlrev_b32_e32 v43, 16, v43
	v_mul_f32_e32 v44, 0xbfb8aa3b, v43
	v_exp_f32_e32 v44, v44
	s_nop 0
	v_add_f32_e32 v44, 1.0, v44
	v_div_scale_f32 v45, s[6:7], v44, v44, v43
	v_rcp_f32_e32 v46, v45
	s_nop 0
	v_fma_f32 v47, -v45, v46, 1.0
	v_fmac_f32_e32 v46, v47, v46
	v_div_scale_f32 v47, vcc, v43, v44, v43
	v_mul_f32_e32 v48, v47, v46
	v_fma_f32 v49, -v45, v48, v47
	v_fmac_f32_e32 v48, v49, v46
	v_fma_f32 v45, -v45, v48, v47
	v_div_fmas_f32 v45, v45, v46, v48
	v_div_fixup_f32 v43, v45, v44, v43
	v_mul_f32_e32 v32, v32, v43
	v_cvt_pk_bf16_f32 v32, v32, s0
	global_store_short v[30:31], v32, off
	s_and_saveexec_b64 s[6:7], s[4:5]
	v_mov_b32_e32 v42, 0xfc0
	v_mov_b32_e32 v41, 6
	v_mov_b32_e32 v40, 63
	v_mov_b32_e32 v39, 0xfffff000
	s_or_b64 exec, exec, s[6:7]
	v_or_b32_e32 v32, 35, v77
	v_and_b32_e32 v30, v39, v1
	v_lshlrev_b32_e32 v39, v41, v32
	v_and_b32_e32 v31, v40, v76
	v_and_b32_e32 v39, v39, v42
	v_or3_b32 v30, v31, v30, v39
	v_ashrrev_i32_e32 v31, 31, v30
	v_lshlrev_b64 v[30:31], 10, v[30:31]
	v_lshl_add_u64 v[30:31], v[66:67], 0, v[30:31]
	v_mov_b32_e32 v39, v119
	v_add_f32_e32 v33, v33, v68
	v_add_f32_e32 v26, v26, v69
	v_lshlrev_b32_e32 v39, 16, v39
	v_mul_f32_e32 v40, 0xbfb8aa3b, v39
	v_exp_f32_e32 v40, v40
	s_nop 0
	v_add_f32_e32 v40, 1.0, v40
	v_div_scale_f32 v41, s[6:7], v40, v40, v39
	v_rcp_f32_e32 v42, v41
	s_nop 0
	v_fma_f32 v43, -v41, v42, 1.0
	v_fmac_f32_e32 v42, v43, v42
	v_div_scale_f32 v43, vcc, v39, v40, v39
	v_mul_f32_e32 v44, v43, v42
	v_fma_f32 v45, -v41, v44, v43
	v_fmac_f32_e32 v44, v45, v42
	v_fma_f32 v41, -v41, v44, v43
	v_div_fmas_f32 v41, v41, v42, v44
	v_div_fixup_f32 v39, v41, v40, v39
	v_mul_f32_e32 v33, v33, v39
	v_cvt_pk_bf16_f32 v33, v33, s0
	global_store_short v[30:31], v33, off
	v_lshl_add_u64 v[30:31], s[0:1], 0, v[36:37]
	v_lshl_add_u64 v[36:37], v[30:31], 0, v[130:131]
	v_mov_b32_e32 v33, v121
	v_lshlrev_b32_e32 v33, 16, v33
	v_mul_f32_e32 v39, 0xbfb8aa3b, v33
	v_exp_f32_e32 v39, v39
	s_nop 0
	v_add_f32_e32 v39, 1.0, v39
	v_div_scale_f32 v40, s[6:7], v39, v39, v33
	v_rcp_f32_e32 v41, v40
	s_nop 0
	v_fma_f32 v42, -v40, v41, 1.0
	v_fmac_f32_e32 v41, v42, v41
	v_div_scale_f32 v42, vcc, v33, v39, v33
	v_mul_f32_e32 v43, v42, v41
	v_fma_f32 v44, -v40, v43, v42
	v_fmac_f32_e32 v43, v44, v41
	v_fma_f32 v40, -v40, v43, v42
	v_div_fmas_f32 v40, v40, v41, v43
	v_div_fixup_f32 v33, v40, v39, v33
	v_mul_f32_e32 v26, v26, v33
	v_cvt_pk_bf16_f32 v26, v26, s0
	global_store_short v[36:37], v26, off
	v_bfrev_b32_e32 v33, 0.5
	v_mov_b32_e32 v36, 2
	v_mov_b32_e32 v37, 3
	v_mov_b32_e32 v39, 0x7fffff00
	v_mov_b32_e32 v26, 0x7fffff00
	v_mov_b32_e32 v40, 3
	v_mov_b32_e32 v41, 2
	v_bfrev_b32_e32 v42, 0.5
	s_and_saveexec_b64 s[6:7], s[2:3]
	v_mov_b32_e32 v42, 0xfc0
	v_mov_b32_e32 v41, 6
	v_mov_b32_e32 v40, 63
	v_mov_b32_e32 v26, 0xfffff000
	s_or_b64 exec, exec, s[6:7]
	v_lshlrev_b32_e32 v41, v41, v38
	v_and_b32_e32 v26, v26, v1
	v_and_b32_e32 v40, v40, v76
	v_and_b32_e32 v41, v41, v42
	v_or3_b32 v40, v40, v26, v41
	v_ashrrev_i32_e32 v41, 31, v40
	v_lshlrev_b64 v[40:41], 10, v[40:41]
	v_lshl_add_u64 v[40:41], s[0:1], 0, v[40:41]
	v_lshl_add_u64 v[40:41], v[40:41], 0, v[130:131]
	v_mov_b32_e32 v26, v138
	v_add_f32_e32 v27, v27, v69
	v_add_f32_e32 v28, v28, v69
	v_lshlrev_b32_e32 v26, 16, v26
	v_mul_f32_e32 v42, 0xbfb8aa3b, v26
	v_exp_f32_e32 v42, v42
	s_nop 0
	v_add_f32_e32 v42, 1.0, v42
	v_div_scale_f32 v43, s[6:7], v42, v42, v26
	v_rcp_f32_e32 v44, v43
	s_nop 0
	v_fma_f32 v45, -v43, v44, 1.0
	v_fmac_f32_e32 v44, v45, v44
	v_div_scale_f32 v45, vcc, v26, v42, v26
	v_mul_f32_e32 v46, v45, v44
	v_fma_f32 v47, -v43, v46, v45
	v_fmac_f32_e32 v46, v47, v44
	v_fma_f32 v43, -v43, v46, v45
	v_div_fmas_f32 v43, v43, v44, v46
	v_div_fixup_f32 v26, v43, v42, v26
	v_mul_f32_e32 v26, v27, v26
	v_cvt_pk_bf16_f32 v26, v26, s0
	global_store_short v[40:41], v26, off
	v_lshl_add_u64 v[26:27], s[0:1], 0, v[34:35]
	v_lshl_add_u64 v[34:35], v[26:27], 0, v[130:131]
	v_mov_b32_e32 v40, v139
	v_lshlrev_b32_e32 v40, 16, v40
	v_mul_f32_e32 v41, 0xbfb8aa3b, v40
	v_exp_f32_e32 v41, v41
	s_nop 0
	v_add_f32_e32 v41, 1.0, v41
	v_div_scale_f32 v42, s[6:7], v41, v41, v40
	v_rcp_f32_e32 v43, v42
	s_nop 0
	v_fma_f32 v44, -v42, v43, 1.0
	v_fmac_f32_e32 v43, v44, v43
	v_div_scale_f32 v44, vcc, v40, v41, v40
	v_mul_f32_e32 v45, v44, v43
	v_fma_f32 v46, -v42, v45, v44
	v_fmac_f32_e32 v45, v46, v43
	v_fma_f32 v42, -v42, v45, v44
	v_div_fmas_f32 v42, v42, v43, v45
	v_div_fixup_f32 v40, v42, v41, v40
	v_mul_f32_e32 v28, v28, v40
	v_cvt_pk_bf16_f32 v28, v28, s0
	global_store_short v[34:35], v28, off
	s_and_saveexec_b64 s[6:7], s[4:5]
	v_mov_b32_e32 v33, 0xfc0
	v_mov_b32_e32 v36, 6
	v_mov_b32_e32 v37, 63
	v_mov_b32_e32 v39, 0xfffff000
	s_or_b64 exec, exec, s[6:7]
	v_lshlrev_b32_e32 v35, v36, v32
	v_and_b32_e32 v28, v39, v1
	v_and_b32_e32 v34, v37, v76
	v_and_b32_e32 v33, v35, v33
	v_or3_b32 v34, v34, v28, v33
	v_ashrrev_i32_e32 v35, 31, v34
	v_lshlrev_b64 v[34:35], 10, v[34:35]
	v_lshl_add_u64 v[34:35], s[0:1], 0, v[34:35]
	v_lshl_add_u64 v[34:35], v[34:35], 0, v[130:131]
	v_mov_b32_e32 v28, v123
	v_add_f32_e32 v29, v29, v69
	v_mov_b32_e32 v59, v131
	v_add_f32_e32 v22, v22, v60
	v_lshlrev_b32_e32 v28, 16, v28
	v_mul_f32_e32 v33, 0xbfb8aa3b, v28
	v_exp_f32_e32 v33, v33
	s_nop 0
	v_add_f32_e32 v33, 1.0, v33
	v_div_scale_f32 v36, s[6:7], v33, v33, v28
	v_rcp_f32_e32 v37, v36
	s_nop 0
	v_fma_f32 v39, -v36, v37, 1.0
	v_fmac_f32_e32 v37, v39, v37
	v_div_scale_f32 v39, vcc, v28, v33, v28
	v_mul_f32_e32 v40, v39, v37
	v_fma_f32 v41, -v36, v40, v39
	v_fmac_f32_e32 v40, v41, v37
	v_fma_f32 v36, -v36, v40, v39
	v_div_fmas_f32 v36, v36, v37, v40
	v_div_fixup_f32 v28, v36, v33, v28
	v_mul_f32_e32 v28, v29, v28
	v_cvt_pk_bf16_f32 v28, v28, s0
	global_store_short v[34:35], v28, off
	v_lshl_add_u64 v[28:29], v[30:31], 0, v[58:59]
	v_mov_b32_e32 v33, v127
	v_lshlrev_b32_e32 v33, 16, v33
	v_mul_f32_e32 v34, 0xbfb8aa3b, v33
	v_exp_f32_e32 v34, v34
	s_nop 0
	v_add_f32_e32 v34, 1.0, v34
	v_div_scale_f32 v35, s[6:7], v34, v34, v33
	v_rcp_f32_e32 v36, v35
	s_nop 0
	v_fma_f32 v37, -v35, v36, 1.0
	v_fmac_f32_e32 v36, v37, v36
	v_div_scale_f32 v37, vcc, v33, v34, v33
	v_mul_f32_e32 v39, v37, v36
	v_fma_f32 v40, -v35, v39, v37
	v_fmac_f32_e32 v39, v40, v36
	v_fma_f32 v35, -v35, v39, v37
	v_div_fmas_f32 v35, v35, v36, v39
	v_div_fixup_f32 v33, v35, v34, v33
	v_mul_f32_e32 v22, v22, v33
	v_cvt_pk_bf16_f32 v22, v22, s0
	global_store_short v[28:29], v22, off
	v_bfrev_b32_e32 v22, 0.5
	v_mov_b32_e32 v28, 2
	v_mov_b32_e32 v29, 3
	v_mov_b32_e32 v33, 0x7fffff00
	v_mov_b32_e32 v34, 0x7fffff00
	v_mov_b32_e32 v35, 3
	v_mov_b32_e32 v36, 2
	v_bfrev_b32_e32 v37, 0.5
	s_and_saveexec_b64 s[6:7], s[2:3]
	v_mov_b32_e32 v37, 0xfc0
	v_mov_b32_e32 v36, 6
	v_mov_b32_e32 v35, 63
	v_mov_b32_e32 v34, 0xfffff000
	s_or_b64 exec, exec, s[6:7]
	v_lshlrev_b32_e32 v36, v36, v38
	v_and_b32_e32 v34, v34, v1
	v_and_b32_e32 v35, v35, v76
	v_and_b32_e32 v36, v36, v37
	v_or3_b32 v34, v35, v34, v36
	v_ashrrev_i32_e32 v35, 31, v34
	v_lshlrev_b64 v[34:35], 10, v[34:35]
	v_lshl_add_u64 v[34:35], s[0:1], 0, v[34:35]
	v_lshl_add_u64 v[34:35], v[34:35], 0, v[58:59]
	v_mov_b32_e32 v36, v147
	v_add_f32_e32 v23, v23, v60
	v_add_f32_e32 v24, v24, v60
	v_lshlrev_b32_e32 v36, 16, v36
	v_mul_f32_e32 v37, 0xbfb8aa3b, v36
	v_exp_f32_e32 v37, v37
	s_nop 0
	v_add_f32_e32 v37, 1.0, v37
	v_div_scale_f32 v39, s[6:7], v37, v37, v36
	v_rcp_f32_e32 v40, v39
	s_nop 0
	v_fma_f32 v41, -v39, v40, 1.0
	v_fmac_f32_e32 v40, v41, v40
	v_div_scale_f32 v41, vcc, v36, v37, v36
	v_mul_f32_e32 v42, v41, v40
	v_fma_f32 v43, -v39, v42, v41
	v_fmac_f32_e32 v42, v43, v40
	v_fma_f32 v39, -v39, v42, v41
	v_div_fmas_f32 v39, v39, v40, v42
	v_div_fixup_f32 v36, v39, v37, v36
	v_mul_f32_e32 v23, v23, v36
	v_cvt_pk_bf16_f32 v23, v23, s0
	global_store_short v[34:35], v23, off
	v_lshl_add_u64 v[34:35], v[26:27], 0, v[58:59]
	v_mov_b32_e32 v23, v125
	v_lshlrev_b32_e32 v23, 16, v23
	v_mul_f32_e32 v36, 0xbfb8aa3b, v23
	v_exp_f32_e32 v36, v36
	s_nop 0
	v_add_f32_e32 v36, 1.0, v36
	v_div_scale_f32 v37, s[6:7], v36, v36, v23
	v_rcp_f32_e32 v39, v37
	s_nop 0
	v_fma_f32 v40, -v37, v39, 1.0
	v_fmac_f32_e32 v39, v40, v39
	v_div_scale_f32 v40, vcc, v23, v36, v23
	v_mul_f32_e32 v41, v40, v39
	v_fma_f32 v42, -v37, v41, v40
	v_fmac_f32_e32 v41, v42, v39
	v_fma_f32 v37, -v37, v41, v40
	v_div_fmas_f32 v37, v37, v39, v41
	v_div_fixup_f32 v23, v37, v36, v23
	v_mul_f32_e32 v23, v24, v23
	v_cvt_pk_bf16_f32 v23, v23, s0
	global_store_short v[34:35], v23, off
	s_and_saveexec_b64 s[6:7], s[4:5]
	v_mov_b32_e32 v22, 0xfc0
	v_mov_b32_e32 v28, 6
	v_mov_b32_e32 v29, 63
	v_mov_b32_e32 v33, 0xfffff000
	s_or_b64 exec, exec, s[6:7]
	v_lshlrev_b32_e32 v28, v28, v32
	v_and_b32_e32 v23, v33, v1
	v_and_b32_e32 v24, v29, v76
	v_and_b32_e32 v22, v28, v22
	v_or3_b32 v22, v24, v23, v22
	v_ashrrev_i32_e32 v23, 31, v22
	v_lshlrev_b64 v[22:23], 10, v[22:23]
	v_lshl_add_u64 v[22:23], s[0:1], 0, v[22:23]
	v_mov_b32_e32 v59, v131
	v_lshl_add_u64 v[22:23], v[22:23], 0, v[58:59]
	v_mov_b32_e32 v24, v129
	v_add_f32_e32 v25, v25, v60
	v_mov_b32_e32 v57, v131
	v_add_f32_e32 v18, v18, v54
	v_lshlrev_b32_e32 v24, 16, v24
	v_mul_f32_e32 v28, 0xbfb8aa3b, v24
	v_exp_f32_e32 v28, v28
	s_nop 0
	v_add_f32_e32 v28, 1.0, v28
	v_div_scale_f32 v29, s[6:7], v28, v28, v24
	v_rcp_f32_e32 v33, v29
	s_nop 0
	v_fma_f32 v34, -v29, v33, 1.0
	v_fmac_f32_e32 v33, v34, v33
	v_div_scale_f32 v34, vcc, v24, v28, v24
	v_mul_f32_e32 v35, v34, v33
	v_fma_f32 v36, -v29, v35, v34
	v_fmac_f32_e32 v35, v36, v33
	v_fma_f32 v29, -v29, v35, v34
	v_div_fmas_f32 v29, v29, v33, v35
	v_div_fixup_f32 v24, v29, v28, v24
	v_mul_f32_e32 v24, v25, v24
	v_cvt_pk_bf16_f32 v24, v24, s0
	global_store_short v[22:23], v24, off
	v_lshl_add_u64 v[22:23], v[30:31], 0, v[56:57]
	v_mov_b32_e32 v24, v140
	v_lshlrev_b32_e32 v24, 16, v24
	v_mul_f32_e32 v25, 0xbfb8aa3b, v24
	v_exp_f32_e32 v25, v25
	s_nop 0
	v_add_f32_e32 v25, 1.0, v25
	v_div_scale_f32 v28, s[6:7], v25, v25, v24
	v_rcp_f32_e32 v29, v28
	s_nop 0
	v_fma_f32 v30, -v28, v29, 1.0
	v_fmac_f32_e32 v29, v30, v29
	v_div_scale_f32 v30, vcc, v24, v25, v24
	v_mul_f32_e32 v31, v30, v29
	v_fma_f32 v33, -v28, v31, v30
	v_fmac_f32_e32 v31, v33, v29
	v_fma_f32 v28, -v28, v31, v30
	v_div_fmas_f32 v28, v28, v29, v31
	v_div_fixup_f32 v24, v28, v25, v24
	v_mul_f32_e32 v18, v18, v24
	v_cvt_pk_bf16_f32 v18, v18, s0
	global_store_short v[22:23], v18, off
	v_bfrev_b32_e32 v18, 0.5
	v_mov_b32_e32 v22, 2
	v_mov_b32_e32 v23, 3
	v_mov_b32_e32 v24, 0x7fffff00
	v_mov_b32_e32 v25, 0x7fffff00
	v_mov_b32_e32 v28, 3
	v_mov_b32_e32 v29, 2
	v_bfrev_b32_e32 v30, 0.5
	s_and_saveexec_b64 s[6:7], s[2:3]
	v_mov_b32_e32 v30, 0xfc0
	v_mov_b32_e32 v29, 6
	v_mov_b32_e32 v28, 63
	v_mov_b32_e32 v25, 0xfffff000
	s_or_b64 exec, exec, s[6:7]
	v_lshlrev_b32_e32 v29, v29, v38
	v_and_b32_e32 v25, v25, v1
	v_and_b32_e32 v28, v28, v76
	v_and_b32_e32 v29, v29, v30
	v_or3_b32 v28, v28, v25, v29
	v_ashrrev_i32_e32 v29, 31, v28
	v_lshlrev_b64 v[28:29], 10, v[28:29]
	v_lshl_add_u64 v[28:29], s[0:1], 0, v[28:29]
	v_lshl_add_u64 v[28:29], v[28:29], 0, v[56:57]
	v_mov_b32_e32 v25, v137
	v_add_f32_e32 v19, v19, v54
	v_lshl_add_u64 v[26:27], v[26:27], 0, v[56:57]
	v_add_f32_e32 v20, v20, v54
	v_lshlrev_b32_e32 v25, 16, v25
	v_mul_f32_e32 v30, 0xbfb8aa3b, v25
	v_exp_f32_e32 v30, v30
	s_nop 0
	v_add_f32_e32 v30, 1.0, v30
	v_div_scale_f32 v31, s[2:3], v30, v30, v25
	v_rcp_f32_e32 v33, v31
	v_div_scale_f32 v34, vcc, v25, v30, v25
	v_fma_f32 v35, -v31, v33, 1.0
	v_fmac_f32_e32 v33, v35, v33
	v_mul_f32_e32 v35, v34, v33
	v_fma_f32 v36, -v31, v35, v34
	v_fmac_f32_e32 v35, v36, v33
	v_fma_f32 v31, -v31, v35, v34
	v_div_fmas_f32 v31, v31, v33, v35
	v_div_fixup_f32 v25, v31, v30, v25
	v_mul_f32_e32 v19, v19, v25
	v_cvt_pk_bf16_f32 v19, v19, s0
	global_store_short v[28:29], v19, off
	v_mov_b32_e32 v19, v142
	v_lshlrev_b32_e32 v19, 16, v19
	v_mul_f32_e32 v25, 0xbfb8aa3b, v19
	v_exp_f32_e32 v25, v25
	s_nop 0
	v_add_f32_e32 v25, 1.0, v25
	v_div_scale_f32 v28, s[2:3], v25, v25, v19
	v_rcp_f32_e32 v29, v28
	v_div_scale_f32 v30, vcc, v19, v25, v19
	v_fma_f32 v31, -v28, v29, 1.0
	v_fmac_f32_e32 v29, v31, v29
	v_mul_f32_e32 v31, v30, v29
	v_fma_f32 v33, -v28, v31, v30
	v_fmac_f32_e32 v31, v33, v29
	v_fma_f32 v28, -v28, v31, v30
	v_div_fmas_f32 v28, v28, v29, v31
	v_div_fixup_f32 v19, v28, v25, v19
	v_mul_f32_e32 v19, v20, v19
	v_cvt_pk_bf16_f32 v19, v19, s0
	global_store_short v[26:27], v19, off
	s_and_saveexec_b64 s[2:3], s[4:5]
	v_mov_b32_e32 v18, 0xfc0
	v_mov_b32_e32 v22, 6
	v_mov_b32_e32 v23, 63
	v_mov_b32_e32 v24, 0xfffff000
	s_or_b64 exec, exec, s[2:3]
	v_lshlrev_b32_e32 v22, v22, v32
	v_and_b32_e32 v19, v24, v1
	v_and_b32_e32 v20, v23, v76
	v_and_b32_e32 v18, v22, v18
	v_or3_b32 v18, v20, v19, v18
	v_ashrrev_i32_e32 v19, 31, v18
	v_lshlrev_b64 v[18:19], 10, v[18:19]
	v_lshl_add_u64 v[18:19], s[0:1], 0, v[18:19]
	v_mov_b32_e32 v57, v131
	v_lshl_add_u64 v[18:19], v[18:19], 0, v[56:57]
	v_mov_b32_e32 v20, v126
	v_add_f32_e32 v21, v21, v54
	v_add_f32_e32 v14, v14, v68
	v_lshlrev_b32_e32 v20, 16, v20
	v_mul_f32_e32 v22, 0xbfb8aa3b, v20
	v_exp_f32_e32 v22, v22
	s_nop 0
	v_add_f32_e32 v22, 1.0, v22
	v_div_scale_f32 v23, s[2:3], v22, v22, v20
	v_rcp_f32_e32 v24, v23
	s_movk_i32 s2, 0x4000
	v_fma_f32 v25, -v23, v24, 1.0
	v_fmac_f32_e32 v24, v25, v24
	v_div_scale_f32 v25, vcc, v20, v22, v20
	v_mul_f32_e32 v26, v25, v24
	v_fma_f32 v27, -v23, v26, v25
	v_fmac_f32_e32 v26, v27, v24
	v_fma_f32 v23, -v23, v26, v25
	v_div_fmas_f32 v23, v23, v24, v26
	v_div_fixup_f32 v20, v23, v22, v20
	v_mul_f32_e32 v20, v21, v20
	v_or_b32_e32 v27, 48, v77
	v_cvt_pk_bf16_f32 v20, v20, s0
	v_cmp_gt_i32_e32 vcc, s2, v27
	global_store_short v[18:19], v20, off
	v_mov_b32_e32 v23, 0x7fffff00
	v_cndmask_b32_e64 v20, 2, 6, vcc
	v_bfrev_b32_e32 v26, 0.5
	v_cndmask_b32_e32 v18, v23, v207, vcc
	v_cndmask_b32_e64 v19, 3, 63, vcc
	v_cndmask_b32_e32 v21, v26, v216, vcc
	v_lshlrev_b32_e32 v20, v20, v27
	v_and_b32_e32 v18, v18, v1
	v_and_b32_e32 v19, v19, v76
	v_and_b32_e32 v20, v20, v21
	v_or3_b32 v18, v19, v18, v20
	v_ashrrev_i32_e32 v19, 31, v18
	v_lshlrev_b64 v[20:21], 10, v[18:19]
	v_lshl_add_u64 v[18:19], v[66:67], 0, v[20:21]
	v_mov_b32_e32 v22, v144
	s_movk_i32 s2, 0x3fff
	v_mov_b32_e32 v24, 3
	v_mov_b32_e32 v25, 2
	v_cmp_gt_i32_e64 s[2:3], s2, v27
	v_lshlrev_b32_e32 v22, 16, v22
	v_mul_f32_e32 v28, 0xbfb8aa3b, v22
	v_exp_f32_e32 v28, v28
	s_nop 0
	v_add_f32_e32 v28, 1.0, v28
	v_div_scale_f32 v29, s[4:5], v28, v28, v22
	v_rcp_f32_e32 v30, v29
	s_nop 0
	v_fma_f32 v31, -v29, v30, 1.0
	v_fmac_f32_e32 v30, v31, v30
	v_div_scale_f32 v31, vcc, v22, v28, v22
	v_mul_f32_e32 v32, v31, v30
	v_fma_f32 v33, -v29, v32, v31
	v_fmac_f32_e32 v32, v33, v30
	v_fma_f32 v29, -v29, v32, v31
	v_div_fmas_f32 v29, v29, v30, v32
	v_div_fixup_f32 v22, v29, v28, v22
	v_mul_f32_e32 v14, v14, v22
	v_cvt_pk_bf16_f32 v14, v14, s0
	global_store_short v[18:19], v14, off
	v_mov_b32_e32 v29, 0x7fffff00
	v_mov_b32_e32 v28, 3
	v_mov_b32_e32 v14, 2
	v_bfrev_b32_e32 v30, 0.5
	s_and_saveexec_b64 s[4:5], s[2:3]
	v_mov_b32_e32 v30, 0xfc0
	v_mov_b32_e32 v14, 6
	v_mov_b32_e32 v28, 63
	v_mov_b32_e32 v29, 0xfffff000
	s_or_b64 exec, exec, s[4:5]
	v_or_b32_e32 v22, 49, v77
	s_movk_i32 s4, 0x3ffe
	v_cmp_gt_i32_e32 vcc, s4, v27
	s_movk_i32 s4, 0x3ffd
	v_lshlrev_b32_e32 v14, v14, v22
	v_cmp_gt_i32_e64 s[4:5], s4, v27
	v_and_b32_e32 v27, v29, v1
	v_and_b32_e32 v28, v28, v76
	v_and_b32_e32 v14, v14, v30
	v_or3_b32 v28, v28, v27, v14
	v_ashrrev_i32_e32 v29, 31, v28
	v_lshlrev_b64 v[28:29], 10, v[28:29]
	v_lshl_add_u64 v[28:29], v[66:67], 0, v[28:29]
	v_mov_b32_e32 v14, v141
	v_or_b32_e32 v18, 50, v77
	v_cndmask_b32_e64 v32, 2, 6, vcc
	v_cndmask_b32_e32 v19, v23, v207, vcc
	v_cndmask_b32_e64 v31, 3, 63, vcc
	v_cndmask_b32_e32 v33, v26, v216, vcc
	v_lshlrev_b32_e32 v18, v32, v18
	v_and_b32_e32 v19, v19, v1
	v_and_b32_e32 v31, v31, v76
	v_and_b32_e32 v18, v18, v33
	v_or3_b32 v18, v31, v19, v18
	v_add_f32_e32 v15, v15, v68
	v_ashrrev_i32_e32 v19, 31, v18
	v_lshlrev_b64 v[18:19], 10, v[18:19]
	v_add_f32_e32 v16, v16, v68
	v_lshlrev_b32_e32 v14, 16, v14
	v_mul_f32_e32 v27, 0xbfb8aa3b, v14
	v_exp_f32_e32 v27, v27
	s_nop 0
	v_add_f32_e32 v27, 1.0, v27
	v_div_scale_f32 v30, s[6:7], v27, v27, v14
	v_rcp_f32_e32 v31, v30
	s_nop 0
	v_fma_f32 v32, -v30, v31, 1.0
	v_fmac_f32_e32 v31, v32, v31
	v_div_scale_f32 v32, vcc, v14, v27, v14
	v_mul_f32_e32 v33, v32, v31
	v_fma_f32 v34, -v30, v33, v32
	v_fmac_f32_e32 v33, v34, v31
	v_fma_f32 v30, -v30, v33, v32
	v_div_fmas_f32 v30, v30, v31, v33
	v_div_fixup_f32 v14, v30, v27, v14
	v_mul_f32_e32 v14, v15, v14
	v_cvt_pk_bf16_f32 v14, v14, s0
	global_store_short v[28:29], v14, off
	v_lshl_add_u64 v[14:15], v[66:67], 0, v[18:19]
	v_mov_b32_e32 v27, v149
	v_lshlrev_b32_e32 v27, 16, v27
	v_mul_f32_e32 v28, 0xbfb8aa3b, v27
	v_exp_f32_e32 v28, v28
	s_nop 0
	v_add_f32_e32 v28, 1.0, v28
	v_div_scale_f32 v29, s[6:7], v28, v28, v27
	v_rcp_f32_e32 v30, v29
	s_nop 0
	v_fma_f32 v31, -v29, v30, 1.0
	v_fmac_f32_e32 v30, v31, v30
	v_div_scale_f32 v31, vcc, v27, v28, v27
	v_mul_f32_e32 v32, v31, v30
	v_fma_f32 v33, -v29, v32, v31
	v_fmac_f32_e32 v32, v33, v30
	v_fma_f32 v29, -v29, v32, v31
	v_div_fmas_f32 v29, v29, v30, v32
	v_div_fixup_f32 v27, v29, v28, v27
	v_mul_f32_e32 v16, v16, v27
	v_cvt_pk_bf16_f32 v16, v16, s0
	global_store_short v[14:15], v16, off
	s_and_saveexec_b64 s[6:7], s[4:5]
	v_mov_b32_e32 v26, 0xfc0
	v_mov_b32_e32 v25, 6
	v_mov_b32_e32 v24, 63
	v_mov_b32_e32 v23, 0xfffff000
	s_or_b64 exec, exec, s[6:7]
	v_or_b32_e32 v16, 51, v77
	v_and_b32_e32 v14, v23, v1
	v_lshlrev_b32_e32 v23, v25, v16
	v_and_b32_e32 v15, v24, v76
	v_and_b32_e32 v23, v23, v26
	v_or3_b32 v14, v15, v14, v23
	v_ashrrev_i32_e32 v15, 31, v14
	v_lshlrev_b64 v[14:15], 10, v[14:15]
	v_lshl_add_u64 v[14:15], v[66:67], 0, v[14:15]
	v_mov_b32_e32 v23, v143
	v_add_f32_e32 v17, v17, v68
	v_add_f32_e32 v10, v10, v69
	v_lshlrev_b32_e32 v23, 16, v23
	v_mul_f32_e32 v24, 0xbfb8aa3b, v23
	v_exp_f32_e32 v24, v24
	s_nop 0
	v_add_f32_e32 v24, 1.0, v24
	v_div_scale_f32 v25, s[6:7], v24, v24, v23
	v_rcp_f32_e32 v26, v25
	s_nop 0
	v_fma_f32 v27, -v25, v26, 1.0
	v_fmac_f32_e32 v26, v27, v26
	v_div_scale_f32 v27, vcc, v23, v24, v23
	v_mul_f32_e32 v28, v27, v26
	v_fma_f32 v29, -v25, v28, v27
	v_fmac_f32_e32 v28, v29, v26
	v_fma_f32 v25, -v25, v28, v27
	v_div_fmas_f32 v25, v25, v26, v28
	v_div_fixup_f32 v23, v25, v24, v23
	v_mul_f32_e32 v17, v17, v23
	v_cvt_pk_bf16_f32 v17, v17, s0
	global_store_short v[14:15], v17, off
	v_lshl_add_u64 v[14:15], s[0:1], 0, v[20:21]
	v_lshl_add_u64 v[20:21], v[14:15], 0, v[130:131]
	v_mov_b32_e32 v17, v145
	v_lshlrev_b32_e32 v17, 16, v17
	v_mul_f32_e32 v23, 0xbfb8aa3b, v17
	v_exp_f32_e32 v23, v23
	s_nop 0
	v_add_f32_e32 v23, 1.0, v23
	v_div_scale_f32 v24, s[6:7], v23, v23, v17
	v_rcp_f32_e32 v25, v24
	s_nop 0
	v_fma_f32 v26, -v24, v25, 1.0
	v_fmac_f32_e32 v25, v26, v25
	v_div_scale_f32 v26, vcc, v17, v23, v17
	v_mul_f32_e32 v27, v26, v25
	v_fma_f32 v28, -v24, v27, v26
	v_fmac_f32_e32 v27, v28, v25
	v_fma_f32 v24, -v24, v27, v26
	v_div_fmas_f32 v24, v24, v25, v27
	v_div_fixup_f32 v17, v24, v23, v17
	v_mul_f32_e32 v10, v10, v17
	v_cvt_pk_bf16_f32 v10, v10, s0
	global_store_short v[20:21], v10, off
	v_bfrev_b32_e32 v17, 0.5
	v_mov_b32_e32 v20, 2
	v_mov_b32_e32 v21, 3
	v_mov_b32_e32 v23, 0x7fffff00
	v_mov_b32_e32 v10, 0x7fffff00
	v_mov_b32_e32 v24, 3
	v_mov_b32_e32 v25, 2
	v_bfrev_b32_e32 v26, 0.5
	s_and_saveexec_b64 s[6:7], s[2:3]
	v_mov_b32_e32 v26, 0xfc0
	v_mov_b32_e32 v25, 6
	v_mov_b32_e32 v24, 63
	v_mov_b32_e32 v10, 0xfffff000
	s_or_b64 exec, exec, s[6:7]
	v_lshlrev_b32_e32 v25, v25, v22
	v_and_b32_e32 v10, v10, v1
	v_and_b32_e32 v24, v24, v76
	v_and_b32_e32 v25, v25, v26
	v_or3_b32 v24, v24, v10, v25
	v_ashrrev_i32_e32 v25, 31, v24
	v_lshlrev_b64 v[24:25], 10, v[24:25]
	v_lshl_add_u64 v[24:25], s[0:1], 0, v[24:25]
	v_lshl_add_u64 v[24:25], v[24:25], 0, v[130:131]
	v_mov_b32_e32 v10, v153
	v_add_f32_e32 v11, v11, v69
	v_add_f32_e32 v12, v12, v69
	v_lshlrev_b32_e32 v10, 16, v10
	v_mul_f32_e32 v26, 0xbfb8aa3b, v10
	v_exp_f32_e32 v26, v26
	s_nop 0
	v_add_f32_e32 v26, 1.0, v26
	v_div_scale_f32 v27, s[6:7], v26, v26, v10
	v_rcp_f32_e32 v28, v27
	s_nop 0
	v_fma_f32 v29, -v27, v28, 1.0
	v_fmac_f32_e32 v28, v29, v28
	v_div_scale_f32 v29, vcc, v10, v26, v10
	v_mul_f32_e32 v30, v29, v28
	v_fma_f32 v31, -v27, v30, v29
	v_fmac_f32_e32 v30, v31, v28
	v_fma_f32 v27, -v27, v30, v29
	v_div_fmas_f32 v27, v27, v28, v30
	v_div_fixup_f32 v10, v27, v26, v10
	v_mul_f32_e32 v10, v11, v10
	v_cvt_pk_bf16_f32 v10, v10, s0
	global_store_short v[24:25], v10, off
	v_lshl_add_u64 v[10:11], s[0:1], 0, v[18:19]
	v_lshl_add_u64 v[18:19], v[10:11], 0, v[130:131]
	v_mov_b32_e32 v24, v154
	v_lshlrev_b32_e32 v24, 16, v24
	v_mul_f32_e32 v25, 0xbfb8aa3b, v24
	v_exp_f32_e32 v25, v25
	s_nop 0
	v_add_f32_e32 v25, 1.0, v25
	v_div_scale_f32 v26, s[6:7], v25, v25, v24
	v_rcp_f32_e32 v27, v26
	s_nop 0
	v_fma_f32 v28, -v26, v27, 1.0
	v_fmac_f32_e32 v27, v28, v27
	v_div_scale_f32 v28, vcc, v24, v25, v24
	v_mul_f32_e32 v29, v28, v27
	v_fma_f32 v30, -v26, v29, v28
	v_fmac_f32_e32 v29, v30, v27
	v_fma_f32 v26, -v26, v29, v28
	v_div_fmas_f32 v26, v26, v27, v29
	v_div_fixup_f32 v24, v26, v25, v24
	v_mul_f32_e32 v12, v12, v24
	v_cvt_pk_bf16_f32 v12, v12, s0
	global_store_short v[18:19], v12, off
	s_and_saveexec_b64 s[6:7], s[4:5]
	v_mov_b32_e32 v17, 0xfc0
	v_mov_b32_e32 v20, 6
	v_mov_b32_e32 v21, 63
	v_mov_b32_e32 v23, 0xfffff000
	s_or_b64 exec, exec, s[6:7]
	v_lshlrev_b32_e32 v19, v20, v16
	v_and_b32_e32 v12, v23, v1
	v_and_b32_e32 v18, v21, v76
	v_and_b32_e32 v17, v19, v17
	v_or3_b32 v18, v18, v12, v17
	v_ashrrev_i32_e32 v19, 31, v18
	v_lshlrev_b64 v[18:19], 10, v[18:19]
	v_lshl_add_u64 v[18:19], s[0:1], 0, v[18:19]
	v_lshl_add_u64 v[18:19], v[18:19], 0, v[130:131]
	v_mov_b32_e32 v12, v146
	v_add_f32_e32 v13, v13, v69
	v_mov_b32_e32 v59, v131
	v_add_f32_e32 v6, v6, v60
	v_lshlrev_b32_e32 v12, 16, v12
	v_mul_f32_e32 v17, 0xbfb8aa3b, v12
	v_exp_f32_e32 v17, v17
	s_nop 0
	v_add_f32_e32 v17, 1.0, v17
	v_div_scale_f32 v20, s[6:7], v17, v17, v12
	v_rcp_f32_e32 v21, v20
	s_nop 0
	v_fma_f32 v23, -v20, v21, 1.0
	v_fmac_f32_e32 v21, v23, v21
	v_div_scale_f32 v23, vcc, v12, v17, v12
	v_mul_f32_e32 v24, v23, v21
	v_fma_f32 v25, -v20, v24, v23
	v_fmac_f32_e32 v24, v25, v21
	v_fma_f32 v20, -v20, v24, v23
	v_div_fmas_f32 v20, v20, v21, v24
	v_div_fixup_f32 v12, v20, v17, v12
	v_mul_f32_e32 v12, v13, v12
	v_cvt_pk_bf16_f32 v12, v12, s0
	global_store_short v[18:19], v12, off
	v_lshl_add_u64 v[12:13], v[14:15], 0, v[58:59]
	v_mov_b32_e32 v17, v151
	v_lshlrev_b32_e32 v17, 16, v17
	v_mul_f32_e32 v18, 0xbfb8aa3b, v17
	v_exp_f32_e32 v18, v18
	s_nop 0
	v_add_f32_e32 v18, 1.0, v18
	v_div_scale_f32 v19, s[6:7], v18, v18, v17
	v_rcp_f32_e32 v20, v19
	s_nop 0
	v_fma_f32 v21, -v19, v20, 1.0
	v_fmac_f32_e32 v20, v21, v20
	v_div_scale_f32 v21, vcc, v17, v18, v17
	v_mul_f32_e32 v23, v21, v20
	v_fma_f32 v24, -v19, v23, v21
	v_fmac_f32_e32 v23, v24, v20
	v_fma_f32 v19, -v19, v23, v21
	v_div_fmas_f32 v19, v19, v20, v23
	v_div_fixup_f32 v17, v19, v18, v17
	v_mul_f32_e32 v6, v6, v17
	v_cvt_pk_bf16_f32 v6, v6, s0
	global_store_short v[12:13], v6, off
	v_bfrev_b32_e32 v6, 0.5
	v_mov_b32_e32 v12, 2
	v_mov_b32_e32 v13, 3
	v_mov_b32_e32 v17, 0x7fffff00
	v_mov_b32_e32 v18, 0x7fffff00
	v_mov_b32_e32 v19, 3
	v_mov_b32_e32 v20, 2
	v_bfrev_b32_e32 v21, 0.5
	s_and_saveexec_b64 s[6:7], s[2:3]
	v_mov_b32_e32 v21, 0xfc0
	v_mov_b32_e32 v20, 6
	v_mov_b32_e32 v19, 63
	v_mov_b32_e32 v18, 0xfffff000
	s_or_b64 exec, exec, s[6:7]
	v_lshlrev_b32_e32 v20, v20, v22
	v_and_b32_e32 v18, v18, v1
	v_and_b32_e32 v19, v19, v76
	v_and_b32_e32 v20, v20, v21
	v_or3_b32 v18, v19, v18, v20
	v_ashrrev_i32_e32 v19, 31, v18
	v_lshlrev_b64 v[18:19], 10, v[18:19]
	v_lshl_add_u64 v[18:19], s[0:1], 0, v[18:19]
	v_lshl_add_u64 v[18:19], v[18:19], 0, v[58:59]
	v_mov_b32_e32 v20, v164
	v_add_f32_e32 v7, v7, v60
	v_add_f32_e32 v8, v8, v60
	v_lshlrev_b32_e32 v20, 16, v20
	v_mul_f32_e32 v21, 0xbfb8aa3b, v20
	v_exp_f32_e32 v21, v21
	s_nop 0
	v_add_f32_e32 v21, 1.0, v21
	v_div_scale_f32 v23, s[6:7], v21, v21, v20
	v_rcp_f32_e32 v24, v23
	s_nop 0
	v_fma_f32 v25, -v23, v24, 1.0
	v_fmac_f32_e32 v24, v25, v24
	v_div_scale_f32 v25, vcc, v20, v21, v20
	v_mul_f32_e32 v26, v25, v24
	v_fma_f32 v27, -v23, v26, v25
	v_fmac_f32_e32 v26, v27, v24
	v_fma_f32 v23, -v23, v26, v25
	v_div_fmas_f32 v23, v23, v24, v26
	v_div_fixup_f32 v20, v23, v21, v20
	v_mul_f32_e32 v7, v7, v20
	v_cvt_pk_bf16_f32 v7, v7, s0
	global_store_short v[18:19], v7, off
	v_lshl_add_u64 v[18:19], v[10:11], 0, v[58:59]
	v_mov_b32_e32 v7, v148
	v_lshlrev_b32_e32 v7, 16, v7
	v_mul_f32_e32 v20, 0xbfb8aa3b, v7
	v_exp_f32_e32 v20, v20
	s_nop 0
	v_add_f32_e32 v20, 1.0, v20
	v_div_scale_f32 v21, s[6:7], v20, v20, v7
	v_rcp_f32_e32 v23, v21
	s_nop 0
	v_fma_f32 v24, -v21, v23, 1.0
	v_fmac_f32_e32 v23, v24, v23
	v_div_scale_f32 v24, vcc, v7, v20, v7
	v_mul_f32_e32 v25, v24, v23
	v_fma_f32 v26, -v21, v25, v24
	v_fmac_f32_e32 v25, v26, v23
	v_fma_f32 v21, -v21, v25, v24
	v_div_fmas_f32 v21, v21, v23, v25
	v_div_fixup_f32 v7, v21, v20, v7
	v_mul_f32_e32 v7, v8, v7
	v_cvt_pk_bf16_f32 v7, v7, s0
	global_store_short v[18:19], v7, off
	s_and_saveexec_b64 s[6:7], s[4:5]
	v_mov_b32_e32 v6, 0xfc0
	v_mov_b32_e32 v12, 6
	v_mov_b32_e32 v13, 63
	v_mov_b32_e32 v17, 0xfffff000
	s_or_b64 exec, exec, s[6:7]
	v_lshlrev_b32_e32 v12, v12, v16
	v_and_b32_e32 v7, v17, v1
	v_and_b32_e32 v8, v13, v76
	v_and_b32_e32 v6, v12, v6
	v_or3_b32 v6, v8, v7, v6
	v_ashrrev_i32_e32 v7, 31, v6
	v_lshlrev_b64 v[6:7], 10, v[6:7]
	v_lshl_add_u64 v[6:7], s[0:1], 0, v[6:7]
	v_mov_b32_e32 v59, v131
	v_lshl_add_u64 v[6:7], v[6:7], 0, v[58:59]
	v_mov_b32_e32 v8, v91
	v_add_f32_e32 v9, v9, v60
	v_mov_b32_e32 v57, v131
	v_add_f32_e32 v2, v2, v54
	v_lshlrev_b32_e32 v8, 16, v8
	v_mul_f32_e32 v12, 0xbfb8aa3b, v8
	v_exp_f32_e32 v12, v12
	s_nop 0
	v_add_f32_e32 v12, 1.0, v12
	v_div_scale_f32 v13, s[6:7], v12, v12, v8
	v_rcp_f32_e32 v17, v13
	s_nop 0
	v_fma_f32 v18, -v13, v17, 1.0
	v_fmac_f32_e32 v17, v18, v17
	v_div_scale_f32 v18, vcc, v8, v12, v8
	v_mul_f32_e32 v19, v18, v17
	v_fma_f32 v20, -v13, v19, v18
	v_fmac_f32_e32 v19, v20, v17
	v_fma_f32 v13, -v13, v19, v18
	v_div_fmas_f32 v13, v13, v17, v19
	v_div_fixup_f32 v8, v13, v12, v8
	v_mul_f32_e32 v8, v9, v8
	v_cvt_pk_bf16_f32 v8, v8, s0
	global_store_short v[6:7], v8, off
	v_lshl_add_u64 v[6:7], v[14:15], 0, v[56:57]
	v_mov_b32_e32 v8, v156
	v_lshlrev_b32_e32 v8, 16, v8
	v_mul_f32_e32 v9, 0xbfb8aa3b, v8
	v_exp_f32_e32 v9, v9
	s_nop 0
	v_add_f32_e32 v9, 1.0, v9
	v_div_scale_f32 v12, s[6:7], v9, v9, v8
	v_rcp_f32_e32 v13, v12
	s_nop 0
	v_fma_f32 v14, -v12, v13, 1.0
	v_fmac_f32_e32 v13, v14, v13
	v_div_scale_f32 v14, vcc, v8, v9, v8
	v_mul_f32_e32 v15, v14, v13
	v_fma_f32 v17, -v12, v15, v14
	v_fmac_f32_e32 v15, v17, v13
	v_fma_f32 v12, -v12, v15, v14
	v_div_fmas_f32 v12, v12, v13, v15
	v_div_fixup_f32 v8, v12, v9, v8
	v_mul_f32_e32 v2, v2, v8
	v_cvt_pk_bf16_f32 v2, v2, s0
	global_store_short v[6:7], v2, off
	v_bfrev_b32_e32 v2, 0.5
	v_mov_b32_e32 v6, 2
	v_mov_b32_e32 v7, 3
	v_mov_b32_e32 v8, 0x7fffff00
	v_mov_b32_e32 v9, 0x7fffff00
	v_mov_b32_e32 v12, 3
	v_mov_b32_e32 v13, 2
	v_bfrev_b32_e32 v14, 0.5
	s_and_saveexec_b64 s[6:7], s[2:3]
	v_mov_b32_e32 v14, 0xfc0
	v_mov_b32_e32 v13, 6
	v_mov_b32_e32 v12, 63
	v_mov_b32_e32 v9, 0xfffff000
	s_or_b64 exec, exec, s[6:7]
	v_lshlrev_b32_e32 v13, v13, v22
	v_and_b32_e32 v9, v9, v1
	v_and_b32_e32 v12, v12, v76
	v_and_b32_e32 v13, v13, v14
	v_or3_b32 v12, v12, v9, v13
	v_ashrrev_i32_e32 v13, 31, v12
	v_lshlrev_b64 v[12:13], 10, v[12:13]
	v_lshl_add_u64 v[12:13], s[0:1], 0, v[12:13]
	v_lshl_add_u64 v[12:13], v[12:13], 0, v[56:57]
	v_mov_b32_e32 v9, v155
	v_add_f32_e32 v3, v3, v54
	v_lshl_add_u64 v[10:11], v[10:11], 0, v[56:57]
	v_add_f32_e32 v4, v4, v54
	v_lshlrev_b32_e32 v9, 16, v9
	v_mul_f32_e32 v14, 0xbfb8aa3b, v9
	v_exp_f32_e32 v14, v14
	s_nop 0
	v_add_f32_e32 v14, 1.0, v14
	v_div_scale_f32 v15, s[2:3], v14, v14, v9
	v_rcp_f32_e32 v17, v15
	v_div_scale_f32 v18, vcc, v9, v14, v9
	v_fma_f32 v19, -v15, v17, 1.0
	v_fmac_f32_e32 v17, v19, v17
	v_mul_f32_e32 v19, v18, v17
	v_fma_f32 v20, -v15, v19, v18
	v_fmac_f32_e32 v19, v20, v17
	v_fma_f32 v15, -v15, v19, v18
	v_div_fmas_f32 v15, v15, v17, v19
	v_div_fixup_f32 v9, v15, v14, v9
	v_mul_f32_e32 v3, v3, v9
	v_cvt_pk_bf16_f32 v3, v3, s0
	global_store_short v[12:13], v3, off
	v_mov_b32_e32 v3, v152
	v_lshlrev_b32_e32 v3, 16, v3
	v_mul_f32_e32 v9, 0xbfb8aa3b, v3
	v_exp_f32_e32 v9, v9
	s_nop 0
	v_add_f32_e32 v9, 1.0, v9
	v_div_scale_f32 v12, s[2:3], v9, v9, v3
	v_rcp_f32_e32 v13, v12
	v_div_scale_f32 v14, vcc, v3, v9, v3
	v_fma_f32 v15, -v12, v13, 1.0
	v_fmac_f32_e32 v13, v15, v13
	v_mul_f32_e32 v15, v14, v13
	v_fma_f32 v17, -v12, v15, v14
	v_fmac_f32_e32 v15, v17, v13
	v_fma_f32 v12, -v12, v15, v14
	v_div_fmas_f32 v12, v12, v13, v15
	v_div_fixup_f32 v3, v12, v9, v3
	v_mul_f32_e32 v3, v4, v3
	v_cvt_pk_bf16_f32 v3, v3, s0
	global_store_short v[10:11], v3, off
	s_and_saveexec_b64 s[2:3], s[4:5]
	v_mov_b32_e32 v2, 0xfc0
	v_mov_b32_e32 v6, 6
	v_mov_b32_e32 v7, 63
	v_mov_b32_e32 v8, 0xfffff000
	s_or_b64 exec, exec, s[2:3]
	v_lshlrev_b32_e32 v4, v6, v16
	v_and_b32_e32 v1, v8, v1
	v_and_b32_e32 v3, v7, v76
	v_and_b32_e32 v2, v4, v2
	v_or3_b32 v2, v3, v1, v2
	v_ashrrev_i32_e32 v3, 31, v2
	v_lshlrev_b64 v[2:3], 10, v[2:3]
	v_lshl_add_u64 v[2:3], s[0:1], 0, v[2:3]
	v_mov_b32_e32 v57, v131
	v_lshl_add_u64 v[2:3], v[2:3], 0, v[56:57]
	v_mov_b32_e32 v1, v100
	v_mov_b32_e32 v134, v5
	v_lshlrev_b32_e32 v1, 16, v1
	v_mul_f32_e32 v4, 0xbfb8aa3b, v1
	v_exp_f32_e32 v55, v4
	s_nop 0
	v_pk_add_f32 v[4:5], v[134:135], v[54:55]
	s_nop 0
	v_div_scale_f32 v6, s[2:3], v5, v5, v1
	v_rcp_f32_e32 v7, v6
	v_div_scale_f32 v8, vcc, v1, v5, v1
	v_fma_f32 v9, -v6, v7, 1.0
	v_fmac_f32_e32 v7, v9, v7
	v_mul_f32_e32 v9, v8, v7
	v_fma_f32 v10, -v6, v9, v8
	v_fmac_f32_e32 v9, v10, v7
	v_fma_f32 v6, -v6, v9, v8
	v_div_fmas_f32 v6, v6, v7, v9
	v_div_fixup_f32 v1, v6, v5, v1
	v_mul_f32_e32 v1, v4, v1
	v_cvt_pk_bf16_f32 v1, v1, s0
	global_store_short v[2:3], v1, off
